# GEMM K loops: per-phase s_setprio flips removed, one static s_setprio 1 for waves 4-7 per GEMM phase
# baseline (speedup 1.0000x reference)
; __device__ __forceinline__ void xcd_barrier(const XcdBarrier& b) {
;     asm volatile("s_waitcnt vmcnt(0)" ::: "memory");
;     __syncthreads();
;     if (threadIdx.x == 0) {
;         unsigned* bar = b.bar;
;         __builtin_amdgcn_s_waitcnt(0);
;         unsigned nloc = b.st[0], nx = b.st[1];
;         if (nloc == 0u) { xcd_barrier_complete(bar, b.x, nloc, nx); b.st[0] = nloc; b.st[1] = nx; }
.LBB0_39:
	s_setprio 0
	s_waitcnt vmcnt(0)
	s_barrier
	s_and_saveexec_b64 s[2:3], s[6:7]
	s_xor_b64 s[2:3], exec, s[2:3]
	s_lshl_b32 s8, s0, 6
	s_mov_b32 s9, 0
	s_or_saveexec_b64 s[2:3], s[2:3]
	v_mov_b64_e32 v[0:1], s[8:9]
	s_xor_b64 exec, exec, s[2:3]
	s_cbranch_execz .LBB0_94
	s_add_i32 s5, 0, 0x26000
	v_mov_b32_e32 v0, s5
	s_waitcnt vmcnt(0) expcnt(0) lgkmcnt(0)
	ds_read_b32 v2, v0
	s_add_i32 s5, 0, 0x26004
	v_mov_b32_e32 v0, s5
	ds_read_b32 v0, v0
	s_waitcnt lgkmcnt(1)
	v_cmp_ne_u32_e32 vcc, 0, v2
	s_cbranch_vccnz .LBB0_57
	s_add_u32 s6, s36, 0x1000
	s_addc_u32 s7, s37, 0
	s_add_u32 s8, s36, 0x1100
	s_addc_u32 s9, s37, 0
	s_add_u32 s10, s36, 0x1200
	s_addc_u32 s11, s37, 0
	s_mul_i32 s5, s39, s1
	s_add_u32 s12, s36, 0x1300
	s_mul_i32 s5, s5, s38
	s_addc_u32 s13, s37, 0
	s_mov_b32 s20, 1
	v_mov_b32_e32 v16, 0
	s_branch .LBB0_45

; #define REP(k) for (int rep_ = 0; rep_ < (((REPMASK) >> (k)) & 1) + 1; ++rep_)
; __device__ __forceinline__ void ph_normmod(const P& p, const float* srclat, const float* srcctx, int rows, int l, int idx, int gw, int ngw, int lane) {
;     const float* mod = (const float*)(p.ws + WS_MOD) + (size_t)l * 9 * 9216;
;     const float* g = p.norm_g + (l * 3 + idx) * DM;
;     bf16_t* A = (bf16_t*)(p.ws + WS_A);
;     for (int m = gw; m < rows; m += ngw) {
;         const float* src = m < MLAT ? srclat + (size_t)m * DM : srcctx + (size_t)(m - MLAT) * DM;
;         const int mr = m < MLAT ? (m >> 11) : 8;
;         const float* sh = mod + mr * 9216 + (3 * idx) * DM; const float* sc = sh + DM;
; __global__ void __launch_bounds__(NTHREADS) mega_fwd(P p) {
;     ...
;     for (int l = 0; l < 2; ++l) {
;         for (int stg = 0; stg < 3; ++stg) {
;             const bool first = (l == 0 && stg == 0);
;             const int cs = l * 3 + stg;
;             const int rows = (l == 1 && stg == 2) ? MLAT : MALL;
;             PH();
;             if (RUN(1)) REP(1) ph_normmod(q, first ? q.x : HLAT, first ? q.ctx : HCTX, rows, l, stg, gw, ngw, lane);
.LBB0_99:
	v_readlane_b32 s3, v254, 51
	s_or_b32 s2, s24, s3
	s_cmp_eq_u32 s2, 0
	s_cselect_b64 s[6:7], -1, 0
	s_mul_i32 s2, s3, 3
	v_writelane_b32 v255, s6, 2
	s_add_i32 s2, s24, s2
	s_cmp_eq_u32 s24, 2
	v_writelane_b32 v255, s7, 3
	v_readlane_b32 s6, v254, 52
	v_writelane_b32 v255, s2, 4
	s_cselect_b64 s[2:3], -1, 0
	v_readlane_b32 s7, v254, 53
	s_and_b64 s[2:3], s[6:7], s[2:3]
	s_and_b64 s[2:3], s[2:3], exec
	v_mov_b32_e32 v144, v146
	v_mov_b32_e32 v0, v1
	s_cselect_b32 s42, s22, 0x4800
	v_readfirstlane_b32 s2, v144
	s_ashr_i32 s2, s2, 6
	v_readlane_b32 s6, v253, 2
	s_add_i32 s2, s2, s6
	v_writelane_b32 v255, s24, 5
	s_mul_i32 s6, s24, 0xc00
	s_mov_b32 s7, s65
	v_writelane_b32 v255, s6, 6
	v_readfirstlane_b32 s3, v0
	s_cmp_lt_i32 s2, s42
	v_writelane_b32 v255, s7, 7
	v_cmp_lt_i32_e64 s[6:7], v188, v186
	v_cmp_lt_i32_e32 vcc, v187, v186
	s_cbranch_scc0 .LBB0_104
	s_load_dwordx4 s[8:11], s[92:93], s3 offset:0xa0
	s_load_dwordx2 s[12:13], s[92:93], s3 offset:0x0
	s_load_dwordx2 s[16:17], s[92:93], s3 offset:0x10
	s_load_dwordx2 s[18:19], s[92:93], s3 offset:0x30
	v_readlane_b32 s24, v255, 2
	v_readlane_b32 s25, v255, 3
	s_and_b64 s[14:15], s[24:25], exec
	s_waitcnt lgkmcnt(0)
	s_cselect_b32 s20, s13, s9
	s_cselect_b32 s21, s12, s8
	s_add_u32 s3, s10, 0x5300000
	s_addc_u32 s12, s11, 0
	s_and_b64 s[8:9], s[24:25], exec
	s_cselect_b32 s15, s16, s3
	v_readlane_b32 s3, v255, 4
	s_cselect_b32 s14, s17, s12
	s_lshl_b32 s64, s3, 10
	s_lshl_b64 s[8:9], s[64:65], 2
	v_lshlrev_b32_e32 v0, 2, v144
	s_add_u32 s8, s18, s8
	v_readlane_b32 s12, v254, 63
	v_and_b32_e32 v2, 0xfc, v0
	s_addc_u32 s9, s19, s9
	v_readlane_b32 s13, v255, 0
	v_lshlrev_b32_e32 v0, 2, v2
	s_lshl_b64 s[12:13], s[12:13], 2
	v_lshl_add_u64 v[10:11], s[8:9], 0, v[0:1]
	v_cmp_lt_i32_e64 s[8:9], v192, v186
	s_add_u32 s3, s10, s12
	s_addc_u32 s16, s11, s13
	v_cndmask_b32_e64 v0, v185, v192, s[8:9]
	v_cmp_lt_i32_e64 s[8:9], v191, v186
	v_readlane_b32 s12, v255, 6
	v_lshlrev_b32_e32 v14, 2, v0
	v_cndmask_b32_e64 v0, v185, v191, s[8:9]
	v_cmp_lt_i32_e64 s[8:9], v190, v186
	v_readlane_b32 s13, v255, 7
	v_lshlrev_b32_e32 v15, 2, v0
	v_cndmask_b32_e64 v0, v185, v190, s[8:9]
	v_cmp_lt_i32_e64 s[8:9], v189, v186
	s_lshl_b64 s[12:13], s[12:13], 2
	v_lshlrev_b32_e32 v16, 2, v0
	v_cndmask_b32_e64 v0, v185, v189, s[8:9]
	s_add_u32 s3, s3, s12
	v_lshlrev_b32_e32 v17, 2, v0
	v_cndmask_b32_e64 v0, v185, v188, s[6:7]
	s_addc_u32 s12, s16, s13
	v_lshlrev_b32_e32 v18, 2, v0
	v_cndmask_b32_e32 v0, v185, v187, vcc
	s_add_u32 s16, s3, 0x100000
	v_lshlrev_b32_e32 v19, 2, v0
	v_lshlrev_b32_e32 v0, 1, v2
	s_addc_u32 s17, s12, 0
	v_lshl_add_u64 v[12:13], s[10:11], 0, v[0:1]
	s_mov_b64 s[6:7], 0x5b00000
	s_ashr_i32 s3, s2, 31
	v_lshl_add_u64 v[12:13], v[12:13], 0, s[6:7]
	s_lshl_b64 s[6:7], s[2:3], 12
	v_or_b32_e32 v4, 0x100, v2
	v_or_b32_e32 v6, 0x200, v2
	v_or_b32_e32 v8, 0x300, v2
	s_add_u32 s8, s21, s6
	s_addc_u32 s9, s20, s7
	v_lshlrev_b32_e32 v0, 2, v2
	v_lshlrev_b32_e32 v20, 2, v4
	v_lshlrev_b32_e32 v21, 2, v6
	v_lshlrev_b32_e32 v22, 2, v8
	s_branch .LBB0_102
	s_nop 0
	s_nop 0
	s_nop 0
	s_nop 0
	s_nop 0
	s_nop 0
	s_nop 0
	s_nop 0
	s_nop 0
	s_nop 0
	s_nop 0
	s_nop 0
	s_nop 0
	s_nop 0
	s_nop 0

; __device__ __forceinline__ void xcd_barrier(const XcdBarrier& b) {
;     asm volatile("s_waitcnt vmcnt(0)" ::: "memory");
;     __syncthreads();
;     if (threadIdx.x == 0) {
;         unsigned* bar = b.bar;
;         __builtin_amdgcn_s_waitcnt(0);
;         unsigned nloc = b.st[0], nx = b.st[1];
;         if (nloc == 0u) { xcd_barrier_complete(bar, b.x, nloc, nx); b.st[0] = nloc; b.st[1] = nx; }
.LBB0_104:
	s_setprio 0
	s_waitcnt vmcnt(0)
	s_barrier
	s_mov_b64 s[2:3], exec
	v_readlane_b32 s6, v253, 0
	v_readlane_b32 s7, v253, 1
	s_and_b64 s[6:7], s[2:3], s[6:7]
	s_xor_b64 s[2:3], s[6:7], s[2:3]
	s_mov_b64 exec, s[6:7]
	s_cbranch_execz .LBB0_153
	v_mov_b32_e32 v0, s96
	s_waitcnt vmcnt(0) expcnt(0) lgkmcnt(0)
	ds_read_b32 v3, v0
	v_readlane_b32 s6, v254, 42
	s_waitcnt lgkmcnt(0)
	v_cmp_ne_u32_e32 vcc, 0, v3
	v_mov_b32_e32 v0, s6
	ds_read_b32 v2, v0
	s_cbranch_vccnz .LBB0_120
	s_mov_b32 s12, 1
	s_branch .LBB0_108

; template <class Epi, class Sched, bool ALIGN_EPI = false, bool SP2 = false>
; __device__ __forceinline__ void gemm_phase(PG8_LAS unsigned char* lds, const Gemm g, const Sched& S, const Epi& E) {
;     ...
;     const int tid = tid_l, wid = __builtin_amdgcn_readfirstlane(tid >> 6), lane = tid & 63, wr = wid >> 2, wc = wid & 3, fr = lane & 15, fq = lane >> 4;
;     const int K = g.K, nt = K / BK;
;     unsigned voffA[2], voffB[2];
; #pragma unroll
;     for (int i = 0; i < 2; ++i) { int R, C; stage_rc(tid * 16 + i * 8192, R, C); const int Rb = Epi::PERM ? ((R & ~31) + perm32(R & 31)) : R;
;         voffA[i] = (unsigned)(R * K + C) * 2u; voffB[i] = (unsigned)(Rb * K + C) * 2u; }
;     const size_t kstep = (size_t)(BK * 2);
;     const size_t hstep = (size_t)HALF * K * 2;
;     const size_t tstep = 2 * hstep;
;     const unsigned ldsw = (unsigned)wid * 1024u;
;     const int aoff = lds_byte(wr * 64 + fr, fq * 8), boff = lds_byte(wc * 32 + fr, fq * 8);
;     ...
;     Unit cur, nxt; int ui = 0;
;     if (!S.next(0, cur)) return;
;     f32x4 acc[2][2][4][2];
; #pragma unroll
;     for (int a = 0; a < 2; ++a)
; #pragma unroll
;         for (int b = 0; b < 2; ++b)
; #pragma unroll
;             for (int m = 0; m < 4; ++m)
; #pragma unroll
;                 for (int n = 0; n < 2; ++n) acc[a][b][m][n] = (f32x4){0.f, 0.f, 0.f, 0.f};
;     bf16x8 At[4][2], B0[2][2], B1[2][2];
;     const char* cA = (const char*)g.A + (size_t)cur.pm * tstep; const char* cB = (const char*)g.Bt + (size_t)cur.pn * tstep;
;     S.a_ready(cur);
;     if constexpr (SP2) {
;         PG8_STAGE(PG8_SB(0, 0), cB, voffB); PG8_STAGE(PG8_SB(0, 1), cB + hstep, voffB); PG8_STAGE(PG8_SA(0, 0), cA, voffA); PG8_STAGE(PG8_SA(0, 1), cA + hstep, voffA);
;         if (wr == 1) PG8_BAR;
;         PG8_WAIT_V(2); PG8_BAR;
;         PG8_STAGE(PG8_SB(1, 0), cB + kstep, voffB); PG8_STAGE(PG8_SA(1, 0), cA + kstep, voffA); PG8_STAGE(PG8_SB(1, 1), cB + hstep + kstep, voffB);
; __global__ void __launch_bounds__(NTHREADS) mega_fwd(P p) {
;     ...
;                     pg8::Gemm gm{ABUF, (const bf16_t*)(q.ws + WS_WUP) + (size_t)(l * 2 + f) * 2 * DFF * DM, rows, 2 * DFF, DM};
;                     pg8::StaticOrder S; S.init(rows, 2 * DFF, G, (int)blockIdx.x);
;                     EpiSwiglu E{(bf16_t*)(q.ws + WS_ACT)};
;                     if (RUN(2)) REP(2) pg8::gemm_phase<EpiSwiglu, pg8::StaticOrder, true, true>(LDSL, gm, S, E);
.LBB0_153:
	s_or_b64 exec, exec, s[2:3]
	v_readlane_b32 s2, v255, 5
	s_cmp_lg_u32 s2, 1
	s_mov_b64 s[2:3], -1
	s_waitcnt lgkmcnt(0)
	s_barrier
	s_cbranch_scc0 .LBB0_172
	v_mov_b32_e32 v146, v144
	v_mov_b32_e32 v0, v1
	v_readlane_b32 s2, v255, 5
	s_lshr_b32 s43, s2, 1
	v_readfirstlane_b32 s6, v0
	s_load_dwordx2 s[2:3], s[92:93], s6 offset:0x40
	s_load_dwordx2 s[8:9], s[92:93], s6 offset:0xa8
	v_readlane_b32 s6, v255, 1
	s_lshr_b32 s45, s42, 8
	s_add_i32 s43, s43, s6
	s_mul_i32 s10, s45, 22
	v_mov_b32_e32 v10, v184
	v_readfirstlane_b32 s44, v146
	s_cmp_ge_i32 s90, s10
	s_nop 0
	v_readfirstlane_b32 s6, v10
	s_cbranch_scc1 .LBB0_170
	v_lshlrev_b32_e32 v2, 4, v10
	v_add_u32_e32 v3, 0x2000, v2
	v_ashrrev_i32_e32 v0, 31, v3
	v_lshrrev_b32_e32 v0, 22, v0
	v_add_u32_e32 v0, v3, v0
	v_ashrrev_i32_e32 v0, 10, v0
	v_mul_i32_i24_e32 v5, 0x400, v0
	v_sub_u32_e32 v3, v3, v5
	v_lshrrev_b32_e32 v5, 4, v3
	v_bitop3_b32 v3, v5, v3, 32 bitop3:0x6c
	v_ashrrev_i32_e32 v5, 31, v3
	v_lshrrev_b32_e32 v5, 26, v5
	v_add_u32_e32 v5, v3, v5
	v_ashrrev_i32_e32 v11, 6, v5
	v_and_b32_e32 v5, 0xc0, v5
	v_sub_u32_e32 v3, v3, v5
	s_waitcnt lgkmcnt(0)
	s_add_u32 s46, s8, 0x5b00000
	v_lshlrev_b32_e32 v4, 5, v0
	v_ashrrev_i16_sdwa v3, v196, sext(v3) dst_sel:DWORD dst_unused:UNUSED_PAD src0_sel:DWORD src1_sel:BYTE_0
	s_addc_u32 s47, s9, 0
	s_mul_i32 s12, s43, 0xb00000
	v_and_b32_e32 v4, 32, v4
	v_bfe_i32 v12, v3, 0, 16
	s_mul_hi_u32 s7, s43, 0xb00000
	s_add_u32 s12, s8, s12
	v_add_u32_e32 v3, v4, v12
	v_lshlrev_b32_e32 v4, 3, v0
	s_addc_u32 s7, s9, s7
	v_and_b32_e32 v4, 0x1ffff0, v4
	s_add_u32 s48, s12, 0x200000
	v_add_lshl_u32 v4, v11, v4, 11
	s_addc_u32 s49, s7, 0
	s_lshr_b32 s76, s10, 3
	s_ashr_i32 s16, s6, 6
	v_lshl_add_u32 v130, v3, 1, v4
	v_bfe_i32 v4, v10, 27, 1
	v_readlane_b32 s12, v254, 2
	s_or_b32 s77, s76, 1
	s_ashr_i32 s7, s6, 8
	s_lshl_b32 s80, s16, 10
	v_lshrrev_b32_e32 v4, 22, v4
	v_readlane_b32 s13, v254, 3
	v_add_u32_e32 v4, v2, v4
	s_and_b64 s[12:13], s[12:13], exec
	v_and_b32_e32 v4, 0xfffffc00, v4
	s_cselect_b32 s12, s77, s76
	v_readlane_b32 s13, v254, 4
	v_sub_u32_e32 v2, v2, v4
	s_mul_i32 s12, s12, s13
	v_readlane_b32 s13, v254, 5
	v_lshrrev_b32_e32 v4, 4, v2
	s_add_i32 s12, s12, s13
	v_bitop3_b32 v2, v4, v2, 32 bitop3:0x6c
	s_mul_hi_i32 s13, s12, 0x2e8ba2e9
	v_ashrrev_i32_e32 v4, 31, v2
	s_lshr_b32 s14, s13, 31
	s_ashr_i32 s13, s13, 4
	v_ashrrev_i32_e32 v3, 31, v10
	v_lshrrev_b32_e32 v4, 26, v4
	s_add_i32 s13, s13, s14
	v_lshrrev_b32_e32 v3, 26, v3
	v_add_u32_e32 v4, v2, v4
	s_lshl_b32 s14, s13, 2
	v_add_u32_e32 v3, v10, v3
	v_ashrrev_i32_e32 v14, 6, v4
	v_and_b32_e32 v4, 0xc0, v4
	s_sub_i32 s15, s45, s14
	v_ashrrev_i32_e32 v13, 6, v3
	v_sub_u32_e32 v2, v2, v4
	s_min_i32 s15, s15, 4
	v_lshlrev_b32_e32 v3, 5, v13
	v_ashrrev_i16_sdwa v2, v196, sext(v2) dst_sel:DWORD dst_unused:UNUSED_PAD src0_sel:DWORD src1_sel:BYTE_0
	s_abs_i32 s17, s15
	v_and_b32_e32 v3, 32, v3
	v_bfe_i32 v15, v2, 0, 16
	v_cvt_f32_u32_e32 v4, s17
	v_add_u32_e32 v2, v3, v15
	v_lshlrev_b32_e32 v3, 3, v13
	v_and_b32_e32 v3, 0x1ffff0, v3
	v_add_lshl_u32 v3, v14, v3, 11
	v_lshl_add_u32 v132, v2, 1, v3
	v_rcp_iflag_f32_e32 v2, v4
	s_sub_i32 s19, 0, s17
	s_mulk_i32 s13, 0x58
	s_sub_i32 s12, s12, s13
	v_mul_f32_e32 v2, 0x4f7ffffe, v2
	v_cvt_u32_f32_e32 v2, v2
	s_abs_i32 s18, s12
	s_xor_b32 s13, s12, s15
	s_ashr_i32 s13, s13, 31
	v_readfirstlane_b32 s20, v2
	s_mul_i32 s19, s19, s20
	s_mul_hi_u32 s19, s20, s19
	s_add_i32 s20, s20, s19
	s_mul_hi_u32 s19, s18, s20
	s_mul_i32 s20, s19, s17
	s_sub_i32 s18, s18, s20
	s_add_i32 s20, s19, 1
	s_sub_i32 s21, s18, s17
	s_cmp_ge_u32 s18, s17
	s_cselect_b32 s19, s20, s19
	s_cselect_b32 s18, s21, s18
	s_add_i32 s20, s19, 1
	s_cmp_ge_u32 s18, s17
	s_cselect_b32 s17, s20, s19
	s_xor_b32 s17, s17, s13
	s_sub_i32 s26, s17, s13
	s_mul_i32 s13, s26, s15
	s_sub_i32 s12, s12, s13
	s_add_i32 s28, s14, s12
	s_ashr_i32 s29, s28, 31
	s_ashr_i32 s27, s26, 31
	s_lshl_b64 s[12:13], s[28:29], 19
	s_lshl_b64 s[14:15], s[26:27], 19
	s_add_u32 s34, s48, s14
	s_addc_u32 s35, s49, s15
	s_add_i32 s29, s80, 0
	s_add_i32 m0, s29, 0x10000
	v_mov_b32_e32 v133, v1
	global_load_lds_dwordx4 v132, s[34:35]
	s_add_i32 m0, s29, 0x12000
	s_add_u32 s14, s34, 0x40000
	global_load_lds_dwordx4 v130, s[34:35]
	s_addc_u32 s15, s35, 0
	s_add_i32 m0, s29, 0x14000
	v_mov_b32_e32 v131, v1
	global_load_lds_dwordx4 v132, s[14:15]
	s_add_i32 m0, s29, 0x16000
	s_add_u32 s30, s46, s12
	s_addc_u32 s31, s47, s13
	s_add_i32 s81, s29, 0x2000
	global_load_lds_dwordx4 v130, s[14:15]
	s_mov_b32 m0, s29
	s_add_u32 s12, s30, 0x40000
	global_load_lds_dwordx4 v132, s[30:31]
	s_mov_b32 m0, s81
	s_addc_u32 s13, s31, 0
	s_add_i32 s82, s29, 0x4000
	global_load_lds_dwordx4 v130, s[30:31]
	s_mov_b32 m0, s82
	s_add_i32 s83, s29, 0x6000
	global_load_lds_dwordx4 v132, s[12:13]
	s_mov_b32 m0, s83
	s_cmp_eq_u32 s7, 1
	global_load_lds_dwordx4 v130, s[12:13]
	s_mov_b32 s11, s65
	v_lshl_add_u64 v[8:9], s[34:35], 0, v[132:133]
	v_lshl_add_u64 v[6:7], s[34:35], 0, v[130:131]
	v_lshl_add_u64 v[2:3], s[30:31], 0, v[132:133]
	s_cselect_b64 s[12:13], -1, 0
	s_cmp_lg_u32 s7, 1
	v_lshl_add_u64 v[4:5], s[30:31], 0, v[130:131]
	s_cbranch_scc1 .LBB0_157
	s_barrier
	s_setprio 1

; #define PG8_STAGE(bufoff, gbase, voff) do { _Pragma("unroll") for (int _i = 0; _i < 2; ++_i) \
;         __builtin_amdgcn_global_load_lds((const unsigned*)((const char*)(gbase) + (voff)[_i]), (PG8_LAS unsigned*)(lds + (bufoff) + ldsw + _i * 8192), 16, 0, 0); } while (0)
; #define PG8_LDA(dst, b, h) do { _Pragma("unroll") for (int m = 0; m < 4; ++m) _Pragma("unroll") for (int k = 0; k < 2; ++k) dst[m][k] = *(const PG8_LAS bf16x8*)(lds + PG8_SA(b, h) + aoff + m * 2048 + k * 1024); } while (0)
; #define PG8_LDB(dst, b, h) do { _Pragma("unroll") for (int n = 0; n < 2; ++n) _Pragma("unroll") for (int k = 0; k < 2; ++k) dst[n][k] = *(const PG8_LAS bf16x8*)(lds + PG8_SB(b, h) + boff + n * 2048 + k * 1024); } while (0)
; #define PG8_MMA(ai, bj, At, Bt) do { __builtin_amdgcn_s_setprio(1); _Pragma("unroll") for (int m = 0; m < 4; ++m) _Pragma("unroll") for (int n = 0; n < 2; ++n) _Pragma("unroll") for (int k = 0; k < 2; ++k) \
;         acc[ai][bj][m][n] = __builtin_amdgcn_mfma_f32_16x16x32_bf16(Bt[n][k], At[m][k], acc[ai][bj][m][n], 0, 0, 0); __builtin_amdgcn_s_setprio(0); } while (0)
; #define PG8_WAIT_V(n) asm volatile("s_waitcnt vmcnt(" #n ")" ::: "memory")
; #define PG8_WAIT_L(n) asm volatile("s_waitcnt lgkmcnt(" #n ")" ::: "memory")
; #define PG8_BAR __builtin_amdgcn_s_barrier()
; #define PG8_SCHED __builtin_amdgcn_sched_barrier(0)
; template <class Epi, class Sched, bool ALIGN_EPI = false, bool SP2 = false>
; __device__ __forceinline__ void gemm_phase(PG8_LAS unsigned char* lds, const Gemm g, const Sched& S, const Epi& E) {
;     ...
;             PG8_LDB(B0, 0, 0); PG8_LDB(B1, 0, 1); PG8_SCHED; PG8_LDA(At, 0, 0); PG8_STAGE(PG8_SA(1, 1), a1 + hstep, voffA);
;             PG8_WAIT_V(8); PG8_WAIT_L(0); PG8_BAR; PG8_MMA(0, 0, At, B0); PG8_MMA(0, 1, At, B1); PG8_BAR; PG8_SCHED;
.Lpeel_u:
	s_add_u32 s34, s30, 0xfffc0080
	s_addc_u32 s35, s31, -1
	s_add_i32 s71, 0, 0x10000
	s_cmp_eq_u32 s62, 12
	s_cselect_b32 s41, s21, s35
	s_cselect_b32 s40, s27, s34
	v_add_u32_e32 v155, s71, v145
	s_cselect_b32 s35, s19, s54
	s_cselect_b32 s34, s50, s52
	s_add_i32 s74, 0, 0x14000
	ds_read_b128 v[156:159], v155
	ds_read_b128 v[160:163], v155 offset:1024
	ds_read_b128 v[164:167], v155 offset:2048
	ds_read_b128 v[168:171], v155 offset:3072
	v_add_u32_e32 v155, s74, v145
	ds_read_b128 v[172:175], v155
	ds_read_b128 v[176:179], v155 offset:1024
	ds_read_b128 v[180:183], v155 offset:2048
	ds_read_b128 v[208:211], v155 offset:3072
	v_lshl_add_u64 v[202:203], s[30:31], 0, v[134:135]
	s_add_i32 m0, s29, 0xc000
	ds_read_b128 v[212:215], v154
	ds_read_b128 v[216:219], v154 offset:1024
	ds_read_b128 v[220:223], v154 offset:2048
	ds_read_b128 v[224:227], v154 offset:3072
	ds_read_b128 v[228:231], v154 offset:4096
	ds_read_b128 v[232:235], v154 offset:5120
	ds_read_b128 v[236:239], v154 offset:6144
	ds_read_b128 v[240:243], v154 offset:7168
	global_load_lds_dwordx4 v[202:203], off
	v_lshl_add_u64 v[202:203], s[30:31], 0, v[136:137]
	s_add_i32 m0, s29, 0xe000
	s_nop 0
	global_load_lds_dwordx4 v[202:203], off
	s_waitcnt vmcnt(8)
	s_waitcnt lgkmcnt(0)
	s_barrier
	s_waitcnt lgkmcnt(0)
	v_mfma_f32_16x16x32_bf16 v[126:129], v[156:159], v[212:215], 0
	v_mfma_f32_16x16x32_bf16 v[122:125], v[164:167], v[212:215], 0
	v_mfma_f32_16x16x32_bf16 v[110:113], v[156:159], v[220:223], 0
	v_mfma_f32_16x16x32_bf16 v[106:109], v[164:167], v[220:223], 0
	v_mfma_f32_16x16x32_bf16 v[94:97], v[156:159], v[228:231], 0
	v_mfma_f32_16x16x32_bf16 v[90:93], v[164:167], v[228:231], 0
	v_mfma_f32_16x16x32_bf16 v[78:81], v[156:159], v[236:239], 0
	v_mfma_f32_16x16x32_bf16 v[74:77], v[164:167], v[236:239], 0
	v_mfma_f32_16x16x32_bf16 v[126:129], v[160:163], v[216:219], v[126:129]
	v_mfma_f32_16x16x32_bf16 v[122:125], v[168:171], v[216:219], v[122:125]
	v_mfma_f32_16x16x32_bf16 v[110:113], v[160:163], v[224:227], v[110:113]
	v_mfma_f32_16x16x32_bf16 v[106:109], v[168:171], v[224:227], v[106:109]
	v_mfma_f32_16x16x32_bf16 v[94:97], v[160:163], v[232:235], v[94:97]
	v_mfma_f32_16x16x32_bf16 v[90:93], v[168:171], v[232:235], v[90:93]
	v_mfma_f32_16x16x32_bf16 v[78:81], v[160:163], v[240:243], v[78:81]
	v_mfma_f32_16x16x32_bf16 v[74:77], v[168:171], v[240:243], v[74:77]
	v_mfma_f32_16x16x32_bf16 v[118:121], v[172:175], v[212:215], 0
	v_mfma_f32_16x16x32_bf16 v[114:117], v[180:183], v[212:215], 0
	v_mfma_f32_16x16x32_bf16 v[102:105], v[172:175], v[220:223], 0
	v_mfma_f32_16x16x32_bf16 v[98:101], v[180:183], v[220:223], 0
	v_mfma_f32_16x16x32_bf16 v[86:89], v[172:175], v[228:231], 0
	v_mfma_f32_16x16x32_bf16 v[82:85], v[180:183], v[228:231], 0
	v_mfma_f32_16x16x32_bf16 v[70:73], v[172:175], v[236:239], 0
	v_mfma_f32_16x16x32_bf16 v[66:69], v[180:183], v[236:239], 0
	v_mfma_f32_16x16x32_bf16 v[118:121], v[176:179], v[216:219], v[118:121]
	v_mfma_f32_16x16x32_bf16 v[114:117], v[208:211], v[216:219], v[114:117]
	v_mfma_f32_16x16x32_bf16 v[102:105], v[176:179], v[224:227], v[102:105]
	v_mfma_f32_16x16x32_bf16 v[98:101], v[208:211], v[224:227], v[98:101]
	v_mfma_f32_16x16x32_bf16 v[86:89], v[176:179], v[232:235], v[86:89]
	v_mfma_f32_16x16x32_bf16 v[82:85], v[208:211], v[232:235], v[82:85]
	v_mfma_f32_16x16x32_bf16 v[70:73], v[176:179], v[240:243], v[70:73]
	v_mfma_f32_16x16x32_bf16 v[66:69], v[208:211], v[240:243], v[66:69]
	s_barrier
	s_add_i32 s71, s71, s80
	v_lshl_add_u64 v[202:203], s[34:35], 0, v[132:133]
	s_mov_b32 m0, s71
	ds_read_b128 v[212:215], v154 offset:16384
	ds_read_b128 v[216:219], v154 offset:17408
	ds_read_b128 v[220:223], v154 offset:18432
	ds_read_b128 v[224:227], v154 offset:19456
	ds_read_b128 v[228:231], v154 offset:20480
	ds_read_b128 v[232:235], v154 offset:21504
	ds_read_b128 v[236:239], v154 offset:22528
	ds_read_b128 v[240:243], v154 offset:23552
	global_load_lds_dwordx4 v[202:203], off
	s_add_i32 m0, s71, 0x2000
	s_add_u32 s72, s34, 0x40000
	v_lshl_add_u64 v[204:205], s[34:35], 0, v[130:131]
	s_addc_u32 s73, s35, 0
	s_add_i32 s71, s74, s80
	global_load_lds_dwordx4 v[204:205], off
	v_lshl_add_u64 v[244:245], s[72:73], 0, v[132:133]
	s_mov_b32 m0, s71
	v_lshl_add_u64 v[246:247], s[40:41], 0, v[130:131]
	global_load_lds_dwordx4 v[244:245], off
	v_lshl_add_u64 v[244:245], s[72:73], 0, v[130:131]
	s_add_i32 m0, s71, 0x2000
	s_nop 0
	global_load_lds_dwordx4 v[244:245], off
	v_lshl_add_u64 v[244:245], s[40:41], 0, v[132:133]
	s_mov_b32 m0, s29
	s_nop 0
	global_load_lds_dwordx4 v[244:245], off
	s_mov_b32 m0, s81
	s_nop 0
	global_load_lds_dwordx4 v[246:247], off
	s_waitcnt vmcnt(8)
	s_waitcnt lgkmcnt(0)
	s_barrier
; #define PG8_STAGE(bufoff, gbase, voff) do { _Pragma("unroll") for (int _i = 0; _i < 2; ++_i) \
;         __builtin_amdgcn_global_load_lds((const unsigned*)((const char*)(gbase) + (voff)[_i]), (PG8_LAS unsigned*)(lds + (bufoff) + ldsw + _i * 8192), 16, 0, 0); } while (0)
; #define PG8_LDA(dst, b, h) do { _Pragma("unroll") for (int m = 0; m < 4; ++m) _Pragma("unroll") for (int k = 0; k < 2; ++k) dst[m][k] = *(const PG8_LAS bf16x8*)(lds + PG8_SA(b, h) + aoff + m * 2048 + k * 1024); } while (0)
; #define PG8_LDB(dst, b, h) do { _Pragma("unroll") for (int n = 0; n < 2; ++n) _Pragma("unroll") for (int k = 0; k < 2; ++k) dst[n][k] = *(const PG8_LAS bf16x8*)(lds + PG8_SB(b, h) + boff + n * 2048 + k * 1024); } while (0)
; #define PG8_MMA(ai, bj, At, Bt) do { __builtin_amdgcn_s_setprio(1); _Pragma("unroll") for (int m = 0; m < 4; ++m) _Pragma("unroll") for (int n = 0; n < 2; ++n) _Pragma("unroll") for (int k = 0; k < 2; ++k) \
;         acc[ai][bj][m][n] = __builtin_amdgcn_mfma_f32_16x16x32_bf16(Bt[n][k], At[m][k], acc[ai][bj][m][n], 0, 0, 0); __builtin_amdgcn_s_setprio(0); } while (0)
; #define PG8_WAIT_V(n) asm volatile("s_waitcnt vmcnt(" #n ")" ::: "memory")
; #define PG8_WAIT_L(n) asm volatile("s_waitcnt lgkmcnt(" #n ")" ::: "memory")
; #define PG8_BAR __builtin_amdgcn_s_barrier()
; #define PG8_SCHED __builtin_amdgcn_sched_barrier(0)
; template <class Epi, class Sched, bool ALIGN_EPI = false, bool SP2 = false>
; __device__ __forceinline__ void gemm_phase(PG8_LAS unsigned char* lds, const Gemm g, const Sched& S, const Epi& E) {
;     ...
;             PG8_WAIT_V(8); PG8_WAIT_L(0); PG8_BAR; PG8_MMA(0, 0, At, B0); PG8_MMA(0, 1, At, B1); PG8_BAR; PG8_SCHED;
;             PG8_LDA(At, 0, 1); PG8_STAGE(PG8_SB(0, 0), b2, voffB); PG8_STAGE(PG8_SB(0, 1), b2 + hstep, voffB); PG8_STAGE(PG8_SA(0, 0), a2, voffA);
;             PG8_WAIT_V(8); PG8_WAIT_L(0); PG8_BAR; PG8_MMA(1, 0, At, B0); PG8_MMA(1, 1, At, B1); PG8_BAR; PG8_SCHED;
;             PG8_LDB(B0, 1, 0); PG8_LDB(B1, 1, 1); PG8_SCHED; PG8_LDA(At, 1, 0); PG8_STAGE(PG8_SA(0, 1), a2 + hstep, voffA);
;             PG8_WAIT_V(8); PG8_WAIT_L(0); PG8_BAR; PG8_MMA(0, 0, At, B0); PG8_MMA(0, 1, At, B1); PG8_BAR; PG8_SCHED;
	s_waitcnt lgkmcnt(0)
	v_mfma_f32_16x16x32_bf16 v[62:65], v[156:159], v[212:215], 0
	v_mfma_f32_16x16x32_bf16 v[58:61], v[164:167], v[212:215], 0
	v_mfma_f32_16x16x32_bf16 v[46:49], v[156:159], v[220:223], 0
	v_mfma_f32_16x16x32_bf16 v[42:45], v[164:167], v[220:223], 0
	v_mfma_f32_16x16x32_bf16 v[30:33], v[156:159], v[228:231], 0
	v_mfma_f32_16x16x32_bf16 v[26:29], v[164:167], v[228:231], 0
	v_mfma_f32_16x16x32_bf16 v[14:17], v[156:159], v[236:239], 0
	v_mfma_f32_16x16x32_bf16 v[10:13], v[164:167], v[236:239], 0
	v_mfma_f32_16x16x32_bf16 v[62:65], v[160:163], v[216:219], v[62:65]
	v_mfma_f32_16x16x32_bf16 v[58:61], v[168:171], v[216:219], v[58:61]
	v_mfma_f32_16x16x32_bf16 v[46:49], v[160:163], v[224:227], v[46:49]
	v_mfma_f32_16x16x32_bf16 v[42:45], v[168:171], v[224:227], v[42:45]
	v_mfma_f32_16x16x32_bf16 v[30:33], v[160:163], v[232:235], v[30:33]
	v_mfma_f32_16x16x32_bf16 v[26:29], v[168:171], v[232:235], v[26:29]
	v_mfma_f32_16x16x32_bf16 v[14:17], v[160:163], v[240:243], v[14:17]
	v_mfma_f32_16x16x32_bf16 v[10:13], v[168:171], v[240:243], v[10:13]
	v_mfma_f32_16x16x32_bf16 v[54:57], v[172:175], v[212:215], 0
	v_mfma_f32_16x16x32_bf16 v[50:53], v[180:183], v[212:215], 0
	v_mfma_f32_16x16x32_bf16 v[38:41], v[172:175], v[220:223], 0
	v_mfma_f32_16x16x32_bf16 v[34:37], v[180:183], v[220:223], 0
	v_mfma_f32_16x16x32_bf16 v[22:25], v[172:175], v[228:231], 0
	v_mfma_f32_16x16x32_bf16 v[18:21], v[180:183], v[228:231], 0
	v_mfma_f32_16x16x32_bf16 v[6:9], v[172:175], v[236:239], 0
	v_mfma_f32_16x16x32_bf16 v[2:5], v[180:183], v[236:239], 0
	v_mfma_f32_16x16x32_bf16 v[54:57], v[176:179], v[216:219], v[54:57]
	v_mfma_f32_16x16x32_bf16 v[50:53], v[208:211], v[216:219], v[50:53]
	v_mfma_f32_16x16x32_bf16 v[38:41], v[176:179], v[224:227], v[38:41]
	v_mfma_f32_16x16x32_bf16 v[34:37], v[208:211], v[224:227], v[34:37]
	v_mfma_f32_16x16x32_bf16 v[22:25], v[176:179], v[232:235], v[22:25]
	v_mfma_f32_16x16x32_bf16 v[18:21], v[208:211], v[232:235], v[18:21]
	v_mfma_f32_16x16x32_bf16 v[6:9], v[176:179], v[240:243], v[6:9]
	v_mfma_f32_16x16x32_bf16 v[2:5], v[208:211], v[240:243], v[2:5]
	s_barrier
	s_add_i32 s71, 0, 0x18000
	v_add_u32_e32 v155, s71, v145
	s_add_i32 s72, 0, 0x1c000
	ds_read_b128 v[156:159], v155
	ds_read_b128 v[160:163], v155 offset:1024
	ds_read_b128 v[164:167], v155 offset:2048
	ds_read_b128 v[168:171], v155 offset:3072
	v_add_u32_e32 v155, s72, v145
	ds_read_b128 v[172:175], v155
	ds_read_b128 v[176:179], v155 offset:1024
	ds_read_b128 v[180:183], v155 offset:2048
	ds_read_b128 v[208:211], v155 offset:3072
	s_add_u32 s40, s40, 0x40000
	s_addc_u32 s41, s41, 0
	s_mov_b32 m0, s82
	v_lshl_add_u64 v[248:249], s[40:41], 0, v[132:133]
	ds_read_b128 v[212:215], v154 offset:32768
	ds_read_b128 v[216:219], v154 offset:33792
	ds_read_b128 v[220:223], v154 offset:34816
	ds_read_b128 v[224:227], v154 offset:35840
	ds_read_b128 v[228:231], v154 offset:36864
	ds_read_b128 v[232:235], v154 offset:37888
	ds_read_b128 v[236:239], v154 offset:38912
	ds_read_b128 v[240:243], v154 offset:39936
	global_load_lds_dwordx4 v[248:249], off
	v_lshl_add_u64 v[248:249], s[40:41], 0, v[130:131]
	s_mov_b32 m0, s83
	s_nop 0
	global_load_lds_dwordx4 v[248:249], off
	s_waitcnt vmcnt(8)
	s_waitcnt lgkmcnt(0)
	s_barrier
	s_waitcnt lgkmcnt(0)
	v_mfma_f32_16x16x32_bf16 v[126:129], v[156:159], v[212:215], v[126:129]
	v_mfma_f32_16x16x32_bf16 v[122:125], v[164:167], v[212:215], v[122:125]
	v_mfma_f32_16x16x32_bf16 v[110:113], v[156:159], v[220:223], v[110:113]
	v_mfma_f32_16x16x32_bf16 v[106:109], v[164:167], v[220:223], v[106:109]
	v_mfma_f32_16x16x32_bf16 v[94:97], v[156:159], v[228:231], v[94:97]
	v_mfma_f32_16x16x32_bf16 v[90:93], v[164:167], v[228:231], v[90:93]
	v_mfma_f32_16x16x32_bf16 v[78:81], v[156:159], v[236:239], v[78:81]
	v_mfma_f32_16x16x32_bf16 v[74:77], v[164:167], v[236:239], v[74:77]
	v_mfma_f32_16x16x32_bf16 v[126:129], v[160:163], v[216:219], v[126:129]
	v_mfma_f32_16x16x32_bf16 v[122:125], v[168:171], v[216:219], v[122:125]
	v_mfma_f32_16x16x32_bf16 v[110:113], v[160:163], v[224:227], v[110:113]
	v_mfma_f32_16x16x32_bf16 v[106:109], v[168:171], v[224:227], v[106:109]
	v_mfma_f32_16x16x32_bf16 v[94:97], v[160:163], v[232:235], v[94:97]
	v_mfma_f32_16x16x32_bf16 v[90:93], v[168:171], v[232:235], v[90:93]
	v_mfma_f32_16x16x32_bf16 v[78:81], v[160:163], v[240:243], v[78:81]
	v_mfma_f32_16x16x32_bf16 v[74:77], v[168:171], v[240:243], v[74:77]
	v_mfma_f32_16x16x32_bf16 v[118:121], v[172:175], v[212:215], v[118:121]
	v_mfma_f32_16x16x32_bf16 v[114:117], v[180:183], v[212:215], v[114:117]
	v_mfma_f32_16x16x32_bf16 v[102:105], v[172:175], v[220:223], v[102:105]
	v_mfma_f32_16x16x32_bf16 v[98:101], v[180:183], v[220:223], v[98:101]
	v_mfma_f32_16x16x32_bf16 v[86:89], v[172:175], v[228:231], v[86:89]
	v_mfma_f32_16x16x32_bf16 v[82:85], v[180:183], v[228:231], v[82:85]
	v_mfma_f32_16x16x32_bf16 v[70:73], v[172:175], v[236:239], v[70:73]
	v_mfma_f32_16x16x32_bf16 v[66:69], v[180:183], v[236:239], v[66:69]
	v_mfma_f32_16x16x32_bf16 v[118:121], v[176:179], v[216:219], v[118:121]
	v_mfma_f32_16x16x32_bf16 v[114:117], v[208:211], v[216:219], v[114:117]
	v_mfma_f32_16x16x32_bf16 v[102:105], v[176:179], v[224:227], v[102:105]
	v_mfma_f32_16x16x32_bf16 v[98:101], v[208:211], v[224:227], v[98:101]
	v_mfma_f32_16x16x32_bf16 v[86:89], v[176:179], v[232:235], v[86:89]
	v_mfma_f32_16x16x32_bf16 v[82:85], v[208:211], v[232:235], v[82:85]
	v_mfma_f32_16x16x32_bf16 v[70:73], v[176:179], v[240:243], v[70:73]
	v_mfma_f32_16x16x32_bf16 v[66:69], v[208:211], v[240:243], v[66:69]
	s_barrier
; #define PG8_STAGE(bufoff, gbase, voff) do { _Pragma("unroll") for (int _i = 0; _i < 2; ++_i) \
;         __builtin_amdgcn_global_load_lds((const unsigned*)((const char*)(gbase) + (voff)[_i]), (PG8_LAS unsigned*)(lds + (bufoff) + ldsw + _i * 8192), 16, 0, 0); } while (0)
; #define PG8_LDA(dst, b, h) do { _Pragma("unroll") for (int m = 0; m < 4; ++m) _Pragma("unroll") for (int k = 0; k < 2; ++k) dst[m][k] = *(const PG8_LAS bf16x8*)(lds + PG8_SA(b, h) + aoff + m * 2048 + k * 1024); } while (0)
; #define PG8_WAIT_V(n) asm volatile("s_waitcnt vmcnt(" #n ")" ::: "memory")
; template <class Epi, class Sched, bool ALIGN_EPI = false, bool SP2 = false>
; __device__ __forceinline__ void gemm_phase(PG8_LAS unsigned char* lds, const Gemm g, const Sched& S, const Epi& E) {
;     ...
;         for (int t = 0; t < nt; t += 2) {
;             const bool last = (t == nt - 2);
;             const char* a1 = cA + (size_t)(t + 1) * kstep;
;             const char* a2 = last ? nA : cA + (size_t)(t + 2) * kstep; const char* b2 = last ? nB : cB + (size_t)(t + 2) * kstep;
;             const char* a3 = a2 + kstep; const char* b3 = b2 + kstep;
;             if (last && has_next) S.a_ready(nxt);
;             if constexpr (SP2) {
;             PG8_LDB(B0, 0, 0); PG8_LDB(B1, 0, 1); PG8_SCHED; PG8_LDA(At, 0, 0); PG8_STAGE(PG8_SA(1, 1), a1 + hstep, voffA);
;             PG8_WAIT_V(8); PG8_WAIT_L(0); PG8_BAR; PG8_MMA(0, 0, At, B0); PG8_MMA(0, 1, At, B1); PG8_BAR; PG8_SCHED;
;             PG8_LDA(At, 0, 1); PG8_STAGE(PG8_SB(0, 0), b2, voffB); PG8_STAGE(PG8_SB(0, 1), b2 + hstep, voffB); PG8_STAGE(PG8_SA(0, 0), a2, voffA);
;             PG8_WAIT_V(8); PG8_WAIT_L(0); PG8_BAR; PG8_MMA(1, 0, At, B0); PG8_MMA(1, 1, At, B1); PG8_BAR; PG8_SCHED;
;             PG8_LDB(B0, 1, 0); PG8_LDB(B1, 1, 1); PG8_SCHED; PG8_LDA(At, 1, 0); PG8_STAGE(PG8_SA(0, 1), a2 + hstep, voffA);
;             PG8_WAIT_V(8); PG8_WAIT_L(0); PG8_BAR; PG8_MMA(0, 0, At, B0); PG8_MMA(0, 1, At, B1); PG8_BAR; PG8_SCHED;
;             PG8_LDA(At, 1, 1); PG8_STAGE(PG8_SB(1, 0), b3, voffB); PG8_STAGE(PG8_SB(1, 1), b3 + hstep, voffB); PG8_STAGE(PG8_SA(1, 0), a3, voffA);
;             PG8_WAIT_V(8); PG8_WAIT_L(0); PG8_BAR; PG8_MMA(1, 0, At, B0); PG8_MMA(1, 1, At, B1); PG8_BAR; PG8_SCHED;
;             } else {
;             PG8_LDB(B0, 0, 0); PG8_SCHED; PG8_LDA(At, 0, 0); PG8_STAGE(PG8_SA(1, 1), a1 + hstep, voffA);
	s_add_i32 s40, s71, s80
	v_lshl_add_u64 v[202:203], v[202:203], 0, s[66:67]
	s_mov_b32 m0, s40
	ds_read_b128 v[212:215], v154 offset:49152
	ds_read_b128 v[216:219], v154 offset:50176
	ds_read_b128 v[220:223], v154 offset:51200
	ds_read_b128 v[224:227], v154 offset:52224
	ds_read_b128 v[228:231], v154 offset:53248
	ds_read_b128 v[232:235], v154 offset:54272
	ds_read_b128 v[236:239], v154 offset:55296
	ds_read_b128 v[240:243], v154 offset:56320
	global_load_lds_dwordx4 v[202:203], off
	s_add_i32 m0, s40, 0x2000
	s_add_u32 s34, s34, 0x40080
	v_lshl_add_u64 v[202:203], v[204:205], 0, s[66:67]
	s_addc_u32 s35, s35, 0
	s_add_i32 s40, s72, s80
	global_load_lds_dwordx4 v[202:203], off
	v_lshl_add_u64 v[202:203], s[34:35], 0, v[132:133]
	s_mov_b32 m0, s40
	s_nop 0
	global_load_lds_dwordx4 v[202:203], off
	v_lshl_add_u64 v[202:203], s[34:35], 0, v[130:131]
	s_add_i32 m0, s40, 0x2000
	s_nop 0
	global_load_lds_dwordx4 v[202:203], off
	v_lshl_add_u64 v[202:203], v[244:245], 0, s[66:67]
	s_mov_b32 m0, s84
	s_nop 0
	global_load_lds_dwordx4 v[202:203], off
	v_lshl_add_u64 v[202:203], v[246:247], 0, s[66:67]
	s_mov_b32 m0, s85
	s_nop 0
	global_load_lds_dwordx4 v[202:203], off
	s_waitcnt vmcnt(8)
	s_waitcnt lgkmcnt(0)
	s_barrier
	s_waitcnt lgkmcnt(0)
	v_mfma_f32_16x16x32_bf16 v[62:65], v[156:159], v[212:215], v[62:65]
	v_mfma_f32_16x16x32_bf16 v[58:61], v[164:167], v[212:215], v[58:61]
	v_mfma_f32_16x16x32_bf16 v[46:49], v[156:159], v[220:223], v[46:49]
	v_mfma_f32_16x16x32_bf16 v[42:45], v[164:167], v[220:223], v[42:45]
	v_mfma_f32_16x16x32_bf16 v[30:33], v[156:159], v[228:231], v[30:33]
	v_mfma_f32_16x16x32_bf16 v[26:29], v[164:167], v[228:231], v[26:29]
	v_mfma_f32_16x16x32_bf16 v[14:17], v[156:159], v[236:239], v[14:17]
	v_mfma_f32_16x16x32_bf16 v[10:13], v[164:167], v[236:239], v[10:13]
	v_mfma_f32_16x16x32_bf16 v[62:65], v[160:163], v[216:219], v[62:65]
	v_mfma_f32_16x16x32_bf16 v[58:61], v[168:171], v[216:219], v[58:61]
	v_mfma_f32_16x16x32_bf16 v[46:49], v[160:163], v[224:227], v[46:49]
	v_mfma_f32_16x16x32_bf16 v[42:45], v[168:171], v[224:227], v[42:45]
	v_mfma_f32_16x16x32_bf16 v[30:33], v[160:163], v[232:235], v[30:33]
	v_mfma_f32_16x16x32_bf16 v[26:29], v[168:171], v[232:235], v[26:29]
	v_mfma_f32_16x16x32_bf16 v[14:17], v[160:163], v[240:243], v[14:17]
	v_mfma_f32_16x16x32_bf16 v[10:13], v[168:171], v[240:243], v[10:13]
	v_mfma_f32_16x16x32_bf16 v[54:57], v[172:175], v[212:215], v[54:57]
	v_mfma_f32_16x16x32_bf16 v[50:53], v[180:183], v[212:215], v[50:53]
	v_mfma_f32_16x16x32_bf16 v[38:41], v[172:175], v[220:223], v[38:41]
	v_mfma_f32_16x16x32_bf16 v[34:37], v[180:183], v[220:223], v[34:37]
	v_mfma_f32_16x16x32_bf16 v[22:25], v[172:175], v[228:231], v[22:25]
	v_mfma_f32_16x16x32_bf16 v[18:21], v[180:183], v[228:231], v[18:21]
	v_mfma_f32_16x16x32_bf16 v[6:9], v[172:175], v[236:239], v[6:9]
	v_mfma_f32_16x16x32_bf16 v[2:5], v[180:183], v[236:239], v[2:5]
	v_mfma_f32_16x16x32_bf16 v[54:57], v[176:179], v[216:219], v[54:57]
	v_mfma_f32_16x16x32_bf16 v[50:53], v[208:211], v[216:219], v[50:53]
	v_mfma_f32_16x16x32_bf16 v[38:41], v[176:179], v[224:227], v[38:41]
	v_mfma_f32_16x16x32_bf16 v[34:37], v[208:211], v[224:227], v[34:37]
	v_mfma_f32_16x16x32_bf16 v[22:25], v[176:179], v[232:235], v[22:25]
	v_mfma_f32_16x16x32_bf16 v[18:21], v[208:211], v[232:235], v[18:21]
	v_mfma_f32_16x16x32_bf16 v[6:9], v[176:179], v[240:243], v[6:9]
	v_mfma_f32_16x16x32_bf16 v[2:5], v[208:211], v[240:243], v[2:5]
	s_barrier
	s_add_i32 s62, s62, 2
	s_add_u32 s30, s30, 0x100
	s_addc_u32 s31, s31, 0
	s_add_u32 s52, s52, 0x100
	s_addc_u32 s54, s54, 0
	s_cmp_gt_u32 s62, 13
	s_cbranch_scc0 .LBB0_163
	s_branch .Lku_exit
	s_nop 0
	s_nop 0
	s_nop 0
	s_nop 0
	s_nop 0
	s_nop 0
	s_nop 0
.LBB0_163:
	s_add_u32 s34, s30, 0xfffc0080
	s_addc_u32 s35, s31, -1
	s_add_i32 s71, 0, 0x10000
	s_cmp_eq_u32 s62, 12
	s_cselect_b32 s41, s21, s35
	s_cselect_b32 s40, s27, s34
	v_add_u32_e32 v155, s71, v145
	s_cselect_b32 s35, s19, s54
	s_cselect_b32 s34, s50, s52
	s_add_i32 s74, 0, 0x14000
	ds_read_b128 v[156:159], v155
	ds_read_b128 v[160:163], v155 offset:1024
	ds_read_b128 v[164:167], v155 offset:2048
	ds_read_b128 v[168:171], v155 offset:3072
	v_add_u32_e32 v155, s74, v145
	ds_read_b128 v[172:175], v155
	ds_read_b128 v[176:179], v155 offset:1024
	ds_read_b128 v[180:183], v155 offset:2048
	ds_read_b128 v[208:211], v155 offset:3072
	v_lshl_add_u64 v[202:203], s[30:31], 0, v[134:135]
	s_add_i32 m0, s29, 0xc000
	ds_read_b128 v[212:215], v154
	ds_read_b128 v[216:219], v154 offset:1024
	ds_read_b128 v[220:223], v154 offset:2048
	ds_read_b128 v[224:227], v154 offset:3072
	ds_read_b128 v[228:231], v154 offset:4096
	ds_read_b128 v[232:235], v154 offset:5120
	ds_read_b128 v[236:239], v154 offset:6144
	ds_read_b128 v[240:243], v154 offset:7168
	global_load_lds_dwordx4 v[202:203], off
	v_lshl_add_u64 v[202:203], s[30:31], 0, v[136:137]
	s_add_i32 m0, s29, 0xe000
	s_nop 0
	global_load_lds_dwordx4 v[202:203], off
	s_waitcnt vmcnt(8)
	s_waitcnt lgkmcnt(0)
	s_barrier
; #define PG8_STAGE(bufoff, gbase, voff) do { _Pragma("unroll") for (int _i = 0; _i < 2; ++_i) \
;         __builtin_amdgcn_global_load_lds((const unsigned*)((const char*)(gbase) + (voff)[_i]), (PG8_LAS unsigned*)(lds + (bufoff) + ldsw + _i * 8192), 16, 0, 0); } while (0)
; #define PG8_LDA(dst, b, h) do { _Pragma("unroll") for (int m = 0; m < 4; ++m) _Pragma("unroll") for (int k = 0; k < 2; ++k) dst[m][k] = *(const PG8_LAS bf16x8*)(lds + PG8_SA(b, h) + aoff + m * 2048 + k * 1024); } while (0)
; #define PG8_LDB(dst, b, h) do { _Pragma("unroll") for (int n = 0; n < 2; ++n) _Pragma("unroll") for (int k = 0; k < 2; ++k) dst[n][k] = *(const PG8_LAS bf16x8*)(lds + PG8_SB(b, h) + boff + n * 2048 + k * 1024); } while (0)
; #define PG8_MMA(ai, bj, At, Bt) do { __builtin_amdgcn_s_setprio(1); _Pragma("unroll") for (int m = 0; m < 4; ++m) _Pragma("unroll") for (int n = 0; n < 2; ++n) _Pragma("unroll") for (int k = 0; k < 2; ++k) \
;         acc[ai][bj][m][n] = __builtin_amdgcn_mfma_f32_16x16x32_bf16(Bt[n][k], At[m][k], acc[ai][bj][m][n], 0, 0, 0); __builtin_amdgcn_s_setprio(0); } while (0)
; #define PG8_WAIT_V(n) asm volatile("s_waitcnt vmcnt(" #n ")" ::: "memory")
; #define PG8_WAIT_L(n) asm volatile("s_waitcnt lgkmcnt(" #n ")" ::: "memory")
; #define PG8_BAR __builtin_amdgcn_s_barrier()
; #define PG8_SCHED __builtin_amdgcn_sched_barrier(0)
; template <class Epi, class Sched, bool ALIGN_EPI = false, bool SP2 = false>
; __device__ __forceinline__ void gemm_phase(PG8_LAS unsigned char* lds, const Gemm g, const Sched& S, const Epi& E) {
;     ...
;             PG8_WAIT_V(8); PG8_WAIT_L(0); PG8_BAR; PG8_MMA(0, 0, At, B0); PG8_MMA(0, 1, At, B1); PG8_BAR; PG8_SCHED;
;             PG8_LDA(At, 0, 1); PG8_STAGE(PG8_SB(0, 0), b2, voffB); PG8_STAGE(PG8_SB(0, 1), b2 + hstep, voffB); PG8_STAGE(PG8_SA(0, 0), a2, voffA);
;             PG8_WAIT_V(8); PG8_WAIT_L(0); PG8_BAR; PG8_MMA(1, 0, At, B0); PG8_MMA(1, 1, At, B1); PG8_BAR; PG8_SCHED;
;             PG8_LDB(B0, 1, 0); PG8_LDB(B1, 1, 1); PG8_SCHED; PG8_LDA(At, 1, 0); PG8_STAGE(PG8_SA(0, 1), a2 + hstep, voffA);
;             PG8_WAIT_V(8); PG8_WAIT_L(0); PG8_BAR; PG8_MMA(0, 0, At, B0); PG8_MMA(0, 1, At, B1); PG8_BAR; PG8_SCHED;
	s_waitcnt lgkmcnt(0)
	v_mfma_f32_16x16x32_bf16 v[126:129], v[156:159], v[212:215], v[126:129]
	v_mfma_f32_16x16x32_bf16 v[122:125], v[164:167], v[212:215], v[122:125]
	v_mfma_f32_16x16x32_bf16 v[110:113], v[156:159], v[220:223], v[110:113]
	v_mfma_f32_16x16x32_bf16 v[106:109], v[164:167], v[220:223], v[106:109]
	v_mfma_f32_16x16x32_bf16 v[94:97], v[156:159], v[228:231], v[94:97]
	v_mfma_f32_16x16x32_bf16 v[90:93], v[164:167], v[228:231], v[90:93]
	v_mfma_f32_16x16x32_bf16 v[78:81], v[156:159], v[236:239], v[78:81]
	v_mfma_f32_16x16x32_bf16 v[74:77], v[164:167], v[236:239], v[74:77]
	v_mfma_f32_16x16x32_bf16 v[126:129], v[160:163], v[216:219], v[126:129]
	v_mfma_f32_16x16x32_bf16 v[122:125], v[168:171], v[216:219], v[122:125]
	v_mfma_f32_16x16x32_bf16 v[110:113], v[160:163], v[224:227], v[110:113]
	v_mfma_f32_16x16x32_bf16 v[106:109], v[168:171], v[224:227], v[106:109]
	v_mfma_f32_16x16x32_bf16 v[94:97], v[160:163], v[232:235], v[94:97]
	v_mfma_f32_16x16x32_bf16 v[90:93], v[168:171], v[232:235], v[90:93]
	v_mfma_f32_16x16x32_bf16 v[78:81], v[160:163], v[240:243], v[78:81]
	v_mfma_f32_16x16x32_bf16 v[74:77], v[168:171], v[240:243], v[74:77]
	v_mfma_f32_16x16x32_bf16 v[118:121], v[172:175], v[212:215], v[118:121]
	v_mfma_f32_16x16x32_bf16 v[114:117], v[180:183], v[212:215], v[114:117]
	v_mfma_f32_16x16x32_bf16 v[102:105], v[172:175], v[220:223], v[102:105]
	v_mfma_f32_16x16x32_bf16 v[98:101], v[180:183], v[220:223], v[98:101]
	v_mfma_f32_16x16x32_bf16 v[86:89], v[172:175], v[228:231], v[86:89]
	v_mfma_f32_16x16x32_bf16 v[82:85], v[180:183], v[228:231], v[82:85]
	v_mfma_f32_16x16x32_bf16 v[70:73], v[172:175], v[236:239], v[70:73]
	v_mfma_f32_16x16x32_bf16 v[66:69], v[180:183], v[236:239], v[66:69]
	v_mfma_f32_16x16x32_bf16 v[118:121], v[176:179], v[216:219], v[118:121]
	v_mfma_f32_16x16x32_bf16 v[114:117], v[208:211], v[216:219], v[114:117]
	v_mfma_f32_16x16x32_bf16 v[102:105], v[176:179], v[224:227], v[102:105]
	v_mfma_f32_16x16x32_bf16 v[98:101], v[208:211], v[224:227], v[98:101]
	v_mfma_f32_16x16x32_bf16 v[86:89], v[176:179], v[232:235], v[86:89]
	v_mfma_f32_16x16x32_bf16 v[82:85], v[208:211], v[232:235], v[82:85]
	v_mfma_f32_16x16x32_bf16 v[70:73], v[176:179], v[240:243], v[70:73]
	v_mfma_f32_16x16x32_bf16 v[66:69], v[208:211], v[240:243], v[66:69]
	s_barrier
	s_add_i32 s71, s71, s80
	v_lshl_add_u64 v[202:203], s[34:35], 0, v[132:133]
	s_mov_b32 m0, s71
	ds_read_b128 v[212:215], v154 offset:16384
	ds_read_b128 v[216:219], v154 offset:17408
	ds_read_b128 v[220:223], v154 offset:18432
	ds_read_b128 v[224:227], v154 offset:19456
	ds_read_b128 v[228:231], v154 offset:20480
	ds_read_b128 v[232:235], v154 offset:21504
	ds_read_b128 v[236:239], v154 offset:22528
	ds_read_b128 v[240:243], v154 offset:23552
	global_load_lds_dwordx4 v[202:203], off
	s_add_i32 m0, s71, 0x2000
	s_add_u32 s72, s34, 0x40000
	v_lshl_add_u64 v[204:205], s[34:35], 0, v[130:131]
	s_addc_u32 s73, s35, 0
	s_add_i32 s71, s74, s80
	global_load_lds_dwordx4 v[204:205], off
	v_lshl_add_u64 v[244:245], s[72:73], 0, v[132:133]
	s_mov_b32 m0, s71
	v_lshl_add_u64 v[246:247], s[40:41], 0, v[130:131]
	global_load_lds_dwordx4 v[244:245], off
	v_lshl_add_u64 v[244:245], s[72:73], 0, v[130:131]
	s_add_i32 m0, s71, 0x2000
	s_nop 0
	global_load_lds_dwordx4 v[244:245], off
	v_lshl_add_u64 v[244:245], s[40:41], 0, v[132:133]
	s_mov_b32 m0, s29
	s_nop 0
	global_load_lds_dwordx4 v[244:245], off
	s_mov_b32 m0, s81
	s_nop 0
	global_load_lds_dwordx4 v[246:247], off
	s_waitcnt vmcnt(8)
	s_waitcnt lgkmcnt(0)
	s_barrier
	s_waitcnt lgkmcnt(0)
	v_mfma_f32_16x16x32_bf16 v[62:65], v[156:159], v[212:215], v[62:65]
	v_mfma_f32_16x16x32_bf16 v[58:61], v[164:167], v[212:215], v[58:61]
	v_mfma_f32_16x16x32_bf16 v[46:49], v[156:159], v[220:223], v[46:49]
	v_mfma_f32_16x16x32_bf16 v[42:45], v[164:167], v[220:223], v[42:45]
	v_mfma_f32_16x16x32_bf16 v[30:33], v[156:159], v[228:231], v[30:33]
	v_mfma_f32_16x16x32_bf16 v[26:29], v[164:167], v[228:231], v[26:29]
	v_mfma_f32_16x16x32_bf16 v[14:17], v[156:159], v[236:239], v[14:17]
	v_mfma_f32_16x16x32_bf16 v[10:13], v[164:167], v[236:239], v[10:13]
	v_mfma_f32_16x16x32_bf16 v[62:65], v[160:163], v[216:219], v[62:65]
	v_mfma_f32_16x16x32_bf16 v[58:61], v[168:171], v[216:219], v[58:61]
	v_mfma_f32_16x16x32_bf16 v[46:49], v[160:163], v[224:227], v[46:49]
	v_mfma_f32_16x16x32_bf16 v[42:45], v[168:171], v[224:227], v[42:45]
	v_mfma_f32_16x16x32_bf16 v[30:33], v[160:163], v[232:235], v[30:33]
	v_mfma_f32_16x16x32_bf16 v[26:29], v[168:171], v[232:235], v[26:29]
	v_mfma_f32_16x16x32_bf16 v[14:17], v[160:163], v[240:243], v[14:17]
	v_mfma_f32_16x16x32_bf16 v[10:13], v[168:171], v[240:243], v[10:13]
	v_mfma_f32_16x16x32_bf16 v[54:57], v[172:175], v[212:215], v[54:57]
	v_mfma_f32_16x16x32_bf16 v[50:53], v[180:183], v[212:215], v[50:53]
	v_mfma_f32_16x16x32_bf16 v[38:41], v[172:175], v[220:223], v[38:41]
	v_mfma_f32_16x16x32_bf16 v[34:37], v[180:183], v[220:223], v[34:37]
	v_mfma_f32_16x16x32_bf16 v[22:25], v[172:175], v[228:231], v[22:25]
	v_mfma_f32_16x16x32_bf16 v[18:21], v[180:183], v[228:231], v[18:21]
	v_mfma_f32_16x16x32_bf16 v[6:9], v[172:175], v[236:239], v[6:9]
	v_mfma_f32_16x16x32_bf16 v[2:5], v[180:183], v[236:239], v[2:5]
	v_mfma_f32_16x16x32_bf16 v[54:57], v[176:179], v[216:219], v[54:57]
	v_mfma_f32_16x16x32_bf16 v[50:53], v[208:211], v[216:219], v[50:53]
	v_mfma_f32_16x16x32_bf16 v[38:41], v[176:179], v[224:227], v[38:41]
	v_mfma_f32_16x16x32_bf16 v[34:37], v[208:211], v[224:227], v[34:37]
	v_mfma_f32_16x16x32_bf16 v[22:25], v[176:179], v[232:235], v[22:25]
	v_mfma_f32_16x16x32_bf16 v[18:21], v[208:211], v[232:235], v[18:21]
	v_mfma_f32_16x16x32_bf16 v[6:9], v[176:179], v[240:243], v[6:9]
	v_mfma_f32_16x16x32_bf16 v[2:5], v[208:211], v[240:243], v[2:5]
	s_barrier
; #define PG8_STAGE(bufoff, gbase, voff) do { _Pragma("unroll") for (int _i = 0; _i < 2; ++_i) \
;         __builtin_amdgcn_global_load_lds((const unsigned*)((const char*)(gbase) + (voff)[_i]), (PG8_LAS unsigned*)(lds + (bufoff) + ldsw + _i * 8192), 16, 0, 0); } while (0)
; #define PG8_LDA(dst, b, h) do { _Pragma("unroll") for (int m = 0; m < 4; ++m) _Pragma("unroll") for (int k = 0; k < 2; ++k) dst[m][k] = *(const PG8_LAS bf16x8*)(lds + PG8_SA(b, h) + aoff + m * 2048 + k * 1024); } while (0)
; #define PG8_LDB(dst, b, h) do { _Pragma("unroll") for (int n = 0; n < 2; ++n) _Pragma("unroll") for (int k = 0; k < 2; ++k) dst[n][k] = *(const PG8_LAS bf16x8*)(lds + PG8_SB(b, h) + boff + n * 2048 + k * 1024); } while (0)
; #define PG8_MMA(ai, bj, At, Bt) do { __builtin_amdgcn_s_setprio(1); _Pragma("unroll") for (int m = 0; m < 4; ++m) _Pragma("unroll") for (int n = 0; n < 2; ++n) _Pragma("unroll") for (int k = 0; k < 2; ++k) \
;         acc[ai][bj][m][n] = __builtin_amdgcn_mfma_f32_16x16x32_bf16(Bt[n][k], At[m][k], acc[ai][bj][m][n], 0, 0, 0); __builtin_amdgcn_s_setprio(0); } while (0)
; #define PG8_WAIT_V(n) asm volatile("s_waitcnt vmcnt(" #n ")" ::: "memory")
; #define PG8_WAIT_L(n) asm volatile("s_waitcnt lgkmcnt(" #n ")" ::: "memory")
; #define PG8_BAR __builtin_amdgcn_s_barrier()
; #define PG8_SCHED __builtin_amdgcn_sched_barrier(0)
; template <class Epi, class Sched, bool ALIGN_EPI = false, bool SP2 = false>
; __device__ __forceinline__ void gemm_phase(PG8_LAS unsigned char* lds, const Gemm g, const Sched& S, const Epi& E) {
;     ...
;             PG8_LDB(B0, 1, 0); PG8_LDB(B1, 1, 1); PG8_SCHED; PG8_LDA(At, 1, 0); PG8_STAGE(PG8_SA(0, 1), a2 + hstep, voffA);
;             PG8_WAIT_V(8); PG8_WAIT_L(0); PG8_BAR; PG8_MMA(0, 0, At, B0); PG8_MMA(0, 1, At, B1); PG8_BAR; PG8_SCHED;
;             PG8_LDA(At, 1, 1); PG8_STAGE(PG8_SB(1, 0), b3, voffB); PG8_STAGE(PG8_SB(1, 1), b3 + hstep, voffB); PG8_STAGE(PG8_SA(1, 0), a3, voffA);
;             PG8_WAIT_V(8); PG8_WAIT_L(0); PG8_BAR; PG8_MMA(1, 0, At, B0); PG8_MMA(1, 1, At, B1); PG8_BAR; PG8_SCHED;
	s_add_i32 s71, 0, 0x18000
	v_add_u32_e32 v155, s71, v145
	s_add_i32 s72, 0, 0x1c000
	ds_read_b128 v[156:159], v155
	ds_read_b128 v[160:163], v155 offset:1024
	ds_read_b128 v[164:167], v155 offset:2048
	ds_read_b128 v[168:171], v155 offset:3072
	v_add_u32_e32 v155, s72, v145
	ds_read_b128 v[172:175], v155
	ds_read_b128 v[176:179], v155 offset:1024
	ds_read_b128 v[180:183], v155 offset:2048
	ds_read_b128 v[208:211], v155 offset:3072
	s_add_u32 s40, s40, 0x40000
	s_addc_u32 s41, s41, 0
	s_mov_b32 m0, s82
	v_lshl_add_u64 v[248:249], s[40:41], 0, v[132:133]
	ds_read_b128 v[212:215], v154 offset:32768
	ds_read_b128 v[216:219], v154 offset:33792
	ds_read_b128 v[220:223], v154 offset:34816
	ds_read_b128 v[224:227], v154 offset:35840
	ds_read_b128 v[228:231], v154 offset:36864
	ds_read_b128 v[232:235], v154 offset:37888
	ds_read_b128 v[236:239], v154 offset:38912
	ds_read_b128 v[240:243], v154 offset:39936
	global_load_lds_dwordx4 v[248:249], off
	v_lshl_add_u64 v[248:249], s[40:41], 0, v[130:131]
	s_mov_b32 m0, s83
	s_nop 0
	global_load_lds_dwordx4 v[248:249], off
	s_waitcnt vmcnt(8)
	s_waitcnt lgkmcnt(0)
	s_barrier
	s_waitcnt lgkmcnt(0)
	v_mfma_f32_16x16x32_bf16 v[126:129], v[156:159], v[212:215], v[126:129]
	v_mfma_f32_16x16x32_bf16 v[122:125], v[164:167], v[212:215], v[122:125]
	v_mfma_f32_16x16x32_bf16 v[110:113], v[156:159], v[220:223], v[110:113]
	v_mfma_f32_16x16x32_bf16 v[106:109], v[164:167], v[220:223], v[106:109]
	v_mfma_f32_16x16x32_bf16 v[94:97], v[156:159], v[228:231], v[94:97]
	v_mfma_f32_16x16x32_bf16 v[90:93], v[164:167], v[228:231], v[90:93]
	v_mfma_f32_16x16x32_bf16 v[78:81], v[156:159], v[236:239], v[78:81]
	v_mfma_f32_16x16x32_bf16 v[74:77], v[164:167], v[236:239], v[74:77]
	v_mfma_f32_16x16x32_bf16 v[126:129], v[160:163], v[216:219], v[126:129]
	v_mfma_f32_16x16x32_bf16 v[122:125], v[168:171], v[216:219], v[122:125]
	v_mfma_f32_16x16x32_bf16 v[110:113], v[160:163], v[224:227], v[110:113]
	v_mfma_f32_16x16x32_bf16 v[106:109], v[168:171], v[224:227], v[106:109]
	v_mfma_f32_16x16x32_bf16 v[94:97], v[160:163], v[232:235], v[94:97]
	v_mfma_f32_16x16x32_bf16 v[90:93], v[168:171], v[232:235], v[90:93]
	v_mfma_f32_16x16x32_bf16 v[78:81], v[160:163], v[240:243], v[78:81]
	v_mfma_f32_16x16x32_bf16 v[74:77], v[168:171], v[240:243], v[74:77]
	v_mfma_f32_16x16x32_bf16 v[118:121], v[172:175], v[212:215], v[118:121]
	v_mfma_f32_16x16x32_bf16 v[114:117], v[180:183], v[212:215], v[114:117]
	v_mfma_f32_16x16x32_bf16 v[102:105], v[172:175], v[220:223], v[102:105]
	v_mfma_f32_16x16x32_bf16 v[98:101], v[180:183], v[220:223], v[98:101]
	v_mfma_f32_16x16x32_bf16 v[86:89], v[172:175], v[228:231], v[86:89]
	v_mfma_f32_16x16x32_bf16 v[82:85], v[180:183], v[228:231], v[82:85]
	v_mfma_f32_16x16x32_bf16 v[70:73], v[172:175], v[236:239], v[70:73]
	v_mfma_f32_16x16x32_bf16 v[66:69], v[180:183], v[236:239], v[66:69]
	v_mfma_f32_16x16x32_bf16 v[118:121], v[176:179], v[216:219], v[118:121]
	v_mfma_f32_16x16x32_bf16 v[114:117], v[208:211], v[216:219], v[114:117]
	v_mfma_f32_16x16x32_bf16 v[102:105], v[176:179], v[224:227], v[102:105]
	v_mfma_f32_16x16x32_bf16 v[98:101], v[208:211], v[224:227], v[98:101]
	v_mfma_f32_16x16x32_bf16 v[86:89], v[176:179], v[232:235], v[86:89]
	v_mfma_f32_16x16x32_bf16 v[82:85], v[208:211], v[232:235], v[82:85]
	v_mfma_f32_16x16x32_bf16 v[70:73], v[176:179], v[240:243], v[70:73]
	v_mfma_f32_16x16x32_bf16 v[66:69], v[208:211], v[240:243], v[66:69]
	s_barrier
	s_add_i32 s40, s71, s80
	v_lshl_add_u64 v[202:203], v[202:203], 0, s[66:67]
	s_mov_b32 m0, s40
	ds_read_b128 v[212:215], v154 offset:49152
	ds_read_b128 v[216:219], v154 offset:50176
	ds_read_b128 v[220:223], v154 offset:51200
	ds_read_b128 v[224:227], v154 offset:52224
	ds_read_b128 v[228:231], v154 offset:53248
	ds_read_b128 v[232:235], v154 offset:54272
	ds_read_b128 v[236:239], v154 offset:55296
	ds_read_b128 v[240:243], v154 offset:56320
	global_load_lds_dwordx4 v[202:203], off
	s_add_i32 m0, s40, 0x2000
	s_add_u32 s34, s34, 0x40080
	v_lshl_add_u64 v[202:203], v[204:205], 0, s[66:67]
	s_addc_u32 s35, s35, 0
	s_add_i32 s40, s72, s80
	global_load_lds_dwordx4 v[202:203], off
	v_lshl_add_u64 v[202:203], s[34:35], 0, v[132:133]
	s_mov_b32 m0, s40
	s_nop 0
	global_load_lds_dwordx4 v[202:203], off
	v_lshl_add_u64 v[202:203], s[34:35], 0, v[130:131]
	s_add_i32 m0, s40, 0x2000
	s_nop 0
	global_load_lds_dwordx4 v[202:203], off
	v_lshl_add_u64 v[202:203], v[244:245], 0, s[66:67]
	s_mov_b32 m0, s84
	s_nop 0
	global_load_lds_dwordx4 v[202:203], off
	v_lshl_add_u64 v[202:203], v[246:247], 0, s[66:67]
	s_mov_b32 m0, s85
	s_nop 0
	global_load_lds_dwordx4 v[202:203], off
	s_waitcnt vmcnt(8)
	s_waitcnt lgkmcnt(0)
	s_barrier
; #define PG8_STAGE(bufoff, gbase, voff) do { _Pragma("unroll") for (int _i = 0; _i < 2; ++_i) \
;         __builtin_amdgcn_global_load_lds((const unsigned*)((const char*)(gbase) + (voff)[_i]), (PG8_LAS unsigned*)(lds + (bufoff) + ldsw + _i * 8192), 16, 0, 0); } while (0)
; #define PG8_LDA(dst, b, h) do { _Pragma("unroll") for (int m = 0; m < 4; ++m) _Pragma("unroll") for (int k = 0; k < 2; ++k) dst[m][k] = *(const PG8_LAS bf16x8*)(lds + PG8_SA(b, h) + aoff + m * 2048 + k * 1024); } while (0)
; #define PG8_LDB(dst, b, h) do { _Pragma("unroll") for (int n = 0; n < 2; ++n) _Pragma("unroll") for (int k = 0; k < 2; ++k) dst[n][k] = *(const PG8_LAS bf16x8*)(lds + PG8_SB(b, h) + boff + n * 2048 + k * 1024); } while (0)
; template <class Epi, class Sched, bool ALIGN_EPI = false, bool SP2 = false>
; __device__ __forceinline__ void gemm_phase(PG8_LAS unsigned char* lds, const Gemm g, const Sched& S, const Epi& E) {
;     ...
;         for (int t = 0; t < nt; t += 2) {
;             const bool last = (t == nt - 2);
;             const char* a1 = cA + (size_t)(t + 1) * kstep;
;             const char* a2 = last ? nA : cA + (size_t)(t + 2) * kstep; const char* b2 = last ? nB : cB + (size_t)(t + 2) * kstep;
;             const char* a3 = a2 + kstep; const char* b3 = b2 + kstep;
;             if (last && has_next) S.a_ready(nxt);
;             if constexpr (SP2) {
;             PG8_LDB(B0, 0, 0); PG8_LDB(B1, 0, 1); PG8_SCHED; PG8_LDA(At, 0, 0); PG8_STAGE(PG8_SA(1, 1), a1 + hstep, voffA);
;             PG8_WAIT_V(8); PG8_WAIT_L(0); PG8_BAR; PG8_MMA(0, 0, At, B0); PG8_MMA(0, 1, At, B1); PG8_BAR; PG8_SCHED;
;             PG8_LDA(At, 0, 1); PG8_STAGE(PG8_SB(0, 0), b2, voffB); PG8_STAGE(PG8_SB(0, 1), b2 + hstep, voffB); PG8_STAGE(PG8_SA(0, 0), a2, voffA);
;             PG8_WAIT_V(8); PG8_WAIT_L(0); PG8_BAR; PG8_MMA(1, 0, At, B0); PG8_MMA(1, 1, At, B1); PG8_BAR; PG8_SCHED;
;             PG8_LDB(B0, 1, 0); PG8_LDB(B1, 1, 1); PG8_SCHED; PG8_LDA(At, 1, 0); PG8_STAGE(PG8_SA(0, 1), a2 + hstep, voffA);
;             PG8_WAIT_V(8); PG8_WAIT_L(0); PG8_BAR; PG8_MMA(0, 0, At, B0); PG8_MMA(0, 1, At, B1); PG8_BAR; PG8_SCHED;
;             PG8_LDA(At, 1, 1); PG8_STAGE(PG8_SB(1, 0), b3, voffB); PG8_STAGE(PG8_SB(1, 1), b3 + hstep, voffB); PG8_STAGE(PG8_SA(1, 0), a3, voffA);
;             PG8_WAIT_V(8); PG8_WAIT_L(0); PG8_BAR; PG8_MMA(1, 0, At, B0); PG8_MMA(1, 1, At, B1); PG8_BAR; PG8_SCHED;
	s_waitcnt lgkmcnt(0)
	v_mfma_f32_16x16x32_bf16 v[62:65], v[156:159], v[212:215], v[62:65]
	v_mfma_f32_16x16x32_bf16 v[58:61], v[164:167], v[212:215], v[58:61]
	v_mfma_f32_16x16x32_bf16 v[46:49], v[156:159], v[220:223], v[46:49]
	v_mfma_f32_16x16x32_bf16 v[42:45], v[164:167], v[220:223], v[42:45]
	v_mfma_f32_16x16x32_bf16 v[30:33], v[156:159], v[228:231], v[30:33]
	v_mfma_f32_16x16x32_bf16 v[26:29], v[164:167], v[228:231], v[26:29]
	v_mfma_f32_16x16x32_bf16 v[14:17], v[156:159], v[236:239], v[14:17]
	v_mfma_f32_16x16x32_bf16 v[10:13], v[164:167], v[236:239], v[10:13]
	v_mfma_f32_16x16x32_bf16 v[62:65], v[160:163], v[216:219], v[62:65]
	v_mfma_f32_16x16x32_bf16 v[58:61], v[168:171], v[216:219], v[58:61]
	v_mfma_f32_16x16x32_bf16 v[46:49], v[160:163], v[224:227], v[46:49]
	v_mfma_f32_16x16x32_bf16 v[42:45], v[168:171], v[224:227], v[42:45]
	v_mfma_f32_16x16x32_bf16 v[30:33], v[160:163], v[232:235], v[30:33]
	v_mfma_f32_16x16x32_bf16 v[26:29], v[168:171], v[232:235], v[26:29]
	v_mfma_f32_16x16x32_bf16 v[14:17], v[160:163], v[240:243], v[14:17]
	v_mfma_f32_16x16x32_bf16 v[10:13], v[168:171], v[240:243], v[10:13]
	v_mfma_f32_16x16x32_bf16 v[54:57], v[172:175], v[212:215], v[54:57]
	v_mfma_f32_16x16x32_bf16 v[50:53], v[180:183], v[212:215], v[50:53]
	v_mfma_f32_16x16x32_bf16 v[38:41], v[172:175], v[220:223], v[38:41]
	v_mfma_f32_16x16x32_bf16 v[34:37], v[180:183], v[220:223], v[34:37]
	v_mfma_f32_16x16x32_bf16 v[22:25], v[172:175], v[228:231], v[22:25]
	v_mfma_f32_16x16x32_bf16 v[18:21], v[180:183], v[228:231], v[18:21]
	v_mfma_f32_16x16x32_bf16 v[6:9], v[172:175], v[236:239], v[6:9]
	v_mfma_f32_16x16x32_bf16 v[2:5], v[180:183], v[236:239], v[2:5]
	v_mfma_f32_16x16x32_bf16 v[54:57], v[176:179], v[216:219], v[54:57]
	v_mfma_f32_16x16x32_bf16 v[50:53], v[208:211], v[216:219], v[50:53]
	v_mfma_f32_16x16x32_bf16 v[38:41], v[176:179], v[224:227], v[38:41]
	v_mfma_f32_16x16x32_bf16 v[34:37], v[208:211], v[224:227], v[34:37]
	v_mfma_f32_16x16x32_bf16 v[22:25], v[176:179], v[232:235], v[22:25]
	v_mfma_f32_16x16x32_bf16 v[18:21], v[208:211], v[232:235], v[18:21]
	v_mfma_f32_16x16x32_bf16 v[6:9], v[176:179], v[240:243], v[6:9]
	v_mfma_f32_16x16x32_bf16 v[2:5], v[208:211], v[240:243], v[2:5]
	s_barrier
	s_add_i32 s62, s62, 2
	s_add_u32 s30, s30, 0x100
	s_addc_u32 s31, s31, 0
	s_add_u32 s52, s52, 0x100
	s_addc_u32 s54, s54, 0
	s_cmp_gt_u32 s62, 13
	s_cbranch_scc0 .LBB0_163
	s_branch .Lku_exit
.Lku_a0:
	s_add_u32 s34, s30, 0xfffc0080
	s_addc_u32 s35, s31, -1
	s_add_i32 s71, 0, 0x10000
	s_cmp_eq_u32 s62, 12
	s_cselect_b32 s41, s21, s35
	s_cselect_b32 s40, s27, s34
	v_add_u32_e32 v155, s71, v145
	s_cselect_b32 s35, s19, s54
	s_cselect_b32 s34, s50, s52
	s_add_i32 s74, 0, 0x14000
	ds_read_b128 v[156:159], v155
	ds_read_b128 v[160:163], v155 offset:1024
	ds_read_b128 v[164:167], v155 offset:2048
	ds_read_b128 v[168:171], v155 offset:3072
	v_add_u32_e32 v155, s74, v145
	ds_read_b128 v[172:175], v155
	ds_read_b128 v[176:179], v155 offset:1024
	ds_read_b128 v[180:183], v155 offset:2048
	ds_read_b128 v[208:211], v155 offset:3072
	v_lshl_add_u64 v[202:203], s[30:31], 0, v[134:135]
	s_add_i32 m0, s29, 0xc000
	ds_read_b128 v[212:215], v154
	ds_read_b128 v[216:219], v154 offset:1024
	ds_read_b128 v[220:223], v154 offset:2048
	ds_read_b128 v[224:227], v154 offset:3072
	ds_read_b128 v[228:231], v154 offset:4096
	ds_read_b128 v[232:235], v154 offset:5120
	ds_read_b128 v[236:239], v154 offset:6144
	ds_read_b128 v[240:243], v154 offset:7168
	v_lshl_add_u64 v[202:203], s[30:31], 0, v[136:137]
	s_add_i32 m0, s29, 0xe000
	s_nop 0
	s_waitcnt vmcnt(6)
	s_waitcnt lgkmcnt(0)
	s_barrier
	s_waitcnt lgkmcnt(0)
	v_mfma_f32_16x16x32_bf16 v[126:129], v[156:159], v[212:215], v[126:129]
	v_mfma_f32_16x16x32_bf16 v[122:125], v[164:167], v[212:215], v[122:125]
	v_mfma_f32_16x16x32_bf16 v[110:113], v[156:159], v[220:223], v[110:113]
	v_mfma_f32_16x16x32_bf16 v[106:109], v[164:167], v[220:223], v[106:109]
	v_mfma_f32_16x16x32_bf16 v[94:97], v[156:159], v[228:231], v[94:97]
	v_mfma_f32_16x16x32_bf16 v[90:93], v[164:167], v[228:231], v[90:93]
	v_mfma_f32_16x16x32_bf16 v[78:81], v[156:159], v[236:239], v[78:81]
	v_mfma_f32_16x16x32_bf16 v[74:77], v[164:167], v[236:239], v[74:77]
	v_mfma_f32_16x16x32_bf16 v[126:129], v[160:163], v[216:219], v[126:129]
	v_mfma_f32_16x16x32_bf16 v[122:125], v[168:171], v[216:219], v[122:125]
	v_mfma_f32_16x16x32_bf16 v[110:113], v[160:163], v[224:227], v[110:113]
	v_mfma_f32_16x16x32_bf16 v[106:109], v[168:171], v[224:227], v[106:109]
	v_mfma_f32_16x16x32_bf16 v[94:97], v[160:163], v[232:235], v[94:97]
	v_mfma_f32_16x16x32_bf16 v[90:93], v[168:171], v[232:235], v[90:93]
	v_mfma_f32_16x16x32_bf16 v[78:81], v[160:163], v[240:243], v[78:81]
	v_mfma_f32_16x16x32_bf16 v[74:77], v[168:171], v[240:243], v[74:77]
	v_mfma_f32_16x16x32_bf16 v[118:121], v[172:175], v[212:215], v[118:121]
	v_mfma_f32_16x16x32_bf16 v[114:117], v[180:183], v[212:215], v[114:117]
	v_mfma_f32_16x16x32_bf16 v[102:105], v[172:175], v[220:223], v[102:105]
	v_mfma_f32_16x16x32_bf16 v[98:101], v[180:183], v[220:223], v[98:101]
	v_mfma_f32_16x16x32_bf16 v[86:89], v[172:175], v[228:231], v[86:89]
	v_mfma_f32_16x16x32_bf16 v[82:85], v[180:183], v[228:231], v[82:85]
	v_mfma_f32_16x16x32_bf16 v[70:73], v[172:175], v[236:239], v[70:73]
	v_mfma_f32_16x16x32_bf16 v[66:69], v[180:183], v[236:239], v[66:69]
	v_mfma_f32_16x16x32_bf16 v[118:121], v[176:179], v[216:219], v[118:121]
	v_mfma_f32_16x16x32_bf16 v[114:117], v[208:211], v[216:219], v[114:117]
	v_mfma_f32_16x16x32_bf16 v[102:105], v[176:179], v[224:227], v[102:105]
	v_mfma_f32_16x16x32_bf16 v[98:101], v[208:211], v[224:227], v[98:101]
	v_mfma_f32_16x16x32_bf16 v[86:89], v[176:179], v[232:235], v[86:89]
	v_mfma_f32_16x16x32_bf16 v[82:85], v[208:211], v[232:235], v[82:85]
	v_mfma_f32_16x16x32_bf16 v[70:73], v[176:179], v[240:243], v[70:73]
	v_mfma_f32_16x16x32_bf16 v[66:69], v[208:211], v[240:243], v[66:69]
	s_barrier
; #define PG8_STAGE(bufoff, gbase, voff) do { _Pragma("unroll") for (int _i = 0; _i < 2; ++_i) \
;         __builtin_amdgcn_global_load_lds((const unsigned*)((const char*)(gbase) + (voff)[_i]), (PG8_LAS unsigned*)(lds + (bufoff) + ldsw + _i * 8192), 16, 0, 0); } while (0)
; #define PG8_LDA(dst, b, h) do { _Pragma("unroll") for (int m = 0; m < 4; ++m) _Pragma("unroll") for (int k = 0; k < 2; ++k) dst[m][k] = *(const PG8_LAS bf16x8*)(lds + PG8_SA(b, h) + aoff + m * 2048 + k * 1024); } while (0)
; #define PG8_LDB(dst, b, h) do { _Pragma("unroll") for (int n = 0; n < 2; ++n) _Pragma("unroll") for (int k = 0; k < 2; ++k) dst[n][k] = *(const PG8_LAS bf16x8*)(lds + PG8_SB(b, h) + boff + n * 2048 + k * 1024); } while (0)
; #define PG8_MMA(ai, bj, At, Bt) do { __builtin_amdgcn_s_setprio(1); _Pragma("unroll") for (int m = 0; m < 4; ++m) _Pragma("unroll") for (int n = 0; n < 2; ++n) _Pragma("unroll") for (int k = 0; k < 2; ++k) \
;         acc[ai][bj][m][n] = __builtin_amdgcn_mfma_f32_16x16x32_bf16(Bt[n][k], At[m][k], acc[ai][bj][m][n], 0, 0, 0); __builtin_amdgcn_s_setprio(0); } while (0)
; #define PG8_WAIT_V(n) asm volatile("s_waitcnt vmcnt(" #n ")" ::: "memory")
; template <class Epi, class Sched, bool ALIGN_EPI = false, bool SP2 = false>
; __device__ __forceinline__ void gemm_phase(PG8_LAS unsigned char* lds, const Gemm g, const Sched& S, const Epi& E) {
;     ...
;             PG8_LDB(B0, 0, 0); PG8_LDB(B1, 0, 1); PG8_SCHED; PG8_LDA(At, 0, 0); PG8_STAGE(PG8_SA(1, 1), a1 + hstep, voffA);
;             PG8_WAIT_V(8); PG8_WAIT_L(0); PG8_BAR; PG8_MMA(0, 0, At, B0); PG8_MMA(0, 1, At, B1); PG8_BAR; PG8_SCHED;
;             PG8_LDA(At, 0, 1); PG8_STAGE(PG8_SB(0, 0), b2, voffB); PG8_STAGE(PG8_SB(0, 1), b2 + hstep, voffB); PG8_STAGE(PG8_SA(0, 0), a2, voffA);
;             PG8_WAIT_V(8); PG8_WAIT_L(0); PG8_BAR; PG8_MMA(1, 0, At, B0); PG8_MMA(1, 1, At, B1); PG8_BAR; PG8_SCHED;
;             PG8_LDB(B0, 1, 0); PG8_LDB(B1, 1, 1); PG8_SCHED; PG8_LDA(At, 1, 0); PG8_STAGE(PG8_SA(0, 1), a2 + hstep, voffA);
;             PG8_WAIT_V(8); PG8_WAIT_L(0); PG8_BAR; PG8_MMA(0, 0, At, B0); PG8_MMA(0, 1, At, B1); PG8_BAR; PG8_SCHED;
;             PG8_LDA(At, 1, 1); PG8_STAGE(PG8_SB(1, 0), b3, voffB); PG8_STAGE(PG8_SB(1, 1), b3 + hstep, voffB); PG8_STAGE(PG8_SA(1, 0), a3, voffA);
;             PG8_WAIT_V(8); PG8_WAIT_L(0); PG8_BAR; PG8_MMA(1, 0, At, B0); PG8_MMA(1, 1, At, B1); PG8_BAR; PG8_SCHED;
	s_add_i32 s71, s71, s80
	v_lshl_add_u64 v[202:203], s[34:35], 0, v[132:133]
	s_mov_b32 m0, s71
	global_load_lds_dwordx4 v[202:203], off
	s_add_i32 m0, s71, 0x2000
	s_add_u32 s72, s34, 0x40000
	v_lshl_add_u64 v[204:205], s[34:35], 0, v[130:131]
	s_addc_u32 s73, s35, 0
	s_add_i32 s71, s74, s80
	global_load_lds_dwordx4 v[204:205], off
	v_lshl_add_u64 v[244:245], s[72:73], 0, v[132:133]
	s_mov_b32 m0, s71
	v_lshl_add_u64 v[246:247], s[40:41], 0, v[130:131]
	global_load_lds_dwordx4 v[244:245], off
	v_lshl_add_u64 v[244:245], s[72:73], 0, v[130:131]
	s_add_i32 m0, s71, 0x2000
	s_nop 0
	global_load_lds_dwordx4 v[244:245], off
	v_lshl_add_u64 v[244:245], s[40:41], 0, v[132:133]
	s_mov_b32 m0, s29
	s_nop 0
	global_load_lds_dwordx4 v[244:245], off
	s_mov_b32 m0, s81
	s_nop 0
	global_load_lds_dwordx4 v[246:247], off
	s_waitcnt vmcnt(6)
	s_waitcnt lgkmcnt(0)
	s_barrier
	s_waitcnt lgkmcnt(0)
	s_barrier
	s_add_i32 s71, 0, 0x18000
	v_add_u32_e32 v155, s71, v145
	s_add_i32 s72, 0, 0x1c000
	ds_read_b128 v[156:159], v155
	ds_read_b128 v[160:163], v155 offset:1024
	ds_read_b128 v[164:167], v155 offset:2048
	ds_read_b128 v[168:171], v155 offset:3072
	v_add_u32_e32 v155, s72, v145
	ds_read_b128 v[172:175], v155
	ds_read_b128 v[176:179], v155 offset:1024
	ds_read_b128 v[180:183], v155 offset:2048
	ds_read_b128 v[208:211], v155 offset:3072
	s_add_u32 s40, s40, 0x40000
	s_addc_u32 s41, s41, 0
	s_mov_b32 m0, s82
	v_lshl_add_u64 v[248:249], s[40:41], 0, v[132:133]
	ds_read_b128 v[212:215], v154 offset:32768
	ds_read_b128 v[216:219], v154 offset:33792
	ds_read_b128 v[220:223], v154 offset:34816
	ds_read_b128 v[224:227], v154 offset:35840
	ds_read_b128 v[228:231], v154 offset:36864
	ds_read_b128 v[232:235], v154 offset:37888
	ds_read_b128 v[236:239], v154 offset:38912
	ds_read_b128 v[240:243], v154 offset:39936
	v_lshl_add_u64 v[248:249], s[40:41], 0, v[130:131]
	s_mov_b32 m0, s83
	s_nop 0
	s_waitcnt vmcnt(6)
	s_waitcnt lgkmcnt(0)
	s_barrier
	s_waitcnt lgkmcnt(0)
	v_mfma_f32_16x16x32_bf16 v[126:129], v[156:159], v[212:215], v[126:129]
	v_mfma_f32_16x16x32_bf16 v[122:125], v[164:167], v[212:215], v[122:125]
	v_mfma_f32_16x16x32_bf16 v[110:113], v[156:159], v[220:223], v[110:113]
	v_mfma_f32_16x16x32_bf16 v[106:109], v[164:167], v[220:223], v[106:109]
	v_mfma_f32_16x16x32_bf16 v[94:97], v[156:159], v[228:231], v[94:97]
	v_mfma_f32_16x16x32_bf16 v[90:93], v[164:167], v[228:231], v[90:93]
	v_mfma_f32_16x16x32_bf16 v[78:81], v[156:159], v[236:239], v[78:81]
	v_mfma_f32_16x16x32_bf16 v[74:77], v[164:167], v[236:239], v[74:77]
	v_mfma_f32_16x16x32_bf16 v[126:129], v[160:163], v[216:219], v[126:129]
	v_mfma_f32_16x16x32_bf16 v[122:125], v[168:171], v[216:219], v[122:125]
	v_mfma_f32_16x16x32_bf16 v[110:113], v[160:163], v[224:227], v[110:113]
	v_mfma_f32_16x16x32_bf16 v[106:109], v[168:171], v[224:227], v[106:109]
	v_mfma_f32_16x16x32_bf16 v[94:97], v[160:163], v[232:235], v[94:97]
	v_mfma_f32_16x16x32_bf16 v[90:93], v[168:171], v[232:235], v[90:93]
	v_mfma_f32_16x16x32_bf16 v[78:81], v[160:163], v[240:243], v[78:81]
	v_mfma_f32_16x16x32_bf16 v[74:77], v[168:171], v[240:243], v[74:77]
	v_mfma_f32_16x16x32_bf16 v[118:121], v[172:175], v[212:215], v[118:121]
	v_mfma_f32_16x16x32_bf16 v[114:117], v[180:183], v[212:215], v[114:117]
	v_mfma_f32_16x16x32_bf16 v[102:105], v[172:175], v[220:223], v[102:105]
	v_mfma_f32_16x16x32_bf16 v[98:101], v[180:183], v[220:223], v[98:101]
	v_mfma_f32_16x16x32_bf16 v[86:89], v[172:175], v[228:231], v[86:89]
	v_mfma_f32_16x16x32_bf16 v[82:85], v[180:183], v[228:231], v[82:85]
	v_mfma_f32_16x16x32_bf16 v[70:73], v[172:175], v[236:239], v[70:73]
	v_mfma_f32_16x16x32_bf16 v[66:69], v[180:183], v[236:239], v[66:69]
	v_mfma_f32_16x16x32_bf16 v[118:121], v[176:179], v[216:219], v[118:121]
	v_mfma_f32_16x16x32_bf16 v[114:117], v[208:211], v[216:219], v[114:117]
	v_mfma_f32_16x16x32_bf16 v[102:105], v[176:179], v[224:227], v[102:105]
	v_mfma_f32_16x16x32_bf16 v[98:101], v[208:211], v[224:227], v[98:101]
	v_mfma_f32_16x16x32_bf16 v[86:89], v[176:179], v[232:235], v[86:89]
	v_mfma_f32_16x16x32_bf16 v[82:85], v[208:211], v[232:235], v[82:85]
	v_mfma_f32_16x16x32_bf16 v[70:73], v[176:179], v[240:243], v[70:73]
	v_mfma_f32_16x16x32_bf16 v[66:69], v[208:211], v[240:243], v[66:69]
	s_barrier
	s_add_i32 s40, s71, s80
	v_lshl_add_u64 v[202:203], v[202:203], 0, s[66:67]
	s_mov_b32 m0, s40
	global_load_lds_dwordx4 v[202:203], off
	s_add_i32 m0, s40, 0x2000
	s_add_u32 s34, s34, 0x40080
	v_lshl_add_u64 v[202:203], v[204:205], 0, s[66:67]
	s_addc_u32 s35, s35, 0
	s_add_i32 s40, s72, s80
	global_load_lds_dwordx4 v[202:203], off
	v_lshl_add_u64 v[202:203], s[34:35], 0, v[132:133]
	s_mov_b32 m0, s40
	s_nop 0
	global_load_lds_dwordx4 v[202:203], off
	v_lshl_add_u64 v[202:203], s[34:35], 0, v[130:131]
	s_add_i32 m0, s40, 0x2000
	s_nop 0
	global_load_lds_dwordx4 v[202:203], off
	v_lshl_add_u64 v[202:203], v[244:245], 0, s[66:67]
	s_mov_b32 m0, s84
	s_nop 0
	global_load_lds_dwordx4 v[202:203], off
	v_lshl_add_u64 v[202:203], v[246:247], 0, s[66:67]
	s_mov_b32 m0, s85
	s_nop 0
	global_load_lds_dwordx4 v[202:203], off
	s_waitcnt vmcnt(6)
	s_waitcnt lgkmcnt(0)
	s_barrier
	s_waitcnt lgkmcnt(0)
	s_barrier
	s_add_i32 s62, s62, 2
	s_add_u32 s30, s30, 0x100
	s_addc_u32 s31, s31, 0
	s_add_u32 s52, s52, 0x100
	s_addc_u32 s54, s54, 0
	s_cmp_gt_u32 s62, 13
	s_cbranch_scc0 .Lku_a0
	s_branch .Lku_exit
; #define PG8_STAGE(bufoff, gbase, voff) do { _Pragma("unroll") for (int _i = 0; _i < 2; ++_i) \
;         __builtin_amdgcn_global_load_lds((const unsigned*)((const char*)(gbase) + (voff)[_i]), (PG8_LAS unsigned*)(lds + (bufoff) + ldsw + _i * 8192), 16, 0, 0); } while (0)
; #define PG8_LDA(dst, b, h) do { _Pragma("unroll") for (int m = 0; m < 4; ++m) _Pragma("unroll") for (int k = 0; k < 2; ++k) dst[m][k] = *(const PG8_LAS bf16x8*)(lds + PG8_SA(b, h) + aoff + m * 2048 + k * 1024); } while (0)
; #define PG8_LDB(dst, b, h) do { _Pragma("unroll") for (int n = 0; n < 2; ++n) _Pragma("unroll") for (int k = 0; k < 2; ++k) dst[n][k] = *(const PG8_LAS bf16x8*)(lds + PG8_SB(b, h) + boff + n * 2048 + k * 1024); } while (0)
; #define PG8_MMA(ai, bj, At, Bt) do { __builtin_amdgcn_s_setprio(1); _Pragma("unroll") for (int m = 0; m < 4; ++m) _Pragma("unroll") for (int n = 0; n < 2; ++n) _Pragma("unroll") for (int k = 0; k < 2; ++k) \
;         acc[ai][bj][m][n] = __builtin_amdgcn_mfma_f32_16x16x32_bf16(Bt[n][k], At[m][k], acc[ai][bj][m][n], 0, 0, 0); __builtin_amdgcn_s_setprio(0); } while (0)
; #define PG8_BAR __builtin_amdgcn_s_barrier()
; template <class Epi, class Sched, bool ALIGN_EPI = false, bool SP2 = false>
; __device__ __forceinline__ void gemm_phase(PG8_LAS unsigned char* lds, const Gemm g, const Sched& S, const Epi& E) {
;     ...
;             if constexpr (SP2) {
;             PG8_LDB(B0, 0, 0); PG8_LDB(B1, 0, 1); PG8_SCHED; PG8_LDA(At, 0, 0); PG8_STAGE(PG8_SA(1, 1), a1 + hstep, voffA);
;             PG8_WAIT_V(8); PG8_WAIT_L(0); PG8_BAR; PG8_MMA(0, 0, At, B0); PG8_MMA(0, 1, At, B1); PG8_BAR; PG8_SCHED;
;             PG8_LDA(At, 0, 1); PG8_STAGE(PG8_SB(0, 0), b2, voffB); PG8_STAGE(PG8_SB(0, 1), b2 + hstep, voffB); PG8_STAGE(PG8_SA(0, 0), a2, voffA);
;             PG8_WAIT_V(8); PG8_WAIT_L(0); PG8_BAR; PG8_MMA(1, 0, At, B0); PG8_MMA(1, 1, At, B1); PG8_BAR; PG8_SCHED;
;             PG8_LDB(B0, 1, 0); PG8_LDB(B1, 1, 1); PG8_SCHED; PG8_LDA(At, 1, 0); PG8_STAGE(PG8_SA(0, 1), a2 + hstep, voffA);
;             PG8_WAIT_V(8); PG8_WAIT_L(0); PG8_BAR; PG8_MMA(0, 0, At, B0); PG8_MMA(0, 1, At, B1); PG8_BAR; PG8_SCHED;
;             PG8_LDA(At, 1, 1); PG8_STAGE(PG8_SB(1, 0), b3, voffB); PG8_STAGE(PG8_SB(1, 1), b3 + hstep, voffB); PG8_STAGE(PG8_SA(1, 0), a3, voffA);
;             PG8_WAIT_V(8); PG8_WAIT_L(0); PG8_BAR; PG8_MMA(1, 0, At, B0); PG8_MMA(1, 1, At, B1); PG8_BAR; PG8_SCHED;
.Lku_a1:
	s_add_u32 s34, s30, 0xfffc0080
	s_addc_u32 s35, s31, -1
	s_add_i32 s71, 0, 0x10000
	s_cmp_eq_u32 s62, 12
	s_cselect_b32 s41, s21, s35
	s_cselect_b32 s40, s27, s34
	v_add_u32_e32 v155, s71, v145
	s_cselect_b32 s35, s19, s54
	s_cselect_b32 s34, s50, s52
	s_add_i32 s74, 0, 0x14000
	ds_read_b128 v[156:159], v155
	ds_read_b128 v[160:163], v155 offset:1024
	ds_read_b128 v[164:167], v155 offset:2048
	ds_read_b128 v[168:171], v155 offset:3072
	v_add_u32_e32 v155, s74, v145
	ds_read_b128 v[172:175], v155
	ds_read_b128 v[176:179], v155 offset:1024
	ds_read_b128 v[180:183], v155 offset:2048
	ds_read_b128 v[208:211], v155 offset:3072
	v_lshl_add_u64 v[202:203], s[30:31], 0, v[134:135]
	s_add_i32 m0, s29, 0xc000
	global_load_lds_dwordx4 v[202:203], off
	v_lshl_add_u64 v[202:203], s[30:31], 0, v[136:137]
	s_add_i32 m0, s29, 0xe000
	s_nop 0
	global_load_lds_dwordx4 v[202:203], off
	s_waitcnt vmcnt(6)
	s_waitcnt lgkmcnt(0)
	s_barrier
	s_waitcnt lgkmcnt(0)
	s_barrier
	s_add_i32 s71, s71, s80
	v_lshl_add_u64 v[202:203], s[34:35], 0, v[132:133]
	s_mov_b32 m0, s71
	ds_read_b128 v[212:215], v154 offset:16384
	ds_read_b128 v[216:219], v154 offset:17408
	ds_read_b128 v[220:223], v154 offset:18432
	ds_read_b128 v[224:227], v154 offset:19456
	ds_read_b128 v[228:231], v154 offset:20480
	ds_read_b128 v[232:235], v154 offset:21504
	ds_read_b128 v[236:239], v154 offset:22528
	ds_read_b128 v[240:243], v154 offset:23552
	global_load_lds_dwordx4 v[202:203], off
	s_add_i32 m0, s71, 0x2000
	s_add_u32 s72, s34, 0x40000
	v_lshl_add_u64 v[204:205], s[34:35], 0, v[130:131]
	s_addc_u32 s73, s35, 0
	s_add_i32 s71, s74, s80
	global_load_lds_dwordx4 v[204:205], off
	v_lshl_add_u64 v[244:245], s[72:73], 0, v[132:133]
	s_mov_b32 m0, s71
	v_lshl_add_u64 v[246:247], s[40:41], 0, v[130:131]
	global_load_lds_dwordx4 v[244:245], off
	v_lshl_add_u64 v[244:245], s[72:73], 0, v[130:131]
	s_add_i32 m0, s71, 0x2000
	s_nop 0
	global_load_lds_dwordx4 v[244:245], off
	v_lshl_add_u64 v[244:245], s[40:41], 0, v[132:133]
	s_mov_b32 m0, s29
	s_nop 0
	s_mov_b32 m0, s81
	s_nop 0
	s_waitcnt vmcnt(6)
	s_waitcnt lgkmcnt(0)
	s_barrier
	s_waitcnt lgkmcnt(0)
	v_mfma_f32_16x16x32_bf16 v[62:65], v[156:159], v[212:215], v[62:65]
	v_mfma_f32_16x16x32_bf16 v[58:61], v[164:167], v[212:215], v[58:61]
	v_mfma_f32_16x16x32_bf16 v[46:49], v[156:159], v[220:223], v[46:49]
	v_mfma_f32_16x16x32_bf16 v[42:45], v[164:167], v[220:223], v[42:45]
	v_mfma_f32_16x16x32_bf16 v[30:33], v[156:159], v[228:231], v[30:33]
	v_mfma_f32_16x16x32_bf16 v[26:29], v[164:167], v[228:231], v[26:29]
	v_mfma_f32_16x16x32_bf16 v[14:17], v[156:159], v[236:239], v[14:17]
	v_mfma_f32_16x16x32_bf16 v[10:13], v[164:167], v[236:239], v[10:13]
	v_mfma_f32_16x16x32_bf16 v[62:65], v[160:163], v[216:219], v[62:65]
	v_mfma_f32_16x16x32_bf16 v[58:61], v[168:171], v[216:219], v[58:61]
	v_mfma_f32_16x16x32_bf16 v[46:49], v[160:163], v[224:227], v[46:49]
	v_mfma_f32_16x16x32_bf16 v[42:45], v[168:171], v[224:227], v[42:45]
	v_mfma_f32_16x16x32_bf16 v[30:33], v[160:163], v[232:235], v[30:33]
	v_mfma_f32_16x16x32_bf16 v[26:29], v[168:171], v[232:235], v[26:29]
	v_mfma_f32_16x16x32_bf16 v[14:17], v[160:163], v[240:243], v[14:17]
	v_mfma_f32_16x16x32_bf16 v[10:13], v[168:171], v[240:243], v[10:13]
	v_mfma_f32_16x16x32_bf16 v[54:57], v[172:175], v[212:215], v[54:57]
	v_mfma_f32_16x16x32_bf16 v[50:53], v[180:183], v[212:215], v[50:53]
	v_mfma_f32_16x16x32_bf16 v[38:41], v[172:175], v[220:223], v[38:41]
	v_mfma_f32_16x16x32_bf16 v[34:37], v[180:183], v[220:223], v[34:37]
	v_mfma_f32_16x16x32_bf16 v[22:25], v[172:175], v[228:231], v[22:25]
	v_mfma_f32_16x16x32_bf16 v[18:21], v[180:183], v[228:231], v[18:21]
	v_mfma_f32_16x16x32_bf16 v[6:9], v[172:175], v[236:239], v[6:9]
	v_mfma_f32_16x16x32_bf16 v[2:5], v[180:183], v[236:239], v[2:5]
	v_mfma_f32_16x16x32_bf16 v[54:57], v[176:179], v[216:219], v[54:57]
	v_mfma_f32_16x16x32_bf16 v[50:53], v[208:211], v[216:219], v[50:53]
	v_mfma_f32_16x16x32_bf16 v[38:41], v[176:179], v[224:227], v[38:41]
	v_mfma_f32_16x16x32_bf16 v[34:37], v[208:211], v[224:227], v[34:37]
	v_mfma_f32_16x16x32_bf16 v[22:25], v[176:179], v[232:235], v[22:25]
	v_mfma_f32_16x16x32_bf16 v[18:21], v[208:211], v[232:235], v[18:21]
	v_mfma_f32_16x16x32_bf16 v[6:9], v[176:179], v[240:243], v[6:9]
	v_mfma_f32_16x16x32_bf16 v[2:5], v[208:211], v[240:243], v[2:5]
	s_barrier
	s_add_i32 s71, 0, 0x18000
	v_add_u32_e32 v155, s71, v145
	s_add_i32 s72, 0, 0x1c000
	ds_read_b128 v[156:159], v155
	ds_read_b128 v[160:163], v155 offset:1024
	ds_read_b128 v[164:167], v155 offset:2048
	ds_read_b128 v[168:171], v155 offset:3072
	v_add_u32_e32 v155, s72, v145
	ds_read_b128 v[172:175], v155
	ds_read_b128 v[176:179], v155 offset:1024
	ds_read_b128 v[180:183], v155 offset:2048
	ds_read_b128 v[208:211], v155 offset:3072
	s_add_u32 s40, s40, 0x40000
	s_addc_u32 s41, s41, 0
	s_mov_b32 m0, s82
	v_lshl_add_u64 v[248:249], s[40:41], 0, v[132:133]
	global_load_lds_dwordx4 v[248:249], off
	v_lshl_add_u64 v[248:249], s[40:41], 0, v[130:131]
	s_mov_b32 m0, s83
	s_nop 0
	global_load_lds_dwordx4 v[248:249], off
	s_waitcnt vmcnt(6)
	s_waitcnt lgkmcnt(0)
	s_barrier
	s_waitcnt lgkmcnt(0)
	s_barrier
; #define PG8_STAGE(bufoff, gbase, voff) do { _Pragma("unroll") for (int _i = 0; _i < 2; ++_i) \
;         __builtin_amdgcn_global_load_lds((const unsigned*)((const char*)(gbase) + (voff)[_i]), (PG8_LAS unsigned*)(lds + (bufoff) + ldsw + _i * 8192), 16, 0, 0); } while (0)
; #define PG8_LDA(dst, b, h) do { _Pragma("unroll") for (int m = 0; m < 4; ++m) _Pragma("unroll") for (int k = 0; k < 2; ++k) dst[m][k] = *(const PG8_LAS bf16x8*)(lds + PG8_SA(b, h) + aoff + m * 2048 + k * 1024); } while (0)
; #define PG8_LDB(dst, b, h) do { _Pragma("unroll") for (int n = 0; n < 2; ++n) _Pragma("unroll") for (int k = 0; k < 2; ++k) dst[n][k] = *(const PG8_LAS bf16x8*)(lds + PG8_SB(b, h) + boff + n * 2048 + k * 1024); } while (0)
; #define PG8_MMA(ai, bj, At, Bt) do { __builtin_amdgcn_s_setprio(1); _Pragma("unroll") for (int m = 0; m < 4; ++m) _Pragma("unroll") for (int n = 0; n < 2; ++n) _Pragma("unroll") for (int k = 0; k < 2; ++k) \
;         acc[ai][bj][m][n] = __builtin_amdgcn_mfma_f32_16x16x32_bf16(Bt[n][k], At[m][k], acc[ai][bj][m][n], 0, 0, 0); __builtin_amdgcn_s_setprio(0); } while (0)
; #define PG8_BAR __builtin_amdgcn_s_barrier()
; template <class Epi, class Sched, bool ALIGN_EPI = false, bool SP2 = false>
; __device__ __forceinline__ void gemm_phase(PG8_LAS unsigned char* lds, const Gemm g, const Sched& S, const Epi& E) {
;     ...
;             if constexpr (SP2) {
;             PG8_LDB(B0, 0, 0); PG8_LDB(B1, 0, 1); PG8_SCHED; PG8_LDA(At, 0, 0); PG8_STAGE(PG8_SA(1, 1), a1 + hstep, voffA);
;             PG8_WAIT_V(8); PG8_WAIT_L(0); PG8_BAR; PG8_MMA(0, 0, At, B0); PG8_MMA(0, 1, At, B1); PG8_BAR; PG8_SCHED;
;             PG8_LDA(At, 0, 1); PG8_STAGE(PG8_SB(0, 0), b2, voffB); PG8_STAGE(PG8_SB(0, 1), b2 + hstep, voffB); PG8_STAGE(PG8_SA(0, 0), a2, voffA);
;             PG8_WAIT_V(8); PG8_WAIT_L(0); PG8_BAR; PG8_MMA(1, 0, At, B0); PG8_MMA(1, 1, At, B1); PG8_BAR; PG8_SCHED;
;             PG8_LDB(B0, 1, 0); PG8_LDB(B1, 1, 1); PG8_SCHED; PG8_LDA(At, 1, 0); PG8_STAGE(PG8_SA(0, 1), a2 + hstep, voffA);
;             PG8_WAIT_V(8); PG8_WAIT_L(0); PG8_BAR; PG8_MMA(0, 0, At, B0); PG8_MMA(0, 1, At, B1); PG8_BAR; PG8_SCHED;
;             PG8_LDA(At, 1, 1); PG8_STAGE(PG8_SB(1, 0), b3, voffB); PG8_STAGE(PG8_SB(1, 1), b3 + hstep, voffB); PG8_STAGE(PG8_SA(1, 0), a3, voffA);
;             PG8_WAIT_V(8); PG8_WAIT_L(0); PG8_BAR; PG8_MMA(1, 0, At, B0); PG8_MMA(1, 1, At, B1); PG8_BAR; PG8_SCHED;
	s_add_i32 s40, s71, s80
	v_lshl_add_u64 v[202:203], v[202:203], 0, s[66:67]
	s_mov_b32 m0, s40
	ds_read_b128 v[212:215], v154 offset:49152
	ds_read_b128 v[216:219], v154 offset:50176
	ds_read_b128 v[220:223], v154 offset:51200
	ds_read_b128 v[224:227], v154 offset:52224
	ds_read_b128 v[228:231], v154 offset:53248
	ds_read_b128 v[232:235], v154 offset:54272
	ds_read_b128 v[236:239], v154 offset:55296
	ds_read_b128 v[240:243], v154 offset:56320
	global_load_lds_dwordx4 v[202:203], off
	s_add_i32 m0, s40, 0x2000
	s_add_u32 s34, s34, 0x40080
	v_lshl_add_u64 v[202:203], v[204:205], 0, s[66:67]
	s_addc_u32 s35, s35, 0
	s_add_i32 s40, s72, s80
	global_load_lds_dwordx4 v[202:203], off
	v_lshl_add_u64 v[202:203], s[34:35], 0, v[132:133]
	s_mov_b32 m0, s40
	s_nop 0
	global_load_lds_dwordx4 v[202:203], off
	v_lshl_add_u64 v[202:203], s[34:35], 0, v[130:131]
	s_add_i32 m0, s40, 0x2000
	s_nop 0
	global_load_lds_dwordx4 v[202:203], off
	v_lshl_add_u64 v[202:203], v[244:245], 0, s[66:67]
	s_mov_b32 m0, s84
	s_nop 0
	v_lshl_add_u64 v[202:203], v[246:247], 0, s[66:67]
	s_mov_b32 m0, s85
	s_nop 0
	s_waitcnt vmcnt(6)
	s_waitcnt lgkmcnt(0)
	s_barrier
	s_waitcnt lgkmcnt(0)
	v_mfma_f32_16x16x32_bf16 v[62:65], v[156:159], v[212:215], v[62:65]
	v_mfma_f32_16x16x32_bf16 v[58:61], v[164:167], v[212:215], v[58:61]
	v_mfma_f32_16x16x32_bf16 v[46:49], v[156:159], v[220:223], v[46:49]
	v_mfma_f32_16x16x32_bf16 v[42:45], v[164:167], v[220:223], v[42:45]
	v_mfma_f32_16x16x32_bf16 v[30:33], v[156:159], v[228:231], v[30:33]
	v_mfma_f32_16x16x32_bf16 v[26:29], v[164:167], v[228:231], v[26:29]
	v_mfma_f32_16x16x32_bf16 v[14:17], v[156:159], v[236:239], v[14:17]
	v_mfma_f32_16x16x32_bf16 v[10:13], v[164:167], v[236:239], v[10:13]
	v_mfma_f32_16x16x32_bf16 v[62:65], v[160:163], v[216:219], v[62:65]
	v_mfma_f32_16x16x32_bf16 v[58:61], v[168:171], v[216:219], v[58:61]
	v_mfma_f32_16x16x32_bf16 v[46:49], v[160:163], v[224:227], v[46:49]
	v_mfma_f32_16x16x32_bf16 v[42:45], v[168:171], v[224:227], v[42:45]
	v_mfma_f32_16x16x32_bf16 v[30:33], v[160:163], v[232:235], v[30:33]
	v_mfma_f32_16x16x32_bf16 v[26:29], v[168:171], v[232:235], v[26:29]
	v_mfma_f32_16x16x32_bf16 v[14:17], v[160:163], v[240:243], v[14:17]
	v_mfma_f32_16x16x32_bf16 v[10:13], v[168:171], v[240:243], v[10:13]
	v_mfma_f32_16x16x32_bf16 v[54:57], v[172:175], v[212:215], v[54:57]
	v_mfma_f32_16x16x32_bf16 v[50:53], v[180:183], v[212:215], v[50:53]
	v_mfma_f32_16x16x32_bf16 v[38:41], v[172:175], v[220:223], v[38:41]
	v_mfma_f32_16x16x32_bf16 v[34:37], v[180:183], v[220:223], v[34:37]
	v_mfma_f32_16x16x32_bf16 v[22:25], v[172:175], v[228:231], v[22:25]
	v_mfma_f32_16x16x32_bf16 v[18:21], v[180:183], v[228:231], v[18:21]
	v_mfma_f32_16x16x32_bf16 v[6:9], v[172:175], v[236:239], v[6:9]
	v_mfma_f32_16x16x32_bf16 v[2:5], v[180:183], v[236:239], v[2:5]
	v_mfma_f32_16x16x32_bf16 v[54:57], v[176:179], v[216:219], v[54:57]
	v_mfma_f32_16x16x32_bf16 v[50:53], v[208:211], v[216:219], v[50:53]
	v_mfma_f32_16x16x32_bf16 v[38:41], v[176:179], v[224:227], v[38:41]
	v_mfma_f32_16x16x32_bf16 v[34:37], v[208:211], v[224:227], v[34:37]
	v_mfma_f32_16x16x32_bf16 v[22:25], v[176:179], v[232:235], v[22:25]
	v_mfma_f32_16x16x32_bf16 v[18:21], v[208:211], v[232:235], v[18:21]
	v_mfma_f32_16x16x32_bf16 v[6:9], v[176:179], v[240:243], v[6:9]
	v_mfma_f32_16x16x32_bf16 v[2:5], v[208:211], v[240:243], v[2:5]
	s_barrier
	s_add_i32 s62, s62, 2
	s_add_u32 s30, s30, 0x100
	s_addc_u32 s31, s31, 0
	s_add_u32 s52, s52, 0x100
	s_addc_u32 s54, s54, 0
	s_cmp_gt_u32 s62, 13
	s_cbranch_scc0 .Lku_a1
	s_branch .Lku_exit
.Lkuq_1:
	s_add_u32 s34, s30, 0xfffc0080
	s_addc_u32 s35, s31, -1
	s_add_i32 s71, 0, 0x10000
	s_cmp_eq_u32 s62, 12
	s_cselect_b32 s41, s21, s35
	s_cselect_b32 s40, s27, s34
	v_add_u32_e32 v155, s71, v145
	s_cselect_b32 s35, s19, s54
	s_cselect_b32 s34, s50, s52
	s_add_i32 s74, 0, 0x14000
	ds_read_b128 v[156:159], v155
	ds_read_b128 v[160:163], v155 offset:1024
	ds_read_b128 v[164:167], v155 offset:2048
	ds_read_b128 v[168:171], v155 offset:3072
	v_add_u32_e32 v155, s74, v145
	v_lshl_add_u64 v[202:203], s[30:31], 0, v[134:135]
	s_add_i32 m0, s29, 0xc000
	ds_read_b128 v[212:215], v154
	ds_read_b128 v[216:219], v154 offset:1024
	ds_read_b128 v[220:223], v154 offset:2048
	ds_read_b128 v[224:227], v154 offset:3072
	ds_read_b128 v[228:231], v154 offset:4096
	ds_read_b128 v[232:235], v154 offset:5120
	ds_read_b128 v[236:239], v154 offset:6144
	ds_read_b128 v[240:243], v154 offset:7168
	v_lshl_add_u64 v[202:203], s[30:31], 0, v[136:137]
	s_add_i32 m0, s29, 0xe000
	s_nop 0
	s_waitcnt vmcnt(4)
	s_waitcnt lgkmcnt(0)
	s_barrier
	s_waitcnt lgkmcnt(0)
	v_mfma_f32_16x16x32_bf16 v[126:129], v[156:159], v[212:215], v[126:129]
	v_mfma_f32_16x16x32_bf16 v[122:125], v[164:167], v[212:215], v[122:125]
	v_mfma_f32_16x16x32_bf16 v[110:113], v[156:159], v[220:223], v[110:113]
	v_mfma_f32_16x16x32_bf16 v[106:109], v[164:167], v[220:223], v[106:109]
	v_mfma_f32_16x16x32_bf16 v[94:97], v[156:159], v[228:231], v[94:97]
	v_mfma_f32_16x16x32_bf16 v[90:93], v[164:167], v[228:231], v[90:93]
	v_mfma_f32_16x16x32_bf16 v[78:81], v[156:159], v[236:239], v[78:81]
	v_mfma_f32_16x16x32_bf16 v[74:77], v[164:167], v[236:239], v[74:77]
	v_mfma_f32_16x16x32_bf16 v[126:129], v[160:163], v[216:219], v[126:129]
	v_mfma_f32_16x16x32_bf16 v[122:125], v[168:171], v[216:219], v[122:125]
	v_mfma_f32_16x16x32_bf16 v[110:113], v[160:163], v[224:227], v[110:113]
	v_mfma_f32_16x16x32_bf16 v[106:109], v[168:171], v[224:227], v[106:109]
	v_mfma_f32_16x16x32_bf16 v[94:97], v[160:163], v[232:235], v[94:97]
	v_mfma_f32_16x16x32_bf16 v[90:93], v[168:171], v[232:235], v[90:93]
	v_mfma_f32_16x16x32_bf16 v[78:81], v[160:163], v[240:243], v[78:81]
	v_mfma_f32_16x16x32_bf16 v[74:77], v[168:171], v[240:243], v[74:77]
	s_barrier
; #define PG8_STAGE(bufoff, gbase, voff) do { _Pragma("unroll") for (int _i = 0; _i < 2; ++_i) \
;         __builtin_amdgcn_global_load_lds((const unsigned*)((const char*)(gbase) + (voff)[_i]), (PG8_LAS unsigned*)(lds + (bufoff) + ldsw + _i * 8192), 16, 0, 0); } while (0)
; #define PG8_LDA(dst, b, h) do { _Pragma("unroll") for (int m = 0; m < 4; ++m) _Pragma("unroll") for (int k = 0; k < 2; ++k) dst[m][k] = *(const PG8_LAS bf16x8*)(lds + PG8_SA(b, h) + aoff + m * 2048 + k * 1024); } while (0)
; #define PG8_LDB(dst, b, h) do { _Pragma("unroll") for (int n = 0; n < 2; ++n) _Pragma("unroll") for (int k = 0; k < 2; ++k) dst[n][k] = *(const PG8_LAS bf16x8*)(lds + PG8_SB(b, h) + boff + n * 2048 + k * 1024); } while (0)
; #define PG8_MMA(ai, bj, At, Bt) do { __builtin_amdgcn_s_setprio(1); _Pragma("unroll") for (int m = 0; m < 4; ++m) _Pragma("unroll") for (int n = 0; n < 2; ++n) _Pragma("unroll") for (int k = 0; k < 2; ++k) \
;         acc[ai][bj][m][n] = __builtin_amdgcn_mfma_f32_16x16x32_bf16(Bt[n][k], At[m][k], acc[ai][bj][m][n], 0, 0, 0); __builtin_amdgcn_s_setprio(0); } while (0)
; #define PG8_BAR __builtin_amdgcn_s_barrier()
; template <class Epi, class Sched, bool ALIGN_EPI = false, bool SP2 = false>
; __device__ __forceinline__ void gemm_phase(PG8_LAS unsigned char* lds, const Gemm g, const Sched& S, const Epi& E) {
;     ...
;             if constexpr (SP2) {
;             PG8_LDB(B0, 0, 0); PG8_LDB(B1, 0, 1); PG8_SCHED; PG8_LDA(At, 0, 0); PG8_STAGE(PG8_SA(1, 1), a1 + hstep, voffA);
;             PG8_WAIT_V(8); PG8_WAIT_L(0); PG8_BAR; PG8_MMA(0, 0, At, B0); PG8_MMA(0, 1, At, B1); PG8_BAR; PG8_SCHED;
;             PG8_LDA(At, 0, 1); PG8_STAGE(PG8_SB(0, 0), b2, voffB); PG8_STAGE(PG8_SB(0, 1), b2 + hstep, voffB); PG8_STAGE(PG8_SA(0, 0), a2, voffA);
;             PG8_WAIT_V(8); PG8_WAIT_L(0); PG8_BAR; PG8_MMA(1, 0, At, B0); PG8_MMA(1, 1, At, B1); PG8_BAR; PG8_SCHED;
;             PG8_LDB(B0, 1, 0); PG8_LDB(B1, 1, 1); PG8_SCHED; PG8_LDA(At, 1, 0); PG8_STAGE(PG8_SA(0, 1), a2 + hstep, voffA);
;             PG8_WAIT_V(8); PG8_WAIT_L(0); PG8_BAR; PG8_MMA(0, 0, At, B0); PG8_MMA(0, 1, At, B1); PG8_BAR; PG8_SCHED;
;             PG8_LDA(At, 1, 1); PG8_STAGE(PG8_SB(1, 0), b3, voffB); PG8_STAGE(PG8_SB(1, 1), b3 + hstep, voffB); PG8_STAGE(PG8_SA(1, 0), a3, voffA);
;             PG8_WAIT_V(8); PG8_WAIT_L(0); PG8_BAR; PG8_MMA(1, 0, At, B0); PG8_MMA(1, 1, At, B1); PG8_BAR; PG8_SCHED;
	s_add_i32 s71, s71, s80
	v_lshl_add_u64 v[202:203], s[34:35], 0, v[132:133]
	s_mov_b32 m0, s71
	global_load_lds_dwordx4 v[202:203], off
	s_add_i32 m0, s71, 0x2000
	s_add_u32 s72, s34, 0x40000
	v_lshl_add_u64 v[204:205], s[34:35], 0, v[130:131]
	s_addc_u32 s73, s35, 0
	s_add_i32 s71, s74, s80
	global_load_lds_dwordx4 v[204:205], off
	v_lshl_add_u64 v[244:245], s[72:73], 0, v[132:133]
	s_mov_b32 m0, s71
	v_lshl_add_u64 v[246:247], s[40:41], 0, v[130:131]
	v_lshl_add_u64 v[244:245], s[72:73], 0, v[130:131]
	s_add_i32 m0, s71, 0x2000
	s_nop 0
	v_lshl_add_u64 v[244:245], s[40:41], 0, v[132:133]
	s_mov_b32 m0, s29
	s_nop 0
	global_load_lds_dwordx4 v[244:245], off
	s_mov_b32 m0, s81
	s_nop 0
	global_load_lds_dwordx4 v[246:247], off
	s_waitcnt vmcnt(4)
	s_waitcnt lgkmcnt(0)
	s_barrier
	s_waitcnt lgkmcnt(0)
	s_barrier
	s_add_i32 s71, 0, 0x18000
	v_add_u32_e32 v155, s71, v145
	s_add_i32 s72, 0, 0x1c000
	ds_read_b128 v[156:159], v155
	ds_read_b128 v[160:163], v155 offset:1024
	ds_read_b128 v[164:167], v155 offset:2048
	ds_read_b128 v[168:171], v155 offset:3072
	v_add_u32_e32 v155, s72, v145
	s_add_u32 s40, s40, 0x40000
	s_addc_u32 s41, s41, 0
	s_mov_b32 m0, s82
	v_lshl_add_u64 v[248:249], s[40:41], 0, v[132:133]
	ds_read_b128 v[212:215], v154 offset:32768
	ds_read_b128 v[216:219], v154 offset:33792
	ds_read_b128 v[220:223], v154 offset:34816
	ds_read_b128 v[224:227], v154 offset:35840
	ds_read_b128 v[228:231], v154 offset:36864
	ds_read_b128 v[232:235], v154 offset:37888
	ds_read_b128 v[236:239], v154 offset:38912
	ds_read_b128 v[240:243], v154 offset:39936
	v_lshl_add_u64 v[248:249], s[40:41], 0, v[130:131]
	s_mov_b32 m0, s83
	s_nop 0
	s_waitcnt vmcnt(4)
	s_waitcnt lgkmcnt(0)
	s_barrier
	s_waitcnt lgkmcnt(0)
	v_mfma_f32_16x16x32_bf16 v[126:129], v[156:159], v[212:215], v[126:129]
	v_mfma_f32_16x16x32_bf16 v[122:125], v[164:167], v[212:215], v[122:125]
	v_mfma_f32_16x16x32_bf16 v[110:113], v[156:159], v[220:223], v[110:113]
	v_mfma_f32_16x16x32_bf16 v[106:109], v[164:167], v[220:223], v[106:109]
	v_mfma_f32_16x16x32_bf16 v[94:97], v[156:159], v[228:231], v[94:97]
	v_mfma_f32_16x16x32_bf16 v[90:93], v[164:167], v[228:231], v[90:93]
	v_mfma_f32_16x16x32_bf16 v[78:81], v[156:159], v[236:239], v[78:81]
	v_mfma_f32_16x16x32_bf16 v[74:77], v[164:167], v[236:239], v[74:77]
	v_mfma_f32_16x16x32_bf16 v[126:129], v[160:163], v[216:219], v[126:129]
	v_mfma_f32_16x16x32_bf16 v[122:125], v[168:171], v[216:219], v[122:125]
	v_mfma_f32_16x16x32_bf16 v[110:113], v[160:163], v[224:227], v[110:113]
	v_mfma_f32_16x16x32_bf16 v[106:109], v[168:171], v[224:227], v[106:109]
	v_mfma_f32_16x16x32_bf16 v[94:97], v[160:163], v[232:235], v[94:97]
	v_mfma_f32_16x16x32_bf16 v[90:93], v[168:171], v[232:235], v[90:93]
	v_mfma_f32_16x16x32_bf16 v[78:81], v[160:163], v[240:243], v[78:81]
	v_mfma_f32_16x16x32_bf16 v[74:77], v[168:171], v[240:243], v[74:77]
	s_barrier
	s_add_i32 s40, s71, s80
	v_lshl_add_u64 v[202:203], v[202:203], 0, s[66:67]
	s_mov_b32 m0, s40
	global_load_lds_dwordx4 v[202:203], off
	s_add_i32 m0, s40, 0x2000
	s_add_u32 s34, s34, 0x40080
	v_lshl_add_u64 v[202:203], v[204:205], 0, s[66:67]
	s_addc_u32 s35, s35, 0
	s_add_i32 s40, s72, s80
	global_load_lds_dwordx4 v[202:203], off
	v_lshl_add_u64 v[202:203], s[34:35], 0, v[132:133]
	s_mov_b32 m0, s40
	s_nop 0
	v_lshl_add_u64 v[202:203], s[34:35], 0, v[130:131]
	s_add_i32 m0, s40, 0x2000
	s_nop 0
	v_lshl_add_u64 v[202:203], v[244:245], 0, s[66:67]
	s_mov_b32 m0, s84
	s_nop 0
	global_load_lds_dwordx4 v[202:203], off
	v_lshl_add_u64 v[202:203], v[246:247], 0, s[66:67]
	s_mov_b32 m0, s85
	s_nop 0
	global_load_lds_dwordx4 v[202:203], off
	s_waitcnt vmcnt(4)
	s_waitcnt lgkmcnt(0)
	s_barrier
	s_waitcnt lgkmcnt(0)
	s_barrier
	s_add_i32 s62, s62, 2
	s_add_u32 s30, s30, 0x100
	s_addc_u32 s31, s31, 0
	s_add_u32 s52, s52, 0x100
	s_addc_u32 s54, s54, 0
	s_cmp_gt_u32 s62, 13
	s_cbranch_scc0 .Lkuq_1
	s_branch .Lku_exit
.Lkuq_2:
	s_add_u32 s34, s30, 0xfffc0080
	s_addc_u32 s35, s31, -1
	s_add_i32 s71, 0, 0x10000
	s_cmp_eq_u32 s62, 12
	s_cselect_b32 s41, s21, s35
	s_cselect_b32 s40, s27, s34
	v_add_u32_e32 v155, s71, v145
	s_cselect_b32 s35, s19, s54
	s_cselect_b32 s34, s50, s52
	s_add_i32 s74, 0, 0x14000
	ds_read_b128 v[156:159], v155
	ds_read_b128 v[160:163], v155 offset:1024
	ds_read_b128 v[164:167], v155 offset:2048
	ds_read_b128 v[168:171], v155 offset:3072
	v_add_u32_e32 v155, s74, v145
	v_lshl_add_u64 v[202:203], s[30:31], 0, v[134:135]
	s_add_i32 m0, s29, 0xc000
	global_load_lds_dwordx4 v[202:203], off
	v_lshl_add_u64 v[202:203], s[30:31], 0, v[136:137]
	s_add_i32 m0, s29, 0xe000
	s_nop 0
	global_load_lds_dwordx4 v[202:203], off
	s_waitcnt vmcnt(4)
	s_waitcnt lgkmcnt(0)
	s_barrier
	s_waitcnt lgkmcnt(0)
	s_barrier
	s_add_i32 s71, s71, s80
	v_lshl_add_u64 v[202:203], s[34:35], 0, v[132:133]
	s_mov_b32 m0, s71
	ds_read_b128 v[212:215], v154 offset:16384
	ds_read_b128 v[216:219], v154 offset:17408
	ds_read_b128 v[220:223], v154 offset:18432
	ds_read_b128 v[224:227], v154 offset:19456
	ds_read_b128 v[228:231], v154 offset:20480
	ds_read_b128 v[232:235], v154 offset:21504
	ds_read_b128 v[236:239], v154 offset:22528
	ds_read_b128 v[240:243], v154 offset:23552
	global_load_lds_dwordx4 v[202:203], off
	s_add_i32 m0, s71, 0x2000
	s_add_u32 s72, s34, 0x40000
	v_lshl_add_u64 v[204:205], s[34:35], 0, v[130:131]
	s_addc_u32 s73, s35, 0
	s_add_i32 s71, s74, s80
	global_load_lds_dwordx4 v[204:205], off
	v_lshl_add_u64 v[244:245], s[72:73], 0, v[132:133]
	s_mov_b32 m0, s71
	v_lshl_add_u64 v[246:247], s[40:41], 0, v[130:131]
	v_lshl_add_u64 v[244:245], s[72:73], 0, v[130:131]
	s_add_i32 m0, s71, 0x2000
	s_nop 0
	v_lshl_add_u64 v[244:245], s[40:41], 0, v[132:133]
	s_mov_b32 m0, s29
	s_nop 0
	s_mov_b32 m0, s81
	s_nop 0
	s_waitcnt vmcnt(4)
	s_waitcnt lgkmcnt(0)
	s_barrier
; #define PG8_STAGE(bufoff, gbase, voff) do { _Pragma("unroll") for (int _i = 0; _i < 2; ++_i) \
;         __builtin_amdgcn_global_load_lds((const unsigned*)((const char*)(gbase) + (voff)[_i]), (PG8_LAS unsigned*)(lds + (bufoff) + ldsw + _i * 8192), 16, 0, 0); } while (0)
; #define PG8_LDA(dst, b, h) do { _Pragma("unroll") for (int m = 0; m < 4; ++m) _Pragma("unroll") for (int k = 0; k < 2; ++k) dst[m][k] = *(const PG8_LAS bf16x8*)(lds + PG8_SA(b, h) + aoff + m * 2048 + k * 1024); } while (0)
; #define PG8_LDB(dst, b, h) do { _Pragma("unroll") for (int n = 0; n < 2; ++n) _Pragma("unroll") for (int k = 0; k < 2; ++k) dst[n][k] = *(const PG8_LAS bf16x8*)(lds + PG8_SB(b, h) + boff + n * 2048 + k * 1024); } while (0)
; #define PG8_MMA(ai, bj, At, Bt) do { __builtin_amdgcn_s_setprio(1); _Pragma("unroll") for (int m = 0; m < 4; ++m) _Pragma("unroll") for (int n = 0; n < 2; ++n) _Pragma("unroll") for (int k = 0; k < 2; ++k) \
;         acc[ai][bj][m][n] = __builtin_amdgcn_mfma_f32_16x16x32_bf16(Bt[n][k], At[m][k], acc[ai][bj][m][n], 0, 0, 0); __builtin_amdgcn_s_setprio(0); } while (0)
; #define PG8_BAR __builtin_amdgcn_s_barrier()
; template <class Epi, class Sched, bool ALIGN_EPI = false, bool SP2 = false>
; __device__ __forceinline__ void gemm_phase(PG8_LAS unsigned char* lds, const Gemm g, const Sched& S, const Epi& E) {
;     ...
;             if constexpr (SP2) {
;             PG8_LDB(B0, 0, 0); PG8_LDB(B1, 0, 1); PG8_SCHED; PG8_LDA(At, 0, 0); PG8_STAGE(PG8_SA(1, 1), a1 + hstep, voffA);
;             PG8_WAIT_V(8); PG8_WAIT_L(0); PG8_BAR; PG8_MMA(0, 0, At, B0); PG8_MMA(0, 1, At, B1); PG8_BAR; PG8_SCHED;
;             PG8_LDA(At, 0, 1); PG8_STAGE(PG8_SB(0, 0), b2, voffB); PG8_STAGE(PG8_SB(0, 1), b2 + hstep, voffB); PG8_STAGE(PG8_SA(0, 0), a2, voffA);
;             PG8_WAIT_V(8); PG8_WAIT_L(0); PG8_BAR; PG8_MMA(1, 0, At, B0); PG8_MMA(1, 1, At, B1); PG8_BAR; PG8_SCHED;
;             PG8_LDB(B0, 1, 0); PG8_LDB(B1, 1, 1); PG8_SCHED; PG8_LDA(At, 1, 0); PG8_STAGE(PG8_SA(0, 1), a2 + hstep, voffA);
;             PG8_WAIT_V(8); PG8_WAIT_L(0); PG8_BAR; PG8_MMA(0, 0, At, B0); PG8_MMA(0, 1, At, B1); PG8_BAR; PG8_SCHED;
;             PG8_LDA(At, 1, 1); PG8_STAGE(PG8_SB(1, 0), b3, voffB); PG8_STAGE(PG8_SB(1, 1), b3 + hstep, voffB); PG8_STAGE(PG8_SA(1, 0), a3, voffA);
;             PG8_WAIT_V(8); PG8_WAIT_L(0); PG8_BAR; PG8_MMA(1, 0, At, B0); PG8_MMA(1, 1, At, B1); PG8_BAR; PG8_SCHED;
	s_waitcnt lgkmcnt(0)
	v_mfma_f32_16x16x32_bf16 v[62:65], v[156:159], v[212:215], v[62:65]
	v_mfma_f32_16x16x32_bf16 v[58:61], v[164:167], v[212:215], v[58:61]
	v_mfma_f32_16x16x32_bf16 v[46:49], v[156:159], v[220:223], v[46:49]
	v_mfma_f32_16x16x32_bf16 v[42:45], v[164:167], v[220:223], v[42:45]
	v_mfma_f32_16x16x32_bf16 v[30:33], v[156:159], v[228:231], v[30:33]
	v_mfma_f32_16x16x32_bf16 v[26:29], v[164:167], v[228:231], v[26:29]
	v_mfma_f32_16x16x32_bf16 v[14:17], v[156:159], v[236:239], v[14:17]
	v_mfma_f32_16x16x32_bf16 v[10:13], v[164:167], v[236:239], v[10:13]
	v_mfma_f32_16x16x32_bf16 v[62:65], v[160:163], v[216:219], v[62:65]
	v_mfma_f32_16x16x32_bf16 v[58:61], v[168:171], v[216:219], v[58:61]
	v_mfma_f32_16x16x32_bf16 v[46:49], v[160:163], v[224:227], v[46:49]
	v_mfma_f32_16x16x32_bf16 v[42:45], v[168:171], v[224:227], v[42:45]
	v_mfma_f32_16x16x32_bf16 v[30:33], v[160:163], v[232:235], v[30:33]
	v_mfma_f32_16x16x32_bf16 v[26:29], v[168:171], v[232:235], v[26:29]
	v_mfma_f32_16x16x32_bf16 v[14:17], v[160:163], v[240:243], v[14:17]
	v_mfma_f32_16x16x32_bf16 v[10:13], v[168:171], v[240:243], v[10:13]
	s_barrier
	s_add_i32 s71, 0, 0x18000
	v_add_u32_e32 v155, s71, v145
	s_add_i32 s72, 0, 0x1c000
	ds_read_b128 v[156:159], v155
	ds_read_b128 v[160:163], v155 offset:1024
	ds_read_b128 v[164:167], v155 offset:2048
	ds_read_b128 v[168:171], v155 offset:3072
	v_add_u32_e32 v155, s72, v145
	s_add_u32 s40, s40, 0x40000
	s_addc_u32 s41, s41, 0
	s_mov_b32 m0, s82
	v_lshl_add_u64 v[248:249], s[40:41], 0, v[132:133]
	global_load_lds_dwordx4 v[248:249], off
	v_lshl_add_u64 v[248:249], s[40:41], 0, v[130:131]
	s_mov_b32 m0, s83
	s_nop 0
	global_load_lds_dwordx4 v[248:249], off
	s_waitcnt vmcnt(4)
	s_waitcnt lgkmcnt(0)
	s_barrier
	s_waitcnt lgkmcnt(0)
	s_barrier
	s_add_i32 s40, s71, s80
	v_lshl_add_u64 v[202:203], v[202:203], 0, s[66:67]
	s_mov_b32 m0, s40
	ds_read_b128 v[212:215], v154 offset:49152
	ds_read_b128 v[216:219], v154 offset:50176
	ds_read_b128 v[220:223], v154 offset:51200
	ds_read_b128 v[224:227], v154 offset:52224
	ds_read_b128 v[228:231], v154 offset:53248
	ds_read_b128 v[232:235], v154 offset:54272
	ds_read_b128 v[236:239], v154 offset:55296
	ds_read_b128 v[240:243], v154 offset:56320
	global_load_lds_dwordx4 v[202:203], off
	s_add_i32 m0, s40, 0x2000
	s_add_u32 s34, s34, 0x40080
	v_lshl_add_u64 v[202:203], v[204:205], 0, s[66:67]
	s_addc_u32 s35, s35, 0
	s_add_i32 s40, s72, s80
	global_load_lds_dwordx4 v[202:203], off
	v_lshl_add_u64 v[202:203], s[34:35], 0, v[132:133]
	s_mov_b32 m0, s40
	s_nop 0
	v_lshl_add_u64 v[202:203], s[34:35], 0, v[130:131]
	s_add_i32 m0, s40, 0x2000
	s_nop 0
	v_lshl_add_u64 v[202:203], v[244:245], 0, s[66:67]
	s_mov_b32 m0, s84
	s_nop 0
	v_lshl_add_u64 v[202:203], v[246:247], 0, s[66:67]
	s_mov_b32 m0, s85
	s_nop 0
	s_waitcnt vmcnt(4)
	s_waitcnt lgkmcnt(0)
	s_barrier
	s_waitcnt lgkmcnt(0)
	v_mfma_f32_16x16x32_bf16 v[62:65], v[156:159], v[212:215], v[62:65]
	v_mfma_f32_16x16x32_bf16 v[58:61], v[164:167], v[212:215], v[58:61]
	v_mfma_f32_16x16x32_bf16 v[46:49], v[156:159], v[220:223], v[46:49]
	v_mfma_f32_16x16x32_bf16 v[42:45], v[164:167], v[220:223], v[42:45]
	v_mfma_f32_16x16x32_bf16 v[30:33], v[156:159], v[228:231], v[30:33]
	v_mfma_f32_16x16x32_bf16 v[26:29], v[164:167], v[228:231], v[26:29]
	v_mfma_f32_16x16x32_bf16 v[14:17], v[156:159], v[236:239], v[14:17]
	v_mfma_f32_16x16x32_bf16 v[10:13], v[164:167], v[236:239], v[10:13]
	v_mfma_f32_16x16x32_bf16 v[62:65], v[160:163], v[216:219], v[62:65]
	v_mfma_f32_16x16x32_bf16 v[58:61], v[168:171], v[216:219], v[58:61]
	v_mfma_f32_16x16x32_bf16 v[46:49], v[160:163], v[224:227], v[46:49]
	v_mfma_f32_16x16x32_bf16 v[42:45], v[168:171], v[224:227], v[42:45]
	v_mfma_f32_16x16x32_bf16 v[30:33], v[160:163], v[232:235], v[30:33]
	v_mfma_f32_16x16x32_bf16 v[26:29], v[168:171], v[232:235], v[26:29]
	v_mfma_f32_16x16x32_bf16 v[14:17], v[160:163], v[240:243], v[14:17]
	v_mfma_f32_16x16x32_bf16 v[10:13], v[168:171], v[240:243], v[10:13]
	s_barrier
	s_add_i32 s62, s62, 2
	s_add_u32 s30, s30, 0x100
	s_addc_u32 s31, s31, 0
	s_add_u32 s52, s52, 0x100
	s_addc_u32 s54, s54, 0
	s_cmp_gt_u32 s62, 13
	s_cbranch_scc0 .Lkuq_2
	s_branch .Lku_exit
.Lkuq_3:
	s_add_u32 s34, s30, 0xfffc0080
	s_addc_u32 s35, s31, -1
	s_add_i32 s71, 0, 0x10000
	s_cmp_eq_u32 s62, 12
	s_cselect_b32 s41, s21, s35
	s_cselect_b32 s40, s27, s34
	v_add_u32_e32 v155, s71, v145
	s_cselect_b32 s35, s19, s54
	s_cselect_b32 s34, s50, s52
	s_add_i32 s74, 0, 0x14000
	v_add_u32_e32 v155, s74, v145
	ds_read_b128 v[172:175], v155
	ds_read_b128 v[176:179], v155 offset:1024
	ds_read_b128 v[180:183], v155 offset:2048
	ds_read_b128 v[208:211], v155 offset:3072
	v_lshl_add_u64 v[202:203], s[30:31], 0, v[134:135]
	s_add_i32 m0, s29, 0xc000
	ds_read_b128 v[212:215], v154
	ds_read_b128 v[216:219], v154 offset:1024
	ds_read_b128 v[220:223], v154 offset:2048
	ds_read_b128 v[224:227], v154 offset:3072
	ds_read_b128 v[228:231], v154 offset:4096
	ds_read_b128 v[232:235], v154 offset:5120
	ds_read_b128 v[236:239], v154 offset:6144
	ds_read_b128 v[240:243], v154 offset:7168
	v_lshl_add_u64 v[202:203], s[30:31], 0, v[136:137]
	s_add_i32 m0, s29, 0xe000
	s_nop 0
	s_waitcnt vmcnt(4)
	s_waitcnt lgkmcnt(0)
	s_barrier
; #define PG8_STAGE(bufoff, gbase, voff) do { _Pragma("unroll") for (int _i = 0; _i < 2; ++_i) \
;         __builtin_amdgcn_global_load_lds((const unsigned*)((const char*)(gbase) + (voff)[_i]), (PG8_LAS unsigned*)(lds + (bufoff) + ldsw + _i * 8192), 16, 0, 0); } while (0)
; #define PG8_LDA(dst, b, h) do { _Pragma("unroll") for (int m = 0; m < 4; ++m) _Pragma("unroll") for (int k = 0; k < 2; ++k) dst[m][k] = *(const PG8_LAS bf16x8*)(lds + PG8_SA(b, h) + aoff + m * 2048 + k * 1024); } while (0)
; #define PG8_LDB(dst, b, h) do { _Pragma("unroll") for (int n = 0; n < 2; ++n) _Pragma("unroll") for (int k = 0; k < 2; ++k) dst[n][k] = *(const PG8_LAS bf16x8*)(lds + PG8_SB(b, h) + boff + n * 2048 + k * 1024); } while (0)
; #define PG8_MMA(ai, bj, At, Bt) do { __builtin_amdgcn_s_setprio(1); _Pragma("unroll") for (int m = 0; m < 4; ++m) _Pragma("unroll") for (int n = 0; n < 2; ++n) _Pragma("unroll") for (int k = 0; k < 2; ++k) \
;         acc[ai][bj][m][n] = __builtin_amdgcn_mfma_f32_16x16x32_bf16(Bt[n][k], At[m][k], acc[ai][bj][m][n], 0, 0, 0); __builtin_amdgcn_s_setprio(0); } while (0)
; #define PG8_BAR __builtin_amdgcn_s_barrier()
; template <class Epi, class Sched, bool ALIGN_EPI = false, bool SP2 = false>
; __device__ __forceinline__ void gemm_phase(PG8_LAS unsigned char* lds, const Gemm g, const Sched& S, const Epi& E) {
;     ...
;             if constexpr (SP2) {
;             PG8_LDB(B0, 0, 0); PG8_LDB(B1, 0, 1); PG8_SCHED; PG8_LDA(At, 0, 0); PG8_STAGE(PG8_SA(1, 1), a1 + hstep, voffA);
;             PG8_WAIT_V(8); PG8_WAIT_L(0); PG8_BAR; PG8_MMA(0, 0, At, B0); PG8_MMA(0, 1, At, B1); PG8_BAR; PG8_SCHED;
;             PG8_LDA(At, 0, 1); PG8_STAGE(PG8_SB(0, 0), b2, voffB); PG8_STAGE(PG8_SB(0, 1), b2 + hstep, voffB); PG8_STAGE(PG8_SA(0, 0), a2, voffA);
;             PG8_WAIT_V(8); PG8_WAIT_L(0); PG8_BAR; PG8_MMA(1, 0, At, B0); PG8_MMA(1, 1, At, B1); PG8_BAR; PG8_SCHED;
;             PG8_LDB(B0, 1, 0); PG8_LDB(B1, 1, 1); PG8_SCHED; PG8_LDA(At, 1, 0); PG8_STAGE(PG8_SA(0, 1), a2 + hstep, voffA);
;             PG8_WAIT_V(8); PG8_WAIT_L(0); PG8_BAR; PG8_MMA(0, 0, At, B0); PG8_MMA(0, 1, At, B1); PG8_BAR; PG8_SCHED;
;             PG8_LDA(At, 1, 1); PG8_STAGE(PG8_SB(1, 0), b3, voffB); PG8_STAGE(PG8_SB(1, 1), b3 + hstep, voffB); PG8_STAGE(PG8_SA(1, 0), a3, voffA);
;             PG8_WAIT_V(8); PG8_WAIT_L(0); PG8_BAR; PG8_MMA(1, 0, At, B0); PG8_MMA(1, 1, At, B1); PG8_BAR; PG8_SCHED;
	s_waitcnt lgkmcnt(0)
	v_mfma_f32_16x16x32_bf16 v[118:121], v[172:175], v[212:215], v[118:121]
	v_mfma_f32_16x16x32_bf16 v[114:117], v[180:183], v[212:215], v[114:117]
	v_mfma_f32_16x16x32_bf16 v[102:105], v[172:175], v[220:223], v[102:105]
	v_mfma_f32_16x16x32_bf16 v[98:101], v[180:183], v[220:223], v[98:101]
	v_mfma_f32_16x16x32_bf16 v[86:89], v[172:175], v[228:231], v[86:89]
	v_mfma_f32_16x16x32_bf16 v[82:85], v[180:183], v[228:231], v[82:85]
	v_mfma_f32_16x16x32_bf16 v[70:73], v[172:175], v[236:239], v[70:73]
	v_mfma_f32_16x16x32_bf16 v[66:69], v[180:183], v[236:239], v[66:69]
	v_mfma_f32_16x16x32_bf16 v[118:121], v[176:179], v[216:219], v[118:121]
	v_mfma_f32_16x16x32_bf16 v[114:117], v[208:211], v[216:219], v[114:117]
	v_mfma_f32_16x16x32_bf16 v[102:105], v[176:179], v[224:227], v[102:105]
	v_mfma_f32_16x16x32_bf16 v[98:101], v[208:211], v[224:227], v[98:101]
	v_mfma_f32_16x16x32_bf16 v[86:89], v[176:179], v[232:235], v[86:89]
	v_mfma_f32_16x16x32_bf16 v[82:85], v[208:211], v[232:235], v[82:85]
	v_mfma_f32_16x16x32_bf16 v[70:73], v[176:179], v[240:243], v[70:73]
	v_mfma_f32_16x16x32_bf16 v[66:69], v[208:211], v[240:243], v[66:69]
	s_barrier
	s_add_i32 s71, s71, s80
	v_lshl_add_u64 v[202:203], s[34:35], 0, v[132:133]
	s_mov_b32 m0, s71
	s_add_i32 m0, s71, 0x2000
	s_add_u32 s72, s34, 0x40000
	v_lshl_add_u64 v[204:205], s[34:35], 0, v[130:131]
	s_addc_u32 s73, s35, 0
	s_add_i32 s71, s74, s80
	v_lshl_add_u64 v[244:245], s[72:73], 0, v[132:133]
	s_mov_b32 m0, s71
	v_lshl_add_u64 v[246:247], s[40:41], 0, v[130:131]
	global_load_lds_dwordx4 v[244:245], off
	v_lshl_add_u64 v[244:245], s[72:73], 0, v[130:131]
	s_add_i32 m0, s71, 0x2000
	s_nop 0
	global_load_lds_dwordx4 v[244:245], off
	v_lshl_add_u64 v[244:245], s[40:41], 0, v[132:133]
	s_mov_b32 m0, s29
	s_nop 0
	global_load_lds_dwordx4 v[244:245], off
	s_mov_b32 m0, s81
	s_nop 0
	global_load_lds_dwordx4 v[246:247], off
	s_waitcnt vmcnt(4)
	s_waitcnt lgkmcnt(0)
	s_barrier
	s_waitcnt lgkmcnt(0)
	s_barrier
	s_add_i32 s71, 0, 0x18000
	v_add_u32_e32 v155, s71, v145
	s_add_i32 s72, 0, 0x1c000
	v_add_u32_e32 v155, s72, v145
	ds_read_b128 v[172:175], v155
	ds_read_b128 v[176:179], v155 offset:1024
	ds_read_b128 v[180:183], v155 offset:2048
	ds_read_b128 v[208:211], v155 offset:3072
	s_add_u32 s40, s40, 0x40000
	s_addc_u32 s41, s41, 0
	s_mov_b32 m0, s82
	v_lshl_add_u64 v[248:249], s[40:41], 0, v[132:133]
	ds_read_b128 v[212:215], v154 offset:32768
	ds_read_b128 v[216:219], v154 offset:33792
	ds_read_b128 v[220:223], v154 offset:34816
	ds_read_b128 v[224:227], v154 offset:35840
	ds_read_b128 v[228:231], v154 offset:36864
	ds_read_b128 v[232:235], v154 offset:37888
	ds_read_b128 v[236:239], v154 offset:38912
	ds_read_b128 v[240:243], v154 offset:39936
	v_lshl_add_u64 v[248:249], s[40:41], 0, v[130:131]
	s_mov_b32 m0, s83
	s_nop 0
	s_waitcnt vmcnt(4)
	s_waitcnt lgkmcnt(0)
	s_barrier
	s_waitcnt lgkmcnt(0)
	v_mfma_f32_16x16x32_bf16 v[118:121], v[172:175], v[212:215], v[118:121]
	v_mfma_f32_16x16x32_bf16 v[114:117], v[180:183], v[212:215], v[114:117]
	v_mfma_f32_16x16x32_bf16 v[102:105], v[172:175], v[220:223], v[102:105]
	v_mfma_f32_16x16x32_bf16 v[98:101], v[180:183], v[220:223], v[98:101]
	v_mfma_f32_16x16x32_bf16 v[86:89], v[172:175], v[228:231], v[86:89]
	v_mfma_f32_16x16x32_bf16 v[82:85], v[180:183], v[228:231], v[82:85]
	v_mfma_f32_16x16x32_bf16 v[70:73], v[172:175], v[236:239], v[70:73]
	v_mfma_f32_16x16x32_bf16 v[66:69], v[180:183], v[236:239], v[66:69]
	v_mfma_f32_16x16x32_bf16 v[118:121], v[176:179], v[216:219], v[118:121]
	v_mfma_f32_16x16x32_bf16 v[114:117], v[208:211], v[216:219], v[114:117]
	v_mfma_f32_16x16x32_bf16 v[102:105], v[176:179], v[224:227], v[102:105]
	v_mfma_f32_16x16x32_bf16 v[98:101], v[208:211], v[224:227], v[98:101]
	v_mfma_f32_16x16x32_bf16 v[86:89], v[176:179], v[232:235], v[86:89]
	v_mfma_f32_16x16x32_bf16 v[82:85], v[208:211], v[232:235], v[82:85]
	v_mfma_f32_16x16x32_bf16 v[70:73], v[176:179], v[240:243], v[70:73]
	v_mfma_f32_16x16x32_bf16 v[66:69], v[208:211], v[240:243], v[66:69]
	s_barrier
	s_add_i32 s40, s71, s80
	v_lshl_add_u64 v[202:203], v[202:203], 0, s[66:67]
	s_mov_b32 m0, s40
	s_add_i32 m0, s40, 0x2000
	s_add_u32 s34, s34, 0x40080
	v_lshl_add_u64 v[202:203], v[204:205], 0, s[66:67]
	s_addc_u32 s35, s35, 0
	s_add_i32 s40, s72, s80
	v_lshl_add_u64 v[202:203], s[34:35], 0, v[132:133]
	s_mov_b32 m0, s40
	s_nop 0
	global_load_lds_dwordx4 v[202:203], off
	v_lshl_add_u64 v[202:203], s[34:35], 0, v[130:131]
	s_add_i32 m0, s40, 0x2000
	s_nop 0
	global_load_lds_dwordx4 v[202:203], off
	v_lshl_add_u64 v[202:203], v[244:245], 0, s[66:67]
	s_mov_b32 m0, s84
	s_nop 0
	global_load_lds_dwordx4 v[202:203], off
	v_lshl_add_u64 v[202:203], v[246:247], 0, s[66:67]
	s_mov_b32 m0, s85
	s_nop 0
	global_load_lds_dwordx4 v[202:203], off
	s_waitcnt vmcnt(4)
	s_waitcnt lgkmcnt(0)
	s_barrier
	s_waitcnt lgkmcnt(0)
	s_barrier
	s_add_i32 s62, s62, 2
	s_add_u32 s30, s30, 0x100
	s_addc_u32 s31, s31, 0
	s_add_u32 s52, s52, 0x100
	s_addc_u32 s54, s54, 0
	s_cmp_gt_u32 s62, 13
	s_cbranch_scc0 .Lkuq_3
	s_branch .Lku_exit
; #define PG8_STAGE(bufoff, gbase, voff) do { _Pragma("unroll") for (int _i = 0; _i < 2; ++_i) \
;         __builtin_amdgcn_global_load_lds((const unsigned*)((const char*)(gbase) + (voff)[_i]), (PG8_LAS unsigned*)(lds + (bufoff) + ldsw + _i * 8192), 16, 0, 0); } while (0)
; #define PG8_LDA(dst, b, h) do { _Pragma("unroll") for (int m = 0; m < 4; ++m) _Pragma("unroll") for (int k = 0; k < 2; ++k) dst[m][k] = *(const PG8_LAS bf16x8*)(lds + PG8_SA(b, h) + aoff + m * 2048 + k * 1024); } while (0)
; #define PG8_LDB(dst, b, h) do { _Pragma("unroll") for (int n = 0; n < 2; ++n) _Pragma("unroll") for (int k = 0; k < 2; ++k) dst[n][k] = *(const PG8_LAS bf16x8*)(lds + PG8_SB(b, h) + boff + n * 2048 + k * 1024); } while (0)
; #define PG8_MMA(ai, bj, At, Bt) do { __builtin_amdgcn_s_setprio(1); _Pragma("unroll") for (int m = 0; m < 4; ++m) _Pragma("unroll") for (int n = 0; n < 2; ++n) _Pragma("unroll") for (int k = 0; k < 2; ++k) \
;         acc[ai][bj][m][n] = __builtin_amdgcn_mfma_f32_16x16x32_bf16(Bt[n][k], At[m][k], acc[ai][bj][m][n], 0, 0, 0); __builtin_amdgcn_s_setprio(0); } while (0)
; #define PG8_BAR __builtin_amdgcn_s_barrier()
; template <class Epi, class Sched, bool ALIGN_EPI = false, bool SP2 = false>
; __device__ __forceinline__ void gemm_phase(PG8_LAS unsigned char* lds, const Gemm g, const Sched& S, const Epi& E) {
;     ...
;             if constexpr (SP2) {
;             PG8_LDB(B0, 0, 0); PG8_LDB(B1, 0, 1); PG8_SCHED; PG8_LDA(At, 0, 0); PG8_STAGE(PG8_SA(1, 1), a1 + hstep, voffA);
;             PG8_WAIT_V(8); PG8_WAIT_L(0); PG8_BAR; PG8_MMA(0, 0, At, B0); PG8_MMA(0, 1, At, B1); PG8_BAR; PG8_SCHED;
;             PG8_LDA(At, 0, 1); PG8_STAGE(PG8_SB(0, 0), b2, voffB); PG8_STAGE(PG8_SB(0, 1), b2 + hstep, voffB); PG8_STAGE(PG8_SA(0, 0), a2, voffA);
;             PG8_WAIT_V(8); PG8_WAIT_L(0); PG8_BAR; PG8_MMA(1, 0, At, B0); PG8_MMA(1, 1, At, B1); PG8_BAR; PG8_SCHED;
;             PG8_LDB(B0, 1, 0); PG8_LDB(B1, 1, 1); PG8_SCHED; PG8_LDA(At, 1, 0); PG8_STAGE(PG8_SA(0, 1), a2 + hstep, voffA);
;             PG8_WAIT_V(8); PG8_WAIT_L(0); PG8_BAR; PG8_MMA(0, 0, At, B0); PG8_MMA(0, 1, At, B1); PG8_BAR; PG8_SCHED;
;             PG8_LDA(At, 1, 1); PG8_STAGE(PG8_SB(1, 0), b3, voffB); PG8_STAGE(PG8_SB(1, 1), b3 + hstep, voffB); PG8_STAGE(PG8_SA(1, 0), a3, voffA);
;             PG8_WAIT_V(8); PG8_WAIT_L(0); PG8_BAR; PG8_MMA(1, 0, At, B0); PG8_MMA(1, 1, At, B1); PG8_BAR; PG8_SCHED;
.Lkuq_4:
	s_add_u32 s34, s30, 0xfffc0080
	s_addc_u32 s35, s31, -1
	s_add_i32 s71, 0, 0x10000
	s_cmp_eq_u32 s62, 12
	s_cselect_b32 s41, s21, s35
	s_cselect_b32 s40, s27, s34
	v_add_u32_e32 v155, s71, v145
	s_cselect_b32 s35, s19, s54
	s_cselect_b32 s34, s50, s52
	s_add_i32 s74, 0, 0x14000
	v_add_u32_e32 v155, s74, v145
	ds_read_b128 v[172:175], v155
	ds_read_b128 v[176:179], v155 offset:1024
	ds_read_b128 v[180:183], v155 offset:2048
	ds_read_b128 v[208:211], v155 offset:3072
	v_lshl_add_u64 v[202:203], s[30:31], 0, v[134:135]
	s_add_i32 m0, s29, 0xc000
	global_load_lds_dwordx4 v[202:203], off
	v_lshl_add_u64 v[202:203], s[30:31], 0, v[136:137]
	s_add_i32 m0, s29, 0xe000
	s_nop 0
	global_load_lds_dwordx4 v[202:203], off
	s_waitcnt vmcnt(4)
	s_waitcnt lgkmcnt(0)
	s_barrier
	s_waitcnt lgkmcnt(0)
	s_barrier
	s_add_i32 s71, s71, s80
	v_lshl_add_u64 v[202:203], s[34:35], 0, v[132:133]
	s_mov_b32 m0, s71
	ds_read_b128 v[212:215], v154 offset:16384
	ds_read_b128 v[216:219], v154 offset:17408
	ds_read_b128 v[220:223], v154 offset:18432
	ds_read_b128 v[224:227], v154 offset:19456
	ds_read_b128 v[228:231], v154 offset:20480
	ds_read_b128 v[232:235], v154 offset:21504
	ds_read_b128 v[236:239], v154 offset:22528
	ds_read_b128 v[240:243], v154 offset:23552
	s_add_i32 m0, s71, 0x2000
	s_add_u32 s72, s34, 0x40000
	v_lshl_add_u64 v[204:205], s[34:35], 0, v[130:131]
	s_addc_u32 s73, s35, 0
	s_add_i32 s71, s74, s80
	v_lshl_add_u64 v[244:245], s[72:73], 0, v[132:133]
	s_mov_b32 m0, s71
	v_lshl_add_u64 v[246:247], s[40:41], 0, v[130:131]
	global_load_lds_dwordx4 v[244:245], off
	v_lshl_add_u64 v[244:245], s[72:73], 0, v[130:131]
	s_add_i32 m0, s71, 0x2000
	s_nop 0
	global_load_lds_dwordx4 v[244:245], off
	v_lshl_add_u64 v[244:245], s[40:41], 0, v[132:133]
	s_mov_b32 m0, s29
	s_nop 0
	s_mov_b32 m0, s81
	s_nop 0
	s_waitcnt vmcnt(4)
	s_waitcnt lgkmcnt(0)
	s_barrier
	s_waitcnt lgkmcnt(0)
	v_mfma_f32_16x16x32_bf16 v[54:57], v[172:175], v[212:215], v[54:57]
	v_mfma_f32_16x16x32_bf16 v[50:53], v[180:183], v[212:215], v[50:53]
	v_mfma_f32_16x16x32_bf16 v[38:41], v[172:175], v[220:223], v[38:41]
	v_mfma_f32_16x16x32_bf16 v[34:37], v[180:183], v[220:223], v[34:37]
	v_mfma_f32_16x16x32_bf16 v[22:25], v[172:175], v[228:231], v[22:25]
	v_mfma_f32_16x16x32_bf16 v[18:21], v[180:183], v[228:231], v[18:21]
	v_mfma_f32_16x16x32_bf16 v[6:9], v[172:175], v[236:239], v[6:9]
	v_mfma_f32_16x16x32_bf16 v[2:5], v[180:183], v[236:239], v[2:5]
	v_mfma_f32_16x16x32_bf16 v[54:57], v[176:179], v[216:219], v[54:57]
	v_mfma_f32_16x16x32_bf16 v[50:53], v[208:211], v[216:219], v[50:53]
	v_mfma_f32_16x16x32_bf16 v[38:41], v[176:179], v[224:227], v[38:41]
	v_mfma_f32_16x16x32_bf16 v[34:37], v[208:211], v[224:227], v[34:37]
	v_mfma_f32_16x16x32_bf16 v[22:25], v[176:179], v[232:235], v[22:25]
	v_mfma_f32_16x16x32_bf16 v[18:21], v[208:211], v[232:235], v[18:21]
	v_mfma_f32_16x16x32_bf16 v[6:9], v[176:179], v[240:243], v[6:9]
	v_mfma_f32_16x16x32_bf16 v[2:5], v[208:211], v[240:243], v[2:5]
	s_barrier
	s_add_i32 s71, 0, 0x18000
	v_add_u32_e32 v155, s71, v145
	s_add_i32 s72, 0, 0x1c000
	v_add_u32_e32 v155, s72, v145
	ds_read_b128 v[172:175], v155
	ds_read_b128 v[176:179], v155 offset:1024
	ds_read_b128 v[180:183], v155 offset:2048
	ds_read_b128 v[208:211], v155 offset:3072
	s_add_u32 s40, s40, 0x40000
	s_addc_u32 s41, s41, 0
	s_mov_b32 m0, s82
	v_lshl_add_u64 v[248:249], s[40:41], 0, v[132:133]
	global_load_lds_dwordx4 v[248:249], off
	v_lshl_add_u64 v[248:249], s[40:41], 0, v[130:131]
	s_mov_b32 m0, s83
	s_nop 0
	global_load_lds_dwordx4 v[248:249], off
	s_waitcnt vmcnt(4)
	s_waitcnt lgkmcnt(0)
	s_barrier
	s_waitcnt lgkmcnt(0)
	s_barrier
	s_add_i32 s40, s71, s80
	v_lshl_add_u64 v[202:203], v[202:203], 0, s[66:67]
	s_mov_b32 m0, s40
	ds_read_b128 v[212:215], v154 offset:49152
	ds_read_b128 v[216:219], v154 offset:50176
	ds_read_b128 v[220:223], v154 offset:51200
	ds_read_b128 v[224:227], v154 offset:52224
	ds_read_b128 v[228:231], v154 offset:53248
	ds_read_b128 v[232:235], v154 offset:54272
	ds_read_b128 v[236:239], v154 offset:55296
	ds_read_b128 v[240:243], v154 offset:56320
	s_add_i32 m0, s40, 0x2000
	s_add_u32 s34, s34, 0x40080
	v_lshl_add_u64 v[202:203], v[204:205], 0, s[66:67]
	s_addc_u32 s35, s35, 0
	s_add_i32 s40, s72, s80
	v_lshl_add_u64 v[202:203], s[34:35], 0, v[132:133]
	s_mov_b32 m0, s40
	s_nop 0
	global_load_lds_dwordx4 v[202:203], off
	v_lshl_add_u64 v[202:203], s[34:35], 0, v[130:131]
	s_add_i32 m0, s40, 0x2000
	s_nop 0
	global_load_lds_dwordx4 v[202:203], off
	v_lshl_add_u64 v[202:203], v[244:245], 0, s[66:67]
	s_mov_b32 m0, s84
	s_nop 0
	v_lshl_add_u64 v[202:203], v[246:247], 0, s[66:67]
	s_mov_b32 m0, s85
	s_nop 0
	s_waitcnt vmcnt(4)
	s_waitcnt lgkmcnt(0)
	s_barrier
	s_waitcnt lgkmcnt(0)
	v_mfma_f32_16x16x32_bf16 v[54:57], v[172:175], v[212:215], v[54:57]
	v_mfma_f32_16x16x32_bf16 v[50:53], v[180:183], v[212:215], v[50:53]
	v_mfma_f32_16x16x32_bf16 v[38:41], v[172:175], v[220:223], v[38:41]
	v_mfma_f32_16x16x32_bf16 v[34:37], v[180:183], v[220:223], v[34:37]
	v_mfma_f32_16x16x32_bf16 v[22:25], v[172:175], v[228:231], v[22:25]
	v_mfma_f32_16x16x32_bf16 v[18:21], v[180:183], v[228:231], v[18:21]
	v_mfma_f32_16x16x32_bf16 v[6:9], v[172:175], v[236:239], v[6:9]
	v_mfma_f32_16x16x32_bf16 v[2:5], v[180:183], v[236:239], v[2:5]
	v_mfma_f32_16x16x32_bf16 v[54:57], v[176:179], v[216:219], v[54:57]
	v_mfma_f32_16x16x32_bf16 v[50:53], v[208:211], v[216:219], v[50:53]
	v_mfma_f32_16x16x32_bf16 v[38:41], v[176:179], v[224:227], v[38:41]
	v_mfma_f32_16x16x32_bf16 v[34:37], v[208:211], v[224:227], v[34:37]
	v_mfma_f32_16x16x32_bf16 v[22:25], v[176:179], v[232:235], v[22:25]
	v_mfma_f32_16x16x32_bf16 v[18:21], v[208:211], v[232:235], v[18:21]
	v_mfma_f32_16x16x32_bf16 v[6:9], v[176:179], v[240:243], v[6:9]
	v_mfma_f32_16x16x32_bf16 v[2:5], v[208:211], v[240:243], v[2:5]
	s_barrier
	s_add_i32 s62, s62, 2
	s_add_u32 s30, s30, 0x100
	s_addc_u32 s31, s31, 0
	s_add_u32 s52, s52, 0x100
	s_addc_u32 s54, s54, 0
	s_cmp_gt_u32 s62, 13
	s_cbranch_scc0 .Lkuq_4

; #define PG8_STAGE(bufoff, gbase, voff) do { _Pragma("unroll") for (int _i = 0; _i < 2; ++_i) \
;         __builtin_amdgcn_global_load_lds((const unsigned*)((const char*)(gbase) + (voff)[_i]), (PG8_LAS unsigned*)(lds + (bufoff) + ldsw + _i * 8192), 16, 0, 0); } while (0)
; #define PG8_BAR __builtin_amdgcn_s_barrier()
;     __host__ __device__ bool next(int i, Unit& u) const {
;         const long L = (long)i * G + c; if (L >= nwg) return false;
;         int wgid = (int)L; { const int q = nwg / NXCD, r = nwg % NXCD, xcd = wgid % NXCD, off = wgid / NXCD; wgid = (xcd < r ? xcd * (q + 1) : r * (q + 1) + (xcd - r) * q) + off; }
;         const int nig = WGM * nN, gid = wgid / nig, fm = gid * WGM, gsz = (nM - fm) < WGM ? (nM - fm) : WGM;
;         u.pm = fm + ((wgid % nig) % gsz); u.pn = (wgid % nig) / gsz; return true;
; template <class Epi, class Sched, bool ALIGN_EPI = false, bool SP2 = false>
; __device__ __forceinline__ void gemm_phase(PG8_LAS unsigned char* lds, const Gemm g, const Sched& S, const Epi& E) {
;     ...
;     for (int i = 0; i < 2; ++i) { int R, C; stage_rc(tid * 16 + i * 8192, R, C); const int Rb = Epi::PERM ? ((R & ~31) + perm32(R & 31)) : R;
;         voffA[i] = (unsigned)(R * K + C) * 2u; voffB[i] = (unsigned)(Rb * K + C) * 2u; }
;     const size_t kstep = (size_t)(BK * 2);
;     const size_t hstep = (size_t)HALF * K * 2;
;     const size_t tstep = 2 * hstep;
;     const unsigned ldsw = (unsigned)wid * 1024u;
;     const int aoff = lds_byte(wr * 64 + fr, fq * 8), boff = lds_byte(wc * 32 + fr, fq * 8);
;     ...
;     Unit cur, nxt; int ui = 0;
;     if (!S.next(0, cur)) return;
;     f32x4 acc[2][2][4][2];
; #pragma unroll
;     for (int a = 0; a < 2; ++a)
; #pragma unroll
;         for (int b = 0; b < 2; ++b)
; #pragma unroll
;             for (int m = 0; m < 4; ++m)
; #pragma unroll
;                 for (int n = 0; n < 2; ++n) acc[a][b][m][n] = (f32x4){0.f, 0.f, 0.f, 0.f};
;     bf16x8 At[4][2], B0[2][2], B1[2][2];
;     const char* cA = (const char*)g.A + (size_t)cur.pm * tstep; const char* cB = (const char*)g.Bt + (size_t)cur.pn * tstep;
;     S.a_ready(cur);
;     if constexpr (SP2) {
;         PG8_STAGE(PG8_SB(0, 0), cB, voffB); PG8_STAGE(PG8_SB(0, 1), cB + hstep, voffB); PG8_STAGE(PG8_SA(0, 0), cA, voffA); PG8_STAGE(PG8_SA(0, 1), cA + hstep, voffA);
;         if (wr == 1) PG8_BAR;
.LBB0_179:
	v_mov_b32_e32 v12, v184
	s_cmp_ge_i32 s8, s10
	s_nop 0
	v_readfirstlane_b32 s9, v12
	s_cbranch_scc1 .LBB0_176
	v_lshlrev_b32_e32 v2, 4, v12
	v_add_u32_e32 v3, 0x2000, v2
	v_ashrrev_i32_e32 v0, 31, v3
	v_lshrrev_b32_e32 v0, 22, v0
	v_add_u32_e32 v0, v3, v0
	v_ashrrev_i32_e32 v0, 10, v0
	v_mul_i32_i24_e32 v5, 0x400, v0
	v_sub_u32_e32 v3, v3, v5
	v_lshrrev_b32_e32 v5, 4, v3
	v_bitop3_b32 v3, v5, v3, 32 bitop3:0x6c
	v_ashrrev_i32_e32 v5, 31, v3
	v_lshrrev_b32_e32 v5, 26, v5
	v_add_u32_e32 v5, v3, v5
	v_ashrrev_i32_e32 v10, 6, v5
	v_and_b32_e32 v5, 0xc0, v5
	v_sub_u32_e32 v3, v3, v5
	v_lshlrev_b32_e32 v4, 5, v0
	v_ashrrev_i16_sdwa v3, v196, sext(v3) dst_sel:DWORD dst_unused:UNUSED_PAD src0_sel:DWORD src1_sel:BYTE_0
	v_and_b32_e32 v4, 32, v4
	v_bfe_i32 v11, v3, 0, 16
	v_add_u32_e32 v3, v4, v11
	v_lshlrev_b32_e32 v4, 3, v0
	v_and_b32_e32 v4, 0x1ffff0, v4
	v_add_lshl_u32 v4, v10, v4, 11
	v_lshl_add_u32 v130, v3, 1, v4
	v_bfe_i32 v4, v12, 27, 1
	v_lshrrev_b32_e32 v4, 22, v4
	v_add_u32_e32 v4, v2, v4
	v_and_b32_e32 v4, 0xfffffc00, v4
	v_sub_u32_e32 v2, v2, v4
	v_lshrrev_b32_e32 v4, 4, v2
	v_bitop3_b32 v2, v4, v2, 32 bitop3:0x6c
	s_load_dwordx2 s[6:7], s[92:93], s6 offset:0xa8
	v_ashrrev_i32_e32 v4, 31, v2
	s_lshr_b32 s44, s10, 3
	s_ashr_i32 s11, s9, 6
	v_ashrrev_i32_e32 v3, 31, v12
	v_lshrrev_b32_e32 v4, 26, v4
	s_or_b32 s45, s44, 1
	s_ashr_i32 s18, s9, 8
	s_lshl_b32 s46, s11, 10
	v_lshrrev_b32_e32 v3, 26, v3
	v_add_u32_e32 v4, v2, v4
	s_and_b64 s[14:15], exec, s[2:3]
	v_add_u32_e32 v3, v12, v3
	v_ashrrev_i32_e32 v14, 6, v4
	v_and_b32_e32 v4, 0xc0, v4
	s_cselect_b32 s14, 0, 0x2000000
	v_ashrrev_i32_e32 v13, 6, v3
	v_sub_u32_e32 v2, v2, v4
	s_cselect_b32 s47, 64, 8
	s_cselect_b32 s48, 24, 8
	s_waitcnt lgkmcnt(0)
	s_add_u32 s14, s6, s14
	v_lshlrev_b32_e32 v3, 5, v13
	v_ashrrev_i16_sdwa v2, v196, sext(v2) dst_sel:DWORD dst_unused:UNUSED_PAD src0_sel:DWORD src1_sel:BYTE_0
	s_addc_u32 s15, s7, 0
	v_and_b32_e32 v3, 32, v3
	v_bfe_i32 v15, v2, 0, 16
	s_add_u32 s49, s14, 0x5b00000
	v_add_u32_e32 v2, v3, v15
	v_lshlrev_b32_e32 v3, 3, v13
	s_addc_u32 s74, s15, 0
	v_and_b32_e32 v3, 0x1ffff0, v3
	s_and_b64 s[14:15], exec, s[2:3]
	v_add_lshl_u32 v3, v14, v3, 11
	s_cselect_b32 s14, 0, 0x200000
	v_lshl_add_u32 v132, v2, 1, v3
	v_cvt_f32_ubyte0_e32 v2, s48
	s_add_u32 s14, s6, s14
	v_rcp_iflag_f32_e32 v2, v2
	s_addc_u32 s15, s7, 0
	s_add_u32 s72, s14, 0x4e00000
	s_addc_u32 s75, s15, 0
	s_ashr_i32 s14, s8, 31
	s_lshr_b32 s14, s14, 29
	v_mul_f32_e32 v2, 0x4f7ffffe, v2
	s_add_i32 s14, s8, s14
	v_cvt_u32_f32_e32 v2, v2
	s_ashr_i32 s15, s14, 3
	s_and_b32 s14, s14, -8
	s_sub_i32 s8, s8, s14
	s_cmp_lt_i32 s8, 0
	s_cselect_b32 s14, s45, s44
	s_sub_i32 s16, 0, s48
	v_readfirstlane_b32 s76, v2
	s_mul_i32 s8, s8, s14
	s_mul_i32 s16, s16, s76
	s_add_i32 s8, s8, s15
	s_mul_hi_u32 s16, s76, s16
	s_abs_i32 s15, s8
	s_add_i32 s76, s76, s16
	s_mul_hi_u32 s16, s15, s76
	s_mul_i32 s17, s16, s48
	s_sub_i32 s15, s15, s17
	s_ashr_i32 s14, s8, 31
	s_add_i32 s17, s16, 1
	s_sub_i32 s19, s15, s48
	s_cmp_ge_u32 s15, s48
	s_cselect_b32 s16, s17, s16
	s_cselect_b32 s15, s19, s15
	s_add_i32 s17, s16, 1
	s_cmp_ge_u32 s15, s48
	s_cselect_b32 s15, s17, s16
	s_xor_b32 s15, s15, s14
	s_sub_i32 s14, s15, s14
	s_lshl_b32 s16, s14, 2
	s_sub_i32 s15, s47, s16
	s_min_i32 s17, s15, 4
	s_sext_i32_i16 s15, s17
	v_cvt_f32_i32_e32 v2, s15
	s_mul_i32 s14, s14, s48
	s_sub_i32 s19, s8, s14
	s_sext_i32_i16 s8, s19
	v_cvt_f32_i32_e32 v3, s8
	v_rcp_iflag_f32_e32 v4, v2
	s_xor_b32 s8, s8, s15
	s_ashr_i32 s8, s8, 30
	s_or_b32 s8, s8, 1
	v_mul_f32_e32 v4, v3, v4
	v_trunc_f32_e32 v4, v4
	v_fma_f32 v3, -v4, v2, v3
	v_cvt_i32_f32_e32 v4, v4
	v_cmp_ge_f32_e64 s[14:15], |v3|, |v2|
	s_and_b64 s[14:15], s[14:15], exec
	s_cselect_b32 s8, s8, 0
	v_readfirstlane_b32 s14, v4
	s_add_i32 s8, s14, s8
	s_mul_i32 s14, s8, s17
	s_sub_i32 s14, s19, s14
	s_sext_i32_i16 s14, s14
	s_add_i32 s28, s16, s14
	s_ashr_i32 s29, s28, 31
	s_bfe_i64 s[16:17], s[8:9], 0x100000
	s_lshl_b64 s[14:15], s[28:29], 19
	s_lshl_b64 s[16:17], s[16:17], 19
	s_add_u32 s34, s72, s16
	s_addc_u32 s35, s75, s17
	s_add_i32 s50, s46, 0
	s_add_i32 m0, s50, 0x10000
	v_mov_b32_e32 v133, v1
	global_load_lds_dwordx4 v132, s[34:35]
	s_add_i32 m0, s50, 0x12000
	s_add_u32 s16, s34, 0x40000
	global_load_lds_dwordx4 v130, s[34:35]
	s_addc_u32 s17, s35, 0
	s_add_i32 m0, s50, 0x14000
	v_mov_b32_e32 v131, v1
	global_load_lds_dwordx4 v132, s[16:17]
	s_add_i32 m0, s50, 0x16000
	s_add_u32 s30, s49, s14
	s_addc_u32 s31, s74, s15
	s_add_i32 s73, s50, 0x2000
	global_load_lds_dwordx4 v130, s[16:17]
	s_mov_b32 m0, s50
	s_add_u32 s14, s30, 0x40000
	global_load_lds_dwordx4 v132, s[30:31]
	s_mov_b32 m0, s73
	s_addc_u32 s15, s31, 0
	s_add_i32 s77, s50, 0x4000
	global_load_lds_dwordx4 v130, s[30:31]
	s_mov_b32 m0, s77
	s_add_i32 s78, s50, 0x6000
	global_load_lds_dwordx4 v132, s[14:15]
	s_mov_b32 m0, s78
	s_cmp_eq_u32 s18, 1
	global_load_lds_dwordx4 v130, s[14:15]
	v_lshl_add_u64 v[8:9], s[34:35], 0, v[132:133]
	v_lshl_add_u64 v[6:7], s[34:35], 0, v[130:131]
	v_lshl_add_u64 v[2:3], s[30:31], 0, v[132:133]
	s_cselect_b64 s[14:15], -1, 0
	s_cmp_lg_u32 s18, 1
	v_lshl_add_u64 v[4:5], s[30:31], 0, v[130:131]
	s_cbranch_scc1 .LBB0_182
	s_barrier
	s_setprio 1

; #define PG8_STAGE(bufoff, gbase, voff) do { _Pragma("unroll") for (int _i = 0; _i < 2; ++_i) \
;         __builtin_amdgcn_global_load_lds((const unsigned*)((const char*)(gbase) + (voff)[_i]), (PG8_LAS unsigned*)(lds + (bufoff) + ldsw + _i * 8192), 16, 0, 0); } while (0)
; #define PG8_LDA(dst, b, h) do { _Pragma("unroll") for (int m = 0; m < 4; ++m) _Pragma("unroll") for (int k = 0; k < 2; ++k) dst[m][k] = *(const PG8_LAS bf16x8*)(lds + PG8_SA(b, h) + aoff + m * 2048 + k * 1024); } while (0)
; #define PG8_LDB(dst, b, h) do { _Pragma("unroll") for (int n = 0; n < 2; ++n) _Pragma("unroll") for (int k = 0; k < 2; ++k) dst[n][k] = *(const PG8_LAS bf16x8*)(lds + PG8_SB(b, h) + boff + n * 2048 + k * 1024); } while (0)
; #define PG8_WAIT_V(n) asm volatile("s_waitcnt vmcnt(" #n ")" ::: "memory")
; #define PG8_WAIT_L(n) asm volatile("s_waitcnt lgkmcnt(" #n ")" ::: "memory")
; #define PG8_BAR __builtin_amdgcn_s_barrier()
; #define PG8_SCHED __builtin_amdgcn_sched_barrier(0)
; template <class Epi, class Sched, bool ALIGN_EPI = false, bool SP2 = false>
; __device__ __forceinline__ void gemm_phase(PG8_LAS unsigned char* lds, const Gemm g, const Sched& S, const Epi& E) {
;     ...
;         const bool has_next = S.next(ui + 1, nxt);
;         const char* nA = has_next ? (const char*)g.A + (size_t)nxt.pm * tstep : cA; const char* nB = has_next ? (const char*)g.Bt + (size_t)nxt.pn * tstep : cB;
;         for (int t = 0; t < nt; t += 2) {
;             const bool last = (t == nt - 2);
;             const char* a1 = cA + (size_t)(t + 1) * kstep;
;             const char* a2 = last ? nA : cA + (size_t)(t + 2) * kstep; const char* b2 = last ? nB : cB + (size_t)(t + 2) * kstep;
;             const char* a3 = a2 + kstep; const char* b3 = b2 + kstep;
;             if (last && has_next) S.a_ready(nxt);
;             if constexpr (SP2) {
;             PG8_LDB(B0, 0, 0); PG8_LDB(B1, 0, 1); PG8_SCHED; PG8_LDA(At, 0, 0); PG8_STAGE(PG8_SA(1, 1), a1 + hstep, voffA);
;             PG8_WAIT_V(8); PG8_WAIT_L(0); PG8_BAR; PG8_MMA(0, 0, At, B0); PG8_MMA(0, 1, At, B1); PG8_BAR; PG8_SCHED;
;             PG8_LDA(At, 0, 1); PG8_STAGE(PG8_SB(0, 0), b2, voffB); PG8_STAGE(PG8_SB(0, 1), b2 + hstep, voffB); PG8_STAGE(PG8_SA(0, 0), a2, voffA);
;             PG8_WAIT_V(8); PG8_WAIT_L(0); PG8_BAR; PG8_MMA(1, 0, At, B0); PG8_MMA(1, 1, At, B1); PG8_BAR; PG8_SCHED;
.LBB0_187:
	s_ashr_i32 s23, s22, 31
	s_lshl_b64 s[24:25], s[22:23], 19
	s_add_u32 s24, s49, s24
	s_addc_u32 s25, s74, s25
	s_and_b64 s[26:27], s[8:9], exec
	s_cselect_b32 s23, s25, s31
	s_cselect_b32 s54, s24, s30
	s_ashr_i32 s21, s20, 31
	s_lshl_b64 s[26:27], s[20:21], 19
	s_add_u32 s26, s72, s26
	s_addc_u32 s27, s75, s27
	s_and_b64 s[40:41], s[8:9], exec
	s_cselect_b32 s21, s27, s35
	s_cselect_b32 s62, s26, s34
	s_add_u32 s30, s30, 0x40080
	s_addc_u32 s31, s31, 0
	s_add_u32 s64, s34, 0x100
	v_mov_b32_e32 v2, 0
	s_addc_u32 s71, s35, 0
	s_mov_b32 s85, -2
	s_add_u32 s34, s30, 0xfffc0080
	s_addc_u32 s35, s31, -1
	s_add_i32 s86, 0, 0x10000
	s_cmp_eq_u32 s85, 12
	s_cselect_b32 s41, s23, s35
	s_cselect_b32 s40, s54, s34
	v_add_u32_e32 v0, s86, v143
	s_cselect_b32 s35, s21, s71
	s_cselect_b32 s34, s62, s64
	s_add_i32 s88, 0, 0x14000
	ds_read_b128 v[152:155], v0
	ds_read_b128 v[156:159], v0 offset:1024
	ds_read_b128 v[160:163], v0 offset:2048
	ds_read_b128 v[164:167], v0 offset:3072
	v_add_u32_e32 v0, s88, v143
	ds_read_b128 v[168:171], v0
	ds_read_b128 v[172:175], v0 offset:1024
	ds_read_b128 v[176:179], v0 offset:2048
	ds_read_b128 v[180:183], v0 offset:3072
	v_lshl_add_u64 v[242:243], s[30:31], 0, v[148:149]
	s_add_i32 m0, s50, 0xc000
	ds_read_b128 v[202:205], v212
	ds_read_b128 v[214:217], v212 offset:1024
	ds_read_b128 v[218:221], v212 offset:2048
	ds_read_b128 v[222:225], v212 offset:3072
	ds_read_b128 v[226:229], v212 offset:4096
	ds_read_b128 v[230:233], v212 offset:5120
	ds_read_b128 v[234:237], v212 offset:6144
	ds_read_b128 v[238:241], v212 offset:7168
	global_load_lds_dwordx4 v[242:243], off
	v_lshl_add_u64 v[242:243], s[30:31], 0, v[150:151]
	s_add_i32 m0, s50, 0xe000
	s_nop 0
	global_load_lds_dwordx4 v[242:243], off
	s_waitcnt vmcnt(8)
	s_waitcnt lgkmcnt(0)
	s_barrier
	s_waitcnt lgkmcnt(0)
	v_mfma_f32_16x16x32_bf16 v[126:129], v[152:155], v[202:205], 0
	v_mfma_f32_16x16x32_bf16 v[122:125], v[160:163], v[202:205], 0
	v_mfma_f32_16x16x32_bf16 v[110:113], v[152:155], v[218:221], 0
	v_mfma_f32_16x16x32_bf16 v[106:109], v[160:163], v[218:221], 0
	v_mfma_f32_16x16x32_bf16 v[94:97], v[152:155], v[226:229], 0
	v_mfma_f32_16x16x32_bf16 v[90:93], v[160:163], v[226:229], 0
	v_mfma_f32_16x16x32_bf16 v[78:81], v[152:155], v[234:237], 0
	v_mfma_f32_16x16x32_bf16 v[74:77], v[160:163], v[234:237], 0
	v_mfma_f32_16x16x32_bf16 v[126:129], v[156:159], v[214:217], v[126:129]
	v_mfma_f32_16x16x32_bf16 v[122:125], v[164:167], v[214:217], v[122:125]
	v_mfma_f32_16x16x32_bf16 v[110:113], v[156:159], v[222:225], v[110:113]
	v_mfma_f32_16x16x32_bf16 v[106:109], v[164:167], v[222:225], v[106:109]
	v_mfma_f32_16x16x32_bf16 v[94:97], v[156:159], v[230:233], v[94:97]
	v_mfma_f32_16x16x32_bf16 v[90:93], v[164:167], v[230:233], v[90:93]
	v_mfma_f32_16x16x32_bf16 v[78:81], v[156:159], v[238:241], v[78:81]
	v_mfma_f32_16x16x32_bf16 v[74:77], v[164:167], v[238:241], v[74:77]
	v_mfma_f32_16x16x32_bf16 v[118:121], v[168:171], v[202:205], 0
	v_mfma_f32_16x16x32_bf16 v[114:117], v[176:179], v[202:205], 0
	v_mfma_f32_16x16x32_bf16 v[102:105], v[168:171], v[218:221], 0
	v_mfma_f32_16x16x32_bf16 v[98:101], v[176:179], v[218:221], 0
	v_mfma_f32_16x16x32_bf16 v[86:89], v[168:171], v[226:229], 0
	v_mfma_f32_16x16x32_bf16 v[82:85], v[176:179], v[226:229], 0
	v_mfma_f32_16x16x32_bf16 v[70:73], v[168:171], v[234:237], 0
	v_mfma_f32_16x16x32_bf16 v[66:69], v[176:179], v[234:237], 0
	v_mfma_f32_16x16x32_bf16 v[118:121], v[172:175], v[214:217], v[118:121]
	v_mfma_f32_16x16x32_bf16 v[114:117], v[180:183], v[214:217], v[114:117]
	v_mfma_f32_16x16x32_bf16 v[102:105], v[172:175], v[222:225], v[102:105]
	v_mfma_f32_16x16x32_bf16 v[98:101], v[180:183], v[222:225], v[98:101]
	v_mfma_f32_16x16x32_bf16 v[86:89], v[172:175], v[230:233], v[86:89]
	v_mfma_f32_16x16x32_bf16 v[82:85], v[180:183], v[230:233], v[82:85]
	v_mfma_f32_16x16x32_bf16 v[70:73], v[172:175], v[238:241], v[70:73]
	v_mfma_f32_16x16x32_bf16 v[66:69], v[180:183], v[238:241], v[66:69]
	s_barrier
	s_add_i32 s86, s86, s46
	v_lshl_add_u64 v[242:243], s[34:35], 0, v[132:133]
	s_mov_b32 m0, s86
	ds_read_b128 v[202:205], v212 offset:16384
	ds_read_b128 v[214:217], v212 offset:17408
	ds_read_b128 v[218:221], v212 offset:18432
	ds_read_b128 v[222:225], v212 offset:19456
	ds_read_b128 v[226:229], v212 offset:20480
	ds_read_b128 v[230:233], v212 offset:21504
	ds_read_b128 v[234:237], v212 offset:22528
	ds_read_b128 v[238:241], v212 offset:23552
	global_load_lds_dwordx4 v[242:243], off
	s_add_i32 m0, s86, 0x2000
	s_add_u32 s86, s34, 0x40000
	v_lshl_add_u64 v[244:245], s[34:35], 0, v[130:131]
	s_addc_u32 s87, s35, 0
	s_add_i32 s88, s88, s46
	global_load_lds_dwordx4 v[244:245], off
	v_lshl_add_u64 v[246:247], s[86:87], 0, v[132:133]
	s_mov_b32 m0, s88
	v_lshl_add_u64 v[248:249], s[40:41], 0, v[130:131]
	global_load_lds_dwordx4 v[246:247], off
	v_lshl_add_u64 v[246:247], s[86:87], 0, v[130:131]
	s_add_i32 m0, s88, 0x2000
	s_nop 0
	global_load_lds_dwordx4 v[246:247], off
	v_lshl_add_u64 v[246:247], s[40:41], 0, v[132:133]
	s_mov_b32 m0, s50
	s_nop 0
	global_load_lds_dwordx4 v[246:247], off
	s_mov_b32 m0, s73
	s_nop 0
	global_load_lds_dwordx4 v[248:249], off
	s_waitcnt vmcnt(8)
	s_waitcnt lgkmcnt(0)
	s_barrier
; #define PG8_STAGE(bufoff, gbase, voff) do { _Pragma("unroll") for (int _i = 0; _i < 2; ++_i) \
;         __builtin_amdgcn_global_load_lds((const unsigned*)((const char*)(gbase) + (voff)[_i]), (PG8_LAS unsigned*)(lds + (bufoff) + ldsw + _i * 8192), 16, 0, 0); } while (0)
; #define PG8_LDA(dst, b, h) do { _Pragma("unroll") for (int m = 0; m < 4; ++m) _Pragma("unroll") for (int k = 0; k < 2; ++k) dst[m][k] = *(const PG8_LAS bf16x8*)(lds + PG8_SA(b, h) + aoff + m * 2048 + k * 1024); } while (0)
; #define PG8_LDB(dst, b, h) do { _Pragma("unroll") for (int n = 0; n < 2; ++n) _Pragma("unroll") for (int k = 0; k < 2; ++k) dst[n][k] = *(const PG8_LAS bf16x8*)(lds + PG8_SB(b, h) + boff + n * 2048 + k * 1024); } while (0)
; #define PG8_MMA(ai, bj, At, Bt) do { __builtin_amdgcn_s_setprio(1); _Pragma("unroll") for (int m = 0; m < 4; ++m) _Pragma("unroll") for (int n = 0; n < 2; ++n) _Pragma("unroll") for (int k = 0; k < 2; ++k) \
;         acc[ai][bj][m][n] = __builtin_amdgcn_mfma_f32_16x16x32_bf16(Bt[n][k], At[m][k], acc[ai][bj][m][n], 0, 0, 0); __builtin_amdgcn_s_setprio(0); } while (0)
; #define PG8_WAIT_V(n) asm volatile("s_waitcnt vmcnt(" #n ")" ::: "memory")
; #define PG8_WAIT_L(n) asm volatile("s_waitcnt lgkmcnt(" #n ")" ::: "memory")
; #define PG8_BAR __builtin_amdgcn_s_barrier()
; #define PG8_SCHED __builtin_amdgcn_sched_barrier(0)
; template <class Epi, class Sched, bool ALIGN_EPI = false, bool SP2 = false>
; __device__ __forceinline__ void gemm_phase(PG8_LAS unsigned char* lds, const Gemm g, const Sched& S, const Epi& E) {
;     ...
;             PG8_WAIT_V(8); PG8_WAIT_L(0); PG8_BAR; PG8_MMA(1, 0, At, B0); PG8_MMA(1, 1, At, B1); PG8_BAR; PG8_SCHED;
;             PG8_LDB(B0, 1, 0); PG8_LDB(B1, 1, 1); PG8_SCHED; PG8_LDA(At, 1, 0); PG8_STAGE(PG8_SA(0, 1), a2 + hstep, voffA);
;             PG8_WAIT_V(8); PG8_WAIT_L(0); PG8_BAR; PG8_MMA(0, 0, At, B0); PG8_MMA(0, 1, At, B1); PG8_BAR; PG8_SCHED;
	s_waitcnt lgkmcnt(0)
	v_mfma_f32_16x16x32_bf16 v[62:65], v[152:155], v[202:205], 0
	v_mfma_f32_16x16x32_bf16 v[58:61], v[160:163], v[202:205], 0
	v_mfma_f32_16x16x32_bf16 v[46:49], v[152:155], v[218:221], 0
	v_mfma_f32_16x16x32_bf16 v[42:45], v[160:163], v[218:221], 0
	v_mfma_f32_16x16x32_bf16 v[30:33], v[152:155], v[226:229], 0
	v_mfma_f32_16x16x32_bf16 v[26:29], v[160:163], v[226:229], 0
	v_mfma_f32_16x16x32_bf16 v[14:17], v[152:155], v[234:237], 0
	v_mfma_f32_16x16x32_bf16 v[10:13], v[160:163], v[234:237], 0
	v_mfma_f32_16x16x32_bf16 v[62:65], v[156:159], v[214:217], v[62:65]
	v_mfma_f32_16x16x32_bf16 v[58:61], v[164:167], v[214:217], v[58:61]
	v_mfma_f32_16x16x32_bf16 v[46:49], v[156:159], v[222:225], v[46:49]
	v_mfma_f32_16x16x32_bf16 v[42:45], v[164:167], v[222:225], v[42:45]
	v_mfma_f32_16x16x32_bf16 v[30:33], v[156:159], v[230:233], v[30:33]
	v_mfma_f32_16x16x32_bf16 v[26:29], v[164:167], v[230:233], v[26:29]
	v_mfma_f32_16x16x32_bf16 v[14:17], v[156:159], v[238:241], v[14:17]
	v_mfma_f32_16x16x32_bf16 v[10:13], v[164:167], v[238:241], v[10:13]
	v_mfma_f32_16x16x32_bf16 v[54:57], v[168:171], v[202:205], 0
	v_mfma_f32_16x16x32_bf16 v[50:53], v[176:179], v[202:205], 0
	v_mfma_f32_16x16x32_bf16 v[38:41], v[168:171], v[218:221], 0
	v_mfma_f32_16x16x32_bf16 v[34:37], v[176:179], v[218:221], 0
	v_mfma_f32_16x16x32_bf16 v[22:25], v[168:171], v[226:229], 0
	v_mfma_f32_16x16x32_bf16 v[18:21], v[176:179], v[226:229], 0
	v_mfma_f32_16x16x32_bf16 v[6:9], v[168:171], v[234:237], 0
	v_mfma_f32_16x16x32_bf16 v[2:5], v[176:179], v[234:237], 0
	v_mfma_f32_16x16x32_bf16 v[54:57], v[172:175], v[214:217], v[54:57]
	v_mfma_f32_16x16x32_bf16 v[50:53], v[180:183], v[214:217], v[50:53]
	v_mfma_f32_16x16x32_bf16 v[38:41], v[172:175], v[222:225], v[38:41]
	v_mfma_f32_16x16x32_bf16 v[34:37], v[180:183], v[222:225], v[34:37]
	v_mfma_f32_16x16x32_bf16 v[22:25], v[172:175], v[230:233], v[22:25]
	v_mfma_f32_16x16x32_bf16 v[18:21], v[180:183], v[230:233], v[18:21]
	v_mfma_f32_16x16x32_bf16 v[6:9], v[172:175], v[238:241], v[6:9]
	v_mfma_f32_16x16x32_bf16 v[2:5], v[180:183], v[238:241], v[2:5]
	s_barrier
	s_add_i32 s86, 0, 0x18000
	v_add_u32_e32 v0, s86, v143
	s_add_i32 s87, 0, 0x1c000
	ds_read_b128 v[152:155], v0
	ds_read_b128 v[156:159], v0 offset:1024
	ds_read_b128 v[160:163], v0 offset:2048
	ds_read_b128 v[164:167], v0 offset:3072
	v_add_u32_e32 v0, s87, v143
	ds_read_b128 v[168:171], v0
	ds_read_b128 v[172:175], v0 offset:1024
	ds_read_b128 v[176:179], v0 offset:2048
	ds_read_b128 v[180:183], v0 offset:3072
	s_add_u32 s40, s40, 0x40000
	s_addc_u32 s41, s41, 0
	s_mov_b32 m0, s77
	v_lshl_add_u64 v[250:251], s[40:41], 0, v[132:133]
	ds_read_b128 v[202:205], v212 offset:32768
	ds_read_b128 v[214:217], v212 offset:33792
	ds_read_b128 v[218:221], v212 offset:34816
	ds_read_b128 v[222:225], v212 offset:35840
	ds_read_b128 v[226:229], v212 offset:36864
	ds_read_b128 v[230:233], v212 offset:37888
	ds_read_b128 v[234:237], v212 offset:38912
	ds_read_b128 v[238:241], v212 offset:39936
	global_load_lds_dwordx4 v[250:251], off
	v_lshl_add_u64 v[250:251], s[40:41], 0, v[130:131]
	s_mov_b32 m0, s78
	s_nop 0
	global_load_lds_dwordx4 v[250:251], off
	s_waitcnt vmcnt(8)
	s_waitcnt lgkmcnt(0)
	s_barrier
	s_waitcnt lgkmcnt(0)
	v_mfma_f32_16x16x32_bf16 v[126:129], v[152:155], v[202:205], v[126:129]
	v_mfma_f32_16x16x32_bf16 v[122:125], v[160:163], v[202:205], v[122:125]
	v_mfma_f32_16x16x32_bf16 v[110:113], v[152:155], v[218:221], v[110:113]
	v_mfma_f32_16x16x32_bf16 v[106:109], v[160:163], v[218:221], v[106:109]
	v_mfma_f32_16x16x32_bf16 v[94:97], v[152:155], v[226:229], v[94:97]
	v_mfma_f32_16x16x32_bf16 v[90:93], v[160:163], v[226:229], v[90:93]
	v_mfma_f32_16x16x32_bf16 v[78:81], v[152:155], v[234:237], v[78:81]
	v_mfma_f32_16x16x32_bf16 v[74:77], v[160:163], v[234:237], v[74:77]
	v_mfma_f32_16x16x32_bf16 v[126:129], v[156:159], v[214:217], v[126:129]
	v_mfma_f32_16x16x32_bf16 v[122:125], v[164:167], v[214:217], v[122:125]
	v_mfma_f32_16x16x32_bf16 v[110:113], v[156:159], v[222:225], v[110:113]
	v_mfma_f32_16x16x32_bf16 v[106:109], v[164:167], v[222:225], v[106:109]
	v_mfma_f32_16x16x32_bf16 v[94:97], v[156:159], v[230:233], v[94:97]
	v_mfma_f32_16x16x32_bf16 v[90:93], v[164:167], v[230:233], v[90:93]
	v_mfma_f32_16x16x32_bf16 v[78:81], v[156:159], v[238:241], v[78:81]
	v_mfma_f32_16x16x32_bf16 v[74:77], v[164:167], v[238:241], v[74:77]
	v_mfma_f32_16x16x32_bf16 v[118:121], v[168:171], v[202:205], v[118:121]
	v_mfma_f32_16x16x32_bf16 v[114:117], v[176:179], v[202:205], v[114:117]
	v_mfma_f32_16x16x32_bf16 v[102:105], v[168:171], v[218:221], v[102:105]
	v_mfma_f32_16x16x32_bf16 v[98:101], v[176:179], v[218:221], v[98:101]
	v_mfma_f32_16x16x32_bf16 v[86:89], v[168:171], v[226:229], v[86:89]
	v_mfma_f32_16x16x32_bf16 v[82:85], v[176:179], v[226:229], v[82:85]
	v_mfma_f32_16x16x32_bf16 v[70:73], v[168:171], v[234:237], v[70:73]
	v_mfma_f32_16x16x32_bf16 v[66:69], v[176:179], v[234:237], v[66:69]
	v_mfma_f32_16x16x32_bf16 v[118:121], v[172:175], v[214:217], v[118:121]
	v_mfma_f32_16x16x32_bf16 v[114:117], v[180:183], v[214:217], v[114:117]
	v_mfma_f32_16x16x32_bf16 v[102:105], v[172:175], v[222:225], v[102:105]
	v_mfma_f32_16x16x32_bf16 v[98:101], v[180:183], v[222:225], v[98:101]
	v_mfma_f32_16x16x32_bf16 v[86:89], v[172:175], v[230:233], v[86:89]
	v_mfma_f32_16x16x32_bf16 v[82:85], v[180:183], v[230:233], v[82:85]
	v_mfma_f32_16x16x32_bf16 v[70:73], v[172:175], v[238:241], v[70:73]
	v_mfma_f32_16x16x32_bf16 v[66:69], v[180:183], v[238:241], v[66:69]
	s_barrier
; #define PG8_STAGE(bufoff, gbase, voff) do { _Pragma("unroll") for (int _i = 0; _i < 2; ++_i) \
;         __builtin_amdgcn_global_load_lds((const unsigned*)((const char*)(gbase) + (voff)[_i]), (PG8_LAS unsigned*)(lds + (bufoff) + ldsw + _i * 8192), 16, 0, 0); } while (0)
; #define PG8_LDA(dst, b, h) do { _Pragma("unroll") for (int m = 0; m < 4; ++m) _Pragma("unroll") for (int k = 0; k < 2; ++k) dst[m][k] = *(const PG8_LAS bf16x8*)(lds + PG8_SA(b, h) + aoff + m * 2048 + k * 1024); } while (0)
; #define PG8_LDB(dst, b, h) do { _Pragma("unroll") for (int n = 0; n < 2; ++n) _Pragma("unroll") for (int k = 0; k < 2; ++k) dst[n][k] = *(const PG8_LAS bf16x8*)(lds + PG8_SB(b, h) + boff + n * 2048 + k * 1024); } while (0)
; #define PG8_MMA(ai, bj, At, Bt) do { __builtin_amdgcn_s_setprio(1); _Pragma("unroll") for (int m = 0; m < 4; ++m) _Pragma("unroll") for (int n = 0; n < 2; ++n) _Pragma("unroll") for (int k = 0; k < 2; ++k) \
;         acc[ai][bj][m][n] = __builtin_amdgcn_mfma_f32_16x16x32_bf16(Bt[n][k], At[m][k], acc[ai][bj][m][n], 0, 0, 0); __builtin_amdgcn_s_setprio(0); } while (0)
; #define PG8_WAIT_V(n) asm volatile("s_waitcnt vmcnt(" #n ")" ::: "memory")
; #define PG8_BAR __builtin_amdgcn_s_barrier()
; template <class Epi, class Sched, bool ALIGN_EPI = false, bool SP2 = false>
; __device__ __forceinline__ void gemm_phase(PG8_LAS unsigned char* lds, const Gemm g, const Sched& S, const Epi& E) {
;     ...
;         for (int t = 0; t < nt; t += 2) {
;             const bool last = (t == nt - 2);
;             const char* a1 = cA + (size_t)(t + 1) * kstep;
;             const char* a2 = last ? nA : cA + (size_t)(t + 2) * kstep; const char* b2 = last ? nB : cB + (size_t)(t + 2) * kstep;
;             const char* a3 = a2 + kstep; const char* b3 = b2 + kstep;
;             if (last && has_next) S.a_ready(nxt);
;             if constexpr (SP2) {
;             PG8_LDB(B0, 0, 0); PG8_LDB(B1, 0, 1); PG8_SCHED; PG8_LDA(At, 0, 0); PG8_STAGE(PG8_SA(1, 1), a1 + hstep, voffA);
;             PG8_WAIT_V(8); PG8_WAIT_L(0); PG8_BAR; PG8_MMA(0, 0, At, B0); PG8_MMA(0, 1, At, B1); PG8_BAR; PG8_SCHED;
;     ...
;             PG8_LDA(At, 1, 1); PG8_STAGE(PG8_SB(1, 0), b3, voffB); PG8_STAGE(PG8_SB(1, 1), b3 + hstep, voffB); PG8_STAGE(PG8_SA(1, 0), a3, voffA);
;             PG8_WAIT_V(8); PG8_WAIT_L(0); PG8_BAR; PG8_MMA(1, 0, At, B0); PG8_MMA(1, 1, At, B1); PG8_BAR; PG8_SCHED;
	s_add_i32 s40, s86, s46
	v_lshl_add_u64 v[242:243], v[242:243], 0, s[66:67]
	s_mov_b32 m0, s40
	ds_read_b128 v[202:205], v212 offset:49152
	ds_read_b128 v[214:217], v212 offset:50176
	ds_read_b128 v[218:221], v212 offset:51200
	ds_read_b128 v[222:225], v212 offset:52224
	ds_read_b128 v[226:229], v212 offset:53248
	ds_read_b128 v[230:233], v212 offset:54272
	ds_read_b128 v[234:237], v212 offset:55296
	ds_read_b128 v[238:241], v212 offset:56320
	global_load_lds_dwordx4 v[242:243], off
	s_add_i32 m0, s40, 0x2000
	s_add_u32 s34, s34, 0x40080
	v_lshl_add_u64 v[242:243], v[244:245], 0, s[66:67]
	s_addc_u32 s35, s35, 0
	s_add_i32 s40, s87, s46
	global_load_lds_dwordx4 v[242:243], off
	v_lshl_add_u64 v[242:243], s[34:35], 0, v[132:133]
	s_mov_b32 m0, s40
	s_nop 0
	global_load_lds_dwordx4 v[242:243], off
	v_lshl_add_u64 v[242:243], s[34:35], 0, v[130:131]
	s_add_i32 m0, s40, 0x2000
	s_nop 0
	global_load_lds_dwordx4 v[242:243], off
	v_lshl_add_u64 v[242:243], v[246:247], 0, s[66:67]
	s_mov_b32 m0, s83
	s_nop 0
	global_load_lds_dwordx4 v[242:243], off
	v_lshl_add_u64 v[242:243], v[248:249], 0, s[66:67]
	s_mov_b32 m0, s84
	s_nop 0
	global_load_lds_dwordx4 v[242:243], off
	s_waitcnt vmcnt(8)
	s_waitcnt lgkmcnt(0)
	s_barrier
	s_waitcnt lgkmcnt(0)
	v_mfma_f32_16x16x32_bf16 v[62:65], v[152:155], v[202:205], v[62:65]
	v_mfma_f32_16x16x32_bf16 v[58:61], v[160:163], v[202:205], v[58:61]
	v_mfma_f32_16x16x32_bf16 v[46:49], v[152:155], v[218:221], v[46:49]
	v_mfma_f32_16x16x32_bf16 v[42:45], v[160:163], v[218:221], v[42:45]
	v_mfma_f32_16x16x32_bf16 v[30:33], v[152:155], v[226:229], v[30:33]
	v_mfma_f32_16x16x32_bf16 v[26:29], v[160:163], v[226:229], v[26:29]
	v_mfma_f32_16x16x32_bf16 v[14:17], v[152:155], v[234:237], v[14:17]
	v_mfma_f32_16x16x32_bf16 v[10:13], v[160:163], v[234:237], v[10:13]
	v_mfma_f32_16x16x32_bf16 v[62:65], v[156:159], v[214:217], v[62:65]
	v_mfma_f32_16x16x32_bf16 v[58:61], v[164:167], v[214:217], v[58:61]
	v_mfma_f32_16x16x32_bf16 v[46:49], v[156:159], v[222:225], v[46:49]
	v_mfma_f32_16x16x32_bf16 v[42:45], v[164:167], v[222:225], v[42:45]
	v_mfma_f32_16x16x32_bf16 v[30:33], v[156:159], v[230:233], v[30:33]
	v_mfma_f32_16x16x32_bf16 v[26:29], v[164:167], v[230:233], v[26:29]
	v_mfma_f32_16x16x32_bf16 v[14:17], v[156:159], v[238:241], v[14:17]
	v_mfma_f32_16x16x32_bf16 v[10:13], v[164:167], v[238:241], v[10:13]
	v_mfma_f32_16x16x32_bf16 v[54:57], v[168:171], v[202:205], v[54:57]
	v_mfma_f32_16x16x32_bf16 v[50:53], v[176:179], v[202:205], v[50:53]
	v_mfma_f32_16x16x32_bf16 v[38:41], v[168:171], v[218:221], v[38:41]
	v_mfma_f32_16x16x32_bf16 v[34:37], v[176:179], v[218:221], v[34:37]
	v_mfma_f32_16x16x32_bf16 v[22:25], v[168:171], v[226:229], v[22:25]
	v_mfma_f32_16x16x32_bf16 v[18:21], v[176:179], v[226:229], v[18:21]
	v_mfma_f32_16x16x32_bf16 v[6:9], v[168:171], v[234:237], v[6:9]
	v_mfma_f32_16x16x32_bf16 v[2:5], v[176:179], v[234:237], v[2:5]
	v_mfma_f32_16x16x32_bf16 v[54:57], v[172:175], v[214:217], v[54:57]
	v_mfma_f32_16x16x32_bf16 v[50:53], v[180:183], v[214:217], v[50:53]
	v_mfma_f32_16x16x32_bf16 v[38:41], v[172:175], v[222:225], v[38:41]
	v_mfma_f32_16x16x32_bf16 v[34:37], v[180:183], v[222:225], v[34:37]
	v_mfma_f32_16x16x32_bf16 v[22:25], v[172:175], v[230:233], v[22:25]
	v_mfma_f32_16x16x32_bf16 v[18:21], v[180:183], v[230:233], v[18:21]
	v_mfma_f32_16x16x32_bf16 v[6:9], v[172:175], v[238:241], v[6:9]
	v_mfma_f32_16x16x32_bf16 v[2:5], v[180:183], v[238:241], v[2:5]
	s_barrier
	s_add_i32 s85, s85, 2
	s_add_u32 s30, s30, 0x100
	s_addc_u32 s31, s31, 0
	s_add_u32 s64, s64, 0x100
	s_addc_u32 s71, s71, 0
	s_cmp_gt_u32 s85, 13
	s_cbranch_scc0 .LBB0_188
	s_branch .Lpeel_o_exit
	s_nop 0
.LBB0_188:
	s_add_u32 s34, s30, 0xfffc0080
	s_addc_u32 s35, s31, -1
	s_add_i32 s86, 0, 0x10000
	s_cmp_eq_u32 s85, 12
	s_cselect_b32 s41, s23, s35
	s_cselect_b32 s40, s54, s34
	v_add_u32_e32 v0, s86, v143
	s_cselect_b32 s35, s21, s71
	s_cselect_b32 s34, s62, s64
	s_add_i32 s88, 0, 0x14000
	ds_read_b128 v[152:155], v0
	ds_read_b128 v[156:159], v0 offset:1024
	ds_read_b128 v[160:163], v0 offset:2048
	ds_read_b128 v[164:167], v0 offset:3072
	v_add_u32_e32 v0, s88, v143
	ds_read_b128 v[168:171], v0
	ds_read_b128 v[172:175], v0 offset:1024
	ds_read_b128 v[176:179], v0 offset:2048
	ds_read_b128 v[180:183], v0 offset:3072
	v_lshl_add_u64 v[242:243], s[30:31], 0, v[148:149]
	s_add_i32 m0, s50, 0xc000
	ds_read_b128 v[202:205], v212
	ds_read_b128 v[214:217], v212 offset:1024
	ds_read_b128 v[218:221], v212 offset:2048
	ds_read_b128 v[222:225], v212 offset:3072
	ds_read_b128 v[226:229], v212 offset:4096
	ds_read_b128 v[230:233], v212 offset:5120
	ds_read_b128 v[234:237], v212 offset:6144
	ds_read_b128 v[238:241], v212 offset:7168
	global_load_lds_dwordx4 v[242:243], off
	v_lshl_add_u64 v[242:243], s[30:31], 0, v[150:151]
	s_add_i32 m0, s50, 0xe000
	s_nop 0
	global_load_lds_dwordx4 v[242:243], off
	s_waitcnt vmcnt(8)
	s_waitcnt lgkmcnt(0)
	s_barrier
; #define PG8_STAGE(bufoff, gbase, voff) do { _Pragma("unroll") for (int _i = 0; _i < 2; ++_i) \
;         __builtin_amdgcn_global_load_lds((const unsigned*)((const char*)(gbase) + (voff)[_i]), (PG8_LAS unsigned*)(lds + (bufoff) + ldsw + _i * 8192), 16, 0, 0); } while (0)
; #define PG8_LDA(dst, b, h) do { _Pragma("unroll") for (int m = 0; m < 4; ++m) _Pragma("unroll") for (int k = 0; k < 2; ++k) dst[m][k] = *(const PG8_LAS bf16x8*)(lds + PG8_SA(b, h) + aoff + m * 2048 + k * 1024); } while (0)
; #define PG8_LDB(dst, b, h) do { _Pragma("unroll") for (int n = 0; n < 2; ++n) _Pragma("unroll") for (int k = 0; k < 2; ++k) dst[n][k] = *(const PG8_LAS bf16x8*)(lds + PG8_SB(b, h) + boff + n * 2048 + k * 1024); } while (0)
; #define PG8_MMA(ai, bj, At, Bt) do { __builtin_amdgcn_s_setprio(1); _Pragma("unroll") for (int m = 0; m < 4; ++m) _Pragma("unroll") for (int n = 0; n < 2; ++n) _Pragma("unroll") for (int k = 0; k < 2; ++k) \
;         acc[ai][bj][m][n] = __builtin_amdgcn_mfma_f32_16x16x32_bf16(Bt[n][k], At[m][k], acc[ai][bj][m][n], 0, 0, 0); __builtin_amdgcn_s_setprio(0); } while (0)
; #define PG8_WAIT_V(n) asm volatile("s_waitcnt vmcnt(" #n ")" ::: "memory")
; #define PG8_WAIT_L(n) asm volatile("s_waitcnt lgkmcnt(" #n ")" ::: "memory")
; #define PG8_BAR __builtin_amdgcn_s_barrier()
; #define PG8_SCHED __builtin_amdgcn_sched_barrier(0)
; template <class Epi, class Sched, bool ALIGN_EPI = false, bool SP2 = false>
; __device__ __forceinline__ void gemm_phase(PG8_LAS unsigned char* lds, const Gemm g, const Sched& S, const Epi& E) {
;     ...
;             PG8_WAIT_V(8); PG8_WAIT_L(0); PG8_BAR; PG8_MMA(0, 0, At, B0); PG8_MMA(0, 1, At, B1); PG8_BAR; PG8_SCHED;
;             PG8_LDA(At, 0, 1); PG8_STAGE(PG8_SB(0, 0), b2, voffB); PG8_STAGE(PG8_SB(0, 1), b2 + hstep, voffB); PG8_STAGE(PG8_SA(0, 0), a2, voffA);
;             PG8_WAIT_V(8); PG8_WAIT_L(0); PG8_BAR; PG8_MMA(1, 0, At, B0); PG8_MMA(1, 1, At, B1); PG8_BAR; PG8_SCHED;
;             PG8_LDB(B0, 1, 0); PG8_LDB(B1, 1, 1); PG8_SCHED; PG8_LDA(At, 1, 0); PG8_STAGE(PG8_SA(0, 1), a2 + hstep, voffA);
;             PG8_WAIT_V(8); PG8_WAIT_L(0); PG8_BAR; PG8_MMA(0, 0, At, B0); PG8_MMA(0, 1, At, B1); PG8_BAR; PG8_SCHED;
	s_waitcnt lgkmcnt(0)
	v_mfma_f32_16x16x32_bf16 v[126:129], v[152:155], v[202:205], v[126:129]
	v_mfma_f32_16x16x32_bf16 v[122:125], v[160:163], v[202:205], v[122:125]
	v_mfma_f32_16x16x32_bf16 v[110:113], v[152:155], v[218:221], v[110:113]
	v_mfma_f32_16x16x32_bf16 v[106:109], v[160:163], v[218:221], v[106:109]
	v_mfma_f32_16x16x32_bf16 v[94:97], v[152:155], v[226:229], v[94:97]
	v_mfma_f32_16x16x32_bf16 v[90:93], v[160:163], v[226:229], v[90:93]
	v_mfma_f32_16x16x32_bf16 v[78:81], v[152:155], v[234:237], v[78:81]
	v_mfma_f32_16x16x32_bf16 v[74:77], v[160:163], v[234:237], v[74:77]
	v_mfma_f32_16x16x32_bf16 v[126:129], v[156:159], v[214:217], v[126:129]
	v_mfma_f32_16x16x32_bf16 v[122:125], v[164:167], v[214:217], v[122:125]
	v_mfma_f32_16x16x32_bf16 v[110:113], v[156:159], v[222:225], v[110:113]
	v_mfma_f32_16x16x32_bf16 v[106:109], v[164:167], v[222:225], v[106:109]
	v_mfma_f32_16x16x32_bf16 v[94:97], v[156:159], v[230:233], v[94:97]
	v_mfma_f32_16x16x32_bf16 v[90:93], v[164:167], v[230:233], v[90:93]
	v_mfma_f32_16x16x32_bf16 v[78:81], v[156:159], v[238:241], v[78:81]
	v_mfma_f32_16x16x32_bf16 v[74:77], v[164:167], v[238:241], v[74:77]
	v_mfma_f32_16x16x32_bf16 v[118:121], v[168:171], v[202:205], v[118:121]
	v_mfma_f32_16x16x32_bf16 v[114:117], v[176:179], v[202:205], v[114:117]
	v_mfma_f32_16x16x32_bf16 v[102:105], v[168:171], v[218:221], v[102:105]
	v_mfma_f32_16x16x32_bf16 v[98:101], v[176:179], v[218:221], v[98:101]
	v_mfma_f32_16x16x32_bf16 v[86:89], v[168:171], v[226:229], v[86:89]
	v_mfma_f32_16x16x32_bf16 v[82:85], v[176:179], v[226:229], v[82:85]
	v_mfma_f32_16x16x32_bf16 v[70:73], v[168:171], v[234:237], v[70:73]
	v_mfma_f32_16x16x32_bf16 v[66:69], v[176:179], v[234:237], v[66:69]
	v_mfma_f32_16x16x32_bf16 v[118:121], v[172:175], v[214:217], v[118:121]
	v_mfma_f32_16x16x32_bf16 v[114:117], v[180:183], v[214:217], v[114:117]
	v_mfma_f32_16x16x32_bf16 v[102:105], v[172:175], v[222:225], v[102:105]
	v_mfma_f32_16x16x32_bf16 v[98:101], v[180:183], v[222:225], v[98:101]
	v_mfma_f32_16x16x32_bf16 v[86:89], v[172:175], v[230:233], v[86:89]
	v_mfma_f32_16x16x32_bf16 v[82:85], v[180:183], v[230:233], v[82:85]
	v_mfma_f32_16x16x32_bf16 v[70:73], v[172:175], v[238:241], v[70:73]
	v_mfma_f32_16x16x32_bf16 v[66:69], v[180:183], v[238:241], v[66:69]
	s_barrier
	s_add_i32 s86, s86, s46
	v_lshl_add_u64 v[242:243], s[34:35], 0, v[132:133]
	s_mov_b32 m0, s86
	ds_read_b128 v[202:205], v212 offset:16384
	ds_read_b128 v[214:217], v212 offset:17408
	ds_read_b128 v[218:221], v212 offset:18432
	ds_read_b128 v[222:225], v212 offset:19456
	ds_read_b128 v[226:229], v212 offset:20480
	ds_read_b128 v[230:233], v212 offset:21504
	ds_read_b128 v[234:237], v212 offset:22528
	ds_read_b128 v[238:241], v212 offset:23552
	global_load_lds_dwordx4 v[242:243], off
	s_add_i32 m0, s86, 0x2000
	s_add_u32 s86, s34, 0x40000
	v_lshl_add_u64 v[244:245], s[34:35], 0, v[130:131]
	s_addc_u32 s87, s35, 0
	s_add_i32 s88, s88, s46
	global_load_lds_dwordx4 v[244:245], off
	v_lshl_add_u64 v[246:247], s[86:87], 0, v[132:133]
	s_mov_b32 m0, s88
	v_lshl_add_u64 v[248:249], s[40:41], 0, v[130:131]
	global_load_lds_dwordx4 v[246:247], off
	v_lshl_add_u64 v[246:247], s[86:87], 0, v[130:131]
	s_add_i32 m0, s88, 0x2000
	s_nop 0
	global_load_lds_dwordx4 v[246:247], off
	v_lshl_add_u64 v[246:247], s[40:41], 0, v[132:133]
	s_mov_b32 m0, s50
	s_nop 0
	global_load_lds_dwordx4 v[246:247], off
	s_mov_b32 m0, s73
	s_nop 0
	global_load_lds_dwordx4 v[248:249], off
	s_waitcnt vmcnt(8)
	s_waitcnt lgkmcnt(0)
	s_barrier
	s_waitcnt lgkmcnt(0)
	v_mfma_f32_16x16x32_bf16 v[62:65], v[152:155], v[202:205], v[62:65]
	v_mfma_f32_16x16x32_bf16 v[58:61], v[160:163], v[202:205], v[58:61]
	v_mfma_f32_16x16x32_bf16 v[46:49], v[152:155], v[218:221], v[46:49]
	v_mfma_f32_16x16x32_bf16 v[42:45], v[160:163], v[218:221], v[42:45]
	v_mfma_f32_16x16x32_bf16 v[30:33], v[152:155], v[226:229], v[30:33]
	v_mfma_f32_16x16x32_bf16 v[26:29], v[160:163], v[226:229], v[26:29]
	v_mfma_f32_16x16x32_bf16 v[14:17], v[152:155], v[234:237], v[14:17]
	v_mfma_f32_16x16x32_bf16 v[10:13], v[160:163], v[234:237], v[10:13]
	v_mfma_f32_16x16x32_bf16 v[62:65], v[156:159], v[214:217], v[62:65]
	v_mfma_f32_16x16x32_bf16 v[58:61], v[164:167], v[214:217], v[58:61]
	v_mfma_f32_16x16x32_bf16 v[46:49], v[156:159], v[222:225], v[46:49]
	v_mfma_f32_16x16x32_bf16 v[42:45], v[164:167], v[222:225], v[42:45]
	v_mfma_f32_16x16x32_bf16 v[30:33], v[156:159], v[230:233], v[30:33]
	v_mfma_f32_16x16x32_bf16 v[26:29], v[164:167], v[230:233], v[26:29]
	v_mfma_f32_16x16x32_bf16 v[14:17], v[156:159], v[238:241], v[14:17]
	v_mfma_f32_16x16x32_bf16 v[10:13], v[164:167], v[238:241], v[10:13]
	v_mfma_f32_16x16x32_bf16 v[54:57], v[168:171], v[202:205], v[54:57]
	v_mfma_f32_16x16x32_bf16 v[50:53], v[176:179], v[202:205], v[50:53]
	v_mfma_f32_16x16x32_bf16 v[38:41], v[168:171], v[218:221], v[38:41]
	v_mfma_f32_16x16x32_bf16 v[34:37], v[176:179], v[218:221], v[34:37]
	v_mfma_f32_16x16x32_bf16 v[22:25], v[168:171], v[226:229], v[22:25]
	v_mfma_f32_16x16x32_bf16 v[18:21], v[176:179], v[226:229], v[18:21]
	v_mfma_f32_16x16x32_bf16 v[6:9], v[168:171], v[234:237], v[6:9]
	v_mfma_f32_16x16x32_bf16 v[2:5], v[176:179], v[234:237], v[2:5]
	v_mfma_f32_16x16x32_bf16 v[54:57], v[172:175], v[214:217], v[54:57]
	v_mfma_f32_16x16x32_bf16 v[50:53], v[180:183], v[214:217], v[50:53]
	v_mfma_f32_16x16x32_bf16 v[38:41], v[172:175], v[222:225], v[38:41]
	v_mfma_f32_16x16x32_bf16 v[34:37], v[180:183], v[222:225], v[34:37]
	v_mfma_f32_16x16x32_bf16 v[22:25], v[172:175], v[230:233], v[22:25]
	v_mfma_f32_16x16x32_bf16 v[18:21], v[180:183], v[230:233], v[18:21]
	v_mfma_f32_16x16x32_bf16 v[6:9], v[172:175], v[238:241], v[6:9]
	v_mfma_f32_16x16x32_bf16 v[2:5], v[180:183], v[238:241], v[2:5]
	s_barrier
; #define PG8_STAGE(bufoff, gbase, voff) do { _Pragma("unroll") for (int _i = 0; _i < 2; ++_i) \
;         __builtin_amdgcn_global_load_lds((const unsigned*)((const char*)(gbase) + (voff)[_i]), (PG8_LAS unsigned*)(lds + (bufoff) + ldsw + _i * 8192), 16, 0, 0); } while (0)
; #define PG8_LDA(dst, b, h) do { _Pragma("unroll") for (int m = 0; m < 4; ++m) _Pragma("unroll") for (int k = 0; k < 2; ++k) dst[m][k] = *(const PG8_LAS bf16x8*)(lds + PG8_SA(b, h) + aoff + m * 2048 + k * 1024); } while (0)
; #define PG8_MMA(ai, bj, At, Bt) do { __builtin_amdgcn_s_setprio(1); _Pragma("unroll") for (int m = 0; m < 4; ++m) _Pragma("unroll") for (int n = 0; n < 2; ++n) _Pragma("unroll") for (int k = 0; k < 2; ++k) \
;         acc[ai][bj][m][n] = __builtin_amdgcn_mfma_f32_16x16x32_bf16(Bt[n][k], At[m][k], acc[ai][bj][m][n], 0, 0, 0); __builtin_amdgcn_s_setprio(0); } while (0)
; #define PG8_WAIT_V(n) asm volatile("s_waitcnt vmcnt(" #n ")" ::: "memory")
; #define PG8_WAIT_L(n) asm volatile("s_waitcnt lgkmcnt(" #n ")" ::: "memory")
; #define PG8_BAR __builtin_amdgcn_s_barrier()
; #define PG8_SCHED __builtin_amdgcn_sched_barrier(0)
; template <class Epi, class Sched, bool ALIGN_EPI = false, bool SP2 = false>
; __device__ __forceinline__ void gemm_phase(PG8_LAS unsigned char* lds, const Gemm g, const Sched& S, const Epi& E) {
;     ...
;             PG8_WAIT_V(8); PG8_WAIT_L(0); PG8_BAR; PG8_MMA(0, 0, At, B0); PG8_MMA(0, 1, At, B1); PG8_BAR; PG8_SCHED;
;             PG8_LDA(At, 1, 1); PG8_STAGE(PG8_SB(1, 0), b3, voffB); PG8_STAGE(PG8_SB(1, 1), b3 + hstep, voffB); PG8_STAGE(PG8_SA(1, 0), a3, voffA);
;             PG8_WAIT_V(8); PG8_WAIT_L(0); PG8_BAR; PG8_MMA(1, 0, At, B0); PG8_MMA(1, 1, At, B1); PG8_BAR; PG8_SCHED;
	s_add_i32 s86, 0, 0x18000
	v_add_u32_e32 v0, s86, v143
	s_add_i32 s87, 0, 0x1c000
	ds_read_b128 v[152:155], v0
	ds_read_b128 v[156:159], v0 offset:1024
	ds_read_b128 v[160:163], v0 offset:2048
	ds_read_b128 v[164:167], v0 offset:3072
	v_add_u32_e32 v0, s87, v143
	ds_read_b128 v[168:171], v0
	ds_read_b128 v[172:175], v0 offset:1024
	ds_read_b128 v[176:179], v0 offset:2048
	ds_read_b128 v[180:183], v0 offset:3072
	s_add_u32 s40, s40, 0x40000
	s_addc_u32 s41, s41, 0
	s_mov_b32 m0, s77
	v_lshl_add_u64 v[250:251], s[40:41], 0, v[132:133]
	ds_read_b128 v[202:205], v212 offset:32768
	ds_read_b128 v[214:217], v212 offset:33792
	ds_read_b128 v[218:221], v212 offset:34816
	ds_read_b128 v[222:225], v212 offset:35840
	ds_read_b128 v[226:229], v212 offset:36864
	ds_read_b128 v[230:233], v212 offset:37888
	ds_read_b128 v[234:237], v212 offset:38912
	ds_read_b128 v[238:241], v212 offset:39936
	global_load_lds_dwordx4 v[250:251], off
	v_lshl_add_u64 v[250:251], s[40:41], 0, v[130:131]
	s_mov_b32 m0, s78
	s_nop 0
	global_load_lds_dwordx4 v[250:251], off
	s_waitcnt vmcnt(8)
	s_waitcnt lgkmcnt(0)
	s_barrier
	s_waitcnt lgkmcnt(0)
	v_mfma_f32_16x16x32_bf16 v[126:129], v[152:155], v[202:205], v[126:129]
	v_mfma_f32_16x16x32_bf16 v[122:125], v[160:163], v[202:205], v[122:125]
	v_mfma_f32_16x16x32_bf16 v[110:113], v[152:155], v[218:221], v[110:113]
	v_mfma_f32_16x16x32_bf16 v[106:109], v[160:163], v[218:221], v[106:109]
	v_mfma_f32_16x16x32_bf16 v[94:97], v[152:155], v[226:229], v[94:97]
	v_mfma_f32_16x16x32_bf16 v[90:93], v[160:163], v[226:229], v[90:93]
	v_mfma_f32_16x16x32_bf16 v[78:81], v[152:155], v[234:237], v[78:81]
	v_mfma_f32_16x16x32_bf16 v[74:77], v[160:163], v[234:237], v[74:77]
	v_mfma_f32_16x16x32_bf16 v[126:129], v[156:159], v[214:217], v[126:129]
	v_mfma_f32_16x16x32_bf16 v[122:125], v[164:167], v[214:217], v[122:125]
	v_mfma_f32_16x16x32_bf16 v[110:113], v[156:159], v[222:225], v[110:113]
	v_mfma_f32_16x16x32_bf16 v[106:109], v[164:167], v[222:225], v[106:109]
	v_mfma_f32_16x16x32_bf16 v[94:97], v[156:159], v[230:233], v[94:97]
	v_mfma_f32_16x16x32_bf16 v[90:93], v[164:167], v[230:233], v[90:93]
	v_mfma_f32_16x16x32_bf16 v[78:81], v[156:159], v[238:241], v[78:81]
	v_mfma_f32_16x16x32_bf16 v[74:77], v[164:167], v[238:241], v[74:77]
	v_mfma_f32_16x16x32_bf16 v[118:121], v[168:171], v[202:205], v[118:121]
	v_mfma_f32_16x16x32_bf16 v[114:117], v[176:179], v[202:205], v[114:117]
	v_mfma_f32_16x16x32_bf16 v[102:105], v[168:171], v[218:221], v[102:105]
	v_mfma_f32_16x16x32_bf16 v[98:101], v[176:179], v[218:221], v[98:101]
	v_mfma_f32_16x16x32_bf16 v[86:89], v[168:171], v[226:229], v[86:89]
	v_mfma_f32_16x16x32_bf16 v[82:85], v[176:179], v[226:229], v[82:85]
	v_mfma_f32_16x16x32_bf16 v[70:73], v[168:171], v[234:237], v[70:73]
	v_mfma_f32_16x16x32_bf16 v[66:69], v[176:179], v[234:237], v[66:69]
	v_mfma_f32_16x16x32_bf16 v[118:121], v[172:175], v[214:217], v[118:121]
	v_mfma_f32_16x16x32_bf16 v[114:117], v[180:183], v[214:217], v[114:117]
	v_mfma_f32_16x16x32_bf16 v[102:105], v[172:175], v[222:225], v[102:105]
	v_mfma_f32_16x16x32_bf16 v[98:101], v[180:183], v[222:225], v[98:101]
	v_mfma_f32_16x16x32_bf16 v[86:89], v[172:175], v[230:233], v[86:89]
	v_mfma_f32_16x16x32_bf16 v[82:85], v[180:183], v[230:233], v[82:85]
	v_mfma_f32_16x16x32_bf16 v[70:73], v[172:175], v[238:241], v[70:73]
	v_mfma_f32_16x16x32_bf16 v[66:69], v[180:183], v[238:241], v[66:69]
	s_barrier
	s_add_i32 s40, s86, s46
	v_lshl_add_u64 v[242:243], v[242:243], 0, s[66:67]
	s_mov_b32 m0, s40
	ds_read_b128 v[202:205], v212 offset:49152
	ds_read_b128 v[214:217], v212 offset:50176
	ds_read_b128 v[218:221], v212 offset:51200
	ds_read_b128 v[222:225], v212 offset:52224
	ds_read_b128 v[226:229], v212 offset:53248
	ds_read_b128 v[230:233], v212 offset:54272
	ds_read_b128 v[234:237], v212 offset:55296
	ds_read_b128 v[238:241], v212 offset:56320
	global_load_lds_dwordx4 v[242:243], off
	s_add_i32 m0, s40, 0x2000
	s_add_u32 s34, s34, 0x40080
	v_lshl_add_u64 v[242:243], v[244:245], 0, s[66:67]
	s_addc_u32 s35, s35, 0
	s_add_i32 s40, s87, s46
	global_load_lds_dwordx4 v[242:243], off
	v_lshl_add_u64 v[242:243], s[34:35], 0, v[132:133]
	s_mov_b32 m0, s40
	s_nop 0
	global_load_lds_dwordx4 v[242:243], off
	v_lshl_add_u64 v[242:243], s[34:35], 0, v[130:131]
	s_add_i32 m0, s40, 0x2000
	s_nop 0
	global_load_lds_dwordx4 v[242:243], off
	v_lshl_add_u64 v[242:243], v[246:247], 0, s[66:67]
	s_mov_b32 m0, s83
	s_nop 0
	global_load_lds_dwordx4 v[242:243], off
	v_lshl_add_u64 v[242:243], v[248:249], 0, s[66:67]
	s_mov_b32 m0, s84
	s_nop 0
	global_load_lds_dwordx4 v[242:243], off
	s_waitcnt vmcnt(8)
	s_waitcnt lgkmcnt(0)
	s_barrier
	s_waitcnt lgkmcnt(0)
	v_mfma_f32_16x16x32_bf16 v[62:65], v[152:155], v[202:205], v[62:65]
	v_mfma_f32_16x16x32_bf16 v[58:61], v[160:163], v[202:205], v[58:61]
	v_mfma_f32_16x16x32_bf16 v[46:49], v[152:155], v[218:221], v[46:49]
	v_mfma_f32_16x16x32_bf16 v[42:45], v[160:163], v[218:221], v[42:45]
	v_mfma_f32_16x16x32_bf16 v[30:33], v[152:155], v[226:229], v[30:33]
	v_mfma_f32_16x16x32_bf16 v[26:29], v[160:163], v[226:229], v[26:29]
	v_mfma_f32_16x16x32_bf16 v[14:17], v[152:155], v[234:237], v[14:17]
	v_mfma_f32_16x16x32_bf16 v[10:13], v[160:163], v[234:237], v[10:13]
	v_mfma_f32_16x16x32_bf16 v[62:65], v[156:159], v[214:217], v[62:65]
	v_mfma_f32_16x16x32_bf16 v[58:61], v[164:167], v[214:217], v[58:61]
	v_mfma_f32_16x16x32_bf16 v[46:49], v[156:159], v[222:225], v[46:49]
	v_mfma_f32_16x16x32_bf16 v[42:45], v[164:167], v[222:225], v[42:45]
	v_mfma_f32_16x16x32_bf16 v[30:33], v[156:159], v[230:233], v[30:33]
	v_mfma_f32_16x16x32_bf16 v[26:29], v[164:167], v[230:233], v[26:29]
	v_mfma_f32_16x16x32_bf16 v[14:17], v[156:159], v[238:241], v[14:17]
	v_mfma_f32_16x16x32_bf16 v[10:13], v[164:167], v[238:241], v[10:13]
	v_mfma_f32_16x16x32_bf16 v[54:57], v[168:171], v[202:205], v[54:57]
	v_mfma_f32_16x16x32_bf16 v[50:53], v[176:179], v[202:205], v[50:53]
	v_mfma_f32_16x16x32_bf16 v[38:41], v[168:171], v[218:221], v[38:41]
	v_mfma_f32_16x16x32_bf16 v[34:37], v[176:179], v[218:221], v[34:37]
	v_mfma_f32_16x16x32_bf16 v[22:25], v[168:171], v[226:229], v[22:25]
	v_mfma_f32_16x16x32_bf16 v[18:21], v[176:179], v[226:229], v[18:21]
	v_mfma_f32_16x16x32_bf16 v[6:9], v[168:171], v[234:237], v[6:9]
	v_mfma_f32_16x16x32_bf16 v[2:5], v[176:179], v[234:237], v[2:5]
	v_mfma_f32_16x16x32_bf16 v[54:57], v[172:175], v[214:217], v[54:57]
	v_mfma_f32_16x16x32_bf16 v[50:53], v[180:183], v[214:217], v[50:53]
	v_mfma_f32_16x16x32_bf16 v[38:41], v[172:175], v[222:225], v[38:41]
	v_mfma_f32_16x16x32_bf16 v[34:37], v[180:183], v[222:225], v[34:37]
	v_mfma_f32_16x16x32_bf16 v[22:25], v[172:175], v[230:233], v[22:25]
	v_mfma_f32_16x16x32_bf16 v[18:21], v[180:183], v[230:233], v[18:21]
	v_mfma_f32_16x16x32_bf16 v[6:9], v[172:175], v[238:241], v[6:9]
	v_mfma_f32_16x16x32_bf16 v[2:5], v[180:183], v[238:241], v[2:5]
	s_barrier
	s_add_i32 s85, s85, 2
	s_add_u32 s30, s30, 0x100
	s_addc_u32 s31, s31, 0
	s_add_u32 s64, s64, 0x100
	s_addc_u32 s71, s71, 0
	s_cmp_gt_u32 s85, 13
	s_cbranch_scc0 .LBB0_188

; #define PG8_WAIT_V(n) asm volatile("s_waitcnt vmcnt(" #n ")" ::: "memory")
; #define PG8_BAR __builtin_amdgcn_s_barrier()
; __device__ __forceinline__ unsigned xb_add(unsigned* p, unsigned v) { return __hip_atomic_fetch_add(p, v, __ATOMIC_RELAXED, __HIP_MEMORY_SCOPE_AGENT); }
; template <class Epi, class Sched, bool ALIGN_EPI = false, bool SP2 = false>
; __device__ __forceinline__ void gemm_phase(PG8_LAS unsigned char* lds, const Gemm g, const Sched& S, const Epi& E) {
;     ...
;     PG8_WAIT_V(0);
;     if constexpr (!ALIGN_EPI) { if (wr == 0) PG8_BAR; }
;     PG8_BAR;
; __device__ __forceinline__ void xcd_barrier(const XcdBarrier& b) {
;     asm volatile("s_waitcnt vmcnt(0)" ::: "memory");
;     __syncthreads();
;     if (threadIdx.x == 0) {
;         unsigned* bar = b.bar;
;         __builtin_amdgcn_s_waitcnt(0);
;         unsigned nloc = b.st[0], nx = b.st[1];
;         if (nloc == 0u) { xcd_barrier_complete(bar, b.x, nloc, nx); b.st[0] = nloc; b.st[1] = nx; }
;         const unsigned old = xb_add(&bar[XB_XSUB(b.x)], 1u);
;         const unsigned gen = old / nloc;
.LBB0_199:
	s_setprio 0
	s_waitcnt vmcnt(0)
	s_waitcnt vmcnt(0)
	s_barrier
	s_mov_b64 s[2:3], exec
	v_readlane_b32 s6, v253, 0
	v_readlane_b32 s7, v253, 1
	s_and_b64 s[6:7], s[2:3], s[6:7]
	s_mov_b64 exec, s[6:7]
	s_cbranch_execz .LBB0_265
	v_mov_b32_e32 v0, s96
	s_waitcnt vmcnt(0) expcnt(0) lgkmcnt(0)
	ds_read_b32 v3, v0
	v_readlane_b32 s1, v254, 42
	s_waitcnt lgkmcnt(0)
	v_cmp_ne_u32_e32 vcc, 0, v3
	v_mov_b32_e32 v0, s1
	ds_read_b32 v2, v0
	s_cbranch_vccnz .LBB0_233
	s_mov_b32 s12, 1
	s_branch .LBB0_203

; __device__ __forceinline__ void swa_block_task(const P& p, int task, unsigned char* sm, int tid) {
;     const int wave = tid >> 6, lane = tid & 63, fr = lane & 15, g = lane >> 4;
;     const bf16_t* Q = (const bf16_t*)(p.ws + WS_SWQ); const bf16_t* K = (const bf16_t*)(p.ws + WS_SWK); const bf16_t* VT = (const bf16_t*)(p.ws + WS_SWVT); bf16_t* Y = (bf16_t*)(p.ws + WS_A);
;     const int g4 = task & 3, qblk = (task >> 2) & 15, b = task >> 6;
;     const int Q0 = qblk * 128, qt = Q0 + wave * 16 + fr; const size_t qrow = (size_t)b * TLAT + qt;
;     AttnState st[4]; bf16x8 q0[4], q1[4];
; #pragma unroll
;     for (int hh = 0; hh < 4; ++hh) {
;         const int hq = g4 * 4 + hh;
;         st[hh].m = p.sink[hq]; st[hh].l = (g == 0) ? 1.f : 0.f;
; #pragma unroll
;         for (int dt = 0; dt < 4; ++dt) st[hh].o[dt] = (f32x4){0.f, 0.f, 0.f, 0.f};
;         const bf16_t* qp = Q + qrow * 1024 + hq * 64 + g * 8;
;         q0[hh] = *(const bf16x8*)qp; q1[hh] = *(const bf16x8*)(qp + 32);
;     }
;     const int cw0 = Q0 >= 128 ? 0 : (128 - Q0) / 32, cw1 = (Q0 + 256 <= TLAT) ? 11 : (TLAT - 1 - (Q0 - 128)) / 32;
;     const int nwin = cw1 - cw0 + 1, nch = nwin + 8;
;     const bool isk = tid < 256; const int lr = isk ? (tid >> 3) : ((tid - 256) >> 2), lp = isk ? (tid & 7) : (tid & 3);
;     auto gload = [&](int i) -> u32x4 {
;         const int tok0 = (i < nwin) ? (Q0 - 128 + 32 * (cw0 + i)) : (TLAT + 32 * (i - nwin));
;         if (isk) { const size_t row = (i < nwin) ? (size_t)b * TLAT + tok0 + lr : (size_t)MLAT + b * TCTX + 32 * (i - nwin) + lr;
;             return *(const u32x4*)(K + row * 256 + g4 * 64 + lp * 8); }
;         return *(const u32x4*)(VT + ((size_t)b * 256 + g4 * 64 + lr) * TT + tok0 + lp * 8);
;     };
;     auto lwrite = [&](int stage, const u32x4& v) {
;         unsigned char* sb = sm + stage * SW_STAGE;
;         if (isk) *(u32x4*)(sb + lr * 144 + lp * 16) = v; else *(u32x4*)(sb + SW_KB + lr * 80 + lp * 16) = v;
;     };
;     u32x4 R = gload(0);
;     lwrite(0, R);
;     if (nch > 1) R = gload(1);
; __global__ void __launch_bounds__(NTHREADS) mega_fwd(P p) {
;     ...
;                     const int vcu = (G % 8 == 0) ? ((int)blockIdx.x % 8) * (G / 8) + (int)blockIdx.x / 8 : (int)blockIdx.x;
;                     if (RUN(11)) REP(11) for (int t = vcu; t < 512; t += G) { swa_block_task(q, t, lds, tidl); __syncthreads(); }
.LBB0_265:
	s_or_b64 exec, exec, s[2:3]
	v_readlane_b32 s2, v254, 0
	v_mov_b32_e32 v0, v1
	v_readlane_b32 s3, v254, 1
	s_waitcnt lgkmcnt(0)
	s_barrier
	s_andn2_b64 vcc, exec, s[2:3]
	v_readfirstlane_b32 s2, v0
	s_cbranch_vccnz .LBB0_292
	s_load_dwordx2 s[10:11], s[92:93], s2 offset:0xa8
	s_nop 0
	s_load_dwordx2 s[2:3], s[92:93], s2 offset:0x90
	v_bfe_u32 v4, v146, 4, 2
	v_ashrrev_i32_e32 v0, 2, v146
	s_movk_i32 s8, 0x100
	s_waitcnt lgkmcnt(0)
	s_add_u32 s12, s10, 0xa800000
	v_and_b32_e32 v145, -16, v0
	v_lshlrev_b32_e32 v152, 4, v4
	v_mov_b32_e32 v153, v1
	v_add_u32_e32 v0, 0xffffff00, v146
	v_cmp_gt_i32_e64 s[8:9], s8, v146
	s_addc_u32 s13, s11, 0
	v_lshl_add_u64 v[2:3], s[10:11], 0, v[152:153]
	s_mov_b64 s[6:7], 0x7f00000
	v_lshrrev_b32_e32 v147, 2, v0
	v_cndmask_b32_e64 v0, 3, 7, s[8:9]
	v_lshlrev_b32_e32 v150, 3, v4
	v_mov_b32_e32 v151, v1
	v_lshl_add_u64 v[154:155], v[2:3], 0, s[6:7]
	s_add_u32 s14, s10, 0x9f00000
	v_and_b32_e32 v2, v0, v146
	v_and_b32_e32 v143, 15, v146
	v_cmp_eq_u32_e32 vcc, 0, v4
	s_addc_u32 s15, s11, 0
	v_lshlrev_b32_e32 v0, 3, v2
	v_lshlrev_b32_e32 v172, 4, v2
	v_lshlrev_b32_e32 v4, 2, v4
	v_lshl_add_u64 v[2:3], s[10:11], 0, v[150:151]
	s_mov_b64 s[10:11], 0x5b00000
	v_cndmask_b32_e64 v148, 0, 1.0, vcc
	s_movk_i32 s1, 0xff
	v_ashrrev_i32_e32 v156, 3, v146
	v_lshl_add_u64 v[158:159], v[2:3], 0, s[10:11]
	v_sub_u32_e32 v2, v4, v143
	v_cmp_lt_i32_e64 s[6:7], s1, v146
	v_cndmask_b32_e64 v153, v147, v156, s[8:9]
	v_ashrrev_i32_e32 v157, 31, v156
	v_mul_u32_u24_e32 v173, 0x90, v143
	v_mul_u32_u24_e32 v174, 0x50, v143
	v_mov_b32_e32 v149, v148
	v_sub_u32_e32 v151, v2, v145
	v_lshlrev_b32_e32 v0, 1, v0
	v_readlane_b32 s22, v254, 17
	v_readlane_b32 s23, v254, 20
	s_branch .LBB0_268
	s_nop 0
	s_nop 0
	s_nop 0
	s_nop 0
	s_nop 0
	s_nop 0
	s_nop 0
	s_nop 0
	s_nop 0
	s_nop 0
	s_nop 0
	s_nop 0
	s_nop 0
; __device__ __forceinline__ unsigned pk2(float lo, float hi) { unsigned r; asm("v_cvt_pk_bf16_f32 %0, %1, %2" : "=v"(r) : "v"(lo), "v"(hi)); return r; }
; __device__ __forceinline__ void attn_finish(AttnState& st, bf16_t* yrow  , int g) {
;     float l = st.l; l += __shfl_xor(l, 16); l += __shfl_xor(l, 32);
;     const float inv = 1.0f / l;
; #pragma unroll
;     for (int dt = 0; dt < 4; ++dt) { const f32x4 o = st.o[dt] * inv; u32x2 w; w.x = pk2(o[0], o[1]); w.y = pk2(o[2], o[3]); *(u32x2*)(yrow + dt * 16 + 4 * g) = w; }
; }
.LBB0_267:
	v_cmp_lt_i32_e32 vcc, v188, v186
	s_lshl_b32 s64, s27, 1
	s_add_i32 s23, s23, s38
	v_cndmask_b32_e32 v26, v185, v188, vcc
	v_lshlrev_b32_e32 v34, 2, v26
	ds_bpermute_b32 v26, v34, v164
	v_cmp_lt_i32_e32 vcc, v187, v186
	s_waitcnt lgkmcnt(0)
	v_add_f32_e32 v28, v164, v26
	v_cndmask_b32_e32 v27, v185, v187, vcc
	v_lshlrev_b32_e32 v35, 2, v27
	ds_bpermute_b32 v29, v35, v28
	v_lshl_add_u64 v[26:27], v[158:159], 0, v[162:163]
	v_lshl_add_u64 v[26:27], v[26:27], 0, s[64:65]
	s_waitcnt lgkmcnt(0)
	v_add_f32_e32 v28, v28, v29
	v_div_scale_f32 v29, s[10:11], v28, v28, 1.0
	v_rcp_f32_e32 v30, v29
	v_div_scale_f32 v31, vcc, 1.0, v28, 1.0
	v_fma_f32 v32, -v29, v30, 1.0
	v_fmac_f32_e32 v30, v32, v30
	v_mul_f32_e32 v32, v31, v30
	v_fma_f32 v33, -v29, v32, v31
	v_fmac_f32_e32 v32, v33, v30
	v_fma_f32 v29, -v29, v32, v31
	v_div_fmas_f32 v29, v29, v30, v32
	v_div_fixup_f32 v28, v29, v28, 1.0
	v_pk_mul_f32 v[32:33], v[98:99], v[28:29] op_sel_hi:[1,0]
	v_pk_mul_f32 v[30:31], v[100:101], v[28:29] op_sel_hi:[1,0]
	v_cvt_pk_bf16_f32 v32, v32, v33
	s_nop 0
	v_cvt_pk_bf16_f32 v33, v30, v31
	global_store_dwordx2 v[26:27], v[32:33], off
	v_pk_mul_f32 v[30:31], v[96:97], v[28:29] op_sel_hi:[1,0]
	v_pk_mul_f32 v[32:33], v[94:95], v[28:29] op_sel_hi:[1,0]
	ds_bpermute_b32 v29, v34, v165
	v_cvt_pk_bf16_f32 v32, v32, v33
	v_cvt_pk_bf16_f32 v33, v30, v31
	global_store_dwordx2 v[26:27], v[32:33], off offset:32
	s_waitcnt lgkmcnt(0)
	v_add_f32_e32 v36, v165, v29
	ds_bpermute_b32 v37, v35, v36
	v_pk_mul_f32 v[32:33], v[86:87], v[28:29] op_sel_hi:[1,0]
	v_pk_mul_f32 v[30:31], v[88:89], v[28:29] op_sel_hi:[1,0]
	v_cvt_pk_bf16_f32 v32, v32, v33
	s_nop 0
	v_cvt_pk_bf16_f32 v33, v30, v31
	global_store_dwordx2 v[26:27], v[32:33], off offset:64
	s_waitcnt lgkmcnt(0)
	v_add_f32_e32 v32, v36, v37
	v_div_scale_f32 v33, s[10:11], v32, v32, 1.0
	v_rcp_f32_e32 v36, v33
	v_pk_mul_f32 v[30:31], v[84:85], v[28:29] op_sel_hi:[1,0]
	v_pk_mul_f32 v[28:29], v[82:83], v[28:29] op_sel_hi:[1,0]
	s_nop 0
	v_cvt_pk_bf16_f32 v28, v28, v29
	v_cvt_pk_bf16_f32 v29, v30, v31
	global_store_dwordx2 v[26:27], v[28:29], off offset:96
	v_fma_f32 v28, -v33, v36, 1.0
	v_fmac_f32_e32 v36, v28, v36
	v_div_scale_f32 v28, vcc, 1.0, v32, 1.0
	v_mul_f32_e32 v29, v28, v36
	v_fma_f32 v30, -v33, v29, v28
	v_fmac_f32_e32 v29, v30, v36
	v_fma_f32 v28, -v33, v29, v28
	v_div_fmas_f32 v28, v28, v36, v29
	v_div_fixup_f32 v28, v28, v32, 1.0
	v_pk_mul_f32 v[32:33], v[78:79], v[28:29] op_sel_hi:[1,0]
	v_pk_mul_f32 v[30:31], v[80:81], v[28:29] op_sel_hi:[1,0]
	v_cvt_pk_bf16_f32 v32, v32, v33
	s_nop 0
	v_cvt_pk_bf16_f32 v33, v30, v31
	global_store_dwordx2 v[26:27], v[32:33], off offset:128
	v_pk_mul_f32 v[30:31], v[76:77], v[28:29] op_sel_hi:[1,0]
	v_pk_mul_f32 v[32:33], v[74:75], v[28:29] op_sel_hi:[1,0]
	ds_bpermute_b32 v29, v34, v160
	v_cvt_pk_bf16_f32 v32, v32, v33
	v_cvt_pk_bf16_f32 v33, v30, v31
	global_store_dwordx2 v[26:27], v[32:33], off offset:160
	s_waitcnt lgkmcnt(0)
	v_add_f32_e32 v36, v160, v29
	ds_bpermute_b32 v37, v35, v36
	v_pk_mul_f32 v[32:33], v[70:71], v[28:29] op_sel_hi:[1,0]
	v_pk_mul_f32 v[30:31], v[72:73], v[28:29] op_sel_hi:[1,0]
	v_cvt_pk_bf16_f32 v32, v32, v33
	s_nop 0
	v_cvt_pk_bf16_f32 v33, v30, v31
	global_store_dwordx2 v[26:27], v[32:33], off offset:192
	s_waitcnt lgkmcnt(0)
	v_add_f32_e32 v32, v36, v37
	v_div_scale_f32 v33, s[10:11], v32, v32, 1.0
	v_rcp_f32_e32 v36, v33
	v_pk_mul_f32 v[30:31], v[68:69], v[28:29] op_sel_hi:[1,0]
	v_pk_mul_f32 v[28:29], v[66:67], v[28:29] op_sel_hi:[1,0]
	s_nop 0
	v_cvt_pk_bf16_f32 v28, v28, v29
	v_cvt_pk_bf16_f32 v29, v30, v31
	global_store_dwordx2 v[26:27], v[28:29], off offset:224
	v_fma_f32 v28, -v33, v36, 1.0
	v_fmac_f32_e32 v36, v28, v36
	v_div_scale_f32 v28, vcc, 1.0, v32, 1.0
	v_mul_f32_e32 v29, v28, v36
	v_fma_f32 v30, -v33, v29, v28
	v_fmac_f32_e32 v29, v30, v36
	v_fma_f32 v28, -v33, v29, v28
	v_div_fmas_f32 v28, v28, v36, v29
	v_div_fixup_f32 v28, v28, v32, 1.0
	v_pk_mul_f32 v[32:33], v[62:63], v[28:29] op_sel_hi:[1,0]
	v_pk_mul_f32 v[30:31], v[64:65], v[28:29] op_sel_hi:[1,0]
	v_cvt_pk_bf16_f32 v32, v32, v33
	s_nop 0
	v_cvt_pk_bf16_f32 v33, v30, v31
	global_store_dwordx2 v[26:27], v[32:33], off offset:256
	v_pk_mul_f32 v[30:31], v[60:61], v[28:29] op_sel_hi:[1,0]
	v_pk_mul_f32 v[32:33], v[58:59], v[28:29] op_sel_hi:[1,0]
	ds_bpermute_b32 v29, v34, v161
	v_cvt_pk_bf16_f32 v32, v32, v33
	v_cvt_pk_bf16_f32 v33, v30, v31
	global_store_dwordx2 v[26:27], v[32:33], off offset:288
	s_waitcnt lgkmcnt(0)
	v_pk_mul_f32 v[24:25], v[24:25], v[28:29] op_sel_hi:[1,0]
	v_pk_mul_f32 v[22:23], v[22:23], v[28:29] op_sel_hi:[1,0]
	v_add_f32_e32 v29, v161, v29
	ds_bpermute_b32 v30, v35, v29
	v_cvt_pk_bf16_f32 v22, v22, v23
	v_cvt_pk_bf16_f32 v23, v24, v25
	global_store_dwordx2 v[26:27], v[22:23], off offset:320
	v_pk_mul_f32 v[18:19], v[18:19], v[28:29] op_sel_hi:[1,0]
	s_waitcnt lgkmcnt(0)
	v_add_f32_e32 v22, v29, v30
	v_div_scale_f32 v23, s[10:11], v22, v22, 1.0
	v_rcp_f32_e32 v24, v23
	v_cvt_pk_bf16_f32 v18, v18, v19
	v_pk_mul_f32 v[20:21], v[20:21], v[28:29] op_sel_hi:[1,0]
	v_readlane_b32 s10, v253, 60
	v_cvt_pk_bf16_f32 v19, v20, v21
	global_store_dwordx2 v[26:27], v[18:19], off offset:352
	v_fma_f32 v18, -v23, v24, 1.0
	v_fmac_f32_e32 v24, v18, v24
	v_div_scale_f32 v18, vcc, 1.0, v22, 1.0
	v_mul_f32_e32 v19, v18, v24
	v_fma_f32 v20, -v23, v19, v18
	v_fmac_f32_e32 v19, v20, v24
	v_fma_f32 v18, -v23, v19, v18
	v_div_fmas_f32 v18, v18, v24, v19
	v_div_fixup_f32 v18, v18, v22, 1.0
	s_add_i32 s22, s22, s10
	v_pk_mul_f32 v[14:15], v[14:15], v[18:19] op_sel_hi:[1,0]
	v_pk_mul_f32 v[10:11], v[10:11], v[18:19] op_sel_hi:[1,0]
	v_pk_mul_f32 v[6:7], v[6:7], v[18:19] op_sel_hi:[1,0]
	v_pk_mul_f32 v[2:3], v[2:3], v[18:19] op_sel_hi:[1,0]
	s_cmpk_lt_i32 s23, 0x200
	v_pk_mul_f32 v[16:17], v[16:17], v[18:19] op_sel_hi:[1,0]
	v_cvt_pk_bf16_f32 v14, v14, v15
	v_pk_mul_f32 v[12:13], v[12:13], v[18:19] op_sel_hi:[1,0]
	v_cvt_pk_bf16_f32 v15, v16, v17
	global_store_dwordx2 v[26:27], v[14:15], off offset:384
	v_cvt_pk_bf16_f32 v10, v10, v11
	v_cvt_pk_bf16_f32 v11, v12, v13
	global_store_dwordx2 v[26:27], v[10:11], off offset:416
	v_pk_mul_f32 v[8:9], v[8:9], v[18:19] op_sel_hi:[1,0]
	v_cvt_pk_bf16_f32 v6, v6, v7
	v_pk_mul_f32 v[4:5], v[4:5], v[18:19] op_sel_hi:[1,0]
	v_cvt_pk_bf16_f32 v7, v8, v9
	global_store_dwordx2 v[26:27], v[6:7], off offset:448
	v_cvt_pk_bf16_f32 v2, v2, v3
	v_cvt_pk_bf16_f32 v3, v4, v5
	global_store_dwordx2 v[26:27], v[2:3], off offset:480
	s_barrier
	s_cbranch_scc0 .LBB0_292

; #define PG8_STAGE(bufoff, gbase, voff) do { _Pragma("unroll") for (int _i = 0; _i < 2; ++_i) \
;         __builtin_amdgcn_global_load_lds((const unsigned*)((const char*)(gbase) + (voff)[_i]), (PG8_LAS unsigned*)(lds + (bufoff) + ldsw + _i * 8192), 16, 0, 0); } while (0)
; #define PG8_BAR __builtin_amdgcn_s_barrier()
;     __host__ __device__ bool next(int i, Unit& u) const {
;         const long L = (long)i * G + c; if (L >= nwg) return false;
;         int wgid = (int)L; { const int q = nwg / NXCD, r = nwg % NXCD, xcd = wgid % NXCD, off = wgid / NXCD; wgid = (xcd < r ? xcd * (q + 1) : r * (q + 1) + (xcd - r) * q) + off; }
;         const int nig = WGM * nN, gid = wgid / nig, fm = gid * WGM, gsz = (nM - fm) < WGM ? (nM - fm) : WGM;
;         u.pm = fm + ((wgid % nig) % gsz); u.pn = (wgid % nig) / gsz; return true;
; template <class Epi, class Sched, bool ALIGN_EPI = false, bool SP2 = false>
; __device__ __forceinline__ void gemm_phase(PG8_LAS unsigned char* lds, const Gemm g, const Sched& S, const Epi& E) {
;     ...
;     for (int i = 0; i < 2; ++i) { int R, C; stage_rc(tid * 16 + i * 8192, R, C); const int Rb = Epi::PERM ? ((R & ~31) + perm32(R & 31)) : R;
;         voffA[i] = (unsigned)(R * K + C) * 2u; voffB[i] = (unsigned)(Rb * K + C) * 2u; }
;     const size_t kstep = (size_t)(BK * 2);
;     const size_t hstep = (size_t)HALF * K * 2;
;     const size_t tstep = 2 * hstep;
;     const unsigned ldsw = (unsigned)wid * 1024u;
;     const int aoff = lds_byte(wr * 64 + fr, fq * 8), boff = lds_byte(wc * 32 + fr, fq * 8);
;     ...
;     Unit cur, nxt; int ui = 0;
;     if (!S.next(0, cur)) return;
;     f32x4 acc[2][2][4][2];
; #pragma unroll
;     for (int a = 0; a < 2; ++a)
; #pragma unroll
;         for (int b = 0; b < 2; ++b)
; #pragma unroll
;             for (int m = 0; m < 4; ++m)
; #pragma unroll
;                 for (int n = 0; n < 2; ++n) acc[a][b][m][n] = (f32x4){0.f, 0.f, 0.f, 0.f};
;     bf16x8 At[4][2], B0[2][2], B1[2][2];
;     const char* cA = (const char*)g.A + (size_t)cur.pm * tstep; const char* cB = (const char*)g.Bt + (size_t)cur.pn * tstep;
;     S.a_ready(cur);
;     if constexpr (SP2) {
;         PG8_STAGE(PG8_SB(0, 0), cB, voffB); PG8_STAGE(PG8_SB(0, 1), cB + hstep, voffB); PG8_STAGE(PG8_SA(0, 0), cA, voffA); PG8_STAGE(PG8_SA(0, 1), cA + hstep, voffA);
;         if (wr == 1) PG8_BAR;
.LBB0_293:
	s_and_b64 vcc, exec, s[2:3]
	s_cbranch_vccz .LBB0_327
	v_readlane_b32 s8, v253, 56
	v_mov_b32_e32 v0, v1
	v_mov_b32_e32 v11, v184
	v_readlane_b32 s9, v253, 57
	s_and_b64 vcc, exec, s[8:9]
	v_readfirstlane_b32 s2, v0
	v_readfirstlane_b32 s6, v11
	s_cbranch_vccz .LBB0_329
	v_lshlrev_b32_e32 v0, 4, v11
	v_add_u32_e32 v2, 0x2000, v0
	v_ashrrev_i32_e32 v3, 31, v2
	v_lshrrev_b32_e32 v3, 22, v3
	v_add_u32_e32 v3, v2, v3
	v_ashrrev_i32_e32 v10, 10, v3
	v_mul_i32_i24_e32 v4, 0x400, v10
	v_sub_u32_e32 v2, v2, v4
	v_lshrrev_b32_e32 v4, 4, v2
	v_bitop3_b32 v2, v4, v2, 32 bitop3:0x6c
	v_ashrrev_i32_e32 v4, 31, v2
	v_lshrrev_b32_e32 v4, 26, v4
	v_add_u32_e32 v4, v2, v4
	v_ashrrev_i32_e32 v12, 6, v4
	v_and_b32_e32 v4, 0xc0, v4
	v_sub_u32_e32 v2, v2, v4
	v_lshlrev_b32_e32 v3, 5, v10
	v_ashrrev_i16_sdwa v2, v196, sext(v2) dst_sel:DWORD dst_unused:UNUSED_PAD src0_sel:DWORD src1_sel:BYTE_0
	v_and_b32_e32 v3, 32, v3
	v_bfe_i32 v13, v2, 0, 16
	v_add_u32_e32 v2, v3, v13
	v_lshlrev_b32_e32 v3, 3, v10
	v_and_b32_e32 v3, 0x1ffff0, v3
	v_add_lshl_u32 v3, v12, v3, 11
	v_lshl_add_u32 v130, v2, 1, v3
	v_bfe_i32 v3, v11, 27, 1
	v_lshrrev_b32_e32 v3, 22, v3
	v_add_u32_e32 v3, v0, v3
	v_and_b32_e32 v3, 0xfffffc00, v3
	v_sub_u32_e32 v0, v0, v3
	s_load_dwordx2 s[2:3], s[92:93], s2 offset:0xa8
	v_lshrrev_b32_e32 v3, 4, v0
	v_bitop3_b32 v0, v3, v0, 32 bitop3:0x6c
	v_ashrrev_i32_e32 v3, 31, v0
	v_ashrrev_i32_e32 v2, 31, v11
	v_lshrrev_b32_e32 v3, 26, v3
	v_lshrrev_b32_e32 v2, 26, v2
	v_add_u32_e32 v3, v0, v3
	s_waitcnt lgkmcnt(0)
	s_add_u32 s34, s2, 0x5b00000
	v_add_u32_e32 v2, v11, v2
	v_ashrrev_i32_e32 v15, 6, v3
	v_and_b32_e32 v3, 0xc0, v3
	s_addc_u32 s35, s3, 0
	v_ashrrev_i32_e32 v14, 6, v2
	v_sub_u32_e32 v0, v0, v3
	s_add_u32 s40, s2, 0x4400000
	v_lshlrev_b32_e32 v2, 5, v14
	v_ashrrev_i16_sdwa v0, v196, sext(v0) dst_sel:DWORD dst_unused:UNUSED_PAD src0_sel:DWORD src1_sel:BYTE_0
	s_addc_u32 s41, s3, 0
	s_ashr_i32 s12, s6, 6
	v_and_b32_e32 v2, 32, v2
	v_bfe_i32 v16, v0, 0, 16
	s_ashr_i32 s7, s6, 8
	s_lshl_b32 s42, s12, 10
	v_add_u32_e32 v0, v2, v16
	v_lshlrev_b32_e32 v2, 3, v14
	v_readlane_b32 s8, v254, 11
	v_and_b32_e32 v2, 0x1ffff0, v2
	v_readlane_b32 s9, v254, 12
	s_add_u32 s28, s40, s8
	v_add_lshl_u32 v2, v15, v2, 11
	s_addc_u32 s29, s41, s9
	s_add_i32 s43, s42, 0
	v_lshl_add_u32 v132, v0, 1, v2
	s_add_i32 m0, s43, 0x10000
	v_mov_b32_e32 v133, v1
	global_load_lds_dwordx4 v132, s[28:29]
	s_add_i32 m0, s43, 0x12000
	s_add_u32 s8, s28, 0x40000
	global_load_lds_dwordx4 v130, s[28:29]
	s_addc_u32 s9, s29, 0
	s_add_i32 m0, s43, 0x14000
	v_mov_b32_e32 v131, v1
	global_load_lds_dwordx4 v132, s[8:9]
	s_add_i32 m0, s43, 0x16000
	v_lshl_add_u64 v[8:9], s[28:29], 0, v[132:133]
	global_load_lds_dwordx4 v130, s[8:9]
	v_readlane_b32 s8, v254, 9
	v_readlane_b32 s9, v254, 10
	s_add_u32 s26, s34, s8
	s_addc_u32 s27, s35, s9
	s_add_i32 s44, s43, 0x2000
	s_mov_b32 m0, s43
	s_add_u32 s8, s26, 0x40000
	global_load_lds_dwordx4 v132, s[26:27]
	s_mov_b32 m0, s44
	s_addc_u32 s9, s27, 0
	s_add_i32 s45, s43, 0x4000
	global_load_lds_dwordx4 v130, s[26:27]
	s_mov_b32 m0, s45
	s_add_i32 s46, s43, 0x6000
	global_load_lds_dwordx4 v132, s[8:9]
	s_mov_b32 m0, s46
	s_cmp_eq_u32 s7, 1
	global_load_lds_dwordx4 v130, s[8:9]
	v_lshl_add_u64 v[6:7], s[28:29], 0, v[130:131]
	v_lshl_add_u64 v[2:3], s[26:27], 0, v[132:133]
	s_cselect_b64 s[8:9], -1, 0
	s_cmp_lg_u32 s7, 1
	v_lshl_add_u64 v[4:5], s[26:27], 0, v[130:131]
	s_cbranch_scc1 .LBB0_297
	s_barrier
	s_setprio 1

; #define PG8_STAGE(bufoff, gbase, voff) do { _Pragma("unroll") for (int _i = 0; _i < 2; ++_i) \
;         __builtin_amdgcn_global_load_lds((const unsigned*)((const char*)(gbase) + (voff)[_i]), (PG8_LAS unsigned*)(lds + (bufoff) + ldsw + _i * 8192), 16, 0, 0); } while (0)
; #define PG8_LDA(dst, b, h) do { _Pragma("unroll") for (int m = 0; m < 4; ++m) _Pragma("unroll") for (int k = 0; k < 2; ++k) dst[m][k] = *(const PG8_LAS bf16x8*)(lds + PG8_SA(b, h) + aoff + m * 2048 + k * 1024); } while (0)
; #define PG8_LDB(dst, b, h) do { _Pragma("unroll") for (int n = 0; n < 2; ++n) _Pragma("unroll") for (int k = 0; k < 2; ++k) dst[n][k] = *(const PG8_LAS bf16x8*)(lds + PG8_SB(b, h) + boff + n * 2048 + k * 1024); } while (0)
; #define PG8_WAIT_V(n) asm volatile("s_waitcnt vmcnt(" #n ")" ::: "memory")
; #define PG8_WAIT_L(n) asm volatile("s_waitcnt lgkmcnt(" #n ")" ::: "memory")
; #define PG8_BAR __builtin_amdgcn_s_barrier()
; #define PG8_SCHED __builtin_amdgcn_sched_barrier(0)
; template <class Epi, class Sched, bool ALIGN_EPI = false, bool SP2 = false>
; __device__ __forceinline__ void gemm_phase(PG8_LAS unsigned char* lds, const Gemm g, const Sched& S, const Epi& E) {
;     ...
;         const bool has_next = S.next(ui + 1, nxt);
;         const char* nA = has_next ? (const char*)g.A + (size_t)nxt.pm * tstep : cA; const char* nB = has_next ? (const char*)g.Bt + (size_t)nxt.pn * tstep : cB;
;         for (int t = 0; t < nt; t += 2) {
;             const bool last = (t == nt - 2);
;             const char* a1 = cA + (size_t)(t + 1) * kstep;
;             const char* a2 = last ? nA : cA + (size_t)(t + 2) * kstep; const char* b2 = last ? nB : cB + (size_t)(t + 2) * kstep;
;             const char* a3 = a2 + kstep; const char* b3 = b2 + kstep;
;             if (last && has_next) S.a_ready(nxt);
;             if constexpr (SP2) {
;             PG8_LDB(B0, 0, 0); PG8_LDB(B1, 0, 1); PG8_SCHED; PG8_LDA(At, 0, 0); PG8_STAGE(PG8_SA(1, 1), a1 + hstep, voffA);
;             PG8_WAIT_V(8); PG8_WAIT_L(0); PG8_BAR; PG8_MMA(0, 0, At, B0); PG8_MMA(0, 1, At, B1); PG8_BAR; PG8_SCHED;
;             PG8_LDA(At, 0, 1); PG8_STAGE(PG8_SB(0, 0), b2, voffB); PG8_STAGE(PG8_SB(0, 1), b2 + hstep, voffB); PG8_STAGE(PG8_SA(0, 0), a2, voffA);
;             PG8_WAIT_V(8); PG8_WAIT_L(0); PG8_BAR; PG8_MMA(1, 0, At, B0); PG8_MMA(1, 1, At, B1); PG8_BAR; PG8_SCHED;
.LBB0_302:
	s_ashr_i32 s21, s20, 31
	s_lshl_b64 s[22:23], s[20:21], 19
	s_add_u32 s22, s34, s22
	s_addc_u32 s23, s35, s23
	s_and_b64 s[24:25], s[6:7], exec
	s_cselect_b32 s17, s23, s27
	s_cselect_b32 s21, s22, s26
	s_ashr_i32 s19, s18, 31
	s_lshl_b64 s[24:25], s[18:19], 19
	s_add_u32 s24, s40, s24
	s_addc_u32 s25, s41, s25
	s_and_b64 s[30:31], s[6:7], exec
	s_cselect_b32 s19, s25, s29
	s_cselect_b32 s54, s24, s28
	s_add_u32 s26, s26, 0x40080
	s_addc_u32 s27, s27, 0
	s_add_u32 s64, s28, 0x100
	v_mov_b32_e32 v2, 0
	s_addc_u32 s71, s29, 0
	s_mov_b32 s73, -2
	s_add_u32 s28, s26, 0xfffc0080
	s_addc_u32 s29, s27, -1
	s_add_i32 s74, 0, 0x10000
	s_cmp_eq_u32 s73, 12
	s_cselect_b32 s31, s17, s29
	s_cselect_b32 s30, s21, s28
	v_add_u32_e32 v145, s74, v137
	s_cselect_b32 s29, s19, s71
	s_cselect_b32 s28, s54, s64
	s_add_i32 s76, 0, 0x14000
	ds_read_b128 v[152:155], v145
	ds_read_b128 v[156:159], v145 offset:1024
	ds_read_b128 v[160:163], v145 offset:2048
	ds_read_b128 v[164:167], v145 offset:3072
	v_add_u32_e32 v145, s76, v137
	ds_read_b128 v[168:171], v145
	ds_read_b128 v[172:175], v145 offset:1024
	ds_read_b128 v[176:179], v145 offset:2048
	ds_read_b128 v[180:183], v145 offset:3072
	v_lshl_add_u64 v[202:203], s[26:27], 0, v[148:149]
	s_add_i32 m0, s43, 0xc000
	ds_read_b128 v[208:211], v143
	ds_read_b128 v[212:215], v143 offset:1024
	ds_read_b128 v[216:219], v143 offset:2048
	ds_read_b128 v[220:223], v143 offset:3072
	ds_read_b128 v[224:227], v143 offset:4096
	ds_read_b128 v[228:231], v143 offset:5120
	ds_read_b128 v[232:235], v143 offset:6144
	ds_read_b128 v[236:239], v143 offset:7168
	global_load_lds_dwordx4 v[202:203], off
	v_lshl_add_u64 v[202:203], s[26:27], 0, v[150:151]
	s_add_i32 m0, s43, 0xe000
	s_nop 0
	global_load_lds_dwordx4 v[202:203], off
	s_waitcnt vmcnt(8)
	s_waitcnt lgkmcnt(0)
	s_barrier
	s_waitcnt lgkmcnt(0)
	v_mfma_f32_16x16x32_bf16 v[126:129], v[152:155], v[208:211], 0
	v_mfma_f32_16x16x32_bf16 v[122:125], v[160:163], v[208:211], 0
	v_mfma_f32_16x16x32_bf16 v[114:117], v[152:155], v[216:219], 0
	v_mfma_f32_16x16x32_bf16 v[106:109], v[160:163], v[216:219], 0
	v_mfma_f32_16x16x32_bf16 v[98:101], v[152:155], v[224:227], 0
	v_mfma_f32_16x16x32_bf16 v[90:93], v[160:163], v[224:227], 0
	v_mfma_f32_16x16x32_bf16 v[82:85], v[152:155], v[232:235], 0
	v_mfma_f32_16x16x32_bf16 v[74:77], v[160:163], v[232:235], 0
	v_mfma_f32_16x16x32_bf16 v[126:129], v[156:159], v[212:215], v[126:129]
	v_mfma_f32_16x16x32_bf16 v[122:125], v[164:167], v[212:215], v[122:125]
	v_mfma_f32_16x16x32_bf16 v[114:117], v[156:159], v[220:223], v[114:117]
	v_mfma_f32_16x16x32_bf16 v[106:109], v[164:167], v[220:223], v[106:109]
	v_mfma_f32_16x16x32_bf16 v[98:101], v[156:159], v[228:231], v[98:101]
	v_mfma_f32_16x16x32_bf16 v[90:93], v[164:167], v[228:231], v[90:93]
	v_mfma_f32_16x16x32_bf16 v[82:85], v[156:159], v[236:239], v[82:85]
	v_mfma_f32_16x16x32_bf16 v[74:77], v[164:167], v[236:239], v[74:77]
	v_mfma_f32_16x16x32_bf16 v[118:121], v[168:171], v[208:211], 0
	v_mfma_f32_16x16x32_bf16 v[110:113], v[176:179], v[208:211], 0
	v_mfma_f32_16x16x32_bf16 v[102:105], v[168:171], v[216:219], 0
	v_mfma_f32_16x16x32_bf16 v[94:97], v[176:179], v[216:219], 0
	v_mfma_f32_16x16x32_bf16 v[86:89], v[168:171], v[224:227], 0
	v_mfma_f32_16x16x32_bf16 v[78:81], v[176:179], v[224:227], 0
	v_mfma_f32_16x16x32_bf16 v[70:73], v[168:171], v[232:235], 0
	v_mfma_f32_16x16x32_bf16 v[66:69], v[176:179], v[232:235], 0
	v_mfma_f32_16x16x32_bf16 v[118:121], v[172:175], v[212:215], v[118:121]
	v_mfma_f32_16x16x32_bf16 v[110:113], v[180:183], v[212:215], v[110:113]
	v_mfma_f32_16x16x32_bf16 v[102:105], v[172:175], v[220:223], v[102:105]
	v_mfma_f32_16x16x32_bf16 v[94:97], v[180:183], v[220:223], v[94:97]
	v_mfma_f32_16x16x32_bf16 v[86:89], v[172:175], v[228:231], v[86:89]
	v_mfma_f32_16x16x32_bf16 v[78:81], v[180:183], v[228:231], v[78:81]
	v_mfma_f32_16x16x32_bf16 v[70:73], v[172:175], v[236:239], v[70:73]
	v_mfma_f32_16x16x32_bf16 v[66:69], v[180:183], v[236:239], v[66:69]
	s_barrier
	s_add_i32 s74, s74, s42
	v_lshl_add_u64 v[202:203], s[28:29], 0, v[132:133]
	s_mov_b32 m0, s74
	ds_read_b128 v[208:211], v143 offset:16384
	ds_read_b128 v[212:215], v143 offset:17408
	ds_read_b128 v[216:219], v143 offset:18432
	ds_read_b128 v[220:223], v143 offset:19456
	ds_read_b128 v[224:227], v143 offset:20480
	ds_read_b128 v[228:231], v143 offset:21504
	ds_read_b128 v[232:235], v143 offset:22528
	ds_read_b128 v[236:239], v143 offset:23552
	global_load_lds_dwordx4 v[202:203], off
	s_add_i32 m0, s74, 0x2000
	s_add_u32 s74, s28, 0x40000
	v_lshl_add_u64 v[204:205], s[28:29], 0, v[130:131]
	s_addc_u32 s75, s29, 0
	s_add_i32 s76, s76, s42
	global_load_lds_dwordx4 v[204:205], off
	v_lshl_add_u64 v[240:241], s[74:75], 0, v[132:133]
	s_mov_b32 m0, s76
	v_lshl_add_u64 v[242:243], s[30:31], 0, v[130:131]
	global_load_lds_dwordx4 v[240:241], off
	v_lshl_add_u64 v[240:241], s[74:75], 0, v[130:131]
	s_add_i32 m0, s76, 0x2000
	s_nop 0
	global_load_lds_dwordx4 v[240:241], off
	v_lshl_add_u64 v[240:241], s[30:31], 0, v[132:133]
	s_mov_b32 m0, s43
	s_nop 0
	global_load_lds_dwordx4 v[240:241], off
	s_mov_b32 m0, s44
	s_nop 0
	global_load_lds_dwordx4 v[242:243], off
	s_waitcnt vmcnt(8)
	s_waitcnt lgkmcnt(0)
	s_barrier
; #define PG8_STAGE(bufoff, gbase, voff) do { _Pragma("unroll") for (int _i = 0; _i < 2; ++_i) \
;         __builtin_amdgcn_global_load_lds((const unsigned*)((const char*)(gbase) + (voff)[_i]), (PG8_LAS unsigned*)(lds + (bufoff) + ldsw + _i * 8192), 16, 0, 0); } while (0)
; #define PG8_LDA(dst, b, h) do { _Pragma("unroll") for (int m = 0; m < 4; ++m) _Pragma("unroll") for (int k = 0; k < 2; ++k) dst[m][k] = *(const PG8_LAS bf16x8*)(lds + PG8_SA(b, h) + aoff + m * 2048 + k * 1024); } while (0)
; #define PG8_LDB(dst, b, h) do { _Pragma("unroll") for (int n = 0; n < 2; ++n) _Pragma("unroll") for (int k = 0; k < 2; ++k) dst[n][k] = *(const PG8_LAS bf16x8*)(lds + PG8_SB(b, h) + boff + n * 2048 + k * 1024); } while (0)
; #define PG8_MMA(ai, bj, At, Bt) do { __builtin_amdgcn_s_setprio(1); _Pragma("unroll") for (int m = 0; m < 4; ++m) _Pragma("unroll") for (int n = 0; n < 2; ++n) _Pragma("unroll") for (int k = 0; k < 2; ++k) \
;         acc[ai][bj][m][n] = __builtin_amdgcn_mfma_f32_16x16x32_bf16(Bt[n][k], At[m][k], acc[ai][bj][m][n], 0, 0, 0); __builtin_amdgcn_s_setprio(0); } while (0)
; #define PG8_WAIT_V(n) asm volatile("s_waitcnt vmcnt(" #n ")" ::: "memory")
; #define PG8_WAIT_L(n) asm volatile("s_waitcnt lgkmcnt(" #n ")" ::: "memory")
; #define PG8_BAR __builtin_amdgcn_s_barrier()
; #define PG8_SCHED __builtin_amdgcn_sched_barrier(0)
; template <class Epi, class Sched, bool ALIGN_EPI = false, bool SP2 = false>
; __device__ __forceinline__ void gemm_phase(PG8_LAS unsigned char* lds, const Gemm g, const Sched& S, const Epi& E) {
;     ...
;             PG8_WAIT_V(8); PG8_WAIT_L(0); PG8_BAR; PG8_MMA(1, 0, At, B0); PG8_MMA(1, 1, At, B1); PG8_BAR; PG8_SCHED;
;             PG8_LDB(B0, 1, 0); PG8_LDB(B1, 1, 1); PG8_SCHED; PG8_LDA(At, 1, 0); PG8_STAGE(PG8_SA(0, 1), a2 + hstep, voffA);
;             PG8_WAIT_V(8); PG8_WAIT_L(0); PG8_BAR; PG8_MMA(0, 0, At, B0); PG8_MMA(0, 1, At, B1); PG8_BAR; PG8_SCHED;
	s_waitcnt lgkmcnt(0)
	v_mfma_f32_16x16x32_bf16 v[62:65], v[152:155], v[208:211], 0
	v_mfma_f32_16x16x32_bf16 v[58:61], v[160:163], v[208:211], 0
	v_mfma_f32_16x16x32_bf16 v[50:53], v[152:155], v[216:219], 0
	v_mfma_f32_16x16x32_bf16 v[42:45], v[160:163], v[216:219], 0
	v_mfma_f32_16x16x32_bf16 v[34:37], v[152:155], v[224:227], 0
	v_mfma_f32_16x16x32_bf16 v[26:29], v[160:163], v[224:227], 0
	v_mfma_f32_16x16x32_bf16 v[18:21], v[152:155], v[232:235], 0
	v_mfma_f32_16x16x32_bf16 v[10:13], v[160:163], v[232:235], 0
	v_mfma_f32_16x16x32_bf16 v[62:65], v[156:159], v[212:215], v[62:65]
	v_mfma_f32_16x16x32_bf16 v[58:61], v[164:167], v[212:215], v[58:61]
	v_mfma_f32_16x16x32_bf16 v[50:53], v[156:159], v[220:223], v[50:53]
	v_mfma_f32_16x16x32_bf16 v[42:45], v[164:167], v[220:223], v[42:45]
	v_mfma_f32_16x16x32_bf16 v[34:37], v[156:159], v[228:231], v[34:37]
	v_mfma_f32_16x16x32_bf16 v[26:29], v[164:167], v[228:231], v[26:29]
	v_mfma_f32_16x16x32_bf16 v[18:21], v[156:159], v[236:239], v[18:21]
	v_mfma_f32_16x16x32_bf16 v[10:13], v[164:167], v[236:239], v[10:13]
	v_mfma_f32_16x16x32_bf16 v[54:57], v[168:171], v[208:211], 0
	v_mfma_f32_16x16x32_bf16 v[46:49], v[176:179], v[208:211], 0
	v_mfma_f32_16x16x32_bf16 v[38:41], v[168:171], v[216:219], 0
	v_mfma_f32_16x16x32_bf16 v[30:33], v[176:179], v[216:219], 0
	v_mfma_f32_16x16x32_bf16 v[22:25], v[168:171], v[224:227], 0
	v_mfma_f32_16x16x32_bf16 v[14:17], v[176:179], v[224:227], 0
	v_mfma_f32_16x16x32_bf16 v[6:9], v[168:171], v[232:235], 0
	v_mfma_f32_16x16x32_bf16 v[2:5], v[176:179], v[232:235], 0
	v_mfma_f32_16x16x32_bf16 v[54:57], v[172:175], v[212:215], v[54:57]
	v_mfma_f32_16x16x32_bf16 v[46:49], v[180:183], v[212:215], v[46:49]
	v_mfma_f32_16x16x32_bf16 v[38:41], v[172:175], v[220:223], v[38:41]
	v_mfma_f32_16x16x32_bf16 v[30:33], v[180:183], v[220:223], v[30:33]
	v_mfma_f32_16x16x32_bf16 v[22:25], v[172:175], v[228:231], v[22:25]
	v_mfma_f32_16x16x32_bf16 v[14:17], v[180:183], v[228:231], v[14:17]
	v_mfma_f32_16x16x32_bf16 v[6:9], v[172:175], v[236:239], v[6:9]
	v_mfma_f32_16x16x32_bf16 v[2:5], v[180:183], v[236:239], v[2:5]
	s_barrier
	s_add_i32 s74, 0, 0x18000
	v_add_u32_e32 v145, s74, v137
	s_add_i32 s75, 0, 0x1c000
	ds_read_b128 v[152:155], v145
	ds_read_b128 v[156:159], v145 offset:1024
	ds_read_b128 v[160:163], v145 offset:2048
	ds_read_b128 v[164:167], v145 offset:3072
	v_add_u32_e32 v145, s75, v137
	ds_read_b128 v[168:171], v145
	ds_read_b128 v[172:175], v145 offset:1024
	ds_read_b128 v[176:179], v145 offset:2048
	ds_read_b128 v[180:183], v145 offset:3072
	s_add_u32 s30, s30, 0x40000
	s_addc_u32 s31, s31, 0
	s_mov_b32 m0, s45
	v_lshl_add_u64 v[244:245], s[30:31], 0, v[132:133]
	ds_read_b128 v[208:211], v143 offset:32768
	ds_read_b128 v[212:215], v143 offset:33792
	ds_read_b128 v[216:219], v143 offset:34816
	ds_read_b128 v[220:223], v143 offset:35840
	ds_read_b128 v[224:227], v143 offset:36864
	ds_read_b128 v[228:231], v143 offset:37888
	ds_read_b128 v[232:235], v143 offset:38912
	ds_read_b128 v[236:239], v143 offset:39936
	global_load_lds_dwordx4 v[244:245], off
	v_lshl_add_u64 v[244:245], s[30:31], 0, v[130:131]
	s_mov_b32 m0, s46
	s_nop 0
	global_load_lds_dwordx4 v[244:245], off
	s_waitcnt vmcnt(8)
	s_waitcnt lgkmcnt(0)
	s_barrier
	s_waitcnt lgkmcnt(0)
	v_mfma_f32_16x16x32_bf16 v[126:129], v[152:155], v[208:211], v[126:129]
	v_mfma_f32_16x16x32_bf16 v[122:125], v[160:163], v[208:211], v[122:125]
	v_mfma_f32_16x16x32_bf16 v[114:117], v[152:155], v[216:219], v[114:117]
	v_mfma_f32_16x16x32_bf16 v[106:109], v[160:163], v[216:219], v[106:109]
	v_mfma_f32_16x16x32_bf16 v[98:101], v[152:155], v[224:227], v[98:101]
	v_mfma_f32_16x16x32_bf16 v[90:93], v[160:163], v[224:227], v[90:93]
	v_mfma_f32_16x16x32_bf16 v[82:85], v[152:155], v[232:235], v[82:85]
	v_mfma_f32_16x16x32_bf16 v[74:77], v[160:163], v[232:235], v[74:77]
	v_mfma_f32_16x16x32_bf16 v[126:129], v[156:159], v[212:215], v[126:129]
	v_mfma_f32_16x16x32_bf16 v[122:125], v[164:167], v[212:215], v[122:125]
	v_mfma_f32_16x16x32_bf16 v[114:117], v[156:159], v[220:223], v[114:117]
	v_mfma_f32_16x16x32_bf16 v[106:109], v[164:167], v[220:223], v[106:109]
	v_mfma_f32_16x16x32_bf16 v[98:101], v[156:159], v[228:231], v[98:101]
	v_mfma_f32_16x16x32_bf16 v[90:93], v[164:167], v[228:231], v[90:93]
	v_mfma_f32_16x16x32_bf16 v[82:85], v[156:159], v[236:239], v[82:85]
	v_mfma_f32_16x16x32_bf16 v[74:77], v[164:167], v[236:239], v[74:77]
	v_mfma_f32_16x16x32_bf16 v[118:121], v[168:171], v[208:211], v[118:121]
	v_mfma_f32_16x16x32_bf16 v[110:113], v[176:179], v[208:211], v[110:113]
	v_mfma_f32_16x16x32_bf16 v[102:105], v[168:171], v[216:219], v[102:105]
	v_mfma_f32_16x16x32_bf16 v[94:97], v[176:179], v[216:219], v[94:97]
	v_mfma_f32_16x16x32_bf16 v[86:89], v[168:171], v[224:227], v[86:89]
	v_mfma_f32_16x16x32_bf16 v[78:81], v[176:179], v[224:227], v[78:81]
	v_mfma_f32_16x16x32_bf16 v[70:73], v[168:171], v[232:235], v[70:73]
	v_mfma_f32_16x16x32_bf16 v[66:69], v[176:179], v[232:235], v[66:69]
	v_mfma_f32_16x16x32_bf16 v[118:121], v[172:175], v[212:215], v[118:121]
	v_mfma_f32_16x16x32_bf16 v[110:113], v[180:183], v[212:215], v[110:113]
	v_mfma_f32_16x16x32_bf16 v[102:105], v[172:175], v[220:223], v[102:105]
	v_mfma_f32_16x16x32_bf16 v[94:97], v[180:183], v[220:223], v[94:97]
	v_mfma_f32_16x16x32_bf16 v[86:89], v[172:175], v[228:231], v[86:89]
	v_mfma_f32_16x16x32_bf16 v[78:81], v[180:183], v[228:231], v[78:81]
	v_mfma_f32_16x16x32_bf16 v[70:73], v[172:175], v[236:239], v[70:73]
	v_mfma_f32_16x16x32_bf16 v[66:69], v[180:183], v[236:239], v[66:69]
	s_barrier
; #define PG8_STAGE(bufoff, gbase, voff) do { _Pragma("unroll") for (int _i = 0; _i < 2; ++_i) \
;         __builtin_amdgcn_global_load_lds((const unsigned*)((const char*)(gbase) + (voff)[_i]), (PG8_LAS unsigned*)(lds + (bufoff) + ldsw + _i * 8192), 16, 0, 0); } while (0)
; #define PG8_LDA(dst, b, h) do { _Pragma("unroll") for (int m = 0; m < 4; ++m) _Pragma("unroll") for (int k = 0; k < 2; ++k) dst[m][k] = *(const PG8_LAS bf16x8*)(lds + PG8_SA(b, h) + aoff + m * 2048 + k * 1024); } while (0)
; #define PG8_LDB(dst, b, h) do { _Pragma("unroll") for (int n = 0; n < 2; ++n) _Pragma("unroll") for (int k = 0; k < 2; ++k) dst[n][k] = *(const PG8_LAS bf16x8*)(lds + PG8_SB(b, h) + boff + n * 2048 + k * 1024); } while (0)
; #define PG8_MMA(ai, bj, At, Bt) do { __builtin_amdgcn_s_setprio(1); _Pragma("unroll") for (int m = 0; m < 4; ++m) _Pragma("unroll") for (int n = 0; n < 2; ++n) _Pragma("unroll") for (int k = 0; k < 2; ++k) \
;         acc[ai][bj][m][n] = __builtin_amdgcn_mfma_f32_16x16x32_bf16(Bt[n][k], At[m][k], acc[ai][bj][m][n], 0, 0, 0); __builtin_amdgcn_s_setprio(0); } while (0)
; #define PG8_WAIT_V(n) asm volatile("s_waitcnt vmcnt(" #n ")" ::: "memory")
; #define PG8_BAR __builtin_amdgcn_s_barrier()
; template <class Epi, class Sched, bool ALIGN_EPI = false, bool SP2 = false>
; __device__ __forceinline__ void gemm_phase(PG8_LAS unsigned char* lds, const Gemm g, const Sched& S, const Epi& E) {
;     ...
;         for (int t = 0; t < nt; t += 2) {
;             const bool last = (t == nt - 2);
;             const char* a1 = cA + (size_t)(t + 1) * kstep;
;             const char* a2 = last ? nA : cA + (size_t)(t + 2) * kstep; const char* b2 = last ? nB : cB + (size_t)(t + 2) * kstep;
;             const char* a3 = a2 + kstep; const char* b3 = b2 + kstep;
;             if (last && has_next) S.a_ready(nxt);
;             if constexpr (SP2) {
;             PG8_LDB(B0, 0, 0); PG8_LDB(B1, 0, 1); PG8_SCHED; PG8_LDA(At, 0, 0); PG8_STAGE(PG8_SA(1, 1), a1 + hstep, voffA);
;             PG8_WAIT_V(8); PG8_WAIT_L(0); PG8_BAR; PG8_MMA(0, 0, At, B0); PG8_MMA(0, 1, At, B1); PG8_BAR; PG8_SCHED;
;     ...
;             PG8_LDA(At, 1, 1); PG8_STAGE(PG8_SB(1, 0), b3, voffB); PG8_STAGE(PG8_SB(1, 1), b3 + hstep, voffB); PG8_STAGE(PG8_SA(1, 0), a3, voffA);
;             PG8_WAIT_V(8); PG8_WAIT_L(0); PG8_BAR; PG8_MMA(1, 0, At, B0); PG8_MMA(1, 1, At, B1); PG8_BAR; PG8_SCHED;
	s_add_i32 s30, s74, s42
	v_lshl_add_u64 v[202:203], v[202:203], 0, s[66:67]
	s_mov_b32 m0, s30
	ds_read_b128 v[208:211], v143 offset:49152
	ds_read_b128 v[212:215], v143 offset:50176
	ds_read_b128 v[216:219], v143 offset:51200
	ds_read_b128 v[220:223], v143 offset:52224
	ds_read_b128 v[224:227], v143 offset:53248
	ds_read_b128 v[228:231], v143 offset:54272
	ds_read_b128 v[232:235], v143 offset:55296
	ds_read_b128 v[236:239], v143 offset:56320
	global_load_lds_dwordx4 v[202:203], off
	s_add_i32 m0, s30, 0x2000
	s_add_u32 s28, s28, 0x40080
	v_lshl_add_u64 v[202:203], v[204:205], 0, s[66:67]
	s_addc_u32 s29, s29, 0
	s_add_i32 s30, s75, s42
	global_load_lds_dwordx4 v[202:203], off
	v_lshl_add_u64 v[202:203], s[28:29], 0, v[132:133]
	s_mov_b32 m0, s30
	s_nop 0
	global_load_lds_dwordx4 v[202:203], off
	v_lshl_add_u64 v[202:203], s[28:29], 0, v[130:131]
	s_add_i32 m0, s30, 0x2000
	s_nop 0
	global_load_lds_dwordx4 v[202:203], off
	v_lshl_add_u64 v[202:203], v[240:241], 0, s[66:67]
	s_mov_b32 m0, s49
	s_nop 0
	global_load_lds_dwordx4 v[202:203], off
	v_lshl_add_u64 v[202:203], v[242:243], 0, s[66:67]
	s_mov_b32 m0, s50
	s_nop 0
	global_load_lds_dwordx4 v[202:203], off
	s_waitcnt vmcnt(8)
	s_waitcnt lgkmcnt(0)
	s_barrier
	s_waitcnt lgkmcnt(0)
	v_mfma_f32_16x16x32_bf16 v[62:65], v[152:155], v[208:211], v[62:65]
	v_mfma_f32_16x16x32_bf16 v[58:61], v[160:163], v[208:211], v[58:61]
	v_mfma_f32_16x16x32_bf16 v[50:53], v[152:155], v[216:219], v[50:53]
	v_mfma_f32_16x16x32_bf16 v[42:45], v[160:163], v[216:219], v[42:45]
	v_mfma_f32_16x16x32_bf16 v[34:37], v[152:155], v[224:227], v[34:37]
	v_mfma_f32_16x16x32_bf16 v[26:29], v[160:163], v[224:227], v[26:29]
	v_mfma_f32_16x16x32_bf16 v[18:21], v[152:155], v[232:235], v[18:21]
	v_mfma_f32_16x16x32_bf16 v[10:13], v[160:163], v[232:235], v[10:13]
	v_mfma_f32_16x16x32_bf16 v[62:65], v[156:159], v[212:215], v[62:65]
	v_mfma_f32_16x16x32_bf16 v[58:61], v[164:167], v[212:215], v[58:61]
	v_mfma_f32_16x16x32_bf16 v[50:53], v[156:159], v[220:223], v[50:53]
	v_mfma_f32_16x16x32_bf16 v[42:45], v[164:167], v[220:223], v[42:45]
	v_mfma_f32_16x16x32_bf16 v[34:37], v[156:159], v[228:231], v[34:37]
	v_mfma_f32_16x16x32_bf16 v[26:29], v[164:167], v[228:231], v[26:29]
	v_mfma_f32_16x16x32_bf16 v[18:21], v[156:159], v[236:239], v[18:21]
	v_mfma_f32_16x16x32_bf16 v[10:13], v[164:167], v[236:239], v[10:13]
	v_mfma_f32_16x16x32_bf16 v[54:57], v[168:171], v[208:211], v[54:57]
	v_mfma_f32_16x16x32_bf16 v[46:49], v[176:179], v[208:211], v[46:49]
	v_mfma_f32_16x16x32_bf16 v[38:41], v[168:171], v[216:219], v[38:41]
	v_mfma_f32_16x16x32_bf16 v[30:33], v[176:179], v[216:219], v[30:33]
	v_mfma_f32_16x16x32_bf16 v[22:25], v[168:171], v[224:227], v[22:25]
	v_mfma_f32_16x16x32_bf16 v[14:17], v[176:179], v[224:227], v[14:17]
	v_mfma_f32_16x16x32_bf16 v[6:9], v[168:171], v[232:235], v[6:9]
	v_mfma_f32_16x16x32_bf16 v[2:5], v[176:179], v[232:235], v[2:5]
	v_mfma_f32_16x16x32_bf16 v[54:57], v[172:175], v[212:215], v[54:57]
	v_mfma_f32_16x16x32_bf16 v[46:49], v[180:183], v[212:215], v[46:49]
	v_mfma_f32_16x16x32_bf16 v[38:41], v[172:175], v[220:223], v[38:41]
	v_mfma_f32_16x16x32_bf16 v[30:33], v[180:183], v[220:223], v[30:33]
	v_mfma_f32_16x16x32_bf16 v[22:25], v[172:175], v[228:231], v[22:25]
	v_mfma_f32_16x16x32_bf16 v[14:17], v[180:183], v[228:231], v[14:17]
	v_mfma_f32_16x16x32_bf16 v[6:9], v[172:175], v[236:239], v[6:9]
	v_mfma_f32_16x16x32_bf16 v[2:5], v[180:183], v[236:239], v[2:5]
	s_barrier
	s_add_i32 s73, s73, 2
	s_add_u32 s26, s26, 0x100
	s_addc_u32 s27, s27, 0
	s_add_u32 s64, s64, 0x100
	s_addc_u32 s71, s71, 0
	s_cmp_gt_u32 s73, 13
	s_cbranch_scc0 .LBB0_303
	s_branch .Lpeel_e_exit
.LBB0_303:
	s_add_u32 s28, s26, 0xfffc0080
	s_addc_u32 s29, s27, -1
	s_add_i32 s74, 0, 0x10000
	s_cmp_eq_u32 s73, 12
	s_cselect_b32 s31, s17, s29
	s_cselect_b32 s30, s21, s28
	v_add_u32_e32 v145, s74, v137
	s_cselect_b32 s29, s19, s71
	s_cselect_b32 s28, s54, s64
	s_add_i32 s76, 0, 0x14000
	ds_read_b128 v[152:155], v145
	ds_read_b128 v[156:159], v145 offset:1024
	ds_read_b128 v[160:163], v145 offset:2048
	ds_read_b128 v[164:167], v145 offset:3072
	v_add_u32_e32 v145, s76, v137
	ds_read_b128 v[168:171], v145
	ds_read_b128 v[172:175], v145 offset:1024
	ds_read_b128 v[176:179], v145 offset:2048
	ds_read_b128 v[180:183], v145 offset:3072
	v_lshl_add_u64 v[202:203], s[26:27], 0, v[148:149]
	s_add_i32 m0, s43, 0xc000
	ds_read_b128 v[208:211], v143
	ds_read_b128 v[212:215], v143 offset:1024
	ds_read_b128 v[216:219], v143 offset:2048
	ds_read_b128 v[220:223], v143 offset:3072
	ds_read_b128 v[224:227], v143 offset:4096
	ds_read_b128 v[228:231], v143 offset:5120
	ds_read_b128 v[232:235], v143 offset:6144
	ds_read_b128 v[236:239], v143 offset:7168
	global_load_lds_dwordx4 v[202:203], off
	v_lshl_add_u64 v[202:203], s[26:27], 0, v[150:151]
	s_add_i32 m0, s43, 0xe000
	s_nop 0
	global_load_lds_dwordx4 v[202:203], off
	s_waitcnt vmcnt(8)
	s_waitcnt lgkmcnt(0)
	s_barrier
; #define PG8_STAGE(bufoff, gbase, voff) do { _Pragma("unroll") for (int _i = 0; _i < 2; ++_i) \
;         __builtin_amdgcn_global_load_lds((const unsigned*)((const char*)(gbase) + (voff)[_i]), (PG8_LAS unsigned*)(lds + (bufoff) + ldsw + _i * 8192), 16, 0, 0); } while (0)
; #define PG8_LDA(dst, b, h) do { _Pragma("unroll") for (int m = 0; m < 4; ++m) _Pragma("unroll") for (int k = 0; k < 2; ++k) dst[m][k] = *(const PG8_LAS bf16x8*)(lds + PG8_SA(b, h) + aoff + m * 2048 + k * 1024); } while (0)
; #define PG8_LDB(dst, b, h) do { _Pragma("unroll") for (int n = 0; n < 2; ++n) _Pragma("unroll") for (int k = 0; k < 2; ++k) dst[n][k] = *(const PG8_LAS bf16x8*)(lds + PG8_SB(b, h) + boff + n * 2048 + k * 1024); } while (0)
; #define PG8_MMA(ai, bj, At, Bt) do { __builtin_amdgcn_s_setprio(1); _Pragma("unroll") for (int m = 0; m < 4; ++m) _Pragma("unroll") for (int n = 0; n < 2; ++n) _Pragma("unroll") for (int k = 0; k < 2; ++k) \
;         acc[ai][bj][m][n] = __builtin_amdgcn_mfma_f32_16x16x32_bf16(Bt[n][k], At[m][k], acc[ai][bj][m][n], 0, 0, 0); __builtin_amdgcn_s_setprio(0); } while (0)
; #define PG8_WAIT_V(n) asm volatile("s_waitcnt vmcnt(" #n ")" ::: "memory")
; #define PG8_WAIT_L(n) asm volatile("s_waitcnt lgkmcnt(" #n ")" ::: "memory")
; #define PG8_BAR __builtin_amdgcn_s_barrier()
; #define PG8_SCHED __builtin_amdgcn_sched_barrier(0)
; template <class Epi, class Sched, bool ALIGN_EPI = false, bool SP2 = false>
; __device__ __forceinline__ void gemm_phase(PG8_LAS unsigned char* lds, const Gemm g, const Sched& S, const Epi& E) {
;     ...
;             PG8_WAIT_V(8); PG8_WAIT_L(0); PG8_BAR; PG8_MMA(0, 0, At, B0); PG8_MMA(0, 1, At, B1); PG8_BAR; PG8_SCHED;
;             PG8_LDA(At, 0, 1); PG8_STAGE(PG8_SB(0, 0), b2, voffB); PG8_STAGE(PG8_SB(0, 1), b2 + hstep, voffB); PG8_STAGE(PG8_SA(0, 0), a2, voffA);
;             PG8_WAIT_V(8); PG8_WAIT_L(0); PG8_BAR; PG8_MMA(1, 0, At, B0); PG8_MMA(1, 1, At, B1); PG8_BAR; PG8_SCHED;
;             PG8_LDB(B0, 1, 0); PG8_LDB(B1, 1, 1); PG8_SCHED; PG8_LDA(At, 1, 0); PG8_STAGE(PG8_SA(0, 1), a2 + hstep, voffA);
;             PG8_WAIT_V(8); PG8_WAIT_L(0); PG8_BAR; PG8_MMA(0, 0, At, B0); PG8_MMA(0, 1, At, B1); PG8_BAR; PG8_SCHED;
	s_waitcnt lgkmcnt(0)
	v_mfma_f32_16x16x32_bf16 v[126:129], v[152:155], v[208:211], v[126:129]
	v_mfma_f32_16x16x32_bf16 v[122:125], v[160:163], v[208:211], v[122:125]
	v_mfma_f32_16x16x32_bf16 v[114:117], v[152:155], v[216:219], v[114:117]
	v_mfma_f32_16x16x32_bf16 v[106:109], v[160:163], v[216:219], v[106:109]
	v_mfma_f32_16x16x32_bf16 v[98:101], v[152:155], v[224:227], v[98:101]
	v_mfma_f32_16x16x32_bf16 v[90:93], v[160:163], v[224:227], v[90:93]
	v_mfma_f32_16x16x32_bf16 v[82:85], v[152:155], v[232:235], v[82:85]
	v_mfma_f32_16x16x32_bf16 v[74:77], v[160:163], v[232:235], v[74:77]
	v_mfma_f32_16x16x32_bf16 v[126:129], v[156:159], v[212:215], v[126:129]
	v_mfma_f32_16x16x32_bf16 v[122:125], v[164:167], v[212:215], v[122:125]
	v_mfma_f32_16x16x32_bf16 v[114:117], v[156:159], v[220:223], v[114:117]
	v_mfma_f32_16x16x32_bf16 v[106:109], v[164:167], v[220:223], v[106:109]
	v_mfma_f32_16x16x32_bf16 v[98:101], v[156:159], v[228:231], v[98:101]
	v_mfma_f32_16x16x32_bf16 v[90:93], v[164:167], v[228:231], v[90:93]
	v_mfma_f32_16x16x32_bf16 v[82:85], v[156:159], v[236:239], v[82:85]
	v_mfma_f32_16x16x32_bf16 v[74:77], v[164:167], v[236:239], v[74:77]
	v_mfma_f32_16x16x32_bf16 v[118:121], v[168:171], v[208:211], v[118:121]
	v_mfma_f32_16x16x32_bf16 v[110:113], v[176:179], v[208:211], v[110:113]
	v_mfma_f32_16x16x32_bf16 v[102:105], v[168:171], v[216:219], v[102:105]
	v_mfma_f32_16x16x32_bf16 v[94:97], v[176:179], v[216:219], v[94:97]
	v_mfma_f32_16x16x32_bf16 v[86:89], v[168:171], v[224:227], v[86:89]
	v_mfma_f32_16x16x32_bf16 v[78:81], v[176:179], v[224:227], v[78:81]
	v_mfma_f32_16x16x32_bf16 v[70:73], v[168:171], v[232:235], v[70:73]
	v_mfma_f32_16x16x32_bf16 v[66:69], v[176:179], v[232:235], v[66:69]
	v_mfma_f32_16x16x32_bf16 v[118:121], v[172:175], v[212:215], v[118:121]
	v_mfma_f32_16x16x32_bf16 v[110:113], v[180:183], v[212:215], v[110:113]
	v_mfma_f32_16x16x32_bf16 v[102:105], v[172:175], v[220:223], v[102:105]
	v_mfma_f32_16x16x32_bf16 v[94:97], v[180:183], v[220:223], v[94:97]
	v_mfma_f32_16x16x32_bf16 v[86:89], v[172:175], v[228:231], v[86:89]
	v_mfma_f32_16x16x32_bf16 v[78:81], v[180:183], v[228:231], v[78:81]
	v_mfma_f32_16x16x32_bf16 v[70:73], v[172:175], v[236:239], v[70:73]
	v_mfma_f32_16x16x32_bf16 v[66:69], v[180:183], v[236:239], v[66:69]
	s_barrier
	s_add_i32 s74, s74, s42
	v_lshl_add_u64 v[202:203], s[28:29], 0, v[132:133]
	s_mov_b32 m0, s74
	ds_read_b128 v[208:211], v143 offset:16384
	ds_read_b128 v[212:215], v143 offset:17408
	ds_read_b128 v[216:219], v143 offset:18432
	ds_read_b128 v[220:223], v143 offset:19456
	ds_read_b128 v[224:227], v143 offset:20480
	ds_read_b128 v[228:231], v143 offset:21504
	ds_read_b128 v[232:235], v143 offset:22528
	ds_read_b128 v[236:239], v143 offset:23552
	global_load_lds_dwordx4 v[202:203], off
	s_add_i32 m0, s74, 0x2000
	s_add_u32 s74, s28, 0x40000
	v_lshl_add_u64 v[204:205], s[28:29], 0, v[130:131]
	s_addc_u32 s75, s29, 0
	s_add_i32 s76, s76, s42
	global_load_lds_dwordx4 v[204:205], off
	v_lshl_add_u64 v[240:241], s[74:75], 0, v[132:133]
	s_mov_b32 m0, s76
	v_lshl_add_u64 v[242:243], s[30:31], 0, v[130:131]
	global_load_lds_dwordx4 v[240:241], off
	v_lshl_add_u64 v[240:241], s[74:75], 0, v[130:131]
	s_add_i32 m0, s76, 0x2000
	s_nop 0
	global_load_lds_dwordx4 v[240:241], off
	v_lshl_add_u64 v[240:241], s[30:31], 0, v[132:133]
	s_mov_b32 m0, s43
	s_nop 0
	global_load_lds_dwordx4 v[240:241], off
	s_mov_b32 m0, s44
	s_nop 0
	global_load_lds_dwordx4 v[242:243], off
	s_waitcnt vmcnt(8)
	s_waitcnt lgkmcnt(0)
	s_barrier
	s_waitcnt lgkmcnt(0)
	v_mfma_f32_16x16x32_bf16 v[62:65], v[152:155], v[208:211], v[62:65]
	v_mfma_f32_16x16x32_bf16 v[58:61], v[160:163], v[208:211], v[58:61]
	v_mfma_f32_16x16x32_bf16 v[50:53], v[152:155], v[216:219], v[50:53]
	v_mfma_f32_16x16x32_bf16 v[42:45], v[160:163], v[216:219], v[42:45]
	v_mfma_f32_16x16x32_bf16 v[34:37], v[152:155], v[224:227], v[34:37]
	v_mfma_f32_16x16x32_bf16 v[26:29], v[160:163], v[224:227], v[26:29]
	v_mfma_f32_16x16x32_bf16 v[18:21], v[152:155], v[232:235], v[18:21]
	v_mfma_f32_16x16x32_bf16 v[10:13], v[160:163], v[232:235], v[10:13]
	v_mfma_f32_16x16x32_bf16 v[62:65], v[156:159], v[212:215], v[62:65]
	v_mfma_f32_16x16x32_bf16 v[58:61], v[164:167], v[212:215], v[58:61]
	v_mfma_f32_16x16x32_bf16 v[50:53], v[156:159], v[220:223], v[50:53]
	v_mfma_f32_16x16x32_bf16 v[42:45], v[164:167], v[220:223], v[42:45]
	v_mfma_f32_16x16x32_bf16 v[34:37], v[156:159], v[228:231], v[34:37]
	v_mfma_f32_16x16x32_bf16 v[26:29], v[164:167], v[228:231], v[26:29]
	v_mfma_f32_16x16x32_bf16 v[18:21], v[156:159], v[236:239], v[18:21]
	v_mfma_f32_16x16x32_bf16 v[10:13], v[164:167], v[236:239], v[10:13]
	v_mfma_f32_16x16x32_bf16 v[54:57], v[168:171], v[208:211], v[54:57]
	v_mfma_f32_16x16x32_bf16 v[46:49], v[176:179], v[208:211], v[46:49]
	v_mfma_f32_16x16x32_bf16 v[38:41], v[168:171], v[216:219], v[38:41]
	v_mfma_f32_16x16x32_bf16 v[30:33], v[176:179], v[216:219], v[30:33]
	v_mfma_f32_16x16x32_bf16 v[22:25], v[168:171], v[224:227], v[22:25]
	v_mfma_f32_16x16x32_bf16 v[14:17], v[176:179], v[224:227], v[14:17]
	v_mfma_f32_16x16x32_bf16 v[6:9], v[168:171], v[232:235], v[6:9]
	v_mfma_f32_16x16x32_bf16 v[2:5], v[176:179], v[232:235], v[2:5]
	v_mfma_f32_16x16x32_bf16 v[54:57], v[172:175], v[212:215], v[54:57]
	v_mfma_f32_16x16x32_bf16 v[46:49], v[180:183], v[212:215], v[46:49]
	v_mfma_f32_16x16x32_bf16 v[38:41], v[172:175], v[220:223], v[38:41]
	v_mfma_f32_16x16x32_bf16 v[30:33], v[180:183], v[220:223], v[30:33]
	v_mfma_f32_16x16x32_bf16 v[22:25], v[172:175], v[228:231], v[22:25]
	v_mfma_f32_16x16x32_bf16 v[14:17], v[180:183], v[228:231], v[14:17]
	v_mfma_f32_16x16x32_bf16 v[6:9], v[172:175], v[236:239], v[6:9]
	v_mfma_f32_16x16x32_bf16 v[2:5], v[180:183], v[236:239], v[2:5]
	s_barrier
; #define PG8_STAGE(bufoff, gbase, voff) do { _Pragma("unroll") for (int _i = 0; _i < 2; ++_i) \
;         __builtin_amdgcn_global_load_lds((const unsigned*)((const char*)(gbase) + (voff)[_i]), (PG8_LAS unsigned*)(lds + (bufoff) + ldsw + _i * 8192), 16, 0, 0); } while (0)
; #define PG8_LDA(dst, b, h) do { _Pragma("unroll") for (int m = 0; m < 4; ++m) _Pragma("unroll") for (int k = 0; k < 2; ++k) dst[m][k] = *(const PG8_LAS bf16x8*)(lds + PG8_SA(b, h) + aoff + m * 2048 + k * 1024); } while (0)
; #define PG8_LDB(dst, b, h) do { _Pragma("unroll") for (int n = 0; n < 2; ++n) _Pragma("unroll") for (int k = 0; k < 2; ++k) dst[n][k] = *(const PG8_LAS bf16x8*)(lds + PG8_SB(b, h) + boff + n * 2048 + k * 1024); } while (0)
; #define PG8_MMA(ai, bj, At, Bt) do { __builtin_amdgcn_s_setprio(1); _Pragma("unroll") for (int m = 0; m < 4; ++m) _Pragma("unroll") for (int n = 0; n < 2; ++n) _Pragma("unroll") for (int k = 0; k < 2; ++k) \
;         acc[ai][bj][m][n] = __builtin_amdgcn_mfma_f32_16x16x32_bf16(Bt[n][k], At[m][k], acc[ai][bj][m][n], 0, 0, 0); __builtin_amdgcn_s_setprio(0); } while (0)
; #define PG8_WAIT_V(n) asm volatile("s_waitcnt vmcnt(" #n ")" ::: "memory")
; #define PG8_WAIT_L(n) asm volatile("s_waitcnt lgkmcnt(" #n ")" ::: "memory")
; #define PG8_BAR __builtin_amdgcn_s_barrier()
; #define PG8_SCHED __builtin_amdgcn_sched_barrier(0)
; template <class Epi, class Sched, bool ALIGN_EPI = false, bool SP2 = false>
; __device__ __forceinline__ void gemm_phase(PG8_LAS unsigned char* lds, const Gemm g, const Sched& S, const Epi& E) {
;     ...
;             PG8_WAIT_V(8); PG8_WAIT_L(0); PG8_BAR; PG8_MMA(1, 0, At, B0); PG8_MMA(1, 1, At, B1); PG8_BAR; PG8_SCHED;
;             PG8_LDB(B0, 1, 0); PG8_LDB(B1, 1, 1); PG8_SCHED; PG8_LDA(At, 1, 0); PG8_STAGE(PG8_SA(0, 1), a2 + hstep, voffA);
;             PG8_WAIT_V(8); PG8_WAIT_L(0); PG8_BAR; PG8_MMA(0, 0, At, B0); PG8_MMA(0, 1, At, B1); PG8_BAR; PG8_SCHED;
	s_add_i32 s74, 0, 0x18000
	v_add_u32_e32 v145, s74, v137
	s_add_i32 s75, 0, 0x1c000
	ds_read_b128 v[152:155], v145
	ds_read_b128 v[156:159], v145 offset:1024
	ds_read_b128 v[160:163], v145 offset:2048
	ds_read_b128 v[164:167], v145 offset:3072
	v_add_u32_e32 v145, s75, v137
	ds_read_b128 v[168:171], v145
	ds_read_b128 v[172:175], v145 offset:1024
	ds_read_b128 v[176:179], v145 offset:2048
	ds_read_b128 v[180:183], v145 offset:3072
	s_add_u32 s30, s30, 0x40000
	s_addc_u32 s31, s31, 0
	s_mov_b32 m0, s45
	v_lshl_add_u64 v[244:245], s[30:31], 0, v[132:133]
	ds_read_b128 v[208:211], v143 offset:32768
	ds_read_b128 v[212:215], v143 offset:33792
	ds_read_b128 v[216:219], v143 offset:34816
	ds_read_b128 v[220:223], v143 offset:35840
	ds_read_b128 v[224:227], v143 offset:36864
	ds_read_b128 v[228:231], v143 offset:37888
	ds_read_b128 v[232:235], v143 offset:38912
	ds_read_b128 v[236:239], v143 offset:39936
	global_load_lds_dwordx4 v[244:245], off
	v_lshl_add_u64 v[244:245], s[30:31], 0, v[130:131]
	s_mov_b32 m0, s46
	s_nop 0
	global_load_lds_dwordx4 v[244:245], off
	s_waitcnt vmcnt(8)
	s_waitcnt lgkmcnt(0)
	s_barrier
	s_waitcnt lgkmcnt(0)
	v_mfma_f32_16x16x32_bf16 v[126:129], v[152:155], v[208:211], v[126:129]
	v_mfma_f32_16x16x32_bf16 v[122:125], v[160:163], v[208:211], v[122:125]
	v_mfma_f32_16x16x32_bf16 v[114:117], v[152:155], v[216:219], v[114:117]
	v_mfma_f32_16x16x32_bf16 v[106:109], v[160:163], v[216:219], v[106:109]
	v_mfma_f32_16x16x32_bf16 v[98:101], v[152:155], v[224:227], v[98:101]
	v_mfma_f32_16x16x32_bf16 v[90:93], v[160:163], v[224:227], v[90:93]
	v_mfma_f32_16x16x32_bf16 v[82:85], v[152:155], v[232:235], v[82:85]
	v_mfma_f32_16x16x32_bf16 v[74:77], v[160:163], v[232:235], v[74:77]
	v_mfma_f32_16x16x32_bf16 v[126:129], v[156:159], v[212:215], v[126:129]
	v_mfma_f32_16x16x32_bf16 v[122:125], v[164:167], v[212:215], v[122:125]
	v_mfma_f32_16x16x32_bf16 v[114:117], v[156:159], v[220:223], v[114:117]
	v_mfma_f32_16x16x32_bf16 v[106:109], v[164:167], v[220:223], v[106:109]
	v_mfma_f32_16x16x32_bf16 v[98:101], v[156:159], v[228:231], v[98:101]
	v_mfma_f32_16x16x32_bf16 v[90:93], v[164:167], v[228:231], v[90:93]
	v_mfma_f32_16x16x32_bf16 v[82:85], v[156:159], v[236:239], v[82:85]
	v_mfma_f32_16x16x32_bf16 v[74:77], v[164:167], v[236:239], v[74:77]
	v_mfma_f32_16x16x32_bf16 v[118:121], v[168:171], v[208:211], v[118:121]
	v_mfma_f32_16x16x32_bf16 v[110:113], v[176:179], v[208:211], v[110:113]
	v_mfma_f32_16x16x32_bf16 v[102:105], v[168:171], v[216:219], v[102:105]
	v_mfma_f32_16x16x32_bf16 v[94:97], v[176:179], v[216:219], v[94:97]
	v_mfma_f32_16x16x32_bf16 v[86:89], v[168:171], v[224:227], v[86:89]
	v_mfma_f32_16x16x32_bf16 v[78:81], v[176:179], v[224:227], v[78:81]
	v_mfma_f32_16x16x32_bf16 v[70:73], v[168:171], v[232:235], v[70:73]
	v_mfma_f32_16x16x32_bf16 v[66:69], v[176:179], v[232:235], v[66:69]
	v_mfma_f32_16x16x32_bf16 v[118:121], v[172:175], v[212:215], v[118:121]
	v_mfma_f32_16x16x32_bf16 v[110:113], v[180:183], v[212:215], v[110:113]
	v_mfma_f32_16x16x32_bf16 v[102:105], v[172:175], v[220:223], v[102:105]
	v_mfma_f32_16x16x32_bf16 v[94:97], v[180:183], v[220:223], v[94:97]
	v_mfma_f32_16x16x32_bf16 v[86:89], v[172:175], v[228:231], v[86:89]
	v_mfma_f32_16x16x32_bf16 v[78:81], v[180:183], v[228:231], v[78:81]
	v_mfma_f32_16x16x32_bf16 v[70:73], v[172:175], v[236:239], v[70:73]
	v_mfma_f32_16x16x32_bf16 v[66:69], v[180:183], v[236:239], v[66:69]
	s_barrier
; #define PG8_STAGE(bufoff, gbase, voff) do { _Pragma("unroll") for (int _i = 0; _i < 2; ++_i) \
;         __builtin_amdgcn_global_load_lds((const unsigned*)((const char*)(gbase) + (voff)[_i]), (PG8_LAS unsigned*)(lds + (bufoff) + ldsw + _i * 8192), 16, 0, 0); } while (0)
; #define PG8_LDA(dst, b, h) do { _Pragma("unroll") for (int m = 0; m < 4; ++m) _Pragma("unroll") for (int k = 0; k < 2; ++k) dst[m][k] = *(const PG8_LAS bf16x8*)(lds + PG8_SA(b, h) + aoff + m * 2048 + k * 1024); } while (0)
; #define PG8_LDB(dst, b, h) do { _Pragma("unroll") for (int n = 0; n < 2; ++n) _Pragma("unroll") for (int k = 0; k < 2; ++k) dst[n][k] = *(const PG8_LAS bf16x8*)(lds + PG8_SB(b, h) + boff + n * 2048 + k * 1024); } while (0)
; #define PG8_MMA(ai, bj, At, Bt) do { __builtin_amdgcn_s_setprio(1); _Pragma("unroll") for (int m = 0; m < 4; ++m) _Pragma("unroll") for (int n = 0; n < 2; ++n) _Pragma("unroll") for (int k = 0; k < 2; ++k) \
;         acc[ai][bj][m][n] = __builtin_amdgcn_mfma_f32_16x16x32_bf16(Bt[n][k], At[m][k], acc[ai][bj][m][n], 0, 0, 0); __builtin_amdgcn_s_setprio(0); } while (0)
; #define PG8_WAIT_V(n) asm volatile("s_waitcnt vmcnt(" #n ")" ::: "memory")
; #define PG8_BAR __builtin_amdgcn_s_barrier()
; template <class Epi, class Sched, bool ALIGN_EPI = false, bool SP2 = false>
; __device__ __forceinline__ void gemm_phase(PG8_LAS unsigned char* lds, const Gemm g, const Sched& S, const Epi& E) {
;     ...
;         for (int t = 0; t < nt; t += 2) {
;             const bool last = (t == nt - 2);
;             const char* a1 = cA + (size_t)(t + 1) * kstep;
;             const char* a2 = last ? nA : cA + (size_t)(t + 2) * kstep; const char* b2 = last ? nB : cB + (size_t)(t + 2) * kstep;
;             const char* a3 = a2 + kstep; const char* b3 = b2 + kstep;
;             if (last && has_next) S.a_ready(nxt);
;             if constexpr (SP2) {
;             PG8_LDB(B0, 0, 0); PG8_LDB(B1, 0, 1); PG8_SCHED; PG8_LDA(At, 0, 0); PG8_STAGE(PG8_SA(1, 1), a1 + hstep, voffA);
;             PG8_WAIT_V(8); PG8_WAIT_L(0); PG8_BAR; PG8_MMA(0, 0, At, B0); PG8_MMA(0, 1, At, B1); PG8_BAR; PG8_SCHED;
;     ...
;             PG8_LDA(At, 1, 1); PG8_STAGE(PG8_SB(1, 0), b3, voffB); PG8_STAGE(PG8_SB(1, 1), b3 + hstep, voffB); PG8_STAGE(PG8_SA(1, 0), a3, voffA);
;             PG8_WAIT_V(8); PG8_WAIT_L(0); PG8_BAR; PG8_MMA(1, 0, At, B0); PG8_MMA(1, 1, At, B1); PG8_BAR; PG8_SCHED;
	s_add_i32 s30, s74, s42
	v_lshl_add_u64 v[202:203], v[202:203], 0, s[66:67]
	s_mov_b32 m0, s30
	ds_read_b128 v[208:211], v143 offset:49152
	ds_read_b128 v[212:215], v143 offset:50176
	ds_read_b128 v[216:219], v143 offset:51200
	ds_read_b128 v[220:223], v143 offset:52224
	ds_read_b128 v[224:227], v143 offset:53248
	ds_read_b128 v[228:231], v143 offset:54272
	ds_read_b128 v[232:235], v143 offset:55296
	ds_read_b128 v[236:239], v143 offset:56320
	global_load_lds_dwordx4 v[202:203], off
	s_add_i32 m0, s30, 0x2000
	s_add_u32 s28, s28, 0x40080
	v_lshl_add_u64 v[202:203], v[204:205], 0, s[66:67]
	s_addc_u32 s29, s29, 0
	s_add_i32 s30, s75, s42
	global_load_lds_dwordx4 v[202:203], off
	v_lshl_add_u64 v[202:203], s[28:29], 0, v[132:133]
	s_mov_b32 m0, s30
	s_nop 0
	global_load_lds_dwordx4 v[202:203], off
	v_lshl_add_u64 v[202:203], s[28:29], 0, v[130:131]
	s_add_i32 m0, s30, 0x2000
	s_nop 0
	global_load_lds_dwordx4 v[202:203], off
	v_lshl_add_u64 v[202:203], v[240:241], 0, s[66:67]
	s_mov_b32 m0, s49
	s_nop 0
	global_load_lds_dwordx4 v[202:203], off
	v_lshl_add_u64 v[202:203], v[242:243], 0, s[66:67]
	s_mov_b32 m0, s50
	s_nop 0
	global_load_lds_dwordx4 v[202:203], off
	s_waitcnt vmcnt(8)
	s_waitcnt lgkmcnt(0)
	s_barrier
	s_waitcnt lgkmcnt(0)
	v_mfma_f32_16x16x32_bf16 v[62:65], v[152:155], v[208:211], v[62:65]
	v_mfma_f32_16x16x32_bf16 v[58:61], v[160:163], v[208:211], v[58:61]
	v_mfma_f32_16x16x32_bf16 v[50:53], v[152:155], v[216:219], v[50:53]
	v_mfma_f32_16x16x32_bf16 v[42:45], v[160:163], v[216:219], v[42:45]
	v_mfma_f32_16x16x32_bf16 v[34:37], v[152:155], v[224:227], v[34:37]
	v_mfma_f32_16x16x32_bf16 v[26:29], v[160:163], v[224:227], v[26:29]
	v_mfma_f32_16x16x32_bf16 v[18:21], v[152:155], v[232:235], v[18:21]
	v_mfma_f32_16x16x32_bf16 v[10:13], v[160:163], v[232:235], v[10:13]
	v_mfma_f32_16x16x32_bf16 v[62:65], v[156:159], v[212:215], v[62:65]
	v_mfma_f32_16x16x32_bf16 v[58:61], v[164:167], v[212:215], v[58:61]
	v_mfma_f32_16x16x32_bf16 v[50:53], v[156:159], v[220:223], v[50:53]
	v_mfma_f32_16x16x32_bf16 v[42:45], v[164:167], v[220:223], v[42:45]
	v_mfma_f32_16x16x32_bf16 v[34:37], v[156:159], v[228:231], v[34:37]
	v_mfma_f32_16x16x32_bf16 v[26:29], v[164:167], v[228:231], v[26:29]
	v_mfma_f32_16x16x32_bf16 v[18:21], v[156:159], v[236:239], v[18:21]
	v_mfma_f32_16x16x32_bf16 v[10:13], v[164:167], v[236:239], v[10:13]
	v_mfma_f32_16x16x32_bf16 v[54:57], v[168:171], v[208:211], v[54:57]
	v_mfma_f32_16x16x32_bf16 v[46:49], v[176:179], v[208:211], v[46:49]
	v_mfma_f32_16x16x32_bf16 v[38:41], v[168:171], v[216:219], v[38:41]
	v_mfma_f32_16x16x32_bf16 v[30:33], v[176:179], v[216:219], v[30:33]
	v_mfma_f32_16x16x32_bf16 v[22:25], v[168:171], v[224:227], v[22:25]
	v_mfma_f32_16x16x32_bf16 v[14:17], v[176:179], v[224:227], v[14:17]
	v_mfma_f32_16x16x32_bf16 v[6:9], v[168:171], v[232:235], v[6:9]
	v_mfma_f32_16x16x32_bf16 v[2:5], v[176:179], v[232:235], v[2:5]
	v_mfma_f32_16x16x32_bf16 v[54:57], v[172:175], v[212:215], v[54:57]
	v_mfma_f32_16x16x32_bf16 v[46:49], v[180:183], v[212:215], v[46:49]
	v_mfma_f32_16x16x32_bf16 v[38:41], v[172:175], v[220:223], v[38:41]
	v_mfma_f32_16x16x32_bf16 v[30:33], v[180:183], v[220:223], v[30:33]
	v_mfma_f32_16x16x32_bf16 v[22:25], v[172:175], v[228:231], v[22:25]
	v_mfma_f32_16x16x32_bf16 v[14:17], v[180:183], v[228:231], v[14:17]
	v_mfma_f32_16x16x32_bf16 v[6:9], v[172:175], v[236:239], v[6:9]
	v_mfma_f32_16x16x32_bf16 v[2:5], v[180:183], v[236:239], v[2:5]
	s_barrier
	s_add_i32 s73, s73, 2
	s_add_u32 s26, s26, 0x100
	s_addc_u32 s27, s27, 0
	s_add_u32 s64, s64, 0x100
	s_addc_u32 s71, s71, 0
	s_cmp_gt_u32 s73, 13
	s_cbranch_scc0 .LBB0_303

; #define PG8_WAIT_V(n) asm volatile("s_waitcnt vmcnt(" #n ")" ::: "memory")
; #define PG8_BAR __builtin_amdgcn_s_barrier()
; __device__ __forceinline__ unsigned xb_add(unsigned* p, unsigned v) { return __hip_atomic_fetch_add(p, v, __ATOMIC_RELAXED, __HIP_MEMORY_SCOPE_AGENT); }
; template <class Epi, class Sched, bool ALIGN_EPI = false, bool SP2 = false>
; __device__ __forceinline__ void gemm_phase(PG8_LAS unsigned char* lds, const Gemm g, const Sched& S, const Epi& E) {
;     ...
;     PG8_WAIT_V(0);
;     if constexpr (!ALIGN_EPI) { if (wr == 0) PG8_BAR; }
;     PG8_BAR;
; __device__ __forceinline__ void xcd_barrier(const XcdBarrier& b) {
;     asm volatile("s_waitcnt vmcnt(0)" ::: "memory");
;     __syncthreads();
;     if (threadIdx.x == 0) {
;         unsigned* bar = b.bar;
;         __builtin_amdgcn_s_waitcnt(0);
;         unsigned nloc = b.st[0], nx = b.st[1];
;         if (nloc == 0u) { xcd_barrier_complete(bar, b.x, nloc, nx); b.st[0] = nloc; b.st[1] = nx; }
;         const unsigned old = xb_add(&bar[XB_XSUB(b.x)], 1u);
;         const unsigned gen = old / nloc;
.LBB0_329:
	s_setprio 0
	s_waitcnt vmcnt(0)
	s_waitcnt vmcnt(0)
	s_barrier
	s_mov_b64 s[2:3], exec
	v_readlane_b32 s6, v253, 0
	v_readlane_b32 s7, v253, 1
	s_and_b64 s[6:7], s[2:3], s[6:7]
	s_xor_b64 s[2:3], s[6:7], s[2:3]
	s_mov_b64 exec, s[6:7]
	s_cbranch_execz .LBB0_378
	v_mov_b32_e32 v0, s96
	s_waitcnt vmcnt(0) expcnt(0) lgkmcnt(0)
	ds_read_b32 v3, v0
	v_readlane_b32 s1, v254, 42
	s_waitcnt lgkmcnt(0)
	v_cmp_ne_u32_e32 vcc, 0, v3
	v_mov_b32_e32 v0, s1
	ds_read_b32 v2, v0
	s_cbranch_vccnz .LBB0_345
	s_mov_b32 s12, 1
	s_branch .LBB0_333

; __device__ __forceinline__ void na_task(const P& p, int task, int lane, float* ldsw  ) {
;     const int fr = lane & 15, g = lane >> 4;
;     const bf16_t* QK = (const bf16_t*)(p.ws + WS_NAQK); const bf16_t* VT = (const bf16_t*)(p.ws + WS_NAVT); bf16_t* Y = (bf16_t*)(p.ws + WS_A);
;     if (task < 2048) {
;         const int h = task & 7, r = (task >> 3) & 31, b = task >> 8;
;         for (int i = lane; i < 465; i += 64) ldsw[i] = p.rpb[h * 465 + i];
;         AttnState st[4];
;         bf16_t* qlds = (bf16_t*)(ldsw + 512) + fr * 72 + g * 8;
;         const size_t qrow0 = (size_t)b * TLAT + r * 64 + fr;
; #pragma unroll
;         for (int j = 0; j < 4; ++j) {
;             st[j].m = -1e30f; st[j].l = 0.f;
; #pragma unroll
;             for (int dt = 0; dt < 4; ++dt) st[j].o[dt] = (f32x4){0.f, 0.f, 0.f, 0.f};
;             const bf16_t* qp = QK + (qrow0 + j * 16) * 1024 + h * 64 + g * 8;
;             *(bf16x8*)(qlds + j * 16 * 72) = *(const bf16x8*)qp; *(bf16x8*)(qlds + j * 16 * 72 + 32) = *(const bf16x8*)(qp + 32);
;         }
;         const int r0 = clampi(r - 4, 0, 24);
;         const bf16_t* vb = VT + ((size_t)b * 512 + h * 64) * TT;
;         const bf16_t* kbase = QK + 512 + h * 64 + g * 8;
;         auto ldk = [&](int i, AttnKn& k) {
;             const bf16_t* k0p = (i < 16) ? kbase + ((size_t)b * TLAT + (r0 + (i >> 1)) * 64 + (i & 1) * 32 + fr) * 1024 : kbase + ((size_t)MLAT + b * TCTX + (i - 16) * 32 + fr) * 1024;
;             k.a00 = *(const bf16x8*)k0p; k.a01 = *(const bf16x8*)(k0p + 32); k.a10 = *(const bf16x8*)(k0p + 16 * 1024); k.a11 = *(const bf16x8*)(k0p + 16 * 1024 + 32);
;         };
;         auto ldv = [&](int i, AttnVn& v) {
;             const int tok0 = (i < 16) ? (r0 + (i >> 1)) * 64 + (i & 1) * 32 : TLAT + (i - 16) * 32;
; #pragma unroll
;             for (int dt = 0; dt < 4; ++dt) { const bf16_t* vp = vb + (size_t)(dt * 16 + fr) * TT + tok0 + 4 * g; v.va[dt][0] = *(const s16x4*)vp; v.va[dt][1] = *(const s16x4*)(vp + 16); }
;         };
;         asm volatile("s_waitcnt lgkmcnt(0)" ::: "memory");
;         AttnKn kc, kn; AttnVn vv; ldk(0, kc);
.LBB0_378:
	s_or_b64 exec, exec, s[2:3]
	v_mov_b32_e32 v0, v1
	s_waitcnt lgkmcnt(0)
	s_barrier
	v_readlane_b32 s2, v254, 18
	v_readfirstlane_b32 s49, v144
	s_ashr_i32 s48, s49, 6
	s_add_i32 s84, s2, s48
	s_cmpk_gt_i32 s84, 0xbff
	v_readfirstlane_b32 s2, v0
	s_cbranch_scc1 .LBB0_418
	s_load_dwordx2 s[44:45], s[92:93], s2 offset:0x58
	s_load_dwordx2 s[46:47], s[92:93], s2 offset:0xa8
	s_mul_i32 s2, s48, 0x3000
	v_and_b32_e32 v2, 48, v144
	v_mov_b32_e32 v3, v1
	s_add_i32 s85, s2, 0
	v_and_b32_e32 v114, 15, v144
	s_waitcnt lgkmcnt(0)
	v_lshl_add_u64 v[4:5], s[46:47], 0, v[2:3]
	s_mov_b64 s[6:7], 0x7f00400
	s_add_u32 s2, s46, 0x7f00000
	v_lshl_add_u64 v[116:117], v[4:5], 0, s[6:7]
	v_mul_u32_u24_e32 v4, 0x90, v114
	v_bfe_u32 v6, v144, 4, 2
	s_addc_u32 s3, s47, 0
	v_add3_u32 v143, s85, v4, v2
	v_subrev_co_u32_e32 v4, vcc, 8, v114
	s_add_u32 s86, s46, 0xa300000
	v_min_u32_e32 v4, 48, v4
	v_lshlrev_b32_e32 v124, 2, v6
	s_addc_u32 s87, s47, 0
	v_cndmask_b32_e64 v8, v4, 0, vcc
	v_or_b32_e32 v170, 16, v124
	s_add_u32 s76, s46, 0x5b00000
	v_add_u32_e32 v9, 16, v8
	v_cmp_lt_u32_e64 s[8:9], v124, v8
	v_cmp_ge_u32_e32 vcc, v170, v8
	v_or_b32_e32 v172, 17, v124
	s_addc_u32 s77, s47, 0
	s_and_b64 s[14:15], vcc, s[8:9]
	v_cmp_ge_u32_e32 vcc, v172, v8
	v_cmp_lt_u32_e64 s[16:17], v172, v9
	v_or_b32_e32 v174, 18, v124
	v_and_b32_e32 v7, 63, v144
	v_or_b32_e32 v167, 1, v124
	v_or_b32_e32 v168, 3, v124
	v_or_b32_e32 v169, 2, v124
	v_sub_u32_e32 v10, v170, v114
	s_and_b64 s[16:17], vcc, s[16:17]
	v_cmp_ge_u32_e32 vcc, v174, v8
	v_cmp_lt_u32_e64 s[18:19], v174, v9
	v_or_b32_e32 v176, 19, v124
	v_or_b32_e32 v5, 48, v7
	v_cmp_lt_u32_e64 s[6:7], v167, v8
	v_cmp_lt_u32_e64 s[10:11], v168, v8
	v_cmp_lt_u32_e64 s[12:13], v169, v8
	v_min_u32_e32 v171, 15, v10
	v_sub_u32_e32 v10, v172, v114
	s_and_b64 s[18:19], vcc, s[18:19]
	v_cmp_ge_u32_e32 vcc, v176, v8
	v_sub_u32_e32 v8, v176, v114
	v_min_u32_e32 v173, 15, v10
	v_sub_u32_e32 v10, v174, v114
	v_min_u32_e32 v177, 15, v8
	v_add_u32_e32 v8, -8, v5
	v_min_u32_e32 v175, 15, v10
	v_min_u32_e32 v8, 48, v8
	v_or_b32_e32 v10, 32, v124
	v_cmp_lt_u32_e64 s[22:23], v10, v8
	v_sub_u32_e32 v10, v10, v5
	v_sub_u32_e64 v183, v10, -15 clamp
	v_or_b32_e32 v10, 33, v124
	v_cmp_lt_u32_e64 s[24:25], v10, v8
	v_sub_u32_e32 v10, v10, v5
	v_sub_u32_e64 v207, v10, -15 clamp
	v_or_b32_e32 v10, 34, v124
	v_cmp_lt_u32_e64 s[26:27], v10, v8
	v_sub_u32_e32 v10, v10, v5
	s_bfe_u32 s49, s49, 0x30006
	v_sub_u32_e64 v208, v10, -15 clamp
	v_or_b32_e32 v10, 35, v124
	v_lshl_add_u64 v[2:3], s[2:3], 0, v[2:3]
	s_lshl_b32 s64, s49, 7
	v_cmp_lt_u32_e64 s[20:21], v176, v9
	v_add_u32_e32 v9, 16, v8
	v_cmp_lt_u32_e64 s[28:29], v10, v8
	v_sub_u32_e32 v8, v10, v5
	v_lshl_add_u64 v[126:127], v[2:3], 0, s[64:65]
	v_lshrrev_b32_e32 v2, 1, v144
	v_sub_u32_e64 v209, v8, -15 clamp
	v_or_b32_e32 v8, 49, v124
	v_or_b32_e32 v10, 48, v124
	v_and_b32_e32 v2, 24, v2
	v_mov_b32_e32 v3, v1
	v_lshlrev_b32_e32 v0, 3, v6
	v_sub_u32_e32 v210, v10, v5
	v_cmp_lt_u32_e64 s[30:31], v8, v9
	v_cmp_lt_u32_e64 s[34:35], v10, v9
	v_or_b32_e32 v8, 51, v124
	v_or_b32_e32 v10, 50, v124
	s_mul_i32 s50, s49, 0x1d1
	v_lshl_add_u64 v[132:133], s[46:47], 0, v[2:3]
	v_readlane_b32 s46, v254, 19
	v_mul_u32_u24_e32 v118, 0x1200, v114
	v_or_b32_e32 v4, 0x800, v124
	v_or_b32_e32 v6, 0x810, v124
	v_cmp_lt_u32_e64 s[40:41], v8, v9
	v_cmp_lt_u32_e64 s[42:43], v10, v9
	v_lshl_add_u64 v[8:9], s[76:77], 0, v[0:1]
	s_add_i32 s89, s46, s48
	s_lshl_b32 s46, s48, 6
	v_readlane_b32 s47, v254, 21
	v_add_lshl_u32 v2, s50, v7, 2
	v_mov_b32_e32 v119, v1
	v_mul_u32_u24_e32 v120, 0x1200, v5
	v_mov_b32_e32 v121, v1
	v_or_b32_e32 v125, 0x4000, v114
	v_mov_b32_e32 v115, v1
	v_mul_hi_u32_u24_e32 v123, 0x1200, v114
	v_mov_b32_e32 v122, v118
	v_bitop3_b32 v145, v144, 15, v144 bitop3:0xc
	s_and_b64 s[20:21], vcc, s[20:21]
	v_or_b32_e32 v178, 16, v114
	v_add_u32_e32 v179, 8, v114
	v_add_u32_e32 v180, 24, v114
	v_or_b32_e32 v181, 32, v114
	v_add_u32_e32 v182, 40, v114
	v_sub_u32_e32 v211, v10, v5
	s_lshl_b32 s88, s49, 6
	v_lshl_add_u64 v[128:129], v[116:117], 0, s[64:65]
	v_lshl_add_u64 v[130:131], v[8:9], 0, s[64:65]
	s_add_i32 s90, s47, s46
	v_lshl_add_u32 v212, v7, 2, s85
	v_or_b32_e32 v213, 0xffffffc0, v7
	v_lshl_add_u64 v[134:135], s[44:45], 0, v[2:3]
	v_lshlrev_b32_e32 v136, 1, v0
	v_lshlrev_b32_e32 v146, 1, v4
	v_lshlrev_b32_e32 v148, 1, v6
	s_branch .LBB0_382
	s_nop 0
	s_nop 0
	s_nop 0
	s_nop 0
	s_nop 0
	s_nop 0
	s_nop 0
	s_nop 0
	s_nop 0
	s_nop 0
	s_nop 0
; __device__ __forceinline__ unsigned pk2(float lo, float hi) { unsigned r; asm("v_cvt_pk_bf16_f32 %0, %1, %2" : "=v"(r) : "v"(lo), "v"(hi)); return r; }
; __device__ __forceinline__ void attn_finish(AttnState& st, bf16_t* yrow  , int g) {
;     float l = st.l; l += __shfl_xor(l, 16); l += __shfl_xor(l, 32);
;     const float inv = 1.0f / l;
; #pragma unroll
;     for (int dt = 0; dt < 4; ++dt) { const f32x4 o = st.o[dt] * inv; u32x2 w; w.x = pk2(o[0], o[1]); w.y = pk2(o[2], o[3]); *(u32x2*)(yrow + dt * 16 + 4 * g) = w; }
; }
; __device__ __forceinline__ void na_task(const P& p, int task, int lane, float* ldsw  ) {
;     ...
;         for (int j = 0; j < 4; ++j) attn_finish(st[j], Y + (qrow0 + j * 16) * 1024 + h * 64, g);
.LBB0_380:
	v_cmp_lt_i32_e32 vcc, v188, v186
	s_nop 1
	v_cndmask_b32_e32 v0, v185, v188, vcc
	v_lshlrev_b32_e32 v70, 2, v0
	ds_bpermute_b32 v0, v70, v215
	v_cmp_lt_i32_e32 vcc, v187, v186
	s_waitcnt lgkmcnt(0)
	v_add_f32_e32 v0, v215, v0
	v_cndmask_b32_e32 v68, v185, v187, vcc
	v_lshlrev_b32_e32 v71, 2, v68
	ds_bpermute_b32 v68, v71, v0
	s_waitcnt lgkmcnt(0)
	v_add_f32_e32 v0, v0, v68
	v_div_scale_f32 v72, s[44:45], v0, v0, 1.0
	v_rcp_f32_e32 v73, v72
	v_div_scale_f32 v74, vcc, 1.0, v0, 1.0
	v_lshl_add_u64 v[68:69], v[130:131], 0, v[156:157]
	v_fma_f32 v75, -v72, v73, 1.0
	v_fmac_f32_e32 v73, v75, v73
	v_mul_f32_e32 v75, v74, v73
	v_fma_f32 v76, -v72, v75, v74
	v_fmac_f32_e32 v75, v76, v73
	v_fma_f32 v72, -v72, v75, v74
	v_div_fmas_f32 v72, v72, v73, v75
	v_div_fixup_f32 v0, v72, v0, 1.0
	v_pk_mul_f32 v[60:61], v[60:61], v[0:1] op_sel_hi:[1,0]
	v_pk_mul_f32 v[58:59], v[58:59], v[0:1] op_sel_hi:[1,0]
	v_pk_mul_f32 v[54:55], v[54:55], v[0:1] op_sel_hi:[1,0]
	v_cvt_pk_bf16_f32 v58, v58, v59
	v_cvt_pk_bf16_f32 v59, v60, v61
	ds_bpermute_b32 v60, v70, v67
	global_store_dwordx2 v[68:69], v[58:59], off offset:32
	v_pk_mul_f32 v[64:65], v[64:65], v[0:1] op_sel_hi:[1,0]
	v_pk_mul_f32 v[62:63], v[62:63], v[0:1] op_sel_hi:[1,0]
	v_pk_mul_f32 v[56:57], v[56:57], v[0:1] op_sel_hi:[1,0]
	s_waitcnt lgkmcnt(0)
	v_add_f32_e32 v58, v67, v60
	ds_bpermute_b32 v59, v71, v58
	v_cvt_pk_bf16_f32 v54, v54, v55
	v_pk_mul_f32 v[48:49], v[48:49], v[0:1] op_sel_hi:[1,0]
	v_pk_mul_f32 v[46:47], v[46:47], v[0:1] op_sel_hi:[1,0]
	v_cvt_pk_bf16_f32 v55, v56, v57
	s_waitcnt lgkmcnt(0)
	v_add_f32_e32 v0, v58, v59
	global_store_dwordx2 v[68:69], v[54:55], off offset:64
	v_div_scale_f32 v54, s[44:45], v0, v0, 1.0
	v_rcp_f32_e32 v55, v54
	v_cvt_pk_bf16_f32 v46, v46, v47
	v_cvt_pk_bf16_f32 v47, v48, v49
	global_store_dwordx2 v[68:69], v[46:47], off offset:96
	v_fma_f32 v46, -v54, v55, 1.0
	v_fmac_f32_e32 v55, v46, v55
	v_div_scale_f32 v46, vcc, 1.0, v0, 1.0
	v_mul_f32_e32 v47, v46, v55
	v_fma_f32 v48, -v54, v47, v46
	v_fmac_f32_e32 v47, v48, v55
	v_fma_f32 v46, -v54, v47, v46
	v_div_fmas_f32 v46, v46, v55, v47
	v_div_fixup_f32 v0, v46, v0, 1.0
	v_pk_mul_f32 v[44:45], v[44:45], v[0:1] op_sel_hi:[1,0]
	v_pk_mul_f32 v[42:43], v[42:43], v[0:1] op_sel_hi:[1,0]
	v_lshl_add_u64 v[46:47], v[130:131], 0, v[154:155]
	v_cvt_pk_bf16_f32 v42, v42, v43
	v_cvt_pk_bf16_f32 v43, v44, v45
	ds_bpermute_b32 v44, v70, v66
	global_store_dwordx2 v[46:47], v[42:43], off offset:32
	v_pk_mul_f32 v[38:39], v[38:39], v[0:1] op_sel_hi:[1,0]
	v_pk_mul_f32 v[48:49], v[52:53], v[0:1] op_sel_hi:[1,0]
	v_pk_mul_f32 v[50:51], v[50:51], v[0:1] op_sel_hi:[1,0]
	s_waitcnt lgkmcnt(0)
	v_add_f32_e32 v42, v66, v44
	ds_bpermute_b32 v43, v71, v42
	v_pk_mul_f32 v[40:41], v[40:41], v[0:1] op_sel_hi:[1,0]
	v_cvt_pk_bf16_f32 v38, v38, v39
	v_pk_mul_f32 v[36:37], v[36:37], v[0:1] op_sel_hi:[1,0]
	v_pk_mul_f32 v[34:35], v[34:35], v[0:1] op_sel_hi:[1,0]
	s_waitcnt lgkmcnt(0)
	v_add_f32_e32 v0, v42, v43
	v_cvt_pk_bf16_f32 v39, v40, v41
	global_store_dwordx2 v[46:47], v[38:39], off offset:64
	v_div_scale_f32 v38, s[44:45], v0, v0, 1.0
	v_rcp_f32_e32 v39, v38
	v_cvt_pk_bf16_f32 v34, v34, v35
	v_cvt_pk_bf16_f32 v35, v36, v37
	global_store_dwordx2 v[46:47], v[34:35], off offset:96
	v_fma_f32 v34, -v38, v39, 1.0
	v_fmac_f32_e32 v39, v34, v39
	v_div_scale_f32 v34, vcc, 1.0, v0, 1.0
	v_mul_f32_e32 v35, v34, v39
	v_fma_f32 v36, -v38, v35, v34
	v_fmac_f32_e32 v35, v36, v39
	v_fma_f32 v34, -v38, v35, v34
	v_div_fmas_f32 v34, v34, v39, v35
	v_div_fixup_f32 v0, v34, v0, 1.0
	v_pk_mul_f32 v[28:29], v[28:29], v[0:1] op_sel_hi:[1,0]
	v_pk_mul_f32 v[26:27], v[26:27], v[0:1] op_sel_hi:[1,0]
	v_lshl_add_u64 v[34:35], v[130:131], 0, v[152:153]
	v_cvt_pk_bf16_f32 v26, v26, v27
	v_cvt_pk_bf16_f32 v27, v28, v29
	ds_bpermute_b32 v28, v70, v137
	global_store_dwordx2 v[34:35], v[26:27], off offset:32
	v_pk_mul_f32 v[22:23], v[22:23], v[0:1] op_sel_hi:[1,0]
	v_pk_mul_f32 v[32:33], v[32:33], v[0:1] op_sel_hi:[1,0]
	v_pk_mul_f32 v[30:31], v[30:31], v[0:1] op_sel_hi:[1,0]
	s_waitcnt lgkmcnt(0)
	v_add_f32_e32 v26, v137, v28
	ds_bpermute_b32 v27, v71, v26
	v_pk_mul_f32 v[24:25], v[24:25], v[0:1] op_sel_hi:[1,0]
	v_cvt_pk_bf16_f32 v22, v22, v23
	v_pk_mul_f32 v[20:21], v[20:21], v[0:1] op_sel_hi:[1,0]
	v_pk_mul_f32 v[18:19], v[18:19], v[0:1] op_sel_hi:[1,0]
	s_waitcnt lgkmcnt(0)
	v_add_f32_e32 v0, v26, v27
	v_cvt_pk_bf16_f32 v23, v24, v25
	global_store_dwordx2 v[34:35], v[22:23], off offset:64
	v_div_scale_f32 v22, s[44:45], v0, v0, 1.0
	v_rcp_f32_e32 v23, v22
	v_cvt_pk_bf16_f32 v18, v18, v19
	v_cvt_pk_bf16_f32 v19, v20, v21
	global_store_dwordx2 v[34:35], v[18:19], off offset:96
	v_fma_f32 v18, -v22, v23, 1.0
	v_fmac_f32_e32 v23, v18, v23
	v_div_scale_f32 v18, vcc, 1.0, v0, 1.0
	v_mul_f32_e32 v19, v18, v23
	v_fma_f32 v20, -v22, v19, v18
	v_fmac_f32_e32 v19, v20, v23
	v_fma_f32 v18, -v22, v19, v18
	v_div_fmas_f32 v18, v18, v23, v19
	v_div_fixup_f32 v0, v18, v0, 1.0
	v_lshl_add_u64 v[18:19], v[130:131], 0, v[150:151]
	v_pk_mul_f32 v[14:15], v[14:15], v[0:1] op_sel_hi:[1,0]
	v_pk_mul_f32 v[10:11], v[10:11], v[0:1] op_sel_hi:[1,0]
	v_pk_mul_f32 v[6:7], v[6:7], v[0:1] op_sel_hi:[1,0]
	v_pk_mul_f32 v[2:3], v[2:3], v[0:1] op_sel_hi:[1,0]
	v_cvt_pk_bf16_f32 v62, v62, v63
	v_cvt_pk_bf16_f32 v63, v64, v65
	global_store_dwordx2 v[68:69], v[62:63], off
	v_cvt_pk_bf16_f32 v50, v50, v51
	v_cvt_pk_bf16_f32 v51, v48, v49
	global_store_dwordx2 v[46:47], v[50:51], off
	v_cvt_pk_bf16_f32 v30, v30, v31
	v_cvt_pk_bf16_f32 v31, v32, v33
	global_store_dwordx2 v[34:35], v[30:31], off
	v_pk_mul_f32 v[16:17], v[16:17], v[0:1] op_sel_hi:[1,0]
	v_cvt_pk_bf16_f32 v14, v14, v15
	v_pk_mul_f32 v[12:13], v[12:13], v[0:1] op_sel_hi:[1,0]
	v_cvt_pk_bf16_f32 v15, v16, v17
	global_store_dwordx2 v[18:19], v[14:15], off
	v_cvt_pk_bf16_f32 v10, v10, v11
	v_cvt_pk_bf16_f32 v11, v12, v13
	global_store_dwordx2 v[18:19], v[10:11], off offset:32
	v_pk_mul_f32 v[8:9], v[8:9], v[0:1] op_sel_hi:[1,0]
	v_cvt_pk_bf16_f32 v6, v6, v7
	v_pk_mul_f32 v[4:5], v[4:5], v[0:1] op_sel_hi:[1,0]
	v_cvt_pk_bf16_f32 v7, v8, v9
	global_store_dwordx2 v[18:19], v[6:7], off offset:64
	v_cvt_pk_bf16_f32 v2, v2, v3
	v_cvt_pk_bf16_f32 v3, v4, v5

; #define PG8_WAIT_V(n) asm volatile("s_waitcnt vmcnt(" #n ")" ::: "memory")
; #define PG8_BAR __builtin_amdgcn_s_barrier()
; __device__ __forceinline__ unsigned xb_add(unsigned* p, unsigned v) { return __hip_atomic_fetch_add(p, v, __ATOMIC_RELAXED, __HIP_MEMORY_SCOPE_AGENT); }
; template <class Epi, class Sched, bool ALIGN_EPI = false, bool SP2 = false>
; __device__ __forceinline__ void gemm_phase(PG8_LAS unsigned char* lds, const Gemm g, const Sched& S, const Epi& E) {
;     ...
;     PG8_WAIT_V(0);
;     if constexpr (!ALIGN_EPI) { if (wr == 0) PG8_BAR; }
;     PG8_BAR;
; __device__ __forceinline__ void xcd_barrier(const XcdBarrier& b) {
;     asm volatile("s_waitcnt vmcnt(0)" ::: "memory");
;     __syncthreads();
;     if (threadIdx.x == 0) {
;         unsigned* bar = b.bar;
;         __builtin_amdgcn_s_waitcnt(0);
;         unsigned nloc = b.st[0], nx = b.st[1];
;         if (nloc == 0u) { xcd_barrier_complete(bar, b.x, nloc, nx); b.st[0] = nloc; b.st[1] = nx; }
;         const unsigned old = xb_add(&bar[XB_XSUB(b.x)], 1u);
;         const unsigned gen = old / nloc;
.LBB0_521:
	s_setprio 0
	s_waitcnt vmcnt(0)
	s_waitcnt lgkmcnt(0)
	s_barrier
	s_mov_b64 s[2:3], exec
	v_readlane_b32 s6, v253, 0
	v_readlane_b32 s7, v253, 1
	s_and_b64 s[6:7], s[2:3], s[6:7]
	s_mov_b64 exec, s[6:7]
	s_cbranch_execz .LBB0_569
	v_mov_b32_e32 v0, s96
	s_waitcnt vmcnt(0) expcnt(0) lgkmcnt(0)
	ds_read_b32 v3, v0
	v_readlane_b32 s1, v254, 42
	s_waitcnt lgkmcnt(0)
	v_cmp_ne_u32_e32 vcc, 0, v3
	v_mov_b32_e32 v0, s1
	ds_read_b32 v2, v0
	s_cbranch_vccnz .LBB0_537
	s_mov_b32 s12, 1
	s_branch .LBB0_525

; __device__ __forceinline__ void dn_prep_task(const P& p, int task, unsigned char* sm, int tid) {
;     const int h = task & 3, bc = task >> 2, ck = bc % 36, b = bc / 36;
;     const int m0 = ck < 4 ? MLAT + b * TCTX + ck * 64 : b * TLAT + (ck - 4) * 64;
;     const int wave = tid >> 6, lane = tid & 63, dir = tid >> 8, t2 = tid & 255;
;     bf16_t* kn_s = (bf16_t*)sm;
;     bf16_t* qn_s = kn_s + 64 * 136;
;     float* KK = (float*)(sm + 34816);
;     float* QK = KK + 64 * 65;
;     float* gc_s = (float*)(sm + 68096);
;     float* be_s = gc_s + 128;
;     float* Ls = be_s + 128;
;     bf16_t* v_s = (bf16_t*)(sm + 101888);
;     {
;         const int r = tid >> 3, c16 = (tid & 7) * 16;
;         const bf16_t* ks = (const bf16_t*)(p.ws + WS_KN) + (size_t)(m0 + r) * 512 + h * 128 + c16;
;         const bf16_t* qs = (const bf16_t*)(p.ws + WS_QN) + (size_t)(m0 + r) * 512 + h * 128 + c16;
;         *(u32x4*)(kn_s + r * 136 + c16) = *(const u32x4*)ks; *(u32x4*)(kn_s + r * 136 + c16 + 8) = *(const u32x4*)(ks + 8);
;         *(u32x4*)(qn_s + r * 136 + c16) = *(const u32x4*)qs; *(u32x4*)(qn_s + r * 136 + c16 + 8) = *(const u32x4*)(qs + 8);
;         const bf16_t* vs = (const bf16_t*)(p.ws + WS_VV) + (size_t)(m0 + r) * 512 + h * 128 + c16;
;         *(u32x4*)(v_s + r * 136 + c16) = *(const u32x4*)vs; *(u32x4*)(v_s + r * 136 + c16 + 8) = *(const u32x4*)(vs + 8);
;     }
;     if (t2 < 64) {
;         const int tok = dir ? 63 - t2 : t2;
;         const float* gb = (const float*)(p.ws + WS_GB) + (size_t)(m0 + tok) * 16;
;         float gv = gb[dir * 4 + h]; const float bv = gb[8 + dir * 4 + h];
; #pragma unroll
;         for (int o = 1; o < 64; o <<= 1) { const float v = __shfl_up(gv, o); if (lane >= o) gv += v; }
;         gc_s[dir * 64 + t2] = gv; be_s[dir * 64 + t2] = bv;
;     }
;     __syncthreads();
;     {
;         const int which = wave >> 2, it = wave & 3, fr = lane & 15, g = lane >> 4;
;         const bf16_t* As = which ? qn_s : kn_s; float* Out = which ? QK : KK;
;         bf16x8 a[4];
; #pragma unroll
;         for (int ks = 0; ks < 4; ++ks) a[ks] = *(const bf16x8*)(As + (it * 16 + fr) * 136 + ks * 32 + g * 8);
; #pragma unroll
;         for (int jt = 0; jt < 4; ++jt) {
;             f32x4 acc = {0.f, 0.f, 0.f, 0.f};
; #pragma unroll
.LBB0_569:
	s_or_b64 exec, exec, s[2:3]
	v_readlane_b32 s2, v253, 62
	v_mov_b32_e32 v0, v1
	v_readlane_b32 s3, v253, 63
	s_waitcnt lgkmcnt(0)
	s_barrier
	s_andn2_b64 vcc, exec, s[2:3]
	v_readfirstlane_b32 s2, v0
	s_cbranch_vccnz .LBB0_665
	v_readlane_b32 s6, v254, 54
	v_readlane_b32 s7, v254, 55
	s_load_dwordx2 s[44:45], s[6:7], s2 offset:0xa8
	s_movk_i32 s1, 0xff
	v_cmp_lt_u32_e64 s[6:7], s1, v144
	v_lshlrev_b32_e32 v88, 4, v144
	v_ashrrev_i32_e32 v9, 3, v144
	s_waitcnt lgkmcnt(0)
	s_add_u32 s46, s44, 0x11300000
	s_addc_u32 s47, s45, 0
	s_add_u32 s48, s44, 0x10100000
	s_addc_u32 s49, s45, 0
	s_add_u32 s28, s44, 0x12500000
	s_addc_u32 s29, s45, 0
	v_writelane_b32 v255, s6, 10
	v_and_b32_e32 v2, 0x70, v88
	s_movk_i32 s3, 0x110
	v_writelane_b32 v255, s7, 11
	s_add_u32 s6, s44, 0xff00000
	v_mul_lo_u32 v0, v9, s3
	v_lshlrev_b32_e32 v3, 1, v2
	v_readlane_b32 s42, v254, 43
	s_addc_u32 s7, s45, 0
	v_add3_u32 v89, 0, v0, v3
	v_add3_u32 v90, s42, v0, v3
	v_and_b32_e32 v0, 63, v144
	v_writelane_b32 v255, s6, 14
	v_and_b32_e32 v8, 0xff, v144
	s_movk_i32 s2, 0x100
	v_writelane_b32 v255, s7, 15
	v_cmp_eq_u32_e64 s[6:7], 0, v0
	v_cmp_gt_u32_e32 vcc, s2, v144
	v_sub_u32_e32 v3, 63, v8
	v_writelane_b32 v255, s6, 16
	v_cndmask_b32_e32 v91, v3, v8, vcc
	v_and_b32_e32 v3, 0xffffff00, v144
	v_writelane_b32 v255, s7, 17
	v_cmp_gt_u32_e64 s[6:7], 2, v0
	v_lshlrev_b32_e32 v6, 2, v8
	v_readlane_b32 s1, v254, 44
	v_writelane_b32 v255, s6, 18
	v_readlane_b32 s50, v254, 45
	v_readlane_b32 s2, v254, 46
	v_writelane_b32 v255, s7, 19
	v_cmp_gt_u32_e64 s[6:7], 4, v0
	s_waitcnt vmcnt(1)
	v_mov_b32_e32 v5, s2
	v_lshrrev_b32_e32 v7, 2, v144
	v_writelane_b32 v255, s6, 20
	v_cndmask_b32_e64 v5, v5, 0, vcc
	v_readlane_b32 s2, v254, 48
	v_writelane_b32 v255, s7, 21
	v_cmp_gt_u32_e64 s[6:7], 8, v0
	v_bfe_u32 v22, v144, 2, 6
	v_ashrrev_i32_e32 v4, 8, v144
	v_writelane_b32 v255, s6, 22
	v_bitop3_b32 v14, v88, 62, 48 bitop3:0x6c
	v_bitop3_b32 v15, v88, 61, 48 bitop3:0x6c
	v_writelane_b32 v255, s7, 23
	v_cmp_gt_u32_e64 s[6:7], 16, v0
	v_bitop3_b32 v13, v88, 63, 48 bitop3:0x6c
	v_bitop3_b32 v20, v88, 60, 48 bitop3:0x6c
	v_writelane_b32 v255, s6, 24
	v_bitop3_b32 v23, v88, 59, 48 bitop3:0x6c
	v_bitop3_b32 v31, v88, 58, 48 bitop3:0x6c
	v_writelane_b32 v255, s7, 25
	v_cmp_gt_u32_e64 s[6:7], 32, v0
	v_or_b32_e32 v0, v3, v6
	v_add_u32_e32 v92, s1, v0
	v_add_u32_e32 v93, s50, v0
	v_and_b32_e32 v0, 15, v144
	v_and_or_b32 v11, v7, 48, v0
	v_mad_u32_u24 v24, v11, s3, v5
	v_mov_b32_e32 v5, s2
	v_readlane_b32 s2, v254, 47
	v_and_b32_e32 v7, 60, v7
	v_mul_u32_u24_e32 v29, 0x104, v7
	v_mov_b32_e32 v11, s2
	v_cndmask_b32_e32 v5, v5, v11, vcc
	v_readlane_b32 s2, v254, 49
	v_xor_b32_e32 v7, 63, v22
	v_writelane_b32 v255, s6, 26
	v_lshl_add_u32 v27, v0, 2, v5
	v_mul_u32_u24_e32 v28, 0x110, v0
	v_lshl_add_u32 v94, v4, 14, s2
	v_and_b32_e32 v0, 48, v88
	v_cndmask_b32_e32 v7, v7, v22, vcc
	s_movk_i32 s2, 0x104
	v_writelane_b32 v255, s7, 27
	v_lshlrev_b32_e32 v11, 8, v22
	v_mad_u32_u24 v12, v7, s2, 0
	v_cmp_gt_u32_e64 s[2:3], v22, v0
	v_lshlrev_b32_e32 v17, 2, v0
	v_add3_u32 v96, v94, v11, v17
	v_writelane_b32 v255, s2, 8
	v_or_b32_e32 v11, 1, v0
	v_or_b32_e32 v21, 4, v0
	v_writelane_b32 v255, s3, 9
	v_cmp_gt_u32_e64 s[2:3], v22, v11
	v_cndmask_b32_e32 v11, v14, v11, vcc
	v_or_b32_e32 v14, 2, v0
	v_writelane_b32 v255, s2, 28
	v_or_b32_e32 v30, 5, v0
	v_or_b32_e32 v32, 6, v0
	v_writelane_b32 v255, s3, 29
	v_cmp_gt_u32_e64 s[2:3], v22, v14
	v_cndmask_b32_e32 v14, v15, v14, vcc
	v_or_b32_e32 v15, 3, v0
	v_writelane_b32 v255, s2, 30
	v_or_b32_e32 v34, 7, v0
	v_or_b32_e32 v36, 8, v0
	v_writelane_b32 v255, s3, 31
	v_cmp_gt_u32_e64 s[2:3], v22, v15
	v_or_b32_e32 v38, 9, v0
	v_or_b32_e32 v40, 10, v0
	v_writelane_b32 v255, s2, 32
	v_or_b32_e32 v42, 11, v0
	v_or_b32_e32 v44, 12, v0
	v_writelane_b32 v255, s3, 33
	v_cmp_gt_u32_e64 s[2:3], v22, v21
	v_or_b32_e32 v46, 13, v0
	v_or_b32_e32 v48, 14, v0
	v_writelane_b32 v255, s2, 34
	v_bitop3_b32 v33, v88, 57, 48 bitop3:0x6c
	v_bitop3_b32 v35, v88, 56, 48 bitop3:0x6c
	v_writelane_b32 v255, s3, 35
	v_cmp_gt_u32_e64 s[2:3], v22, v30
	v_bitop3_b32 v37, v88, 55, 48 bitop3:0x6c
	v_bitop3_b32 v39, v88, 54, 48 bitop3:0x6c
	v_writelane_b32 v255, s2, 36
	v_bitop3_b32 v41, v88, 53, 48 bitop3:0x6c
	v_bitop3_b32 v43, v88, 52, 48 bitop3:0x6c
	v_writelane_b32 v255, s3, 37
	v_cmp_gt_u32_e64 s[2:3], v22, v32
	v_bitop3_b32 v45, v88, 51, 48 bitop3:0x6c
	v_bitop3_b32 v47, v88, 50, 48 bitop3:0x6c
	v_writelane_b32 v255, s2, 38
	v_bitop3_b32 v49, v88, 49, 48 bitop3:0x6c
	v_or_b32_e32 v50, 15, v0
	v_writelane_b32 v255, s3, 39
	v_cmp_gt_u32_e64 s[2:3], v22, v34
	v_bitop3_b32 v51, v88, 48, v88 bitop3:0xc
	v_cndmask_b32_e32 v13, v13, v0, vcc
	v_writelane_b32 v255, s2, 40
	v_cndmask_b32_e32 v15, v20, v15, vcc
	v_cndmask_b32_e32 v21, v23, v21, vcc
	v_writelane_b32 v255, s3, 41
	v_cmp_gt_u32_e64 s[2:3], v22, v36
	v_cndmask_b32_e32 v30, v31, v30, vcc
	v_cndmask_b32_e32 v32, v33, v32, vcc
	v_writelane_b32 v255, s2, 42
	v_cndmask_b32_e32 v34, v35, v34, vcc
	v_cndmask_b32_e32 v36, v37, v36, vcc
	v_writelane_b32 v255, s3, 43
	v_cmp_gt_u32_e64 s[2:3], v22, v38
	v_cndmask_b32_e32 v38, v39, v38, vcc
	v_cmp_gt_u32_e64 s[86:87], v22, v50
	v_writelane_b32 v255, s2, 44
	v_cndmask_b32_e32 v50, v51, v50, vcc
	v_lshlrev_b32_e32 v16, 2, v13
	v_writelane_b32 v255, s3, 45
	v_cmp_gt_u32_e64 s[2:3], v22, v40
	v_cndmask_b32_e32 v40, v41, v40, vcc
; __device__ __forceinline__ void dn_prep_task(const P& p, int task, unsigned char* sm, int tid) {
;     const int h = task & 3, bc = task >> 2, ck = bc % 36, b = bc / 36;
;     const int m0 = ck < 4 ? MLAT + b * TCTX + ck * 64 : b * TLAT + (ck - 4) * 64;
;     const int wave = tid >> 6, lane = tid & 63, dir = tid >> 8, t2 = tid & 255;
;     bf16_t* kn_s = (bf16_t*)sm;
;     bf16_t* qn_s = kn_s + 64 * 136;
;     float* KK = (float*)(sm + 34816);
;     float* QK = KK + 64 * 65;
;     float* gc_s = (float*)(sm + 68096);
;     float* be_s = gc_s + 128;
;     float* Ls = be_s + 128;
;     bf16_t* v_s = (bf16_t*)(sm + 101888);
;     {
;         const int r = tid >> 3, c16 = (tid & 7) * 16;
;         const bf16_t* ks = (const bf16_t*)(p.ws + WS_KN) + (size_t)(m0 + r) * 512 + h * 128 + c16;
;         const bf16_t* qs = (const bf16_t*)(p.ws + WS_QN) + (size_t)(m0 + r) * 512 + h * 128 + c16;
;         *(u32x4*)(kn_s + r * 136 + c16) = *(const u32x4*)ks; *(u32x4*)(kn_s + r * 136 + c16 + 8) = *(const u32x4*)(ks + 8);
;         *(u32x4*)(qn_s + r * 136 + c16) = *(const u32x4*)qs; *(u32x4*)(qn_s + r * 136 + c16 + 8) = *(const u32x4*)(qs + 8);
;         const bf16_t* vs = (const bf16_t*)(p.ws + WS_VV) + (size_t)(m0 + r) * 512 + h * 128 + c16;
;         *(u32x4*)(v_s + r * 136 + c16) = *(const u32x4*)vs; *(u32x4*)(v_s + r * 136 + c16 + 8) = *(const u32x4*)(vs + 8);
;     }
;     if (t2 < 64) {
;         const int tok = dir ? 63 - t2 : t2;
;         const float* gb = (const float*)(p.ws + WS_GB) + (size_t)(m0 + tok) * 16;
;         float gv = gb[dir * 4 + h]; const float bv = gb[8 + dir * 4 + h];
; #pragma unroll
;         for (int o = 1; o < 64; o <<= 1) { const float v = __shfl_up(gv, o); if (lane >= o) gv += v; }
;         gc_s[dir * 64 + t2] = gv; be_s[dir * 64 + t2] = bv;
;     }
;     __syncthreads();
;     {
;         const int which = wave >> 2, it = wave & 3, fr = lane & 15, g = lane >> 4;
;         const bf16_t* As = which ? qn_s : kn_s; float* Out = which ? QK : KK;
;         bf16x8 a[4];
; #pragma unroll
;         for (int ks = 0; ks < 4; ++ks) a[ks] = *(const bf16x8*)(As + (it * 16 + fr) * 136 + ks * 32 + g * 8);
; #pragma unroll
;         for (int jt = 0; jt < 4; ++jt) {
;             f32x4 acc = {0.f, 0.f, 0.f, 0.f};
; #pragma unroll
	v_lshlrev_b32_e32 v18, 2, v11
	v_writelane_b32 v255, s2, 46
	v_lshlrev_b32_e32 v19, 2, v14
	v_lshlrev_b32_e32 v20, 2, v15
	v_writelane_b32 v255, s3, 47
	v_cmp_gt_u32_e64 s[2:3], v22, v42
	v_cndmask_b32_e32 v42, v43, v42, vcc
	v_lshlrev_b32_e32 v23, 2, v21
	v_writelane_b32 v255, s2, 48
	v_lshlrev_b32_e32 v31, 2, v30
	v_lshlrev_b32_e32 v33, 2, v32
	v_writelane_b32 v255, s3, 49
	v_cmp_gt_u32_e64 s[2:3], v22, v44
	v_cndmask_b32_e32 v44, v45, v44, vcc
	v_lshlrev_b32_e32 v35, 2, v34
	v_writelane_b32 v255, s2, 50
	v_lshlrev_b32_e32 v37, 2, v36
	v_lshlrev_b32_e32 v39, 2, v38
	v_writelane_b32 v255, s3, 51
	v_cmp_gt_u32_e64 s[2:3], v22, v46
	v_cndmask_b32_e32 v46, v47, v46, vcc
	v_lshlrev_b32_e32 v41, 2, v40
	v_writelane_b32 v255, s2, 52
	v_lshlrev_b32_e32 v43, 2, v42
	v_lshlrev_b32_e32 v45, 2, v44
	v_writelane_b32 v255, s3, 53
	v_cmp_gt_u32_e64 s[2:3], v22, v48
	v_cndmask_b32_e32 v48, v49, v48, vcc
	v_lshlrev_b32_e32 v47, 2, v46
	v_writelane_b32 v255, s2, 54
	v_lshlrev_b32_e32 v49, 2, v48
	v_lshlrev_b32_e32 v51, 2, v50
	v_writelane_b32 v255, s3, 55
	v_cmp_eq_u32_e64 s[2:3], 0, v8
	v_cmp_ge_u32_e64 s[8:9], v7, v32
	v_mul_u32_u24_e32 v32, 0x110, v0
	v_writelane_b32 v255, s2, 56
	v_lshlrev_b32_e32 v0, 1, v8
	v_readlane_b32 s76, v254, 28
	v_writelane_b32 v255, s3, 57
	s_movk_i32 s2, 0x80
	v_ashrrev_i32_e32 v5, 31, v4
	v_add_u32_e32 v95, v12, v16
	v_add_u32_e32 v97, v12, v18
	v_add_u32_e32 v98, v12, v19
	v_add_u32_e32 v99, v12, v20
	v_add_u32_e32 v100, v12, v23
	v_add_u32_e32 v101, v12, v31
	v_add_u32_e32 v102, v12, v33
	v_add_u32_e32 v103, v12, v35
	v_add_u32_e32 v104, v12, v37
	v_add_u32_e32 v105, v12, v39
	v_add_u32_e32 v106, v12, v41
	v_add_u32_e32 v107, v12, v43
	v_add_u32_e32 v108, v12, v45
	v_add_u32_e32 v109, v12, v47
	v_add_u32_e32 v110, v12, v49
	v_add_u32_e32 v111, v12, v51
	v_mul_u32_u24_e32 v12, 0x104, v22
	v_cmp_gt_u32_e64 s[30:31], s2, v8
	s_movk_i32 s2, 0x7f
	v_add_u32_e32 v113, 0, v0
	v_add_u32_e32 v115, s42, v0
	v_add_u32_e32 v116, v94, v0
	v_lshlrev_b32_e32 v0, 6, v144
	v_add_u32_e32 v119, s1, v3
	v_readlane_b32 s77, v254, 29
	v_readlane_b32 s72, v254, 38
	v_cmp_ge_u32_e64 s[88:89], v7, v13
	v_add3_u32 v112, 0, v12, v17
	v_cmp_ge_u32_e64 s[90:91], v7, v11
	v_cmp_ge_u32_e64 s[84:85], v7, v21
	v_ashrrev_i32_e32 v11, 2, v144
	v_cmp_lt_u32_e64 s[34:35], s2, v8
	v_add_u32_e32 v128, v119, v20
	v_lshl_add_u64 v[12:13], v[0:1], 1, s[76:77]
	v_and_b32_e32 v0, 3, v144
	v_readlane_b32 s2, v254, 32
	v_lshlrev_b64 v[20:21], 10, v[4:5]
	v_readlane_b32 s73, v254, 39
	v_lshlrev_b32_e32 v10, 2, v4
	v_cmp_ge_u32_e64 s[92:93], v7, v14
	v_cmp_ge_u32_e64 s[94:95], v7, v15
	v_cmp_ge_u32_e64 s[6:7], v7, v30
	v_cmp_ge_u32_e64 s[10:11], v7, v34
	v_cmp_ge_u32_e64 s[12:13], v7, v36
	v_cmp_ge_u32_e64 s[14:15], v7, v38
	v_cmp_ge_u32_e64 s[16:17], v7, v40
	v_cmp_ge_u32_e64 s[18:19], v7, v42
	v_cmp_ge_u32_e64 s[20:21], v7, v44
	v_cmp_ge_u32_e64 s[22:23], v7, v46
	v_cmp_ge_u32_e64 s[24:25], v7, v48
	v_cmp_ge_u32_e64 s[26:27], v7, v50
	v_lshlrev_b32_e32 v14, 6, v11
	v_lshl_add_u32 v124, v7, 2, v119
	v_add_u32_e32 v126, v119, v18
	v_add_u32_e32 v127, v119, v19
	v_lshlrev_b32_e32 v0, 5, v0
	v_readlane_b32 s3, v254, 33
	v_lshl_add_u64 v[18:19], s[72:73], 0, v[20:21]
	v_mov_b32_e32 v7, v1
	v_lshlrev_b64 v[4:5], 13, v[4:5]
	v_and_b32_e32 v25, 48, v144
	v_ashrrev_i32_e32 v15, 31, v14
	v_add_u32_e32 v123, v119, v17
	v_add_u32_e32 v125, v119, v16
	v_lshl_add_u64 v[16:17], s[2:3], 0, v[0:1]
	v_lshl_add_u64 v[18:19], v[18:19], 0, v[6:7]
	v_readlane_b32 s72, v254, 40
	v_lshl_add_u64 v[4:5], s[2:3], 0, v[4:5]
	v_lshlrev_b32_e32 v6, 7, v22
	v_add_u32_e32 v26, 0, v25
	v_lshl_add_u32 v30, v11, 1, 0
	s_add_u32 s42, s44, 0x7f00000
	v_add_u32_e32 v120, s50, v3
	v_and_b32_e32 v3, 0xfc, v144
	v_lshl_add_u64 v[14:15], v[14:15], 1, v[16:17]
	v_lshlrev_b32_e32 v16, 7, v8
	v_mov_b32_e32 v17, v1
	v_readlane_b32 s73, v254, 41
	v_lshl_add_u64 v[4:5], v[4:5], 0, v[6:7]
	v_cmp_gt_u32_e64 s[40:41], 64, v8
	v_add_u32_e32 v114, 0xffffff00, v113
	v_add_u32_e32 v117, 0xffffff00, v116
	s_addc_u32 s43, s45, 0
	v_lshlrev_b32_e32 v118, 4, v8
	v_add_u32_e32 v121, v119, v3
	v_add_u32_e32 v122, v120, v3
	v_add_u32_e32 v129, v119, v23
	v_add_u32_e32 v130, v119, v31
	v_add_u32_e32 v131, v119, v33
	v_add_u32_e32 v132, v119, v35
	v_add_u32_e32 v133, v119, v37
	v_add_u32_e32 v134, v119, v39
	v_add_u32_e32 v135, v119, v41
	v_add_u32_e32 v136, v119, v43
	v_add_u32_e32 v137, v119, v45
	v_add_u32_e32 v143, v119, v47
	v_add_u32_e32 v145, v119, v49
	v_add_u32_e32 v146, v119, v51
	v_lshl_add_u32 v147, v91, 2, v119
	v_ashrrev_i32_e32 v11, 31, v10
	v_lshl_add_u64 v[16:17], s[76:77], 0, v[16:17]
	v_lshl_add_u64 v[20:21], s[72:73], 0, v[20:21]
	v_lshl_add_u64 v[22:23], v[4:5], 0, v[0:1]
	v_lshlrev_b32_e32 v0, 1, v2
	v_add_u32_e32 v148, v24, v25
	v_add_u32_e32 v149, v26, v28
	v_add_u32_e32 v150, v27, v29
	v_add_u32_e32 v151, v30, v32
	v_lshlrev_b32_e32 v24, 4, v8
	v_readlane_b32 s2, v254, 56
	v_readlane_b32 s3, v254, 57
	s_branch .LBB0_573
	s_nop 0
	s_nop 0
	s_nop 0
	s_nop 0
	s_nop 0
	s_nop 0
.LBB0_573:
	s_ashr_i32 s3, s2, 2
	s_mul_hi_i32 s50, s3, 0x38e38e39
	s_lshr_b32 s52, s50, 31
	s_ashr_i32 s50, s50, 3
	s_add_i32 s50, s50, s52
	s_mul_i32 s52, s50, 36
	s_sub_i32 s52, s3, s52
	s_cmp_gt_i32 s52, 3
	s_mov_b64 s[80:81], -1
	s_cbranch_scc0 .LBB0_575
	s_lshl_b32 s3, s50, 11
	s_lshl_b32 s54, s52, 6
	s_add_i32 s3, s54, s3
	s_addk_i32 s3, 0xff00
	s_mov_b64 s[80:81], 0

; #define PG8_WAIT_V(n) asm volatile("s_waitcnt vmcnt(" #n ")" ::: "memory")
; #define PG8_BAR __builtin_amdgcn_s_barrier()
; template <class Epi, class Sched, bool ALIGN_EPI = false, bool SP2 = false>
; __device__ __forceinline__ void gemm_phase(PG8_LAS unsigned char* lds, const Gemm g, const Sched& S, const Epi& E) {
;     ...
;     PG8_WAIT_V(0);
;     if constexpr (!ALIGN_EPI) { if (wr == 0) PG8_BAR; }
;     PG8_BAR;
; __device__ __forceinline__ void xcd_barrier(const XcdBarrier& b) {
;     asm volatile("s_waitcnt vmcnt(0)" ::: "memory");
;     __syncthreads();
;     if (threadIdx.x == 0) {
;         unsigned* bar = b.bar;
;         __builtin_amdgcn_s_waitcnt(0);
;         unsigned nloc = b.st[0], nx = b.st[1];
;         if (nloc == 0u) { xcd_barrier_complete(bar, b.x, nloc, nx); b.st[0] = nloc; b.st[1] = nx; }
.LBB0_665:
	s_setprio 0
	s_waitcnt vmcnt(0)
	s_barrier
	s_mov_b64 s[2:3], exec
	v_readlane_b32 s6, v253, 0
	v_readlane_b32 s7, v253, 1
	v_readlane_b32 s92, v254, 54
	v_readlane_b32 s90, v254, 56
	s_and_b64 s[6:7], s[2:3], s[6:7]
	v_readlane_b32 s93, v254, 55
	v_readlane_b32 s91, v254, 57
	s_mov_b64 exec, s[6:7]
	s_cbranch_execz .LBB0_713
	v_mov_b32_e32 v0, s96
	s_waitcnt vmcnt(0) expcnt(0) lgkmcnt(0)
	ds_read_b32 v3, v0
	v_readlane_b32 s1, v254, 42
	s_waitcnt lgkmcnt(0)
	v_cmp_ne_u32_e32 vcc, 0, v3
	v_mov_b32_e32 v0, s1
	ds_read_b32 v2, v0
	s_cbranch_vccnz .LBB0_681
	s_mov_b32 s12, 1
	s_branch .LBB0_669

; #define PG8_WAIT_V(n) asm volatile("s_waitcnt vmcnt(" #n ")" ::: "memory")
; #define PG8_BAR __builtin_amdgcn_s_barrier()
; template <class Epi, class Sched, bool ALIGN_EPI = false, bool SP2 = false>
; __device__ __forceinline__ void gemm_phase(PG8_LAS unsigned char* lds, const Gemm g, const Sched& S, const Epi& E) {
;     ...
;     PG8_WAIT_V(0);
;     if constexpr (!ALIGN_EPI) { if (wr == 0) PG8_BAR; }
;     PG8_BAR;
; __device__ __forceinline__ void xcd_barrier(const XcdBarrier& b) {
;     asm volatile("s_waitcnt vmcnt(0)" ::: "memory");
;     __syncthreads();
;     if (threadIdx.x == 0) {
;         unsigned* bar = b.bar;
;         __builtin_amdgcn_s_waitcnt(0);
;         unsigned nloc = b.st[0], nx = b.st[1];
;         if (nloc == 0u) { xcd_barrier_complete(bar, b.x, nloc, nx); b.st[0] = nloc; b.st[1] = nx; }
.LBB0_733:
	s_setprio 0
	s_waitcnt vmcnt(0)
	s_barrier
	s_mov_b64 s[2:3], exec
	v_readlane_b32 s6, v253, 0
	v_readlane_b32 s7, v253, 1
	s_and_b64 s[6:7], s[2:3], s[6:7]
	s_mov_b64 exec, s[6:7]
	s_cbranch_execz .LBB0_781
	v_mov_b32_e32 v0, s96
	s_waitcnt vmcnt(0) expcnt(0) lgkmcnt(0)
	ds_read_b32 v3, v0
	v_readlane_b32 s1, v254, 42
	s_waitcnt lgkmcnt(0)
	v_cmp_ne_u32_e32 vcc, 0, v3
	v_mov_b32_e32 v0, s1
	ds_read_b32 v2, v0
	s_cbranch_vccnz .LBB0_749
	s_mov_b32 s12, 1
	s_branch .LBB0_737

; #define PG8_WAIT_V(n) asm volatile("s_waitcnt vmcnt(" #n ")" ::: "memory")
; #define PG8_BAR __builtin_amdgcn_s_barrier()
; template <class Epi, class Sched, bool ALIGN_EPI = false, bool SP2 = false>
; __device__ __forceinline__ void gemm_phase(PG8_LAS unsigned char* lds, const Gemm g, const Sched& S, const Epi& E) {
;     ...
;     PG8_WAIT_V(0);
;     if constexpr (!ALIGN_EPI) { if (wr == 0) PG8_BAR; }
;     PG8_BAR;
; __device__ __forceinline__ void xcd_barrier(const XcdBarrier& b) {
;     asm volatile("s_waitcnt vmcnt(0)" ::: "memory");
;     __syncthreads();
;     if (threadIdx.x == 0) {
;         unsigned* bar = b.bar;
;         __builtin_amdgcn_s_waitcnt(0);
;         unsigned nloc = b.st[0], nx = b.st[1];
;         if (nloc == 0u) { xcd_barrier_complete(bar, b.x, nloc, nx); b.st[0] = nloc; b.st[1] = nx; }
.LBB0_788:
	s_setprio 0
	s_waitcnt vmcnt(0)
	s_waitcnt vmcnt(0)
	s_barrier
	s_mov_b64 s[10:11], exec
	v_readlane_b32 s12, v253, 0
	v_readlane_b32 s13, v253, 1
	s_and_b64 s[12:13], s[10:11], s[12:13]
	s_mov_b64 exec, s[12:13]
	s_cbranch_execz .LBB0_836
	v_mov_b32_e32 v0, s96
	s_waitcnt vmcnt(0) expcnt(0) lgkmcnt(0)
	ds_read_b32 v3, v0
	v_readlane_b32 s1, v254, 42
	s_waitcnt lgkmcnt(0)
	v_cmp_ne_u32_e32 vcc, 0, v3
	v_mov_b32_e32 v0, s1
	ds_read_b32 v2, v0
	s_cbranch_vccnz .LBB0_804
	s_mov_b32 s18, 1
	s_branch .LBB0_792

; #define PG8_STAGE(bufoff, gbase, voff) do { _Pragma("unroll") for (int _i = 0; _i < 2; ++_i) \
;         __builtin_amdgcn_global_load_lds((const unsigned*)((const char*)(gbase) + (voff)[_i]), (PG8_LAS unsigned*)(lds + (bufoff) + ldsw + _i * 8192), 16, 0, 0); } while (0)
; #define PG8_BAR __builtin_amdgcn_s_barrier()
;     __host__ __device__ bool next(int i, Unit& u) const {
;         const long L = (long)i * G + c; if (L >= nwg) return false;
;         int wgid = (int)L; { const int q = nwg / NXCD, r = nwg % NXCD, xcd = wgid % NXCD, off = wgid / NXCD; wgid = (xcd < r ? xcd * (q + 1) : r * (q + 1) + (xcd - r) * q) + off; }
;         const int nig = WGM * nN, gid = wgid / nig, fm = gid * WGM, gsz = (nM - fm) < WGM ? (nM - fm) : WGM;
;         u.pm = fm + ((wgid % nig) % gsz); u.pn = (wgid % nig) / gsz; return true;
; template <class Epi, class Sched, bool ALIGN_EPI = false, bool SP2 = false>
; __device__ __forceinline__ void gemm_phase(PG8_LAS unsigned char* lds, const Gemm g, const Sched& S, const Epi& E) {
;     ...
;     const char* cA = (const char*)g.A + (size_t)cur.pm * tstep; const char* cB = (const char*)g.Bt + (size_t)cur.pn * tstep;
;     S.a_ready(cur);
;     if constexpr (SP2) {
;         PG8_STAGE(PG8_SB(0, 0), cB, voffB); PG8_STAGE(PG8_SB(0, 1), cB + hstep, voffB); PG8_STAGE(PG8_SA(0, 0), cA, voffA); PG8_STAGE(PG8_SA(0, 1), cA + hstep, voffA);
;         if (wr == 1) PG8_BAR;
.Lsw_pdone:
	v_and_b32_e32 v2, 0xfffffc00, v2
	s_ashr_i32 s9, s8, 31
	v_sub_u32_e32 v0, v0, v2
	s_lshr_b32 s9, s9, 28
	v_lshlrev_b32_e32 v6, 3, v3
	v_lshrrev_b32_e32 v2, 4, v0
	s_add_i32 s9, s8, s9
	v_writelane_b32 v255, s28, 10
	v_and_b32_e32 v6, 0x7ffffff0, v6
	v_bitop3_b32 v0, v2, v0, 32 bitop3:0x6c
	s_ashr_i32 s28, s9, 4
	v_add_u32_e32 v5, v5, v6
	v_lshlrev_b32_e32 v3, 5, v3
	v_ashrrev_i32_e32 v2, 31, v0
	s_lshl_b32 s28, s28, 2
	v_mul_lo_u32 v14, v5, s3
	v_and_b32_e32 v15, 32, v3
	v_lshrrev_b32_e32 v2, 26, v2
	s_sub_i32 s29, s89, s28
	v_or_b32_e32 v3, v14, v15
	v_add_u32_e32 v2, v0, v2
	s_min_i32 s29, s29, 4
	v_add_lshl_u32 v130, v3, v16, 1
	v_ashrrev_i32_e32 v3, 6, v2
	v_and_b32_e32 v2, 0xc0, v2
	s_abs_i32 s35, s29
	v_sub_u32_e32 v0, v0, v2
	v_cvt_f32_u32_e32 v2, s35
	s_sub_i32 s42, 0, s35
	s_and_b32 s9, s9, -16
	s_sub_i32 s8, s8, s9
	v_rcp_iflag_f32_e32 v2, v2
	s_abs_i32 s34, s8
	s_xor_b32 s9, s8, s29
	s_ashr_i32 s9, s9, 31
	v_mul_f32_e32 v2, 0x4f7ffffe, v2
	v_cvt_u32_f32_e32 v2, v2
	v_ashrrev_i32_e32 v4, 31, v20
	v_lshrrev_b32_e32 v4, 26, v4
	v_add_u32_e32 v4, v20, v4
	v_readfirstlane_b32 s43, v2
	s_mul_i32 s42, s42, s43
	s_mul_hi_u32 s42, s43, s42
	s_add_i32 s43, s43, s42
	s_mul_hi_u32 s42, s34, s43
	s_mul_i32 s43, s42, s35
	s_sub_i32 s34, s34, s43
	s_add_i32 s43, s42, 1
	s_sub_i32 s45, s34, s35
	s_cmp_ge_u32 s34, s35
	s_cselect_b32 s42, s43, s42
	s_cselect_b32 s34, s45, s34
	s_add_i32 s43, s42, 1
	s_cmp_ge_u32 s34, s35
	s_cselect_b32 s34, s43, s42
	v_ashrrev_i32_e32 v4, 6, v4
	s_xor_b32 s34, s34, s9
	v_lshlrev_b32_e32 v5, 3, v4
	s_sub_i32 s62, s34, s9
	v_and_b32_e32 v5, 0x7ffffff0, v5
	s_mul_i32 s9, s62, s29
	v_add_u32_e32 v3, v3, v5
	s_sub_i32 s8, s8, s9
	v_mul_lo_u32 v17, v3, s3
	v_lshlrev_b32_e32 v3, 5, v4
	s_add_i32 s52, s28, s8
	s_mul_i32 s9, s90, s62
	v_and_b32_e32 v18, 32, v3
	v_ashrrev_i16_sdwa v0, v196, sext(v0) dst_sel:DWORD dst_unused:UNUSED_PAD src0_sel:DWORD src1_sel:BYTE_0
	s_mul_hi_i32 s8, s90, s62
	s_add_u32 s76, s87, s9
	v_or_b32_e32 v3, v17, v18
	v_bfe_i32 v19, v0, 0, 16
	s_addc_u32 s77, s88, s8
	s_add_i32 s94, s93, 0
	v_add_lshl_u32 v0, v3, v19, 1
	s_add_i32 m0, s94, 0x10000
	s_mul_i32 s29, s90, s52
	global_load_lds_dwordx4 v0, s[76:77]
	s_add_i32 m0, s94, 0x12000
	s_add_u32 s8, s76, s10
	global_load_lds_dwordx4 v130, s[76:77]
	s_addc_u32 s9, s77, 0
	s_add_i32 m0, s94, 0x14000
	s_mul_hi_i32 s28, s90, s52
	global_load_lds_dwordx4 v0, s[8:9]
	s_add_i32 m0, s94, 0x16000
	s_add_u32 s48, s85, s29
	v_mov_b32_e32 v131, v1
	s_addc_u32 s49, s86, s28
	s_add_i32 s95, s94, 0x2000
	v_lshl_add_u64 v[6:7], s[8:9], 0, v[0:1]
	v_lshl_add_u64 v[8:9], s[8:9], 0, v[130:131]
	global_load_lds_dwordx4 v130, s[8:9]
	s_mov_b32 m0, s94
	s_add_u32 s8, s48, s10
	global_load_lds_dwordx4 v0, s[48:49]
	s_mov_b32 m0, s95
	s_addc_u32 s9, s49, 0
	s_add_i32 s84, s94, 0x4000
	global_load_lds_dwordx4 v130, s[48:49]
	s_mov_b32 m0, s84
	s_add_i32 s74, s94, 0x6000
	global_load_lds_dwordx4 v0, s[8:9]
	s_mov_b32 m0, s74
	s_cmp_eq_u32 s7, 1
	global_load_lds_dwordx4 v130, s[8:9]
	s_mov_b32 s11, s65
	v_lshl_add_u64 v[2:3], s[76:77], 0, v[0:1]
	v_lshl_add_u64 v[4:5], s[76:77], 0, v[130:131]
	v_lshl_add_u64 v[10:11], s[48:49], 0, v[0:1]
	v_lshl_add_u64 v[12:13], s[48:49], 0, v[130:131]
	s_cselect_b64 s[28:29], -1, 0
	s_cmp_lg_u32 s7, 1
	s_cbranch_scc1 .LBB0_839
	s_barrier
	s_setprio 1

; #define PG8_STAGE(bufoff, gbase, voff) do { _Pragma("unroll") for (int _i = 0; _i < 2; ++_i) \
;         __builtin_amdgcn_global_load_lds((const unsigned*)((const char*)(gbase) + (voff)[_i]), (PG8_LAS unsigned*)(lds + (bufoff) + ldsw + _i * 8192), 16, 0, 0); } while (0)
; #define PG8_LDA(dst, b, h) do { _Pragma("unroll") for (int m = 0; m < 4; ++m) _Pragma("unroll") for (int k = 0; k < 2; ++k) dst[m][k] = *(const PG8_LAS bf16x8*)(lds + PG8_SA(b, h) + aoff + m * 2048 + k * 1024); } while (0)
; #define PG8_LDB(dst, b, h) do { _Pragma("unroll") for (int n = 0; n < 2; ++n) _Pragma("unroll") for (int k = 0; k < 2; ++k) dst[n][k] = *(const PG8_LAS bf16x8*)(lds + PG8_SB(b, h) + boff + n * 2048 + k * 1024); } while (0)
; #define PG8_MMA(ai, bj, At, Bt) do { __builtin_amdgcn_s_setprio(1); _Pragma("unroll") for (int m = 0; m < 4; ++m) _Pragma("unroll") for (int n = 0; n < 2; ++n) _Pragma("unroll") for (int k = 0; k < 2; ++k) \
;         acc[ai][bj][m][n] = __builtin_amdgcn_mfma_f32_16x16x32_bf16(Bt[n][k], At[m][k], acc[ai][bj][m][n], 0, 0, 0); __builtin_amdgcn_s_setprio(0); } while (0)
; #define PG8_WAIT_V(n) asm volatile("s_waitcnt vmcnt(" #n ")" ::: "memory")
; #define PG8_WAIT_L(n) asm volatile("s_waitcnt lgkmcnt(" #n ")" ::: "memory")
; #define PG8_BAR __builtin_amdgcn_s_barrier()
; #define PG8_SCHED __builtin_amdgcn_sched_barrier(0)
; template <class Epi, class Sched, bool ALIGN_EPI = false, bool SP2 = false>
; __device__ __forceinline__ void gemm_phase(PG8_LAS unsigned char* lds, const Gemm g, const Sched& S, const Epi& E) {
;     ...
;             PG8_LDB(B0, 0, 0); PG8_LDB(B1, 0, 1); PG8_SCHED; PG8_LDA(At, 0, 0); PG8_STAGE(PG8_SA(1, 1), a1 + hstep, voffA);
;             PG8_WAIT_V(8); PG8_WAIT_L(0); PG8_BAR; PG8_MMA(0, 0, At, B0); PG8_MMA(0, 1, At, B1); PG8_BAR; PG8_SCHED;
;             PG8_LDA(At, 0, 1); PG8_STAGE(PG8_SB(0, 0), b2, voffB); PG8_STAGE(PG8_SB(0, 1), b2 + hstep, voffB); PG8_STAGE(PG8_SA(0, 0), a2, voffA);
;             PG8_WAIT_V(8); PG8_WAIT_L(0); PG8_BAR; PG8_MMA(1, 0, At, B0); PG8_MMA(1, 1, At, B1); PG8_BAR; PG8_SCHED;
.Lpeel_r:
	s_add_i32 s82, s76, 2
	s_add_u32 s83, s48, 0x80
	s_addc_u32 s77, s49, 0
	s_add_i32 s59, 0, 0x10000
	s_cmp_eq_u32 s72, s76
	s_cselect_b32 s77, s9, s77
	s_cselect_b32 s76, s8, s83
	v_add_u32_e32 v136, s59, v147
	s_cselect_b32 vcc_hi, s47, s81
	s_cselect_b32 vcc_lo, s46, s80
	s_add_i32 s83, 0, 0x14000
	ds_read_b128 v[148:151], v136
	ds_read_b128 v[152:155], v136 offset:1024
	ds_read_b128 v[156:159], v136 offset:2048
	ds_read_b128 v[160:163], v136 offset:3072
	v_add_u32_e32 v136, s83, v147
	ds_read_b128 v[166:169], v136
	ds_read_b128 v[170:173], v136 offset:1024
	ds_read_b128 v[174:177], v136 offset:2048
	ds_read_b128 v[178:181], v136 offset:3072
	v_lshl_add_u64 v[136:137], s[48:49], 0, v[132:133]
	s_add_i32 m0, s94, 0xc000
	ds_read_b128 v[202:205], v165
	ds_read_b128 v[208:211], v165 offset:1024
	ds_read_b128 v[212:215], v165 offset:2048
	ds_read_b128 v[216:219], v165 offset:3072
	ds_read_b128 v[220:223], v165 offset:4096
	ds_read_b128 v[224:227], v165 offset:5120
	ds_read_b128 v[228:231], v165 offset:6144
	ds_read_b128 v[232:235], v165 offset:7168
	global_load_lds_dwordx4 v[136:137], off
	v_lshl_add_u64 v[136:137], s[48:49], 0, v[134:135]
	s_add_i32 m0, s94, 0xe000
	s_nop 0
	global_load_lds_dwordx4 v[136:137], off
	s_waitcnt vmcnt(8)
	s_waitcnt lgkmcnt(0)
	s_barrier
	s_waitcnt lgkmcnt(0)
	v_mfma_f32_16x16x32_bf16 v[126:129], v[148:151], v[202:205], 0
	v_mfma_f32_16x16x32_bf16 v[122:125], v[156:159], v[202:205], 0
	v_mfma_f32_16x16x32_bf16 v[110:113], v[148:151], v[212:215], 0
	v_mfma_f32_16x16x32_bf16 v[106:109], v[156:159], v[212:215], 0
	v_mfma_f32_16x16x32_bf16 v[94:97], v[148:151], v[220:223], 0
	v_mfma_f32_16x16x32_bf16 v[90:93], v[156:159], v[220:223], 0
	v_mfma_f32_16x16x32_bf16 v[78:81], v[148:151], v[228:231], 0
	v_mfma_f32_16x16x32_bf16 v[74:77], v[156:159], v[228:231], 0
	v_mfma_f32_16x16x32_bf16 v[126:129], v[152:155], v[208:211], v[126:129]
	v_mfma_f32_16x16x32_bf16 v[122:125], v[160:163], v[208:211], v[122:125]
	v_mfma_f32_16x16x32_bf16 v[110:113], v[152:155], v[216:219], v[110:113]
	v_mfma_f32_16x16x32_bf16 v[106:109], v[160:163], v[216:219], v[106:109]
	v_mfma_f32_16x16x32_bf16 v[94:97], v[152:155], v[224:227], v[94:97]
	v_mfma_f32_16x16x32_bf16 v[90:93], v[160:163], v[224:227], v[90:93]
	v_mfma_f32_16x16x32_bf16 v[78:81], v[152:155], v[232:235], v[78:81]
	v_mfma_f32_16x16x32_bf16 v[74:77], v[160:163], v[232:235], v[74:77]
	v_mfma_f32_16x16x32_bf16 v[118:121], v[166:169], v[202:205], 0
	v_mfma_f32_16x16x32_bf16 v[114:117], v[174:177], v[202:205], 0
	v_mfma_f32_16x16x32_bf16 v[102:105], v[166:169], v[212:215], 0
	v_mfma_f32_16x16x32_bf16 v[98:101], v[174:177], v[212:215], 0
	v_mfma_f32_16x16x32_bf16 v[86:89], v[166:169], v[220:223], 0
	v_mfma_f32_16x16x32_bf16 v[82:85], v[174:177], v[220:223], 0
	v_mfma_f32_16x16x32_bf16 v[70:73], v[166:169], v[228:231], 0
	v_mfma_f32_16x16x32_bf16 v[66:69], v[174:177], v[228:231], 0
	v_mfma_f32_16x16x32_bf16 v[118:121], v[170:173], v[208:211], v[118:121]
	v_mfma_f32_16x16x32_bf16 v[114:117], v[178:181], v[208:211], v[114:117]
	v_mfma_f32_16x16x32_bf16 v[102:105], v[170:173], v[216:219], v[102:105]
	v_mfma_f32_16x16x32_bf16 v[98:101], v[178:181], v[216:219], v[98:101]
	v_mfma_f32_16x16x32_bf16 v[86:89], v[170:173], v[224:227], v[86:89]
	v_mfma_f32_16x16x32_bf16 v[82:85], v[178:181], v[224:227], v[82:85]
	v_mfma_f32_16x16x32_bf16 v[70:73], v[170:173], v[232:235], v[70:73]
	v_mfma_f32_16x16x32_bf16 v[66:69], v[178:181], v[232:235], v[66:69]
	s_barrier
	s_add_i32 s59, s59, s93
	v_lshl_add_u64 v[136:137], vcc, 0, v[0:1]
	s_mov_b32 m0, s59
	ds_read_b128 v[202:205], v165 offset:16384
	ds_read_b128 v[208:211], v165 offset:17408
	ds_read_b128 v[212:215], v165 offset:18432
	ds_read_b128 v[216:219], v165 offset:19456
	ds_read_b128 v[220:223], v165 offset:20480
	ds_read_b128 v[224:227], v165 offset:21504
	ds_read_b128 v[228:231], v165 offset:22528
	ds_read_b128 v[232:235], v165 offset:23552
	global_load_lds_dwordx4 v[136:137], off
	s_add_i32 m0, s59, 0x2000
	v_lshl_add_u64 v[144:145], vcc, 0, v[130:131]
	s_add_u32 vcc_lo, vcc_lo, s10
	s_addc_u32 vcc_hi, vcc_hi, 0
	s_add_i32 s59, s83, s93
	global_load_lds_dwordx4 v[144:145], off
	v_lshl_add_u64 v[182:183], vcc, 0, v[0:1]
	s_mov_b32 m0, s59
	v_lshl_add_u64 v[236:237], vcc, 0, v[130:131]
	global_load_lds_dwordx4 v[182:183], off
	s_add_i32 m0, s59, 0x2000
	v_lshl_add_u64 v[238:239], s[76:77], 0, v[0:1]
	global_load_lds_dwordx4 v[236:237], off
	s_mov_b32 m0, s94
	v_lshl_add_u64 v[240:241], s[76:77], 0, v[130:131]
	global_load_lds_dwordx4 v[238:239], off
	s_mov_b32 m0, s95
	s_nop 0
	global_load_lds_dwordx4 v[240:241], off
	s_waitcnt vmcnt(8)
	s_waitcnt lgkmcnt(0)
	s_barrier
; #define PG8_STAGE(bufoff, gbase, voff) do { _Pragma("unroll") for (int _i = 0; _i < 2; ++_i) \
;         __builtin_amdgcn_global_load_lds((const unsigned*)((const char*)(gbase) + (voff)[_i]), (PG8_LAS unsigned*)(lds + (bufoff) + ldsw + _i * 8192), 16, 0, 0); } while (0)
; #define PG8_LDA(dst, b, h) do { _Pragma("unroll") for (int m = 0; m < 4; ++m) _Pragma("unroll") for (int k = 0; k < 2; ++k) dst[m][k] = *(const PG8_LAS bf16x8*)(lds + PG8_SA(b, h) + aoff + m * 2048 + k * 1024); } while (0)
; #define PG8_LDB(dst, b, h) do { _Pragma("unroll") for (int n = 0; n < 2; ++n) _Pragma("unroll") for (int k = 0; k < 2; ++k) dst[n][k] = *(const PG8_LAS bf16x8*)(lds + PG8_SB(b, h) + boff + n * 2048 + k * 1024); } while (0)
; #define PG8_MMA(ai, bj, At, Bt) do { __builtin_amdgcn_s_setprio(1); _Pragma("unroll") for (int m = 0; m < 4; ++m) _Pragma("unroll") for (int n = 0; n < 2; ++n) _Pragma("unroll") for (int k = 0; k < 2; ++k) \
;         acc[ai][bj][m][n] = __builtin_amdgcn_mfma_f32_16x16x32_bf16(Bt[n][k], At[m][k], acc[ai][bj][m][n], 0, 0, 0); __builtin_amdgcn_s_setprio(0); } while (0)
; #define PG8_WAIT_V(n) asm volatile("s_waitcnt vmcnt(" #n ")" ::: "memory")
; #define PG8_WAIT_L(n) asm volatile("s_waitcnt lgkmcnt(" #n ")" ::: "memory")
; #define PG8_BAR __builtin_amdgcn_s_barrier()
; #define PG8_SCHED __builtin_amdgcn_sched_barrier(0)
; template <class Epi, class Sched, bool ALIGN_EPI = false, bool SP2 = false>
; __device__ __forceinline__ void gemm_phase(PG8_LAS unsigned char* lds, const Gemm g, const Sched& S, const Epi& E) {
;     ...
;             PG8_WAIT_V(8); PG8_WAIT_L(0); PG8_BAR; PG8_MMA(1, 0, At, B0); PG8_MMA(1, 1, At, B1); PG8_BAR; PG8_SCHED;
;             PG8_LDB(B0, 1, 0); PG8_LDB(B1, 1, 1); PG8_SCHED; PG8_LDA(At, 1, 0); PG8_STAGE(PG8_SA(0, 1), a2 + hstep, voffA);
;             PG8_WAIT_V(8); PG8_WAIT_L(0); PG8_BAR; PG8_MMA(0, 0, At, B0); PG8_MMA(0, 1, At, B1); PG8_BAR; PG8_SCHED;
	s_waitcnt lgkmcnt(0)
	v_mfma_f32_16x16x32_bf16 v[62:65], v[148:151], v[202:205], 0
	v_mfma_f32_16x16x32_bf16 v[58:61], v[156:159], v[202:205], 0
	v_mfma_f32_16x16x32_bf16 v[46:49], v[148:151], v[212:215], 0
	v_mfma_f32_16x16x32_bf16 v[42:45], v[156:159], v[212:215], 0
	v_mfma_f32_16x16x32_bf16 v[30:33], v[148:151], v[220:223], 0
	v_mfma_f32_16x16x32_bf16 v[26:29], v[156:159], v[220:223], 0
	v_mfma_f32_16x16x32_bf16 v[14:17], v[148:151], v[228:231], 0
	v_mfma_f32_16x16x32_bf16 v[10:13], v[156:159], v[228:231], 0
	v_mfma_f32_16x16x32_bf16 v[62:65], v[152:155], v[208:211], v[62:65]
	v_mfma_f32_16x16x32_bf16 v[58:61], v[160:163], v[208:211], v[58:61]
	v_mfma_f32_16x16x32_bf16 v[46:49], v[152:155], v[216:219], v[46:49]
	v_mfma_f32_16x16x32_bf16 v[42:45], v[160:163], v[216:219], v[42:45]
	v_mfma_f32_16x16x32_bf16 v[30:33], v[152:155], v[224:227], v[30:33]
	v_mfma_f32_16x16x32_bf16 v[26:29], v[160:163], v[224:227], v[26:29]
	v_mfma_f32_16x16x32_bf16 v[14:17], v[152:155], v[232:235], v[14:17]
	v_mfma_f32_16x16x32_bf16 v[10:13], v[160:163], v[232:235], v[10:13]
	v_mfma_f32_16x16x32_bf16 v[54:57], v[166:169], v[202:205], 0
	v_mfma_f32_16x16x32_bf16 v[50:53], v[174:177], v[202:205], 0
	v_mfma_f32_16x16x32_bf16 v[38:41], v[166:169], v[212:215], 0
	v_mfma_f32_16x16x32_bf16 v[34:37], v[174:177], v[212:215], 0
	v_mfma_f32_16x16x32_bf16 v[22:25], v[166:169], v[220:223], 0
	v_mfma_f32_16x16x32_bf16 v[18:21], v[174:177], v[220:223], 0
	v_mfma_f32_16x16x32_bf16 v[6:9], v[166:169], v[228:231], 0
	v_mfma_f32_16x16x32_bf16 v[2:5], v[174:177], v[228:231], 0
	v_mfma_f32_16x16x32_bf16 v[54:57], v[170:173], v[208:211], v[54:57]
	v_mfma_f32_16x16x32_bf16 v[50:53], v[178:181], v[208:211], v[50:53]
	v_mfma_f32_16x16x32_bf16 v[38:41], v[170:173], v[216:219], v[38:41]
	v_mfma_f32_16x16x32_bf16 v[34:37], v[178:181], v[216:219], v[34:37]
	v_mfma_f32_16x16x32_bf16 v[22:25], v[170:173], v[224:227], v[22:25]
	v_mfma_f32_16x16x32_bf16 v[18:21], v[178:181], v[224:227], v[18:21]
	v_mfma_f32_16x16x32_bf16 v[6:9], v[170:173], v[232:235], v[6:9]
	v_mfma_f32_16x16x32_bf16 v[2:5], v[178:181], v[232:235], v[2:5]
	s_barrier
	s_add_i32 s59, 0, 0x18000
	s_add_i32 s83, 0, 0x1c000
	v_add_u32_e32 v160, s59, v147
	v_add_u32_e32 v178, s83, v147
	ds_read_b128 v[148:151], v160
	ds_read_b128 v[152:155], v160 offset:1024
	ds_read_b128 v[156:159], v160 offset:2048
	ds_read_b128 v[160:163], v160 offset:3072
	ds_read_b128 v[166:169], v178
	ds_read_b128 v[170:173], v178 offset:1024
	ds_read_b128 v[174:177], v178 offset:2048
	ds_read_b128 v[178:181], v178 offset:3072
	s_add_u32 s76, s76, s10
	s_addc_u32 s77, s77, 0
	s_mov_b32 m0, s84
	v_lshl_add_u64 v[242:243], s[76:77], 0, v[0:1]
	ds_read_b128 v[202:205], v165 offset:32768
	ds_read_b128 v[208:211], v165 offset:33792
	ds_read_b128 v[212:215], v165 offset:34816
	ds_read_b128 v[216:219], v165 offset:35840
	ds_read_b128 v[220:223], v165 offset:36864
	ds_read_b128 v[224:227], v165 offset:37888
	ds_read_b128 v[228:231], v165 offset:38912
	ds_read_b128 v[232:235], v165 offset:39936
	global_load_lds_dwordx4 v[242:243], off
	v_lshl_add_u64 v[242:243], s[76:77], 0, v[130:131]
	s_mov_b32 m0, s74
	s_nop 0
	global_load_lds_dwordx4 v[242:243], off
	s_waitcnt vmcnt(8)
	s_waitcnt lgkmcnt(0)
	s_barrier
	s_waitcnt lgkmcnt(0)
	v_mfma_f32_16x16x32_bf16 v[126:129], v[148:151], v[202:205], v[126:129]
	v_mfma_f32_16x16x32_bf16 v[122:125], v[156:159], v[202:205], v[122:125]
	v_mfma_f32_16x16x32_bf16 v[110:113], v[148:151], v[212:215], v[110:113]
	v_mfma_f32_16x16x32_bf16 v[106:109], v[156:159], v[212:215], v[106:109]
	v_mfma_f32_16x16x32_bf16 v[94:97], v[148:151], v[220:223], v[94:97]
	v_mfma_f32_16x16x32_bf16 v[90:93], v[156:159], v[220:223], v[90:93]
	v_mfma_f32_16x16x32_bf16 v[78:81], v[148:151], v[228:231], v[78:81]
	v_mfma_f32_16x16x32_bf16 v[74:77], v[156:159], v[228:231], v[74:77]
	v_mfma_f32_16x16x32_bf16 v[126:129], v[152:155], v[208:211], v[126:129]
	v_mfma_f32_16x16x32_bf16 v[122:125], v[160:163], v[208:211], v[122:125]
	v_mfma_f32_16x16x32_bf16 v[110:113], v[152:155], v[216:219], v[110:113]
	v_mfma_f32_16x16x32_bf16 v[106:109], v[160:163], v[216:219], v[106:109]
	v_mfma_f32_16x16x32_bf16 v[94:97], v[152:155], v[224:227], v[94:97]
	v_mfma_f32_16x16x32_bf16 v[90:93], v[160:163], v[224:227], v[90:93]
	v_mfma_f32_16x16x32_bf16 v[78:81], v[152:155], v[232:235], v[78:81]
	v_mfma_f32_16x16x32_bf16 v[74:77], v[160:163], v[232:235], v[74:77]
	v_mfma_f32_16x16x32_bf16 v[118:121], v[166:169], v[202:205], v[118:121]
	v_mfma_f32_16x16x32_bf16 v[114:117], v[174:177], v[202:205], v[114:117]
	v_mfma_f32_16x16x32_bf16 v[102:105], v[166:169], v[212:215], v[102:105]
	v_mfma_f32_16x16x32_bf16 v[98:101], v[174:177], v[212:215], v[98:101]
	v_mfma_f32_16x16x32_bf16 v[86:89], v[166:169], v[220:223], v[86:89]
	v_mfma_f32_16x16x32_bf16 v[82:85], v[174:177], v[220:223], v[82:85]
	v_mfma_f32_16x16x32_bf16 v[70:73], v[166:169], v[228:231], v[70:73]
	v_mfma_f32_16x16x32_bf16 v[66:69], v[174:177], v[228:231], v[66:69]
	v_mfma_f32_16x16x32_bf16 v[118:121], v[170:173], v[208:211], v[118:121]
	v_mfma_f32_16x16x32_bf16 v[114:117], v[178:181], v[208:211], v[114:117]
	v_mfma_f32_16x16x32_bf16 v[102:105], v[170:173], v[216:219], v[102:105]
	v_mfma_f32_16x16x32_bf16 v[98:101], v[178:181], v[216:219], v[98:101]
	v_mfma_f32_16x16x32_bf16 v[86:89], v[170:173], v[224:227], v[86:89]
	v_mfma_f32_16x16x32_bf16 v[82:85], v[178:181], v[224:227], v[82:85]
	v_mfma_f32_16x16x32_bf16 v[70:73], v[170:173], v[232:235], v[70:73]
	v_mfma_f32_16x16x32_bf16 v[66:69], v[178:181], v[232:235], v[66:69]
	s_barrier
; #define PG8_STAGE(bufoff, gbase, voff) do { _Pragma("unroll") for (int _i = 0; _i < 2; ++_i) \
;         __builtin_amdgcn_global_load_lds((const unsigned*)((const char*)(gbase) + (voff)[_i]), (PG8_LAS unsigned*)(lds + (bufoff) + ldsw + _i * 8192), 16, 0, 0); } while (0)
; #define PG8_LDA(dst, b, h) do { _Pragma("unroll") for (int m = 0; m < 4; ++m) _Pragma("unroll") for (int k = 0; k < 2; ++k) dst[m][k] = *(const PG8_LAS bf16x8*)(lds + PG8_SA(b, h) + aoff + m * 2048 + k * 1024); } while (0)
; #define PG8_LDB(dst, b, h) do { _Pragma("unroll") for (int n = 0; n < 2; ++n) _Pragma("unroll") for (int k = 0; k < 2; ++k) dst[n][k] = *(const PG8_LAS bf16x8*)(lds + PG8_SB(b, h) + boff + n * 2048 + k * 1024); } while (0)
; #define PG8_MMA(ai, bj, At, Bt) do { __builtin_amdgcn_s_setprio(1); _Pragma("unroll") for (int m = 0; m < 4; ++m) _Pragma("unroll") for (int n = 0; n < 2; ++n) _Pragma("unroll") for (int k = 0; k < 2; ++k) \
;         acc[ai][bj][m][n] = __builtin_amdgcn_mfma_f32_16x16x32_bf16(Bt[n][k], At[m][k], acc[ai][bj][m][n], 0, 0, 0); __builtin_amdgcn_s_setprio(0); } while (0)
; #define PG8_WAIT_V(n) asm volatile("s_waitcnt vmcnt(" #n ")" ::: "memory")
; template <class Epi, class Sched, bool ALIGN_EPI = false, bool SP2 = false>
; __device__ __forceinline__ void gemm_phase(PG8_LAS unsigned char* lds, const Gemm g, const Sched& S, const Epi& E) {
;     ...
;             PG8_LDB(B0, 0, 0); PG8_LDB(B1, 0, 1); PG8_SCHED; PG8_LDA(At, 0, 0); PG8_STAGE(PG8_SA(1, 1), a1 + hstep, voffA);
;             PG8_WAIT_V(8); PG8_WAIT_L(0); PG8_BAR; PG8_MMA(0, 0, At, B0); PG8_MMA(0, 1, At, B1); PG8_BAR; PG8_SCHED;
;             PG8_LDA(At, 0, 1); PG8_STAGE(PG8_SB(0, 0), b2, voffB); PG8_STAGE(PG8_SB(0, 1), b2 + hstep, voffB); PG8_STAGE(PG8_SA(0, 0), a2, voffA);
;             PG8_WAIT_V(8); PG8_WAIT_L(0); PG8_BAR; PG8_MMA(1, 0, At, B0); PG8_MMA(1, 1, At, B1); PG8_BAR; PG8_SCHED;
;             PG8_LDB(B0, 1, 0); PG8_LDB(B1, 1, 1); PG8_SCHED; PG8_LDA(At, 1, 0); PG8_STAGE(PG8_SA(0, 1), a2 + hstep, voffA);
;             PG8_WAIT_V(8); PG8_WAIT_L(0); PG8_BAR; PG8_MMA(0, 0, At, B0); PG8_MMA(0, 1, At, B1); PG8_BAR; PG8_SCHED;
;             PG8_LDA(At, 1, 1); PG8_STAGE(PG8_SB(1, 0), b3, voffB); PG8_STAGE(PG8_SB(1, 1), b3 + hstep, voffB); PG8_STAGE(PG8_SA(1, 0), a3, voffA);
;             PG8_WAIT_V(8); PG8_WAIT_L(0); PG8_BAR; PG8_MMA(1, 0, At, B0); PG8_MMA(1, 1, At, B1); PG8_BAR; PG8_SCHED;
	s_add_i32 s59, s59, s93
	v_lshl_add_u64 v[136:137], v[136:137], 0, s[66:67]
	s_mov_b32 m0, s59
	ds_read_b128 v[202:205], v165 offset:49152
	ds_read_b128 v[208:211], v165 offset:50176
	ds_read_b128 v[212:215], v165 offset:51200
	ds_read_b128 v[216:219], v165 offset:52224
	ds_read_b128 v[220:223], v165 offset:53248
	ds_read_b128 v[224:227], v165 offset:54272
	ds_read_b128 v[228:231], v165 offset:55296
	ds_read_b128 v[232:235], v165 offset:56320
	global_load_lds_dwordx4 v[136:137], off
	v_lshl_add_u64 v[136:137], v[144:145], 0, s[66:67]
	s_add_i32 m0, s59, 0x2000
	s_add_i32 s59, s83, s93
	global_load_lds_dwordx4 v[136:137], off
	v_lshl_add_u64 v[136:137], v[182:183], 0, s[66:67]
	s_mov_b32 m0, s59
	s_nop 0
	global_load_lds_dwordx4 v[136:137], off
	v_lshl_add_u64 v[136:137], v[236:237], 0, s[66:67]
	s_add_i32 m0, s59, 0x2000
	s_nop 0
	global_load_lds_dwordx4 v[136:137], off
	v_lshl_add_u64 v[136:137], v[238:239], 0, s[66:67]
	s_mov_b32 m0, s73
	s_nop 0
	global_load_lds_dwordx4 v[136:137], off
	v_lshl_add_u64 v[136:137], v[240:241], 0, s[66:67]
	s_mov_b32 m0, s50
	s_nop 0
	global_load_lds_dwordx4 v[136:137], off
	s_waitcnt vmcnt(8)
	s_waitcnt lgkmcnt(0)
	s_barrier
	s_waitcnt lgkmcnt(0)
	v_mfma_f32_16x16x32_bf16 v[62:65], v[148:151], v[202:205], v[62:65]
	v_mfma_f32_16x16x32_bf16 v[58:61], v[156:159], v[202:205], v[58:61]
	v_mfma_f32_16x16x32_bf16 v[46:49], v[148:151], v[212:215], v[46:49]
	v_mfma_f32_16x16x32_bf16 v[42:45], v[156:159], v[212:215], v[42:45]
	v_mfma_f32_16x16x32_bf16 v[30:33], v[148:151], v[220:223], v[30:33]
	v_mfma_f32_16x16x32_bf16 v[26:29], v[156:159], v[220:223], v[26:29]
	v_mfma_f32_16x16x32_bf16 v[14:17], v[148:151], v[228:231], v[14:17]
	v_mfma_f32_16x16x32_bf16 v[10:13], v[156:159], v[228:231], v[10:13]
	v_mfma_f32_16x16x32_bf16 v[62:65], v[152:155], v[208:211], v[62:65]
	v_mfma_f32_16x16x32_bf16 v[58:61], v[160:163], v[208:211], v[58:61]
	v_mfma_f32_16x16x32_bf16 v[46:49], v[152:155], v[216:219], v[46:49]
	v_mfma_f32_16x16x32_bf16 v[42:45], v[160:163], v[216:219], v[42:45]
	v_mfma_f32_16x16x32_bf16 v[30:33], v[152:155], v[224:227], v[30:33]
	v_mfma_f32_16x16x32_bf16 v[26:29], v[160:163], v[224:227], v[26:29]
	v_mfma_f32_16x16x32_bf16 v[14:17], v[152:155], v[232:235], v[14:17]
	v_mfma_f32_16x16x32_bf16 v[10:13], v[160:163], v[232:235], v[10:13]
	v_mfma_f32_16x16x32_bf16 v[54:57], v[166:169], v[202:205], v[54:57]
	v_mfma_f32_16x16x32_bf16 v[50:53], v[174:177], v[202:205], v[50:53]
	v_mfma_f32_16x16x32_bf16 v[38:41], v[166:169], v[212:215], v[38:41]
	v_mfma_f32_16x16x32_bf16 v[34:37], v[174:177], v[212:215], v[34:37]
	v_mfma_f32_16x16x32_bf16 v[22:25], v[166:169], v[220:223], v[22:25]
	v_mfma_f32_16x16x32_bf16 v[18:21], v[174:177], v[220:223], v[18:21]
	v_mfma_f32_16x16x32_bf16 v[6:9], v[166:169], v[228:231], v[6:9]
	v_mfma_f32_16x16x32_bf16 v[2:5], v[174:177], v[228:231], v[2:5]
	v_mfma_f32_16x16x32_bf16 v[54:57], v[170:173], v[208:211], v[54:57]
	v_mfma_f32_16x16x32_bf16 v[50:53], v[178:181], v[208:211], v[50:53]
	v_mfma_f32_16x16x32_bf16 v[38:41], v[170:173], v[216:219], v[38:41]
	v_mfma_f32_16x16x32_bf16 v[34:37], v[178:181], v[216:219], v[34:37]
	v_mfma_f32_16x16x32_bf16 v[22:25], v[170:173], v[224:227], v[22:25]
	v_mfma_f32_16x16x32_bf16 v[18:21], v[178:181], v[224:227], v[18:21]
	v_mfma_f32_16x16x32_bf16 v[6:9], v[170:173], v[232:235], v[6:9]
	v_mfma_f32_16x16x32_bf16 v[2:5], v[178:181], v[232:235], v[2:5]
	s_barrier
	s_add_u32 s48, s48, 0x100
	s_addc_u32 s49, s49, 0
	s_add_u32 s80, s80, 0x100
	s_addc_u32 s81, s81, 0
	s_cmp_ge_u32 s82, s79
	s_mov_b32 s76, s82
	s_cbranch_scc0 .LBB0_849
	s_branch .Lkq_exit
	s_nop 0
	s_nop 0
	s_nop 0
	s_nop 0
	s_nop 0
.LBB0_849:
	s_add_i32 s82, s76, 2
	s_add_u32 s83, s48, 0x80
	s_addc_u32 s77, s49, 0
	s_add_i32 s59, 0, 0x10000
	s_cmp_eq_u32 s72, s76
	s_cselect_b32 s77, s9, s77
	s_cselect_b32 s76, s8, s83
	v_add_u32_e32 v136, s59, v147
	s_cselect_b32 vcc_hi, s47, s81
	s_cselect_b32 vcc_lo, s46, s80
	s_add_i32 s83, 0, 0x14000
	ds_read_b128 v[148:151], v136
	ds_read_b128 v[152:155], v136 offset:1024
	ds_read_b128 v[156:159], v136 offset:2048
	ds_read_b128 v[160:163], v136 offset:3072
	v_add_u32_e32 v136, s83, v147
	ds_read_b128 v[166:169], v136
	ds_read_b128 v[170:173], v136 offset:1024
	ds_read_b128 v[174:177], v136 offset:2048
	ds_read_b128 v[178:181], v136 offset:3072
	v_lshl_add_u64 v[136:137], s[48:49], 0, v[132:133]
	s_add_i32 m0, s94, 0xc000
	ds_read_b128 v[202:205], v165
	ds_read_b128 v[208:211], v165 offset:1024
	ds_read_b128 v[212:215], v165 offset:2048
	ds_read_b128 v[216:219], v165 offset:3072
	ds_read_b128 v[220:223], v165 offset:4096
	ds_read_b128 v[224:227], v165 offset:5120
	ds_read_b128 v[228:231], v165 offset:6144
	ds_read_b128 v[232:235], v165 offset:7168
	global_load_lds_dwordx4 v[136:137], off
	v_lshl_add_u64 v[136:137], s[48:49], 0, v[134:135]
	s_add_i32 m0, s94, 0xe000
	s_nop 0
	global_load_lds_dwordx4 v[136:137], off
	s_waitcnt vmcnt(8)
	s_waitcnt lgkmcnt(0)
	s_barrier
; #define PG8_STAGE(bufoff, gbase, voff) do { _Pragma("unroll") for (int _i = 0; _i < 2; ++_i) \
;         __builtin_amdgcn_global_load_lds((const unsigned*)((const char*)(gbase) + (voff)[_i]), (PG8_LAS unsigned*)(lds + (bufoff) + ldsw + _i * 8192), 16, 0, 0); } while (0)
; #define PG8_LDA(dst, b, h) do { _Pragma("unroll") for (int m = 0; m < 4; ++m) _Pragma("unroll") for (int k = 0; k < 2; ++k) dst[m][k] = *(const PG8_LAS bf16x8*)(lds + PG8_SA(b, h) + aoff + m * 2048 + k * 1024); } while (0)
; #define PG8_LDB(dst, b, h) do { _Pragma("unroll") for (int n = 0; n < 2; ++n) _Pragma("unroll") for (int k = 0; k < 2; ++k) dst[n][k] = *(const PG8_LAS bf16x8*)(lds + PG8_SB(b, h) + boff + n * 2048 + k * 1024); } while (0)
; #define PG8_MMA(ai, bj, At, Bt) do { __builtin_amdgcn_s_setprio(1); _Pragma("unroll") for (int m = 0; m < 4; ++m) _Pragma("unroll") for (int n = 0; n < 2; ++n) _Pragma("unroll") for (int k = 0; k < 2; ++k) \
;         acc[ai][bj][m][n] = __builtin_amdgcn_mfma_f32_16x16x32_bf16(Bt[n][k], At[m][k], acc[ai][bj][m][n], 0, 0, 0); __builtin_amdgcn_s_setprio(0); } while (0)
; #define PG8_WAIT_V(n) asm volatile("s_waitcnt vmcnt(" #n ")" ::: "memory")
; #define PG8_WAIT_L(n) asm volatile("s_waitcnt lgkmcnt(" #n ")" ::: "memory")
; #define PG8_BAR __builtin_amdgcn_s_barrier()
; #define PG8_SCHED __builtin_amdgcn_sched_barrier(0)
; template <class Epi, class Sched, bool ALIGN_EPI = false, bool SP2 = false>
; __device__ __forceinline__ void gemm_phase(PG8_LAS unsigned char* lds, const Gemm g, const Sched& S, const Epi& E) {
;     ...
;             PG8_WAIT_V(8); PG8_WAIT_L(0); PG8_BAR; PG8_MMA(0, 0, At, B0); PG8_MMA(0, 1, At, B1); PG8_BAR; PG8_SCHED;
;             PG8_LDA(At, 0, 1); PG8_STAGE(PG8_SB(0, 0), b2, voffB); PG8_STAGE(PG8_SB(0, 1), b2 + hstep, voffB); PG8_STAGE(PG8_SA(0, 0), a2, voffA);
;             PG8_WAIT_V(8); PG8_WAIT_L(0); PG8_BAR; PG8_MMA(1, 0, At, B0); PG8_MMA(1, 1, At, B1); PG8_BAR; PG8_SCHED;
;             PG8_LDB(B0, 1, 0); PG8_LDB(B1, 1, 1); PG8_SCHED; PG8_LDA(At, 1, 0); PG8_STAGE(PG8_SA(0, 1), a2 + hstep, voffA);
	s_waitcnt lgkmcnt(0)
	v_mfma_f32_16x16x32_bf16 v[126:129], v[148:151], v[202:205], v[126:129]
	v_mfma_f32_16x16x32_bf16 v[122:125], v[156:159], v[202:205], v[122:125]
	v_mfma_f32_16x16x32_bf16 v[110:113], v[148:151], v[212:215], v[110:113]
	v_mfma_f32_16x16x32_bf16 v[106:109], v[156:159], v[212:215], v[106:109]
	v_mfma_f32_16x16x32_bf16 v[94:97], v[148:151], v[220:223], v[94:97]
	v_mfma_f32_16x16x32_bf16 v[90:93], v[156:159], v[220:223], v[90:93]
	v_mfma_f32_16x16x32_bf16 v[78:81], v[148:151], v[228:231], v[78:81]
	v_mfma_f32_16x16x32_bf16 v[74:77], v[156:159], v[228:231], v[74:77]
	v_mfma_f32_16x16x32_bf16 v[126:129], v[152:155], v[208:211], v[126:129]
	v_mfma_f32_16x16x32_bf16 v[122:125], v[160:163], v[208:211], v[122:125]
	v_mfma_f32_16x16x32_bf16 v[110:113], v[152:155], v[216:219], v[110:113]
	v_mfma_f32_16x16x32_bf16 v[106:109], v[160:163], v[216:219], v[106:109]
	v_mfma_f32_16x16x32_bf16 v[94:97], v[152:155], v[224:227], v[94:97]
	v_mfma_f32_16x16x32_bf16 v[90:93], v[160:163], v[224:227], v[90:93]
	v_mfma_f32_16x16x32_bf16 v[78:81], v[152:155], v[232:235], v[78:81]
	v_mfma_f32_16x16x32_bf16 v[74:77], v[160:163], v[232:235], v[74:77]
	v_mfma_f32_16x16x32_bf16 v[118:121], v[166:169], v[202:205], v[118:121]
	v_mfma_f32_16x16x32_bf16 v[114:117], v[174:177], v[202:205], v[114:117]
	v_mfma_f32_16x16x32_bf16 v[102:105], v[166:169], v[212:215], v[102:105]
	v_mfma_f32_16x16x32_bf16 v[98:101], v[174:177], v[212:215], v[98:101]
	v_mfma_f32_16x16x32_bf16 v[86:89], v[166:169], v[220:223], v[86:89]
	v_mfma_f32_16x16x32_bf16 v[82:85], v[174:177], v[220:223], v[82:85]
	v_mfma_f32_16x16x32_bf16 v[70:73], v[166:169], v[228:231], v[70:73]
	v_mfma_f32_16x16x32_bf16 v[66:69], v[174:177], v[228:231], v[66:69]
	v_mfma_f32_16x16x32_bf16 v[118:121], v[170:173], v[208:211], v[118:121]
	v_mfma_f32_16x16x32_bf16 v[114:117], v[178:181], v[208:211], v[114:117]
	v_mfma_f32_16x16x32_bf16 v[102:105], v[170:173], v[216:219], v[102:105]
	v_mfma_f32_16x16x32_bf16 v[98:101], v[178:181], v[216:219], v[98:101]
	v_mfma_f32_16x16x32_bf16 v[86:89], v[170:173], v[224:227], v[86:89]
	v_mfma_f32_16x16x32_bf16 v[82:85], v[178:181], v[224:227], v[82:85]
	v_mfma_f32_16x16x32_bf16 v[70:73], v[170:173], v[232:235], v[70:73]
	v_mfma_f32_16x16x32_bf16 v[66:69], v[178:181], v[232:235], v[66:69]
	s_barrier
	s_add_i32 s59, s59, s93
	v_lshl_add_u64 v[136:137], vcc, 0, v[0:1]
	s_mov_b32 m0, s59
	ds_read_b128 v[202:205], v165 offset:16384
	ds_read_b128 v[208:211], v165 offset:17408
	ds_read_b128 v[212:215], v165 offset:18432
	ds_read_b128 v[216:219], v165 offset:19456
	ds_read_b128 v[220:223], v165 offset:20480
	ds_read_b128 v[224:227], v165 offset:21504
	ds_read_b128 v[228:231], v165 offset:22528
	ds_read_b128 v[232:235], v165 offset:23552
	global_load_lds_dwordx4 v[136:137], off
	s_add_i32 m0, s59, 0x2000
	v_lshl_add_u64 v[144:145], vcc, 0, v[130:131]
	s_add_u32 vcc_lo, vcc_lo, s10
	s_addc_u32 vcc_hi, vcc_hi, 0
	s_add_i32 s59, s83, s93
	global_load_lds_dwordx4 v[144:145], off
	v_lshl_add_u64 v[182:183], vcc, 0, v[0:1]
	s_mov_b32 m0, s59
	v_lshl_add_u64 v[236:237], vcc, 0, v[130:131]
	global_load_lds_dwordx4 v[182:183], off
	s_add_i32 m0, s59, 0x2000
	v_lshl_add_u64 v[238:239], s[76:77], 0, v[0:1]
	global_load_lds_dwordx4 v[236:237], off
	s_mov_b32 m0, s94
	v_lshl_add_u64 v[240:241], s[76:77], 0, v[130:131]
	global_load_lds_dwordx4 v[238:239], off
	s_mov_b32 m0, s95
	s_nop 0
	global_load_lds_dwordx4 v[240:241], off
	s_waitcnt vmcnt(8)
	s_waitcnt lgkmcnt(0)
	s_barrier
	s_waitcnt lgkmcnt(0)
	v_mfma_f32_16x16x32_bf16 v[62:65], v[148:151], v[202:205], v[62:65]
	v_mfma_f32_16x16x32_bf16 v[58:61], v[156:159], v[202:205], v[58:61]
	v_mfma_f32_16x16x32_bf16 v[46:49], v[148:151], v[212:215], v[46:49]
	v_mfma_f32_16x16x32_bf16 v[42:45], v[156:159], v[212:215], v[42:45]
	v_mfma_f32_16x16x32_bf16 v[30:33], v[148:151], v[220:223], v[30:33]
	v_mfma_f32_16x16x32_bf16 v[26:29], v[156:159], v[220:223], v[26:29]
	v_mfma_f32_16x16x32_bf16 v[14:17], v[148:151], v[228:231], v[14:17]
	v_mfma_f32_16x16x32_bf16 v[10:13], v[156:159], v[228:231], v[10:13]
	v_mfma_f32_16x16x32_bf16 v[62:65], v[152:155], v[208:211], v[62:65]
	v_mfma_f32_16x16x32_bf16 v[58:61], v[160:163], v[208:211], v[58:61]
	v_mfma_f32_16x16x32_bf16 v[46:49], v[152:155], v[216:219], v[46:49]
	v_mfma_f32_16x16x32_bf16 v[42:45], v[160:163], v[216:219], v[42:45]
	v_mfma_f32_16x16x32_bf16 v[30:33], v[152:155], v[224:227], v[30:33]
	v_mfma_f32_16x16x32_bf16 v[26:29], v[160:163], v[224:227], v[26:29]
	v_mfma_f32_16x16x32_bf16 v[14:17], v[152:155], v[232:235], v[14:17]
	v_mfma_f32_16x16x32_bf16 v[10:13], v[160:163], v[232:235], v[10:13]
	v_mfma_f32_16x16x32_bf16 v[54:57], v[166:169], v[202:205], v[54:57]
	v_mfma_f32_16x16x32_bf16 v[50:53], v[174:177], v[202:205], v[50:53]
	v_mfma_f32_16x16x32_bf16 v[38:41], v[166:169], v[212:215], v[38:41]
	v_mfma_f32_16x16x32_bf16 v[34:37], v[174:177], v[212:215], v[34:37]
	v_mfma_f32_16x16x32_bf16 v[22:25], v[166:169], v[220:223], v[22:25]
	v_mfma_f32_16x16x32_bf16 v[18:21], v[174:177], v[220:223], v[18:21]
	v_mfma_f32_16x16x32_bf16 v[6:9], v[166:169], v[228:231], v[6:9]
	v_mfma_f32_16x16x32_bf16 v[2:5], v[174:177], v[228:231], v[2:5]
	v_mfma_f32_16x16x32_bf16 v[54:57], v[170:173], v[208:211], v[54:57]
	v_mfma_f32_16x16x32_bf16 v[50:53], v[178:181], v[208:211], v[50:53]
	v_mfma_f32_16x16x32_bf16 v[38:41], v[170:173], v[216:219], v[38:41]
	v_mfma_f32_16x16x32_bf16 v[34:37], v[178:181], v[216:219], v[34:37]
	v_mfma_f32_16x16x32_bf16 v[22:25], v[170:173], v[224:227], v[22:25]
	v_mfma_f32_16x16x32_bf16 v[18:21], v[178:181], v[224:227], v[18:21]
	v_mfma_f32_16x16x32_bf16 v[6:9], v[170:173], v[232:235], v[6:9]
	v_mfma_f32_16x16x32_bf16 v[2:5], v[178:181], v[232:235], v[2:5]
	s_barrier
; #define PG8_STAGE(bufoff, gbase, voff) do { _Pragma("unroll") for (int _i = 0; _i < 2; ++_i) \
;         __builtin_amdgcn_global_load_lds((const unsigned*)((const char*)(gbase) + (voff)[_i]), (PG8_LAS unsigned*)(lds + (bufoff) + ldsw + _i * 8192), 16, 0, 0); } while (0)
; #define PG8_LDA(dst, b, h) do { _Pragma("unroll") for (int m = 0; m < 4; ++m) _Pragma("unroll") for (int k = 0; k < 2; ++k) dst[m][k] = *(const PG8_LAS bf16x8*)(lds + PG8_SA(b, h) + aoff + m * 2048 + k * 1024); } while (0)
; #define PG8_LDB(dst, b, h) do { _Pragma("unroll") for (int n = 0; n < 2; ++n) _Pragma("unroll") for (int k = 0; k < 2; ++k) dst[n][k] = *(const PG8_LAS bf16x8*)(lds + PG8_SB(b, h) + boff + n * 2048 + k * 1024); } while (0)
; #define PG8_MMA(ai, bj, At, Bt) do { __builtin_amdgcn_s_setprio(1); _Pragma("unroll") for (int m = 0; m < 4; ++m) _Pragma("unroll") for (int n = 0; n < 2; ++n) _Pragma("unroll") for (int k = 0; k < 2; ++k) \
;         acc[ai][bj][m][n] = __builtin_amdgcn_mfma_f32_16x16x32_bf16(Bt[n][k], At[m][k], acc[ai][bj][m][n], 0, 0, 0); __builtin_amdgcn_s_setprio(0); } while (0)
; #define PG8_WAIT_V(n) asm volatile("s_waitcnt vmcnt(" #n ")" ::: "memory")
; #define PG8_WAIT_L(n) asm volatile("s_waitcnt lgkmcnt(" #n ")" ::: "memory")
; #define PG8_BAR __builtin_amdgcn_s_barrier()
; #define PG8_SCHED __builtin_amdgcn_sched_barrier(0)
; template <class Epi, class Sched, bool ALIGN_EPI = false, bool SP2 = false>
; __device__ __forceinline__ void gemm_phase(PG8_LAS unsigned char* lds, const Gemm g, const Sched& S, const Epi& E) {
;     ...
;             PG8_LDB(B0, 1, 0); PG8_LDB(B1, 1, 1); PG8_SCHED; PG8_LDA(At, 1, 0); PG8_STAGE(PG8_SA(0, 1), a2 + hstep, voffA);
;             PG8_WAIT_V(8); PG8_WAIT_L(0); PG8_BAR; PG8_MMA(0, 0, At, B0); PG8_MMA(0, 1, At, B1); PG8_BAR; PG8_SCHED;
;             PG8_LDA(At, 1, 1); PG8_STAGE(PG8_SB(1, 0), b3, voffB); PG8_STAGE(PG8_SB(1, 1), b3 + hstep, voffB); PG8_STAGE(PG8_SA(1, 0), a3, voffA);
;             PG8_WAIT_V(8); PG8_WAIT_L(0); PG8_BAR; PG8_MMA(1, 0, At, B0); PG8_MMA(1, 1, At, B1); PG8_BAR; PG8_SCHED;
	s_add_i32 s59, 0, 0x18000
	s_add_i32 s83, 0, 0x1c000
	v_add_u32_e32 v160, s59, v147
	v_add_u32_e32 v178, s83, v147
	ds_read_b128 v[148:151], v160
	ds_read_b128 v[152:155], v160 offset:1024
	ds_read_b128 v[156:159], v160 offset:2048
	ds_read_b128 v[160:163], v160 offset:3072
	ds_read_b128 v[166:169], v178
	ds_read_b128 v[170:173], v178 offset:1024
	ds_read_b128 v[174:177], v178 offset:2048
	ds_read_b128 v[178:181], v178 offset:3072
	s_add_u32 s76, s76, s10
	s_addc_u32 s77, s77, 0
	s_mov_b32 m0, s84
	v_lshl_add_u64 v[242:243], s[76:77], 0, v[0:1]
	ds_read_b128 v[202:205], v165 offset:32768
	ds_read_b128 v[208:211], v165 offset:33792
	ds_read_b128 v[212:215], v165 offset:34816
	ds_read_b128 v[216:219], v165 offset:35840
	ds_read_b128 v[220:223], v165 offset:36864
	ds_read_b128 v[224:227], v165 offset:37888
	ds_read_b128 v[228:231], v165 offset:38912
	ds_read_b128 v[232:235], v165 offset:39936
	global_load_lds_dwordx4 v[242:243], off
	v_lshl_add_u64 v[242:243], s[76:77], 0, v[130:131]
	s_mov_b32 m0, s74
	s_nop 0
	global_load_lds_dwordx4 v[242:243], off
	s_waitcnt vmcnt(8)
	s_waitcnt lgkmcnt(0)
	s_barrier
	s_waitcnt lgkmcnt(0)
	v_mfma_f32_16x16x32_bf16 v[126:129], v[148:151], v[202:205], v[126:129]
	v_mfma_f32_16x16x32_bf16 v[122:125], v[156:159], v[202:205], v[122:125]
	v_mfma_f32_16x16x32_bf16 v[110:113], v[148:151], v[212:215], v[110:113]
	v_mfma_f32_16x16x32_bf16 v[106:109], v[156:159], v[212:215], v[106:109]
	v_mfma_f32_16x16x32_bf16 v[94:97], v[148:151], v[220:223], v[94:97]
	v_mfma_f32_16x16x32_bf16 v[90:93], v[156:159], v[220:223], v[90:93]
	v_mfma_f32_16x16x32_bf16 v[78:81], v[148:151], v[228:231], v[78:81]
	v_mfma_f32_16x16x32_bf16 v[74:77], v[156:159], v[228:231], v[74:77]
	v_mfma_f32_16x16x32_bf16 v[126:129], v[152:155], v[208:211], v[126:129]
	v_mfma_f32_16x16x32_bf16 v[122:125], v[160:163], v[208:211], v[122:125]
	v_mfma_f32_16x16x32_bf16 v[110:113], v[152:155], v[216:219], v[110:113]
	v_mfma_f32_16x16x32_bf16 v[106:109], v[160:163], v[216:219], v[106:109]
	v_mfma_f32_16x16x32_bf16 v[94:97], v[152:155], v[224:227], v[94:97]
	v_mfma_f32_16x16x32_bf16 v[90:93], v[160:163], v[224:227], v[90:93]
	v_mfma_f32_16x16x32_bf16 v[78:81], v[152:155], v[232:235], v[78:81]
	v_mfma_f32_16x16x32_bf16 v[74:77], v[160:163], v[232:235], v[74:77]
	v_mfma_f32_16x16x32_bf16 v[118:121], v[166:169], v[202:205], v[118:121]
	v_mfma_f32_16x16x32_bf16 v[114:117], v[174:177], v[202:205], v[114:117]
	v_mfma_f32_16x16x32_bf16 v[102:105], v[166:169], v[212:215], v[102:105]
	v_mfma_f32_16x16x32_bf16 v[98:101], v[174:177], v[212:215], v[98:101]
	v_mfma_f32_16x16x32_bf16 v[86:89], v[166:169], v[220:223], v[86:89]
	v_mfma_f32_16x16x32_bf16 v[82:85], v[174:177], v[220:223], v[82:85]
	v_mfma_f32_16x16x32_bf16 v[70:73], v[166:169], v[228:231], v[70:73]
	v_mfma_f32_16x16x32_bf16 v[66:69], v[174:177], v[228:231], v[66:69]
	v_mfma_f32_16x16x32_bf16 v[118:121], v[170:173], v[208:211], v[118:121]
	v_mfma_f32_16x16x32_bf16 v[114:117], v[178:181], v[208:211], v[114:117]
	v_mfma_f32_16x16x32_bf16 v[102:105], v[170:173], v[216:219], v[102:105]
	v_mfma_f32_16x16x32_bf16 v[98:101], v[178:181], v[216:219], v[98:101]
	v_mfma_f32_16x16x32_bf16 v[86:89], v[170:173], v[224:227], v[86:89]
	v_mfma_f32_16x16x32_bf16 v[82:85], v[178:181], v[224:227], v[82:85]
	v_mfma_f32_16x16x32_bf16 v[70:73], v[170:173], v[232:235], v[70:73]
	v_mfma_f32_16x16x32_bf16 v[66:69], v[178:181], v[232:235], v[66:69]
	s_barrier
	s_add_i32 s59, s59, s93
	v_lshl_add_u64 v[136:137], v[136:137], 0, s[66:67]
	s_mov_b32 m0, s59
	ds_read_b128 v[202:205], v165 offset:49152
	ds_read_b128 v[208:211], v165 offset:50176
	ds_read_b128 v[212:215], v165 offset:51200
	ds_read_b128 v[216:219], v165 offset:52224
	ds_read_b128 v[220:223], v165 offset:53248
	ds_read_b128 v[224:227], v165 offset:54272
	ds_read_b128 v[228:231], v165 offset:55296
	ds_read_b128 v[232:235], v165 offset:56320
	global_load_lds_dwordx4 v[136:137], off
	v_lshl_add_u64 v[136:137], v[144:145], 0, s[66:67]
	s_add_i32 m0, s59, 0x2000
	s_add_i32 s59, s83, s93
	global_load_lds_dwordx4 v[136:137], off
	v_lshl_add_u64 v[136:137], v[182:183], 0, s[66:67]
	s_mov_b32 m0, s59
	s_nop 0
	global_load_lds_dwordx4 v[136:137], off
	v_lshl_add_u64 v[136:137], v[236:237], 0, s[66:67]
	s_add_i32 m0, s59, 0x2000
	s_nop 0
	global_load_lds_dwordx4 v[136:137], off
	v_lshl_add_u64 v[136:137], v[238:239], 0, s[66:67]
	s_mov_b32 m0, s73
	s_nop 0
	global_load_lds_dwordx4 v[136:137], off
	v_lshl_add_u64 v[136:137], v[240:241], 0, s[66:67]
	s_mov_b32 m0, s50
	s_nop 0
	global_load_lds_dwordx4 v[136:137], off
	s_waitcnt vmcnt(8)
	s_waitcnt lgkmcnt(0)
	s_barrier
	s_waitcnt lgkmcnt(0)
	v_mfma_f32_16x16x32_bf16 v[62:65], v[148:151], v[202:205], v[62:65]
	v_mfma_f32_16x16x32_bf16 v[58:61], v[156:159], v[202:205], v[58:61]
	v_mfma_f32_16x16x32_bf16 v[46:49], v[148:151], v[212:215], v[46:49]
	v_mfma_f32_16x16x32_bf16 v[42:45], v[156:159], v[212:215], v[42:45]
	v_mfma_f32_16x16x32_bf16 v[30:33], v[148:151], v[220:223], v[30:33]
	v_mfma_f32_16x16x32_bf16 v[26:29], v[156:159], v[220:223], v[26:29]
	v_mfma_f32_16x16x32_bf16 v[14:17], v[148:151], v[228:231], v[14:17]
	v_mfma_f32_16x16x32_bf16 v[10:13], v[156:159], v[228:231], v[10:13]
	v_mfma_f32_16x16x32_bf16 v[62:65], v[152:155], v[208:211], v[62:65]
	v_mfma_f32_16x16x32_bf16 v[58:61], v[160:163], v[208:211], v[58:61]
	v_mfma_f32_16x16x32_bf16 v[46:49], v[152:155], v[216:219], v[46:49]
	v_mfma_f32_16x16x32_bf16 v[42:45], v[160:163], v[216:219], v[42:45]
	v_mfma_f32_16x16x32_bf16 v[30:33], v[152:155], v[224:227], v[30:33]
	v_mfma_f32_16x16x32_bf16 v[26:29], v[160:163], v[224:227], v[26:29]
	v_mfma_f32_16x16x32_bf16 v[14:17], v[152:155], v[232:235], v[14:17]
	v_mfma_f32_16x16x32_bf16 v[10:13], v[160:163], v[232:235], v[10:13]
	v_mfma_f32_16x16x32_bf16 v[54:57], v[166:169], v[202:205], v[54:57]
	v_mfma_f32_16x16x32_bf16 v[50:53], v[174:177], v[202:205], v[50:53]
	v_mfma_f32_16x16x32_bf16 v[38:41], v[166:169], v[212:215], v[38:41]
	v_mfma_f32_16x16x32_bf16 v[34:37], v[174:177], v[212:215], v[34:37]
	v_mfma_f32_16x16x32_bf16 v[22:25], v[166:169], v[220:223], v[22:25]
	v_mfma_f32_16x16x32_bf16 v[18:21], v[174:177], v[220:223], v[18:21]
	v_mfma_f32_16x16x32_bf16 v[6:9], v[166:169], v[228:231], v[6:9]
	v_mfma_f32_16x16x32_bf16 v[2:5], v[174:177], v[228:231], v[2:5]
	v_mfma_f32_16x16x32_bf16 v[54:57], v[170:173], v[208:211], v[54:57]
	v_mfma_f32_16x16x32_bf16 v[50:53], v[178:181], v[208:211], v[50:53]
	v_mfma_f32_16x16x32_bf16 v[38:41], v[170:173], v[216:219], v[38:41]
	v_mfma_f32_16x16x32_bf16 v[34:37], v[178:181], v[216:219], v[34:37]
	v_mfma_f32_16x16x32_bf16 v[22:25], v[170:173], v[224:227], v[22:25]
	v_mfma_f32_16x16x32_bf16 v[18:21], v[178:181], v[224:227], v[18:21]
	v_mfma_f32_16x16x32_bf16 v[6:9], v[170:173], v[232:235], v[6:9]
	v_mfma_f32_16x16x32_bf16 v[2:5], v[178:181], v[232:235], v[2:5]
	s_barrier
	s_add_u32 s48, s48, 0x100
	s_addc_u32 s49, s49, 0
	s_add_u32 s80, s80, 0x100
	s_addc_u32 s81, s81, 0
	s_cmp_ge_u32 s82, s79
	s_mov_b32 s76, s82
	s_cbranch_scc0 .LBB0_849
	s_branch .Lkq_exit

; #define PG8_STAGE(bufoff, gbase, voff) do { _Pragma("unroll") for (int _i = 0; _i < 2; ++_i) \
;         __builtin_amdgcn_global_load_lds((const unsigned*)((const char*)(gbase) + (voff)[_i]), (PG8_LAS unsigned*)(lds + (bufoff) + ldsw + _i * 8192), 16, 0, 0); } while (0)
; #define PG8_LDA(dst, b, h) do { _Pragma("unroll") for (int m = 0; m < 4; ++m) _Pragma("unroll") for (int k = 0; k < 2; ++k) dst[m][k] = *(const PG8_LAS bf16x8*)(lds + PG8_SA(b, h) + aoff + m * 2048 + k * 1024); } while (0)
; #define PG8_LDB(dst, b, h) do { _Pragma("unroll") for (int n = 0; n < 2; ++n) _Pragma("unroll") for (int k = 0; k < 2; ++k) dst[n][k] = *(const PG8_LAS bf16x8*)(lds + PG8_SB(b, h) + boff + n * 2048 + k * 1024); } while (0)
; template <class Epi, class Sched, bool ALIGN_EPI = false, bool SP2 = false>
; __device__ __forceinline__ void gemm_phase(PG8_LAS unsigned char* lds, const Gemm g, const Sched& S, const Epi& E) {
;     ...
;         for (int t = 0; t < nt; t += 2) {
;             const bool last = (t == nt - 2);
;             const char* a1 = cA + (size_t)(t + 1) * kstep;
;             const char* a2 = last ? nA : cA + (size_t)(t + 2) * kstep; const char* b2 = last ? nB : cB + (size_t)(t + 2) * kstep;
;             const char* a3 = a2 + kstep; const char* b3 = b2 + kstep;
;             if (last && has_next) S.a_ready(nxt);
;             if constexpr (SP2) {
;             PG8_LDB(B0, 0, 0); PG8_LDB(B1, 0, 1); PG8_SCHED; PG8_LDA(At, 0, 0); PG8_STAGE(PG8_SA(1, 1), a1 + hstep, voffA);
;             PG8_WAIT_V(8); PG8_WAIT_L(0); PG8_BAR; PG8_MMA(0, 0, At, B0); PG8_MMA(0, 1, At, B1); PG8_BAR; PG8_SCHED;
;             PG8_LDA(At, 0, 1); PG8_STAGE(PG8_SB(0, 0), b2, voffB); PG8_STAGE(PG8_SB(0, 1), b2 + hstep, voffB); PG8_STAGE(PG8_SA(0, 0), a2, voffA);
;             PG8_WAIT_V(8); PG8_WAIT_L(0); PG8_BAR; PG8_MMA(1, 0, At, B0); PG8_MMA(1, 1, At, B1); PG8_BAR; PG8_SCHED;
;             PG8_LDB(B0, 1, 0); PG8_LDB(B1, 1, 1); PG8_SCHED; PG8_LDA(At, 1, 0); PG8_STAGE(PG8_SA(0, 1), a2 + hstep, voffA);
;             PG8_WAIT_V(8); PG8_WAIT_L(0); PG8_BAR; PG8_MMA(0, 0, At, B0); PG8_MMA(0, 1, At, B1); PG8_BAR; PG8_SCHED;
;             PG8_LDA(At, 1, 1); PG8_STAGE(PG8_SB(1, 0), b3, voffB); PG8_STAGE(PG8_SB(1, 1), b3 + hstep, voffB); PG8_STAGE(PG8_SA(1, 0), a3, voffA);
;             PG8_WAIT_V(8); PG8_WAIT_L(0); PG8_BAR; PG8_MMA(1, 0, At, B0); PG8_MMA(1, 1, At, B1); PG8_BAR; PG8_SCHED;
.Lkq_1_loop:
	v_add_u32_e32 v136, 0x10000, v147
	ds_read_b128 v[148:151], v136
	ds_read_b128 v[152:155], v136 offset:1024
	ds_read_b128 v[156:159], v136 offset:2048
	ds_read_b128 v[160:163], v136 offset:3072
	ds_read_b128 v[202:205], v165
	ds_read_b128 v[208:211], v165 offset:1024
	ds_read_b128 v[212:215], v165 offset:2048
	ds_read_b128 v[216:219], v165 offset:3072
	ds_read_b128 v[220:223], v165 offset:4096
	ds_read_b128 v[224:227], v165 offset:5120
	ds_read_b128 v[228:231], v165 offset:6144
	ds_read_b128 v[232:235], v165 offset:7168
	v_lshl_add_u64 v[136:137], s[76:77], 0, v[0:1]
	s_add_i32 m0, s94, 0xc000
	v_lshl_add_u64 v[144:145], s[76:77], 0, v[130:131]
	global_load_lds_dwordx4 v[136:137], off
	s_add_i32 m0, s94, 0xe000
	s_nop 0
	global_load_lds_dwordx4 v[144:145], off
	v_lshl_add_u64 v[182:183], vcc, 0, v[0:1]
	s_add_i32 m0, s93, 0x1c000
	v_lshl_add_u64 v[236:237], vcc, 0, v[130:131]
	global_load_lds_dwordx4 v[182:183], off
	s_add_i32 m0, s93, 0x1e000
	s_nop 0
	global_load_lds_dwordx4 v[236:237], off
	s_cmp_lt_u32 s82, s59
	s_cselect_b32 s83, 0x80, 0
	s_add_u32 s76, s76, s83
	s_addc_u32 s77, s77, 0
	s_add_u32 vcc_lo, vcc_lo, s83
	s_addc_u32 vcc_hi, vcc_hi, 0
	s_add_i32 s82, s82, 1
	s_waitcnt vmcnt(8)
	s_waitcnt lgkmcnt(0)
	s_barrier
	v_mfma_f32_16x16x32_bf16 v[126:129], v[148:151], v[202:205], v[126:129]
	v_mfma_f32_16x16x32_bf16 v[122:125], v[156:159], v[202:205], v[122:125]
	v_mfma_f32_16x16x32_bf16 v[110:113], v[148:151], v[212:215], v[110:113]
	v_mfma_f32_16x16x32_bf16 v[106:109], v[156:159], v[212:215], v[106:109]
	v_mfma_f32_16x16x32_bf16 v[94:97], v[148:151], v[220:223], v[94:97]
	v_mfma_f32_16x16x32_bf16 v[90:93], v[156:159], v[220:223], v[90:93]
	v_mfma_f32_16x16x32_bf16 v[78:81], v[148:151], v[228:231], v[78:81]
	v_mfma_f32_16x16x32_bf16 v[74:77], v[156:159], v[228:231], v[74:77]
	v_mfma_f32_16x16x32_bf16 v[126:129], v[152:155], v[208:211], v[126:129]
	v_mfma_f32_16x16x32_bf16 v[122:125], v[160:163], v[208:211], v[122:125]
	v_mfma_f32_16x16x32_bf16 v[110:113], v[152:155], v[216:219], v[110:113]
	v_mfma_f32_16x16x32_bf16 v[106:109], v[160:163], v[216:219], v[106:109]
	v_mfma_f32_16x16x32_bf16 v[94:97], v[152:155], v[224:227], v[94:97]
	v_mfma_f32_16x16x32_bf16 v[90:93], v[160:163], v[224:227], v[90:93]
	v_mfma_f32_16x16x32_bf16 v[78:81], v[152:155], v[232:235], v[78:81]
	v_mfma_f32_16x16x32_bf16 v[74:77], v[160:163], v[232:235], v[74:77]
	s_barrier
	v_add_u32_e32 v136, 0x18000, v147
	ds_read_b128 v[148:151], v136
	ds_read_b128 v[152:155], v136 offset:1024
	ds_read_b128 v[156:159], v136 offset:2048
	ds_read_b128 v[160:163], v136 offset:3072
	ds_read_b128 v[202:205], v165 offset:32768
	ds_read_b128 v[208:211], v165 offset:33792
	ds_read_b128 v[212:215], v165 offset:34816
	ds_read_b128 v[216:219], v165 offset:35840
	ds_read_b128 v[220:223], v165 offset:36864
	ds_read_b128 v[224:227], v165 offset:37888
	ds_read_b128 v[228:231], v165 offset:38912
	ds_read_b128 v[232:235], v165 offset:39936
	v_lshl_add_u64 v[136:137], s[76:77], 0, v[0:1]
	s_add_i32 m0, s94, 0x0
	v_lshl_add_u64 v[144:145], s[76:77], 0, v[130:131]
	global_load_lds_dwordx4 v[136:137], off
	s_add_i32 m0, s94, 0x2000
	s_nop 0
	global_load_lds_dwordx4 v[144:145], off
	v_lshl_add_u64 v[182:183], vcc, 0, v[0:1]
	s_add_i32 m0, s93, 0x10000
	v_lshl_add_u64 v[236:237], vcc, 0, v[130:131]
	global_load_lds_dwordx4 v[182:183], off
	s_add_i32 m0, s93, 0x12000
	s_nop 0
	global_load_lds_dwordx4 v[236:237], off
	s_cmp_lt_u32 s82, s59
	s_cselect_b32 s83, 0x80, 0
	s_add_u32 s76, s76, s83
	s_addc_u32 s77, s77, 0
	s_add_u32 vcc_lo, vcc_lo, s83
	s_addc_u32 vcc_hi, vcc_hi, 0
	s_add_i32 s82, s82, 1
	s_waitcnt vmcnt(8)
	s_waitcnt lgkmcnt(0)
	s_barrier
	v_mfma_f32_16x16x32_bf16 v[126:129], v[148:151], v[202:205], v[126:129]
	v_mfma_f32_16x16x32_bf16 v[122:125], v[156:159], v[202:205], v[122:125]
	v_mfma_f32_16x16x32_bf16 v[110:113], v[148:151], v[212:215], v[110:113]
	v_mfma_f32_16x16x32_bf16 v[106:109], v[156:159], v[212:215], v[106:109]
	v_mfma_f32_16x16x32_bf16 v[94:97], v[148:151], v[220:223], v[94:97]
	v_mfma_f32_16x16x32_bf16 v[90:93], v[156:159], v[220:223], v[90:93]
	v_mfma_f32_16x16x32_bf16 v[78:81], v[148:151], v[228:231], v[78:81]
	v_mfma_f32_16x16x32_bf16 v[74:77], v[156:159], v[228:231], v[74:77]
	v_mfma_f32_16x16x32_bf16 v[126:129], v[152:155], v[208:211], v[126:129]
	v_mfma_f32_16x16x32_bf16 v[122:125], v[160:163], v[208:211], v[122:125]
	v_mfma_f32_16x16x32_bf16 v[110:113], v[152:155], v[216:219], v[110:113]
	v_mfma_f32_16x16x32_bf16 v[106:109], v[160:163], v[216:219], v[106:109]
	v_mfma_f32_16x16x32_bf16 v[94:97], v[152:155], v[224:227], v[94:97]
	v_mfma_f32_16x16x32_bf16 v[90:93], v[160:163], v[224:227], v[90:93]
	v_mfma_f32_16x16x32_bf16 v[78:81], v[152:155], v[232:235], v[78:81]
	v_mfma_f32_16x16x32_bf16 v[74:77], v[160:163], v[232:235], v[74:77]
	s_barrier
	v_add_u32_e32 v136, 0x14000, v147
	ds_read_b128 v[148:151], v136
	ds_read_b128 v[152:155], v136 offset:1024
	ds_read_b128 v[156:159], v136 offset:2048
	ds_read_b128 v[160:163], v136 offset:3072
	ds_read_b128 v[202:205], v165 offset:16384
	ds_read_b128 v[208:211], v165 offset:17408
	ds_read_b128 v[212:215], v165 offset:18432
	ds_read_b128 v[216:219], v165 offset:19456
	ds_read_b128 v[220:223], v165 offset:20480
	ds_read_b128 v[224:227], v165 offset:21504
	ds_read_b128 v[228:231], v165 offset:22528
	ds_read_b128 v[232:235], v165 offset:23552
	v_lshl_add_u64 v[136:137], s[76:77], 0, v[0:1]
	s_add_i32 m0, s94, 0x8000
	v_lshl_add_u64 v[144:145], s[76:77], 0, v[130:131]
	global_load_lds_dwordx4 v[136:137], off
	s_add_i32 m0, s94, 0xa000
	s_nop 0
	global_load_lds_dwordx4 v[144:145], off
	v_lshl_add_u64 v[182:183], vcc, 0, v[0:1]
	s_add_i32 m0, s93, 0x18000
	v_lshl_add_u64 v[236:237], vcc, 0, v[130:131]
	global_load_lds_dwordx4 v[182:183], off
	s_add_i32 m0, s93, 0x1a000
	s_nop 0
	global_load_lds_dwordx4 v[236:237], off
	s_cmp_lt_u32 s82, s59
	s_cselect_b32 s83, 0x80, 0
	s_add_u32 s76, s76, s83
	s_addc_u32 s77, s77, 0
	s_add_u32 vcc_lo, vcc_lo, s83
	s_addc_u32 vcc_hi, vcc_hi, 0
	s_add_i32 s82, s82, 1
	s_waitcnt vmcnt(8)
	s_waitcnt lgkmcnt(0)
	s_barrier
; #define PG8_STAGE(bufoff, gbase, voff) do { _Pragma("unroll") for (int _i = 0; _i < 2; ++_i) \
;         __builtin_amdgcn_global_load_lds((const unsigned*)((const char*)(gbase) + (voff)[_i]), (PG8_LAS unsigned*)(lds + (bufoff) + ldsw + _i * 8192), 16, 0, 0); } while (0)
; #define PG8_LDA(dst, b, h) do { _Pragma("unroll") for (int m = 0; m < 4; ++m) _Pragma("unroll") for (int k = 0; k < 2; ++k) dst[m][k] = *(const PG8_LAS bf16x8*)(lds + PG8_SA(b, h) + aoff + m * 2048 + k * 1024); } while (0)
; #define PG8_LDB(dst, b, h) do { _Pragma("unroll") for (int n = 0; n < 2; ++n) _Pragma("unroll") for (int k = 0; k < 2; ++k) dst[n][k] = *(const PG8_LAS bf16x8*)(lds + PG8_SB(b, h) + boff + n * 2048 + k * 1024); } while (0)
; template <class Epi, class Sched, bool ALIGN_EPI = false, bool SP2 = false>
; __device__ __forceinline__ void gemm_phase(PG8_LAS unsigned char* lds, const Gemm g, const Sched& S, const Epi& E) {
;     ...
;         for (int t = 0; t < nt; t += 2) {
;             const bool last = (t == nt - 2);
;             const char* a1 = cA + (size_t)(t + 1) * kstep;
;             const char* a2 = last ? nA : cA + (size_t)(t + 2) * kstep; const char* b2 = last ? nB : cB + (size_t)(t + 2) * kstep;
;             const char* a3 = a2 + kstep; const char* b3 = b2 + kstep;
;             if (last && has_next) S.a_ready(nxt);
;             if constexpr (SP2) {
;             PG8_LDB(B0, 0, 0); PG8_LDB(B1, 0, 1); PG8_SCHED; PG8_LDA(At, 0, 0); PG8_STAGE(PG8_SA(1, 1), a1 + hstep, voffA);
;             PG8_WAIT_V(8); PG8_WAIT_L(0); PG8_BAR; PG8_MMA(0, 0, At, B0); PG8_MMA(0, 1, At, B1); PG8_BAR; PG8_SCHED;
;             PG8_LDA(At, 0, 1); PG8_STAGE(PG8_SB(0, 0), b2, voffB); PG8_STAGE(PG8_SB(0, 1), b2 + hstep, voffB); PG8_STAGE(PG8_SA(0, 0), a2, voffA);
;             PG8_WAIT_V(8); PG8_WAIT_L(0); PG8_BAR; PG8_MMA(1, 0, At, B0); PG8_MMA(1, 1, At, B1); PG8_BAR; PG8_SCHED;
;             PG8_LDB(B0, 1, 0); PG8_LDB(B1, 1, 1); PG8_SCHED; PG8_LDA(At, 1, 0); PG8_STAGE(PG8_SA(0, 1), a2 + hstep, voffA);
;             PG8_WAIT_V(8); PG8_WAIT_L(0); PG8_BAR; PG8_MMA(0, 0, At, B0); PG8_MMA(0, 1, At, B1); PG8_BAR; PG8_SCHED;
;             PG8_LDA(At, 1, 1); PG8_STAGE(PG8_SB(1, 0), b3, voffB); PG8_STAGE(PG8_SB(1, 1), b3 + hstep, voffB); PG8_STAGE(PG8_SA(1, 0), a3, voffA);
;             PG8_WAIT_V(8); PG8_WAIT_L(0); PG8_BAR; PG8_MMA(1, 0, At, B0); PG8_MMA(1, 1, At, B1); PG8_BAR; PG8_SCHED;
	v_mfma_f32_16x16x32_bf16 v[126:129], v[148:151], v[202:205], v[126:129]
	v_mfma_f32_16x16x32_bf16 v[122:125], v[156:159], v[202:205], v[122:125]
	v_mfma_f32_16x16x32_bf16 v[110:113], v[148:151], v[212:215], v[110:113]
	v_mfma_f32_16x16x32_bf16 v[106:109], v[156:159], v[212:215], v[106:109]
	v_mfma_f32_16x16x32_bf16 v[94:97], v[148:151], v[220:223], v[94:97]
	v_mfma_f32_16x16x32_bf16 v[90:93], v[156:159], v[220:223], v[90:93]
	v_mfma_f32_16x16x32_bf16 v[78:81], v[148:151], v[228:231], v[78:81]
	v_mfma_f32_16x16x32_bf16 v[74:77], v[156:159], v[228:231], v[74:77]
	v_mfma_f32_16x16x32_bf16 v[126:129], v[152:155], v[208:211], v[126:129]
	v_mfma_f32_16x16x32_bf16 v[122:125], v[160:163], v[208:211], v[122:125]
	v_mfma_f32_16x16x32_bf16 v[110:113], v[152:155], v[216:219], v[110:113]
	v_mfma_f32_16x16x32_bf16 v[106:109], v[160:163], v[216:219], v[106:109]
	v_mfma_f32_16x16x32_bf16 v[94:97], v[152:155], v[224:227], v[94:97]
	v_mfma_f32_16x16x32_bf16 v[90:93], v[160:163], v[224:227], v[90:93]
	v_mfma_f32_16x16x32_bf16 v[78:81], v[152:155], v[232:235], v[78:81]
	v_mfma_f32_16x16x32_bf16 v[74:77], v[160:163], v[232:235], v[74:77]
	s_barrier
	v_add_u32_e32 v136, 0x1c000, v147
	ds_read_b128 v[148:151], v136
	ds_read_b128 v[152:155], v136 offset:1024
	ds_read_b128 v[156:159], v136 offset:2048
	ds_read_b128 v[160:163], v136 offset:3072
	ds_read_b128 v[202:205], v165 offset:49152
	ds_read_b128 v[208:211], v165 offset:50176
	ds_read_b128 v[212:215], v165 offset:51200
	ds_read_b128 v[216:219], v165 offset:52224
	ds_read_b128 v[220:223], v165 offset:53248
	ds_read_b128 v[224:227], v165 offset:54272
	ds_read_b128 v[228:231], v165 offset:55296
	ds_read_b128 v[232:235], v165 offset:56320
	v_lshl_add_u64 v[136:137], s[76:77], 0, v[0:1]
	s_add_i32 m0, s94, 0x4000
	v_lshl_add_u64 v[144:145], s[76:77], 0, v[130:131]
	global_load_lds_dwordx4 v[136:137], off
	s_add_i32 m0, s94, 0x6000
	s_nop 0
	global_load_lds_dwordx4 v[144:145], off
	v_lshl_add_u64 v[182:183], vcc, 0, v[0:1]
	s_add_i32 m0, s93, 0x14000
	v_lshl_add_u64 v[236:237], vcc, 0, v[130:131]
	global_load_lds_dwordx4 v[182:183], off
	s_add_i32 m0, s93, 0x16000
	s_nop 0
	global_load_lds_dwordx4 v[236:237], off
	s_cmp_lt_u32 s82, s59
	s_cselect_b32 s83, 0x80, 0
	s_add_u32 s76, s76, s83
	s_addc_u32 s77, s77, 0
	s_add_u32 vcc_lo, vcc_lo, s83
	s_addc_u32 vcc_hi, vcc_hi, 0
	s_add_i32 s82, s82, 1
	s_waitcnt vmcnt(8)
	s_waitcnt lgkmcnt(0)
	s_barrier
	v_mfma_f32_16x16x32_bf16 v[126:129], v[148:151], v[202:205], v[126:129]
	v_mfma_f32_16x16x32_bf16 v[122:125], v[156:159], v[202:205], v[122:125]
	v_mfma_f32_16x16x32_bf16 v[110:113], v[148:151], v[212:215], v[110:113]
	v_mfma_f32_16x16x32_bf16 v[106:109], v[156:159], v[212:215], v[106:109]
	v_mfma_f32_16x16x32_bf16 v[94:97], v[148:151], v[220:223], v[94:97]
	v_mfma_f32_16x16x32_bf16 v[90:93], v[156:159], v[220:223], v[90:93]
	v_mfma_f32_16x16x32_bf16 v[78:81], v[148:151], v[228:231], v[78:81]
	v_mfma_f32_16x16x32_bf16 v[74:77], v[156:159], v[228:231], v[74:77]
	v_mfma_f32_16x16x32_bf16 v[126:129], v[152:155], v[208:211], v[126:129]
	v_mfma_f32_16x16x32_bf16 v[122:125], v[160:163], v[208:211], v[122:125]
	v_mfma_f32_16x16x32_bf16 v[110:113], v[152:155], v[216:219], v[110:113]
	v_mfma_f32_16x16x32_bf16 v[106:109], v[160:163], v[216:219], v[106:109]
	v_mfma_f32_16x16x32_bf16 v[94:97], v[152:155], v[224:227], v[94:97]
	v_mfma_f32_16x16x32_bf16 v[90:93], v[160:163], v[224:227], v[90:93]
	v_mfma_f32_16x16x32_bf16 v[78:81], v[152:155], v[232:235], v[78:81]
	v_mfma_f32_16x16x32_bf16 v[74:77], v[160:163], v[232:235], v[74:77]
	s_barrier
	s_add_i32 s83, s82, -3
	s_cmp_lt_u32 s83, s79
	s_cbranch_scc1 .Lkq_1_loop
	s_mov_b64 s[76:77], s[8:9]
	s_mov_b64 vcc, s[46:47]
	v_lshl_add_u64 v[136:137], vcc, 0, v[0:1]
	s_add_i32 m0, s93, 0x10000
	v_lshl_add_u64 v[144:145], vcc, 0, v[130:131]
	global_load_lds_dwordx4 v[136:137], off
	s_add_i32 m0, s93, 0x12000
	s_nop 0
	global_load_lds_dwordx4 v[144:145], off
	s_add_u32 vcc_lo, vcc_lo, s10
	s_addc_u32 vcc_hi, vcc_hi, 0
	v_lshl_add_u64 v[136:137], vcc, 0, v[0:1]
	s_add_i32 m0, s93, 0x14000
	v_lshl_add_u64 v[144:145], vcc, 0, v[130:131]
	global_load_lds_dwordx4 v[136:137], off
	s_add_i32 m0, s93, 0x16000
	s_nop 0
	global_load_lds_dwordx4 v[144:145], off
	v_lshl_add_u64 v[136:137], s[76:77], 0, v[0:1]
	s_add_i32 m0, s94, 0x0
	v_lshl_add_u64 v[144:145], s[76:77], 0, v[130:131]
	global_load_lds_dwordx4 v[136:137], off
	s_add_i32 m0, s94, 0x2000
	s_nop 0
	global_load_lds_dwordx4 v[144:145], off
	s_add_u32 s76, s76, s10
	s_addc_u32 s77, s77, 0
	v_lshl_add_u64 v[136:137], s[76:77], 0, v[0:1]
	s_add_i32 m0, s94, 0x4000
	v_lshl_add_u64 v[144:145], s[76:77], 0, v[130:131]
	global_load_lds_dwordx4 v[136:137], off
	s_add_i32 m0, s94, 0x6000
	s_nop 0
	global_load_lds_dwordx4 v[144:145], off
	s_add_u32 s76, s8, 0x80
	s_addc_u32 s77, s9, 0
	s_add_u32 vcc_lo, s46, 0x80
	s_addc_u32 vcc_hi, s47, 0
	v_lshl_add_u64 v[136:137], vcc, 0, v[0:1]
	s_add_i32 m0, s93, 0x18000
	v_lshl_add_u64 v[144:145], vcc, 0, v[130:131]
	global_load_lds_dwordx4 v[136:137], off
	s_add_i32 m0, s93, 0x1a000
	s_nop 0
	global_load_lds_dwordx4 v[144:145], off
	s_add_u32 vcc_lo, vcc_lo, s10
	s_addc_u32 vcc_hi, vcc_hi, 0
	v_lshl_add_u64 v[136:137], vcc, 0, v[0:1]
	s_add_i32 m0, s93, 0x1c000
	v_lshl_add_u64 v[144:145], vcc, 0, v[130:131]
	global_load_lds_dwordx4 v[136:137], off
	s_add_i32 m0, s93, 0x1e000
	s_nop 0
	global_load_lds_dwordx4 v[144:145], off
	v_lshl_add_u64 v[136:137], s[76:77], 0, v[0:1]
	s_add_i32 m0, s94, 0x8000
	v_lshl_add_u64 v[144:145], s[76:77], 0, v[130:131]
	global_load_lds_dwordx4 v[136:137], off
	s_add_i32 m0, s94, 0xa000
	s_nop 0
	global_load_lds_dwordx4 v[144:145], off
	s_branch .Lkq_exit
	s_nop 0
	s_nop 0
	s_nop 0
	s_nop 0
	s_nop 0
	s_nop 0
	s_nop 0
	s_nop 0

; #define PG8_STAGE(bufoff, gbase, voff) do { _Pragma("unroll") for (int _i = 0; _i < 2; ++_i) \
;         __builtin_amdgcn_global_load_lds((const unsigned*)((const char*)(gbase) + (voff)[_i]), (PG8_LAS unsigned*)(lds + (bufoff) + ldsw + _i * 8192), 16, 0, 0); } while (0)
; #define PG8_LDA(dst, b, h) do { _Pragma("unroll") for (int m = 0; m < 4; ++m) _Pragma("unroll") for (int k = 0; k < 2; ++k) dst[m][k] = *(const PG8_LAS bf16x8*)(lds + PG8_SA(b, h) + aoff + m * 2048 + k * 1024); } while (0)
; #define PG8_LDB(dst, b, h) do { _Pragma("unroll") for (int n = 0; n < 2; ++n) _Pragma("unroll") for (int k = 0; k < 2; ++k) dst[n][k] = *(const PG8_LAS bf16x8*)(lds + PG8_SB(b, h) + boff + n * 2048 + k * 1024); } while (0)
; template <class Epi, class Sched, bool ALIGN_EPI = false, bool SP2 = false>
; __device__ __forceinline__ void gemm_phase(PG8_LAS unsigned char* lds, const Gemm g, const Sched& S, const Epi& E) {
;     ...
;         for (int t = 0; t < nt; t += 2) {
;             const bool last = (t == nt - 2);
;             const char* a1 = cA + (size_t)(t + 1) * kstep;
;             const char* a2 = last ? nA : cA + (size_t)(t + 2) * kstep; const char* b2 = last ? nB : cB + (size_t)(t + 2) * kstep;
;             const char* a3 = a2 + kstep; const char* b3 = b2 + kstep;
;             if (last && has_next) S.a_ready(nxt);
;             if constexpr (SP2) {
;             PG8_LDB(B0, 0, 0); PG8_LDB(B1, 0, 1); PG8_SCHED; PG8_LDA(At, 0, 0); PG8_STAGE(PG8_SA(1, 1), a1 + hstep, voffA);
;             PG8_WAIT_V(8); PG8_WAIT_L(0); PG8_BAR; PG8_MMA(0, 0, At, B0); PG8_MMA(0, 1, At, B1); PG8_BAR; PG8_SCHED;
;             PG8_LDA(At, 0, 1); PG8_STAGE(PG8_SB(0, 0), b2, voffB); PG8_STAGE(PG8_SB(0, 1), b2 + hstep, voffB); PG8_STAGE(PG8_SA(0, 0), a2, voffA);
;             PG8_WAIT_V(8); PG8_WAIT_L(0); PG8_BAR; PG8_MMA(1, 0, At, B0); PG8_MMA(1, 1, At, B1); PG8_BAR; PG8_SCHED;
;             PG8_LDB(B0, 1, 0); PG8_LDB(B1, 1, 1); PG8_SCHED; PG8_LDA(At, 1, 0); PG8_STAGE(PG8_SA(0, 1), a2 + hstep, voffA);
;             PG8_WAIT_V(8); PG8_WAIT_L(0); PG8_BAR; PG8_MMA(0, 0, At, B0); PG8_MMA(0, 1, At, B1); PG8_BAR; PG8_SCHED;
;             PG8_LDA(At, 1, 1); PG8_STAGE(PG8_SB(1, 0), b3, voffB); PG8_STAGE(PG8_SB(1, 1), b3 + hstep, voffB); PG8_STAGE(PG8_SA(1, 0), a3, voffA);
;             PG8_WAIT_V(8); PG8_WAIT_L(0); PG8_BAR; PG8_MMA(1, 0, At, B0); PG8_MMA(1, 1, At, B1); PG8_BAR; PG8_SCHED;
.Lkq_2_loop:
	v_add_u32_e32 v136, 0x10000, v147
	ds_read_b128 v[148:151], v136
	ds_read_b128 v[152:155], v136 offset:1024
	ds_read_b128 v[156:159], v136 offset:2048
	ds_read_b128 v[160:163], v136 offset:3072
	ds_read_b128 v[202:205], v165 offset:16384
	ds_read_b128 v[208:211], v165 offset:17408
	ds_read_b128 v[212:215], v165 offset:18432
	ds_read_b128 v[216:219], v165 offset:19456
	ds_read_b128 v[220:223], v165 offset:20480
	ds_read_b128 v[224:227], v165 offset:21504
	ds_read_b128 v[228:231], v165 offset:22528
	ds_read_b128 v[232:235], v165 offset:23552
	v_lshl_add_u64 v[136:137], s[76:77], 0, v[0:1]
	s_add_i32 m0, s94, 0x8000
	v_lshl_add_u64 v[144:145], s[76:77], 0, v[130:131]
	global_load_lds_dwordx4 v[136:137], off
	s_add_i32 m0, s94, 0xa000
	s_nop 0
	global_load_lds_dwordx4 v[144:145], off
	v_lshl_add_u64 v[182:183], vcc, 0, v[0:1]
	s_add_i32 m0, s93, 0x1c000
	v_lshl_add_u64 v[236:237], vcc, 0, v[130:131]
	global_load_lds_dwordx4 v[182:183], off
	s_add_i32 m0, s93, 0x1e000
	s_nop 0
	global_load_lds_dwordx4 v[236:237], off
	s_cmp_lt_u32 s82, s59
	s_cselect_b32 s83, 0x80, 0
	s_add_u32 s76, s76, s83
	s_addc_u32 s77, s77, 0
	s_add_u32 vcc_lo, vcc_lo, s83
	s_addc_u32 vcc_hi, vcc_hi, 0
	s_add_i32 s82, s82, 1
	s_waitcnt vmcnt(8)
	s_waitcnt lgkmcnt(0)
	s_barrier
	v_mfma_f32_16x16x32_bf16 v[62:65], v[148:151], v[202:205], v[62:65]
	v_mfma_f32_16x16x32_bf16 v[58:61], v[156:159], v[202:205], v[58:61]
	v_mfma_f32_16x16x32_bf16 v[46:49], v[148:151], v[212:215], v[46:49]
	v_mfma_f32_16x16x32_bf16 v[42:45], v[156:159], v[212:215], v[42:45]
	v_mfma_f32_16x16x32_bf16 v[30:33], v[148:151], v[220:223], v[30:33]
	v_mfma_f32_16x16x32_bf16 v[26:29], v[156:159], v[220:223], v[26:29]
	v_mfma_f32_16x16x32_bf16 v[14:17], v[148:151], v[228:231], v[14:17]
	v_mfma_f32_16x16x32_bf16 v[10:13], v[156:159], v[228:231], v[10:13]
	v_mfma_f32_16x16x32_bf16 v[62:65], v[152:155], v[208:211], v[62:65]
	v_mfma_f32_16x16x32_bf16 v[58:61], v[160:163], v[208:211], v[58:61]
	v_mfma_f32_16x16x32_bf16 v[46:49], v[152:155], v[216:219], v[46:49]
	v_mfma_f32_16x16x32_bf16 v[42:45], v[160:163], v[216:219], v[42:45]
	v_mfma_f32_16x16x32_bf16 v[30:33], v[152:155], v[224:227], v[30:33]
	v_mfma_f32_16x16x32_bf16 v[26:29], v[160:163], v[224:227], v[26:29]
	v_mfma_f32_16x16x32_bf16 v[14:17], v[152:155], v[232:235], v[14:17]
	v_mfma_f32_16x16x32_bf16 v[10:13], v[160:163], v[232:235], v[10:13]
	s_barrier
	v_add_u32_e32 v136, 0x18000, v147
	ds_read_b128 v[148:151], v136
	ds_read_b128 v[152:155], v136 offset:1024
	ds_read_b128 v[156:159], v136 offset:2048
	ds_read_b128 v[160:163], v136 offset:3072
	ds_read_b128 v[202:205], v165 offset:49152
	ds_read_b128 v[208:211], v165 offset:50176
	ds_read_b128 v[212:215], v165 offset:51200
	ds_read_b128 v[216:219], v165 offset:52224
	ds_read_b128 v[220:223], v165 offset:53248
	ds_read_b128 v[224:227], v165 offset:54272
	ds_read_b128 v[228:231], v165 offset:55296
	ds_read_b128 v[232:235], v165 offset:56320
	v_lshl_add_u64 v[136:137], s[76:77], 0, v[0:1]
	s_add_i32 m0, s94, 0x4000
	v_lshl_add_u64 v[144:145], s[76:77], 0, v[130:131]
	global_load_lds_dwordx4 v[136:137], off
	s_add_i32 m0, s94, 0x6000
	s_nop 0
	global_load_lds_dwordx4 v[144:145], off
	v_lshl_add_u64 v[182:183], vcc, 0, v[0:1]
	s_add_i32 m0, s93, 0x10000
	v_lshl_add_u64 v[236:237], vcc, 0, v[130:131]
	global_load_lds_dwordx4 v[182:183], off
	s_add_i32 m0, s93, 0x12000
	s_nop 0
	global_load_lds_dwordx4 v[236:237], off
	s_cmp_lt_u32 s82, s59
	s_cselect_b32 s83, 0x80, 0
	s_add_u32 s76, s76, s83
	s_addc_u32 s77, s77, 0
	s_add_u32 vcc_lo, vcc_lo, s83
	s_addc_u32 vcc_hi, vcc_hi, 0
	s_add_i32 s82, s82, 1
	s_waitcnt vmcnt(8)
	s_waitcnt lgkmcnt(0)
	s_barrier
	v_mfma_f32_16x16x32_bf16 v[62:65], v[148:151], v[202:205], v[62:65]
	v_mfma_f32_16x16x32_bf16 v[58:61], v[156:159], v[202:205], v[58:61]
	v_mfma_f32_16x16x32_bf16 v[46:49], v[148:151], v[212:215], v[46:49]
	v_mfma_f32_16x16x32_bf16 v[42:45], v[156:159], v[212:215], v[42:45]
	v_mfma_f32_16x16x32_bf16 v[30:33], v[148:151], v[220:223], v[30:33]
	v_mfma_f32_16x16x32_bf16 v[26:29], v[156:159], v[220:223], v[26:29]
	v_mfma_f32_16x16x32_bf16 v[14:17], v[148:151], v[228:231], v[14:17]
	v_mfma_f32_16x16x32_bf16 v[10:13], v[156:159], v[228:231], v[10:13]
	v_mfma_f32_16x16x32_bf16 v[62:65], v[152:155], v[208:211], v[62:65]
	v_mfma_f32_16x16x32_bf16 v[58:61], v[160:163], v[208:211], v[58:61]
	v_mfma_f32_16x16x32_bf16 v[46:49], v[152:155], v[216:219], v[46:49]
	v_mfma_f32_16x16x32_bf16 v[42:45], v[160:163], v[216:219], v[42:45]
	v_mfma_f32_16x16x32_bf16 v[30:33], v[152:155], v[224:227], v[30:33]
	v_mfma_f32_16x16x32_bf16 v[26:29], v[160:163], v[224:227], v[26:29]
	v_mfma_f32_16x16x32_bf16 v[14:17], v[152:155], v[232:235], v[14:17]
	v_mfma_f32_16x16x32_bf16 v[10:13], v[160:163], v[232:235], v[10:13]
	s_barrier
	v_add_u32_e32 v136, 0x14000, v147
	ds_read_b128 v[148:151], v136
	ds_read_b128 v[152:155], v136 offset:1024
	ds_read_b128 v[156:159], v136 offset:2048
	ds_read_b128 v[160:163], v136 offset:3072
	ds_read_b128 v[202:205], v165
	ds_read_b128 v[208:211], v165 offset:1024
	ds_read_b128 v[212:215], v165 offset:2048
	ds_read_b128 v[216:219], v165 offset:3072
	ds_read_b128 v[220:223], v165 offset:4096
	ds_read_b128 v[224:227], v165 offset:5120
	ds_read_b128 v[228:231], v165 offset:6144
	ds_read_b128 v[232:235], v165 offset:7168
	v_lshl_add_u64 v[136:137], s[76:77], 0, v[0:1]
	s_add_i32 m0, s94, 0xc000
	v_lshl_add_u64 v[144:145], s[76:77], 0, v[130:131]
	global_load_lds_dwordx4 v[136:137], off
	s_add_i32 m0, s94, 0xe000
	s_nop 0
	global_load_lds_dwordx4 v[144:145], off
	v_lshl_add_u64 v[182:183], vcc, 0, v[0:1]
	s_add_i32 m0, s93, 0x18000
	v_lshl_add_u64 v[236:237], vcc, 0, v[130:131]
	global_load_lds_dwordx4 v[182:183], off
	s_add_i32 m0, s93, 0x1a000
	s_nop 0
	global_load_lds_dwordx4 v[236:237], off
	s_cmp_lt_u32 s82, s59
	s_cselect_b32 s83, 0x80, 0
	s_add_u32 s76, s76, s83
	s_addc_u32 s77, s77, 0
	s_add_u32 vcc_lo, vcc_lo, s83
	s_addc_u32 vcc_hi, vcc_hi, 0
	s_add_i32 s82, s82, 1
	s_waitcnt vmcnt(8)
	s_waitcnt lgkmcnt(0)
	s_barrier
; #define PG8_STAGE(bufoff, gbase, voff) do { _Pragma("unroll") for (int _i = 0; _i < 2; ++_i) \
;         __builtin_amdgcn_global_load_lds((const unsigned*)((const char*)(gbase) + (voff)[_i]), (PG8_LAS unsigned*)(lds + (bufoff) + ldsw + _i * 8192), 16, 0, 0); } while (0)
; #define PG8_LDA(dst, b, h) do { _Pragma("unroll") for (int m = 0; m < 4; ++m) _Pragma("unroll") for (int k = 0; k < 2; ++k) dst[m][k] = *(const PG8_LAS bf16x8*)(lds + PG8_SA(b, h) + aoff + m * 2048 + k * 1024); } while (0)
; #define PG8_LDB(dst, b, h) do { _Pragma("unroll") for (int n = 0; n < 2; ++n) _Pragma("unroll") for (int k = 0; k < 2; ++k) dst[n][k] = *(const PG8_LAS bf16x8*)(lds + PG8_SB(b, h) + boff + n * 2048 + k * 1024); } while (0)
; template <class Epi, class Sched, bool ALIGN_EPI = false, bool SP2 = false>
; __device__ __forceinline__ void gemm_phase(PG8_LAS unsigned char* lds, const Gemm g, const Sched& S, const Epi& E) {
;     ...
;         for (int t = 0; t < nt; t += 2) {
;             const bool last = (t == nt - 2);
;             const char* a1 = cA + (size_t)(t + 1) * kstep;
;             const char* a2 = last ? nA : cA + (size_t)(t + 2) * kstep; const char* b2 = last ? nB : cB + (size_t)(t + 2) * kstep;
;             const char* a3 = a2 + kstep; const char* b3 = b2 + kstep;
;             if (last && has_next) S.a_ready(nxt);
;             if constexpr (SP2) {
;             PG8_LDB(B0, 0, 0); PG8_LDB(B1, 0, 1); PG8_SCHED; PG8_LDA(At, 0, 0); PG8_STAGE(PG8_SA(1, 1), a1 + hstep, voffA);
;             PG8_WAIT_V(8); PG8_WAIT_L(0); PG8_BAR; PG8_MMA(0, 0, At, B0); PG8_MMA(0, 1, At, B1); PG8_BAR; PG8_SCHED;
;             PG8_LDA(At, 0, 1); PG8_STAGE(PG8_SB(0, 0), b2, voffB); PG8_STAGE(PG8_SB(0, 1), b2 + hstep, voffB); PG8_STAGE(PG8_SA(0, 0), a2, voffA);
;             PG8_WAIT_V(8); PG8_WAIT_L(0); PG8_BAR; PG8_MMA(1, 0, At, B0); PG8_MMA(1, 1, At, B1); PG8_BAR; PG8_SCHED;
;             PG8_LDB(B0, 1, 0); PG8_LDB(B1, 1, 1); PG8_SCHED; PG8_LDA(At, 1, 0); PG8_STAGE(PG8_SA(0, 1), a2 + hstep, voffA);
;             PG8_WAIT_V(8); PG8_WAIT_L(0); PG8_BAR; PG8_MMA(0, 0, At, B0); PG8_MMA(0, 1, At, B1); PG8_BAR; PG8_SCHED;
;             PG8_LDA(At, 1, 1); PG8_STAGE(PG8_SB(1, 0), b3, voffB); PG8_STAGE(PG8_SB(1, 1), b3 + hstep, voffB); PG8_STAGE(PG8_SA(1, 0), a3, voffA);
;             PG8_WAIT_V(8); PG8_WAIT_L(0); PG8_BAR; PG8_MMA(1, 0, At, B0); PG8_MMA(1, 1, At, B1); PG8_BAR; PG8_SCHED;
	v_mfma_f32_16x16x32_bf16 v[62:65], v[148:151], v[202:205], v[62:65]
	v_mfma_f32_16x16x32_bf16 v[58:61], v[156:159], v[202:205], v[58:61]
	v_mfma_f32_16x16x32_bf16 v[46:49], v[148:151], v[212:215], v[46:49]
	v_mfma_f32_16x16x32_bf16 v[42:45], v[156:159], v[212:215], v[42:45]
	v_mfma_f32_16x16x32_bf16 v[30:33], v[148:151], v[220:223], v[30:33]
	v_mfma_f32_16x16x32_bf16 v[26:29], v[156:159], v[220:223], v[26:29]
	v_mfma_f32_16x16x32_bf16 v[14:17], v[148:151], v[228:231], v[14:17]
	v_mfma_f32_16x16x32_bf16 v[10:13], v[156:159], v[228:231], v[10:13]
	v_mfma_f32_16x16x32_bf16 v[62:65], v[152:155], v[208:211], v[62:65]
	v_mfma_f32_16x16x32_bf16 v[58:61], v[160:163], v[208:211], v[58:61]
	v_mfma_f32_16x16x32_bf16 v[46:49], v[152:155], v[216:219], v[46:49]
	v_mfma_f32_16x16x32_bf16 v[42:45], v[160:163], v[216:219], v[42:45]
	v_mfma_f32_16x16x32_bf16 v[30:33], v[152:155], v[224:227], v[30:33]
	v_mfma_f32_16x16x32_bf16 v[26:29], v[160:163], v[224:227], v[26:29]
	v_mfma_f32_16x16x32_bf16 v[14:17], v[152:155], v[232:235], v[14:17]
	v_mfma_f32_16x16x32_bf16 v[10:13], v[160:163], v[232:235], v[10:13]
	s_barrier
	v_add_u32_e32 v136, 0x1c000, v147
	ds_read_b128 v[148:151], v136
	ds_read_b128 v[152:155], v136 offset:1024
	ds_read_b128 v[156:159], v136 offset:2048
	ds_read_b128 v[160:163], v136 offset:3072
	ds_read_b128 v[202:205], v165 offset:32768
	ds_read_b128 v[208:211], v165 offset:33792
	ds_read_b128 v[212:215], v165 offset:34816
	ds_read_b128 v[216:219], v165 offset:35840
	ds_read_b128 v[220:223], v165 offset:36864
	ds_read_b128 v[224:227], v165 offset:37888
	ds_read_b128 v[228:231], v165 offset:38912
	ds_read_b128 v[232:235], v165 offset:39936
	v_lshl_add_u64 v[136:137], s[76:77], 0, v[0:1]
	s_add_i32 m0, s94, 0x0
	v_lshl_add_u64 v[144:145], s[76:77], 0, v[130:131]
	global_load_lds_dwordx4 v[136:137], off
	s_add_i32 m0, s94, 0x2000
	s_nop 0
	global_load_lds_dwordx4 v[144:145], off
	v_lshl_add_u64 v[182:183], vcc, 0, v[0:1]
	s_add_i32 m0, s93, 0x14000
	v_lshl_add_u64 v[236:237], vcc, 0, v[130:131]
	global_load_lds_dwordx4 v[182:183], off
	s_add_i32 m0, s93, 0x16000
	s_nop 0
	global_load_lds_dwordx4 v[236:237], off
	s_cmp_lt_u32 s82, s59
	s_cselect_b32 s83, 0x80, 0
	s_add_u32 s76, s76, s83
	s_addc_u32 s77, s77, 0
	s_add_u32 vcc_lo, vcc_lo, s83
	s_addc_u32 vcc_hi, vcc_hi, 0
	s_add_i32 s82, s82, 1
	s_waitcnt vmcnt(8)
	s_waitcnt lgkmcnt(0)
	s_barrier
	v_mfma_f32_16x16x32_bf16 v[62:65], v[148:151], v[202:205], v[62:65]
	v_mfma_f32_16x16x32_bf16 v[58:61], v[156:159], v[202:205], v[58:61]
	v_mfma_f32_16x16x32_bf16 v[46:49], v[148:151], v[212:215], v[46:49]
	v_mfma_f32_16x16x32_bf16 v[42:45], v[156:159], v[212:215], v[42:45]
	v_mfma_f32_16x16x32_bf16 v[30:33], v[148:151], v[220:223], v[30:33]
	v_mfma_f32_16x16x32_bf16 v[26:29], v[156:159], v[220:223], v[26:29]
	v_mfma_f32_16x16x32_bf16 v[14:17], v[148:151], v[228:231], v[14:17]
	v_mfma_f32_16x16x32_bf16 v[10:13], v[156:159], v[228:231], v[10:13]
	v_mfma_f32_16x16x32_bf16 v[62:65], v[152:155], v[208:211], v[62:65]
	v_mfma_f32_16x16x32_bf16 v[58:61], v[160:163], v[208:211], v[58:61]
	v_mfma_f32_16x16x32_bf16 v[46:49], v[152:155], v[216:219], v[46:49]
	v_mfma_f32_16x16x32_bf16 v[42:45], v[160:163], v[216:219], v[42:45]
	v_mfma_f32_16x16x32_bf16 v[30:33], v[152:155], v[224:227], v[30:33]
	v_mfma_f32_16x16x32_bf16 v[26:29], v[160:163], v[224:227], v[26:29]
	v_mfma_f32_16x16x32_bf16 v[14:17], v[152:155], v[232:235], v[14:17]
	v_mfma_f32_16x16x32_bf16 v[10:13], v[160:163], v[232:235], v[10:13]
	s_barrier
	s_add_i32 s83, s82, -3
	s_cmp_lt_u32 s83, s79
	s_cbranch_scc1 .Lkq_2_loop
	s_mov_b64 s[76:77], s[8:9]
	s_mov_b64 vcc, s[46:47]
	v_lshl_add_u64 v[136:137], vcc, 0, v[0:1]
	s_add_i32 m0, s93, 0x10000
	v_lshl_add_u64 v[144:145], vcc, 0, v[130:131]
	global_load_lds_dwordx4 v[136:137], off
	s_add_i32 m0, s93, 0x12000
	s_nop 0
	global_load_lds_dwordx4 v[144:145], off
	s_add_u32 vcc_lo, vcc_lo, s10
	s_addc_u32 vcc_hi, vcc_hi, 0
	v_lshl_add_u64 v[136:137], vcc, 0, v[0:1]
	s_add_i32 m0, s93, 0x14000
	v_lshl_add_u64 v[144:145], vcc, 0, v[130:131]
	global_load_lds_dwordx4 v[136:137], off
	s_add_i32 m0, s93, 0x16000
	s_nop 0
	global_load_lds_dwordx4 v[144:145], off
	v_lshl_add_u64 v[136:137], s[76:77], 0, v[0:1]
	s_add_i32 m0, s94, 0x0
	v_lshl_add_u64 v[144:145], s[76:77], 0, v[130:131]
	global_load_lds_dwordx4 v[136:137], off
	s_add_i32 m0, s94, 0x2000
	s_nop 0
	global_load_lds_dwordx4 v[144:145], off
	s_add_u32 s76, s76, s10
	s_addc_u32 s77, s77, 0
	v_lshl_add_u64 v[136:137], s[76:77], 0, v[0:1]
	s_add_i32 m0, s94, 0x4000
	v_lshl_add_u64 v[144:145], s[76:77], 0, v[130:131]
	global_load_lds_dwordx4 v[136:137], off
	s_add_i32 m0, s94, 0x6000
	s_nop 0
	global_load_lds_dwordx4 v[144:145], off
	s_add_u32 s76, s8, 0x80
	s_addc_u32 s77, s9, 0
	s_add_u32 vcc_lo, s46, 0x80
	s_addc_u32 vcc_hi, s47, 0
	v_lshl_add_u64 v[136:137], vcc, 0, v[0:1]
	s_add_i32 m0, s93, 0x18000
	v_lshl_add_u64 v[144:145], vcc, 0, v[130:131]
	global_load_lds_dwordx4 v[136:137], off
	s_add_i32 m0, s93, 0x1a000
	s_nop 0
	global_load_lds_dwordx4 v[144:145], off
	s_add_u32 vcc_lo, vcc_lo, s10
	s_addc_u32 vcc_hi, vcc_hi, 0
	v_lshl_add_u64 v[136:137], vcc, 0, v[0:1]
	s_add_i32 m0, s93, 0x1c000
	v_lshl_add_u64 v[144:145], vcc, 0, v[130:131]
	global_load_lds_dwordx4 v[136:137], off
	s_add_i32 m0, s93, 0x1e000
	s_nop 0
	global_load_lds_dwordx4 v[144:145], off
	v_lshl_add_u64 v[136:137], s[76:77], 0, v[0:1]
	s_add_i32 m0, s94, 0x8000
	v_lshl_add_u64 v[144:145], s[76:77], 0, v[130:131]
	global_load_lds_dwordx4 v[136:137], off
	s_add_i32 m0, s94, 0xa000
	s_nop 0
	global_load_lds_dwordx4 v[144:145], off
	s_branch .Lkq_exit
	s_nop 0
	s_nop 0
	s_nop 0
	s_nop 0
	s_nop 0
	s_nop 0
	s_nop 0
	s_nop 0

; #define PG8_STAGE(bufoff, gbase, voff) do { _Pragma("unroll") for (int _i = 0; _i < 2; ++_i) \
;         __builtin_amdgcn_global_load_lds((const unsigned*)((const char*)(gbase) + (voff)[_i]), (PG8_LAS unsigned*)(lds + (bufoff) + ldsw + _i * 8192), 16, 0, 0); } while (0)
; #define PG8_LDA(dst, b, h) do { _Pragma("unroll") for (int m = 0; m < 4; ++m) _Pragma("unroll") for (int k = 0; k < 2; ++k) dst[m][k] = *(const PG8_LAS bf16x8*)(lds + PG8_SA(b, h) + aoff + m * 2048 + k * 1024); } while (0)
; #define PG8_LDB(dst, b, h) do { _Pragma("unroll") for (int n = 0; n < 2; ++n) _Pragma("unroll") for (int k = 0; k < 2; ++k) dst[n][k] = *(const PG8_LAS bf16x8*)(lds + PG8_SB(b, h) + boff + n * 2048 + k * 1024); } while (0)
; template <class Epi, class Sched, bool ALIGN_EPI = false, bool SP2 = false>
; __device__ __forceinline__ void gemm_phase(PG8_LAS unsigned char* lds, const Gemm g, const Sched& S, const Epi& E) {
;     ...
;         for (int t = 0; t < nt; t += 2) {
;             const bool last = (t == nt - 2);
;             const char* a1 = cA + (size_t)(t + 1) * kstep;
;             const char* a2 = last ? nA : cA + (size_t)(t + 2) * kstep; const char* b2 = last ? nB : cB + (size_t)(t + 2) * kstep;
;             const char* a3 = a2 + kstep; const char* b3 = b2 + kstep;
;             if (last && has_next) S.a_ready(nxt);
;             if constexpr (SP2) {
;             PG8_LDB(B0, 0, 0); PG8_LDB(B1, 0, 1); PG8_SCHED; PG8_LDA(At, 0, 0); PG8_STAGE(PG8_SA(1, 1), a1 + hstep, voffA);
;             PG8_WAIT_V(8); PG8_WAIT_L(0); PG8_BAR; PG8_MMA(0, 0, At, B0); PG8_MMA(0, 1, At, B1); PG8_BAR; PG8_SCHED;
;             PG8_LDA(At, 0, 1); PG8_STAGE(PG8_SB(0, 0), b2, voffB); PG8_STAGE(PG8_SB(0, 1), b2 + hstep, voffB); PG8_STAGE(PG8_SA(0, 0), a2, voffA);
;             PG8_WAIT_V(8); PG8_WAIT_L(0); PG8_BAR; PG8_MMA(1, 0, At, B0); PG8_MMA(1, 1, At, B1); PG8_BAR; PG8_SCHED;
;             PG8_LDB(B0, 1, 0); PG8_LDB(B1, 1, 1); PG8_SCHED; PG8_LDA(At, 1, 0); PG8_STAGE(PG8_SA(0, 1), a2 + hstep, voffA);
;             PG8_WAIT_V(8); PG8_WAIT_L(0); PG8_BAR; PG8_MMA(0, 0, At, B0); PG8_MMA(0, 1, At, B1); PG8_BAR; PG8_SCHED;
;             PG8_LDA(At, 1, 1); PG8_STAGE(PG8_SB(1, 0), b3, voffB); PG8_STAGE(PG8_SB(1, 1), b3 + hstep, voffB); PG8_STAGE(PG8_SA(1, 0), a3, voffA);
;             PG8_WAIT_V(8); PG8_WAIT_L(0); PG8_BAR; PG8_MMA(1, 0, At, B0); PG8_MMA(1, 1, At, B1); PG8_BAR; PG8_SCHED;
.Lkq_3_loop:
	v_add_u32_e32 v136, 0x14000, v147
	ds_read_b128 v[166:169], v136
	ds_read_b128 v[170:173], v136 offset:1024
	ds_read_b128 v[174:177], v136 offset:2048
	ds_read_b128 v[178:181], v136 offset:3072
	ds_read_b128 v[202:205], v165
	ds_read_b128 v[208:211], v165 offset:1024
	ds_read_b128 v[212:215], v165 offset:2048
	ds_read_b128 v[216:219], v165 offset:3072
	ds_read_b128 v[220:223], v165 offset:4096
	ds_read_b128 v[224:227], v165 offset:5120
	ds_read_b128 v[228:231], v165 offset:6144
	ds_read_b128 v[232:235], v165 offset:7168
	v_lshl_add_u64 v[136:137], s[76:77], 0, v[0:1]
	s_add_i32 m0, s94, 0xc000
	v_lshl_add_u64 v[144:145], s[76:77], 0, v[130:131]
	global_load_lds_dwordx4 v[136:137], off
	s_add_i32 m0, s94, 0xe000
	s_nop 0
	global_load_lds_dwordx4 v[144:145], off
	v_lshl_add_u64 v[182:183], vcc, 0, v[0:1]
	s_add_i32 m0, s93, 0x18000
	v_lshl_add_u64 v[236:237], vcc, 0, v[130:131]
	global_load_lds_dwordx4 v[182:183], off
	s_add_i32 m0, s93, 0x1a000
	s_nop 0
	global_load_lds_dwordx4 v[236:237], off
	s_cmp_lt_u32 s82, s59
	s_cselect_b32 s83, 0x80, 0
	s_add_u32 s76, s76, s83
	s_addc_u32 s77, s77, 0
	s_add_u32 vcc_lo, vcc_lo, s83
	s_addc_u32 vcc_hi, vcc_hi, 0
	s_add_i32 s82, s82, 1
	s_waitcnt vmcnt(8)
	s_waitcnt lgkmcnt(0)
	s_barrier
	v_mfma_f32_16x16x32_bf16 v[118:121], v[166:169], v[202:205], v[118:121]
	v_mfma_f32_16x16x32_bf16 v[114:117], v[174:177], v[202:205], v[114:117]
	v_mfma_f32_16x16x32_bf16 v[102:105], v[166:169], v[212:215], v[102:105]
	v_mfma_f32_16x16x32_bf16 v[98:101], v[174:177], v[212:215], v[98:101]
	v_mfma_f32_16x16x32_bf16 v[86:89], v[166:169], v[220:223], v[86:89]
	v_mfma_f32_16x16x32_bf16 v[82:85], v[174:177], v[220:223], v[82:85]
	v_mfma_f32_16x16x32_bf16 v[70:73], v[166:169], v[228:231], v[70:73]
	v_mfma_f32_16x16x32_bf16 v[66:69], v[174:177], v[228:231], v[66:69]
	v_mfma_f32_16x16x32_bf16 v[118:121], v[170:173], v[208:211], v[118:121]
	v_mfma_f32_16x16x32_bf16 v[114:117], v[178:181], v[208:211], v[114:117]
	v_mfma_f32_16x16x32_bf16 v[102:105], v[170:173], v[216:219], v[102:105]
	v_mfma_f32_16x16x32_bf16 v[98:101], v[178:181], v[216:219], v[98:101]
	v_mfma_f32_16x16x32_bf16 v[86:89], v[170:173], v[224:227], v[86:89]
	v_mfma_f32_16x16x32_bf16 v[82:85], v[178:181], v[224:227], v[82:85]
	v_mfma_f32_16x16x32_bf16 v[70:73], v[170:173], v[232:235], v[70:73]
	v_mfma_f32_16x16x32_bf16 v[66:69], v[178:181], v[232:235], v[66:69]
	s_barrier
	v_add_u32_e32 v136, 0x1c000, v147
	ds_read_b128 v[166:169], v136
	ds_read_b128 v[170:173], v136 offset:1024
	ds_read_b128 v[174:177], v136 offset:2048
	ds_read_b128 v[178:181], v136 offset:3072
	ds_read_b128 v[202:205], v165 offset:32768
	ds_read_b128 v[208:211], v165 offset:33792
	ds_read_b128 v[212:215], v165 offset:34816
	ds_read_b128 v[216:219], v165 offset:35840
	ds_read_b128 v[220:223], v165 offset:36864
	ds_read_b128 v[224:227], v165 offset:37888
	ds_read_b128 v[228:231], v165 offset:38912
	ds_read_b128 v[232:235], v165 offset:39936
	v_lshl_add_u64 v[136:137], s[76:77], 0, v[0:1]
	s_add_i32 m0, s94, 0x0
	v_lshl_add_u64 v[144:145], s[76:77], 0, v[130:131]
	global_load_lds_dwordx4 v[136:137], off
	s_add_i32 m0, s94, 0x2000
	s_nop 0
	global_load_lds_dwordx4 v[144:145], off
	v_lshl_add_u64 v[182:183], vcc, 0, v[0:1]
	s_add_i32 m0, s93, 0x14000
	v_lshl_add_u64 v[236:237], vcc, 0, v[130:131]
	global_load_lds_dwordx4 v[182:183], off
	s_add_i32 m0, s93, 0x16000
	s_nop 0
	global_load_lds_dwordx4 v[236:237], off
	s_cmp_lt_u32 s82, s59
	s_cselect_b32 s83, 0x80, 0
	s_add_u32 s76, s76, s83
	s_addc_u32 s77, s77, 0
	s_add_u32 vcc_lo, vcc_lo, s83
	s_addc_u32 vcc_hi, vcc_hi, 0
	s_add_i32 s82, s82, 1
	s_waitcnt vmcnt(8)
	s_waitcnt lgkmcnt(0)
	s_barrier
	v_mfma_f32_16x16x32_bf16 v[118:121], v[166:169], v[202:205], v[118:121]
	v_mfma_f32_16x16x32_bf16 v[114:117], v[174:177], v[202:205], v[114:117]
	v_mfma_f32_16x16x32_bf16 v[102:105], v[166:169], v[212:215], v[102:105]
	v_mfma_f32_16x16x32_bf16 v[98:101], v[174:177], v[212:215], v[98:101]
	v_mfma_f32_16x16x32_bf16 v[86:89], v[166:169], v[220:223], v[86:89]
	v_mfma_f32_16x16x32_bf16 v[82:85], v[174:177], v[220:223], v[82:85]
	v_mfma_f32_16x16x32_bf16 v[70:73], v[166:169], v[228:231], v[70:73]
	v_mfma_f32_16x16x32_bf16 v[66:69], v[174:177], v[228:231], v[66:69]
	v_mfma_f32_16x16x32_bf16 v[118:121], v[170:173], v[208:211], v[118:121]
	v_mfma_f32_16x16x32_bf16 v[114:117], v[178:181], v[208:211], v[114:117]
	v_mfma_f32_16x16x32_bf16 v[102:105], v[170:173], v[216:219], v[102:105]
	v_mfma_f32_16x16x32_bf16 v[98:101], v[178:181], v[216:219], v[98:101]
	v_mfma_f32_16x16x32_bf16 v[86:89], v[170:173], v[224:227], v[86:89]
	v_mfma_f32_16x16x32_bf16 v[82:85], v[178:181], v[224:227], v[82:85]
	v_mfma_f32_16x16x32_bf16 v[70:73], v[170:173], v[232:235], v[70:73]
	v_mfma_f32_16x16x32_bf16 v[66:69], v[178:181], v[232:235], v[66:69]
	s_barrier
	v_add_u32_e32 v136, 0x10000, v147
	ds_read_b128 v[166:169], v136
	ds_read_b128 v[170:173], v136 offset:1024
	ds_read_b128 v[174:177], v136 offset:2048
	ds_read_b128 v[178:181], v136 offset:3072
	ds_read_b128 v[202:205], v165 offset:16384
	ds_read_b128 v[208:211], v165 offset:17408
	ds_read_b128 v[212:215], v165 offset:18432
	ds_read_b128 v[216:219], v165 offset:19456
	ds_read_b128 v[220:223], v165 offset:20480
	ds_read_b128 v[224:227], v165 offset:21504
	ds_read_b128 v[228:231], v165 offset:22528
	ds_read_b128 v[232:235], v165 offset:23552
	v_lshl_add_u64 v[136:137], s[76:77], 0, v[0:1]
	s_add_i32 m0, s94, 0x8000
	v_lshl_add_u64 v[144:145], s[76:77], 0, v[130:131]
	global_load_lds_dwordx4 v[136:137], off
	s_add_i32 m0, s94, 0xa000
	s_nop 0
	global_load_lds_dwordx4 v[144:145], off
	v_lshl_add_u64 v[182:183], vcc, 0, v[0:1]
	s_add_i32 m0, s93, 0x1c000
	v_lshl_add_u64 v[236:237], vcc, 0, v[130:131]
	global_load_lds_dwordx4 v[182:183], off
	s_add_i32 m0, s93, 0x1e000
	s_nop 0
	global_load_lds_dwordx4 v[236:237], off
	s_cmp_lt_u32 s82, s59
	s_cselect_b32 s83, 0x80, 0
	s_add_u32 s76, s76, s83
	s_addc_u32 s77, s77, 0
	s_add_u32 vcc_lo, vcc_lo, s83
	s_addc_u32 vcc_hi, vcc_hi, 0
	s_add_i32 s82, s82, 1
	s_waitcnt vmcnt(8)
	s_waitcnt lgkmcnt(0)
	s_barrier
; #define PG8_STAGE(bufoff, gbase, voff) do { _Pragma("unroll") for (int _i = 0; _i < 2; ++_i) \
;         __builtin_amdgcn_global_load_lds((const unsigned*)((const char*)(gbase) + (voff)[_i]), (PG8_LAS unsigned*)(lds + (bufoff) + ldsw + _i * 8192), 16, 0, 0); } while (0)
; #define PG8_LDA(dst, b, h) do { _Pragma("unroll") for (int m = 0; m < 4; ++m) _Pragma("unroll") for (int k = 0; k < 2; ++k) dst[m][k] = *(const PG8_LAS bf16x8*)(lds + PG8_SA(b, h) + aoff + m * 2048 + k * 1024); } while (0)
; #define PG8_LDB(dst, b, h) do { _Pragma("unroll") for (int n = 0; n < 2; ++n) _Pragma("unroll") for (int k = 0; k < 2; ++k) dst[n][k] = *(const PG8_LAS bf16x8*)(lds + PG8_SB(b, h) + boff + n * 2048 + k * 1024); } while (0)
; template <class Epi, class Sched, bool ALIGN_EPI = false, bool SP2 = false>
; __device__ __forceinline__ void gemm_phase(PG8_LAS unsigned char* lds, const Gemm g, const Sched& S, const Epi& E) {
;     ...
;         for (int t = 0; t < nt; t += 2) {
;             const bool last = (t == nt - 2);
;             const char* a1 = cA + (size_t)(t + 1) * kstep;
;             const char* a2 = last ? nA : cA + (size_t)(t + 2) * kstep; const char* b2 = last ? nB : cB + (size_t)(t + 2) * kstep;
;             const char* a3 = a2 + kstep; const char* b3 = b2 + kstep;
;             if (last && has_next) S.a_ready(nxt);
;             if constexpr (SP2) {
;             PG8_LDB(B0, 0, 0); PG8_LDB(B1, 0, 1); PG8_SCHED; PG8_LDA(At, 0, 0); PG8_STAGE(PG8_SA(1, 1), a1 + hstep, voffA);
;             PG8_WAIT_V(8); PG8_WAIT_L(0); PG8_BAR; PG8_MMA(0, 0, At, B0); PG8_MMA(0, 1, At, B1); PG8_BAR; PG8_SCHED;
;             PG8_LDA(At, 0, 1); PG8_STAGE(PG8_SB(0, 0), b2, voffB); PG8_STAGE(PG8_SB(0, 1), b2 + hstep, voffB); PG8_STAGE(PG8_SA(0, 0), a2, voffA);
;             PG8_WAIT_V(8); PG8_WAIT_L(0); PG8_BAR; PG8_MMA(1, 0, At, B0); PG8_MMA(1, 1, At, B1); PG8_BAR; PG8_SCHED;
;             PG8_LDB(B0, 1, 0); PG8_LDB(B1, 1, 1); PG8_SCHED; PG8_LDA(At, 1, 0); PG8_STAGE(PG8_SA(0, 1), a2 + hstep, voffA);
;             PG8_WAIT_V(8); PG8_WAIT_L(0); PG8_BAR; PG8_MMA(0, 0, At, B0); PG8_MMA(0, 1, At, B1); PG8_BAR; PG8_SCHED;
;             PG8_LDA(At, 1, 1); PG8_STAGE(PG8_SB(1, 0), b3, voffB); PG8_STAGE(PG8_SB(1, 1), b3 + hstep, voffB); PG8_STAGE(PG8_SA(1, 0), a3, voffA);
;             PG8_WAIT_V(8); PG8_WAIT_L(0); PG8_BAR; PG8_MMA(1, 0, At, B0); PG8_MMA(1, 1, At, B1); PG8_BAR; PG8_SCHED;
	v_mfma_f32_16x16x32_bf16 v[118:121], v[166:169], v[202:205], v[118:121]
	v_mfma_f32_16x16x32_bf16 v[114:117], v[174:177], v[202:205], v[114:117]
	v_mfma_f32_16x16x32_bf16 v[102:105], v[166:169], v[212:215], v[102:105]
	v_mfma_f32_16x16x32_bf16 v[98:101], v[174:177], v[212:215], v[98:101]
	v_mfma_f32_16x16x32_bf16 v[86:89], v[166:169], v[220:223], v[86:89]
	v_mfma_f32_16x16x32_bf16 v[82:85], v[174:177], v[220:223], v[82:85]
	v_mfma_f32_16x16x32_bf16 v[70:73], v[166:169], v[228:231], v[70:73]
	v_mfma_f32_16x16x32_bf16 v[66:69], v[174:177], v[228:231], v[66:69]
	v_mfma_f32_16x16x32_bf16 v[118:121], v[170:173], v[208:211], v[118:121]
	v_mfma_f32_16x16x32_bf16 v[114:117], v[178:181], v[208:211], v[114:117]
	v_mfma_f32_16x16x32_bf16 v[102:105], v[170:173], v[216:219], v[102:105]
	v_mfma_f32_16x16x32_bf16 v[98:101], v[178:181], v[216:219], v[98:101]
	v_mfma_f32_16x16x32_bf16 v[86:89], v[170:173], v[224:227], v[86:89]
	v_mfma_f32_16x16x32_bf16 v[82:85], v[178:181], v[224:227], v[82:85]
	v_mfma_f32_16x16x32_bf16 v[70:73], v[170:173], v[232:235], v[70:73]
	v_mfma_f32_16x16x32_bf16 v[66:69], v[178:181], v[232:235], v[66:69]
	s_barrier
	v_add_u32_e32 v136, 0x18000, v147
	ds_read_b128 v[166:169], v136
	ds_read_b128 v[170:173], v136 offset:1024
	ds_read_b128 v[174:177], v136 offset:2048
	ds_read_b128 v[178:181], v136 offset:3072
	ds_read_b128 v[202:205], v165 offset:49152
	ds_read_b128 v[208:211], v165 offset:50176
	ds_read_b128 v[212:215], v165 offset:51200
	ds_read_b128 v[216:219], v165 offset:52224
	ds_read_b128 v[220:223], v165 offset:53248
	ds_read_b128 v[224:227], v165 offset:54272
	ds_read_b128 v[228:231], v165 offset:55296
	ds_read_b128 v[232:235], v165 offset:56320
	v_lshl_add_u64 v[136:137], s[76:77], 0, v[0:1]
	s_add_i32 m0, s94, 0x4000
	v_lshl_add_u64 v[144:145], s[76:77], 0, v[130:131]
	global_load_lds_dwordx4 v[136:137], off
	s_add_i32 m0, s94, 0x6000
	s_nop 0
	global_load_lds_dwordx4 v[144:145], off
	v_lshl_add_u64 v[182:183], vcc, 0, v[0:1]
	s_add_i32 m0, s93, 0x10000
	v_lshl_add_u64 v[236:237], vcc, 0, v[130:131]
	global_load_lds_dwordx4 v[182:183], off
	s_add_i32 m0, s93, 0x12000
	s_nop 0
	global_load_lds_dwordx4 v[236:237], off
	s_cmp_lt_u32 s82, s59
	s_cselect_b32 s83, 0x80, 0
	s_add_u32 s76, s76, s83
	s_addc_u32 s77, s77, 0
	s_add_u32 vcc_lo, vcc_lo, s83
	s_addc_u32 vcc_hi, vcc_hi, 0
	s_add_i32 s82, s82, 1
	s_waitcnt vmcnt(8)
	s_waitcnt lgkmcnt(0)
	s_barrier
	v_mfma_f32_16x16x32_bf16 v[118:121], v[166:169], v[202:205], v[118:121]
	v_mfma_f32_16x16x32_bf16 v[114:117], v[174:177], v[202:205], v[114:117]
	v_mfma_f32_16x16x32_bf16 v[102:105], v[166:169], v[212:215], v[102:105]
	v_mfma_f32_16x16x32_bf16 v[98:101], v[174:177], v[212:215], v[98:101]
	v_mfma_f32_16x16x32_bf16 v[86:89], v[166:169], v[220:223], v[86:89]
	v_mfma_f32_16x16x32_bf16 v[82:85], v[174:177], v[220:223], v[82:85]
	v_mfma_f32_16x16x32_bf16 v[70:73], v[166:169], v[228:231], v[70:73]
	v_mfma_f32_16x16x32_bf16 v[66:69], v[174:177], v[228:231], v[66:69]
	v_mfma_f32_16x16x32_bf16 v[118:121], v[170:173], v[208:211], v[118:121]
	v_mfma_f32_16x16x32_bf16 v[114:117], v[178:181], v[208:211], v[114:117]
	v_mfma_f32_16x16x32_bf16 v[102:105], v[170:173], v[216:219], v[102:105]
	v_mfma_f32_16x16x32_bf16 v[98:101], v[178:181], v[216:219], v[98:101]
	v_mfma_f32_16x16x32_bf16 v[86:89], v[170:173], v[224:227], v[86:89]
	v_mfma_f32_16x16x32_bf16 v[82:85], v[178:181], v[224:227], v[82:85]
	v_mfma_f32_16x16x32_bf16 v[70:73], v[170:173], v[232:235], v[70:73]
	v_mfma_f32_16x16x32_bf16 v[66:69], v[178:181], v[232:235], v[66:69]
	s_barrier
	s_add_i32 s83, s82, -3
	s_cmp_lt_u32 s83, s79
	s_cbranch_scc1 .Lkq_3_loop
	s_mov_b64 s[76:77], s[8:9]
	s_mov_b64 vcc, s[46:47]
	v_lshl_add_u64 v[136:137], vcc, 0, v[0:1]
	s_add_i32 m0, s93, 0x10000
	v_lshl_add_u64 v[144:145], vcc, 0, v[130:131]
	global_load_lds_dwordx4 v[136:137], off
	s_add_i32 m0, s93, 0x12000
	s_nop 0
	global_load_lds_dwordx4 v[144:145], off
	s_add_u32 vcc_lo, vcc_lo, s10
	s_addc_u32 vcc_hi, vcc_hi, 0
	v_lshl_add_u64 v[136:137], vcc, 0, v[0:1]
	s_add_i32 m0, s93, 0x14000
	v_lshl_add_u64 v[144:145], vcc, 0, v[130:131]
	global_load_lds_dwordx4 v[136:137], off
	s_add_i32 m0, s93, 0x16000
	s_nop 0
	global_load_lds_dwordx4 v[144:145], off
	v_lshl_add_u64 v[136:137], s[76:77], 0, v[0:1]
	s_add_i32 m0, s94, 0x0
	v_lshl_add_u64 v[144:145], s[76:77], 0, v[130:131]
	global_load_lds_dwordx4 v[136:137], off
	s_add_i32 m0, s94, 0x2000
	s_nop 0
	global_load_lds_dwordx4 v[144:145], off
	s_add_u32 s76, s76, s10
	s_addc_u32 s77, s77, 0
	v_lshl_add_u64 v[136:137], s[76:77], 0, v[0:1]
	s_add_i32 m0, s94, 0x4000
	v_lshl_add_u64 v[144:145], s[76:77], 0, v[130:131]
	global_load_lds_dwordx4 v[136:137], off
	s_add_i32 m0, s94, 0x6000
	s_nop 0
	global_load_lds_dwordx4 v[144:145], off
	s_add_u32 s76, s8, 0x80
	s_addc_u32 s77, s9, 0
	s_add_u32 vcc_lo, s46, 0x80
	s_addc_u32 vcc_hi, s47, 0
	v_lshl_add_u64 v[136:137], vcc, 0, v[0:1]
	s_add_i32 m0, s93, 0x18000
	v_lshl_add_u64 v[144:145], vcc, 0, v[130:131]
	global_load_lds_dwordx4 v[136:137], off
	s_add_i32 m0, s93, 0x1a000
	s_nop 0
	global_load_lds_dwordx4 v[144:145], off
	s_add_u32 vcc_lo, vcc_lo, s10
	s_addc_u32 vcc_hi, vcc_hi, 0
	v_lshl_add_u64 v[136:137], vcc, 0, v[0:1]
	s_add_i32 m0, s93, 0x1c000
	v_lshl_add_u64 v[144:145], vcc, 0, v[130:131]
	global_load_lds_dwordx4 v[136:137], off
	s_add_i32 m0, s93, 0x1e000
	s_nop 0
	global_load_lds_dwordx4 v[144:145], off
	v_lshl_add_u64 v[136:137], s[76:77], 0, v[0:1]
	s_add_i32 m0, s94, 0x8000
	v_lshl_add_u64 v[144:145], s[76:77], 0, v[130:131]
	global_load_lds_dwordx4 v[136:137], off
	s_add_i32 m0, s94, 0xa000
	s_nop 0
	global_load_lds_dwordx4 v[144:145], off
	s_branch .Lkq_exit
	s_nop 0
	s_nop 0
	s_nop 0
	s_nop 0
	s_nop 0
	s_nop 0
	s_nop 0
	s_nop 0

; #define PG8_STAGE(bufoff, gbase, voff) do { _Pragma("unroll") for (int _i = 0; _i < 2; ++_i) \
;         __builtin_amdgcn_global_load_lds((const unsigned*)((const char*)(gbase) + (voff)[_i]), (PG8_LAS unsigned*)(lds + (bufoff) + ldsw + _i * 8192), 16, 0, 0); } while (0)
; #define PG8_LDA(dst, b, h) do { _Pragma("unroll") for (int m = 0; m < 4; ++m) _Pragma("unroll") for (int k = 0; k < 2; ++k) dst[m][k] = *(const PG8_LAS bf16x8*)(lds + PG8_SA(b, h) + aoff + m * 2048 + k * 1024); } while (0)
; #define PG8_LDB(dst, b, h) do { _Pragma("unroll") for (int n = 0; n < 2; ++n) _Pragma("unroll") for (int k = 0; k < 2; ++k) dst[n][k] = *(const PG8_LAS bf16x8*)(lds + PG8_SB(b, h) + boff + n * 2048 + k * 1024); } while (0)
; template <class Epi, class Sched, bool ALIGN_EPI = false, bool SP2 = false>
; __device__ __forceinline__ void gemm_phase(PG8_LAS unsigned char* lds, const Gemm g, const Sched& S, const Epi& E) {
;     ...
;         for (int t = 0; t < nt; t += 2) {
;             const bool last = (t == nt - 2);
;             const char* a1 = cA + (size_t)(t + 1) * kstep;
;             const char* a2 = last ? nA : cA + (size_t)(t + 2) * kstep; const char* b2 = last ? nB : cB + (size_t)(t + 2) * kstep;
;             const char* a3 = a2 + kstep; const char* b3 = b2 + kstep;
;             if (last && has_next) S.a_ready(nxt);
;             if constexpr (SP2) {
;             PG8_LDB(B0, 0, 0); PG8_LDB(B1, 0, 1); PG8_SCHED; PG8_LDA(At, 0, 0); PG8_STAGE(PG8_SA(1, 1), a1 + hstep, voffA);
;             PG8_WAIT_V(8); PG8_WAIT_L(0); PG8_BAR; PG8_MMA(0, 0, At, B0); PG8_MMA(0, 1, At, B1); PG8_BAR; PG8_SCHED;
;             PG8_LDA(At, 0, 1); PG8_STAGE(PG8_SB(0, 0), b2, voffB); PG8_STAGE(PG8_SB(0, 1), b2 + hstep, voffB); PG8_STAGE(PG8_SA(0, 0), a2, voffA);
;             PG8_WAIT_V(8); PG8_WAIT_L(0); PG8_BAR; PG8_MMA(1, 0, At, B0); PG8_MMA(1, 1, At, B1); PG8_BAR; PG8_SCHED;
;             PG8_LDB(B0, 1, 0); PG8_LDB(B1, 1, 1); PG8_SCHED; PG8_LDA(At, 1, 0); PG8_STAGE(PG8_SA(0, 1), a2 + hstep, voffA);
;             PG8_WAIT_V(8); PG8_WAIT_L(0); PG8_BAR; PG8_MMA(0, 0, At, B0); PG8_MMA(0, 1, At, B1); PG8_BAR; PG8_SCHED;
;             PG8_LDA(At, 1, 1); PG8_STAGE(PG8_SB(1, 0), b3, voffB); PG8_STAGE(PG8_SB(1, 1), b3 + hstep, voffB); PG8_STAGE(PG8_SA(1, 0), a3, voffA);
;             PG8_WAIT_V(8); PG8_WAIT_L(0); PG8_BAR; PG8_MMA(1, 0, At, B0); PG8_MMA(1, 1, At, B1); PG8_BAR; PG8_SCHED;
.Lkq_4_loop:
	v_add_u32_e32 v136, 0x14000, v147
	ds_read_b128 v[166:169], v136
	ds_read_b128 v[170:173], v136 offset:1024
	ds_read_b128 v[174:177], v136 offset:2048
	ds_read_b128 v[178:181], v136 offset:3072
	ds_read_b128 v[202:205], v165 offset:16384
	ds_read_b128 v[208:211], v165 offset:17408
	ds_read_b128 v[212:215], v165 offset:18432
	ds_read_b128 v[216:219], v165 offset:19456
	ds_read_b128 v[220:223], v165 offset:20480
	ds_read_b128 v[224:227], v165 offset:21504
	ds_read_b128 v[228:231], v165 offset:22528
	ds_read_b128 v[232:235], v165 offset:23552
	v_lshl_add_u64 v[136:137], s[76:77], 0, v[0:1]
	s_add_i32 m0, s94, 0x8000
	v_lshl_add_u64 v[144:145], s[76:77], 0, v[130:131]
	global_load_lds_dwordx4 v[136:137], off
	s_add_i32 m0, s94, 0xa000
	s_nop 0
	global_load_lds_dwordx4 v[144:145], off
	v_lshl_add_u64 v[182:183], vcc, 0, v[0:1]
	s_add_i32 m0, s93, 0x18000
	v_lshl_add_u64 v[236:237], vcc, 0, v[130:131]
	global_load_lds_dwordx4 v[182:183], off
	s_add_i32 m0, s93, 0x1a000
	s_nop 0
	global_load_lds_dwordx4 v[236:237], off
	s_cmp_lt_u32 s82, s59
	s_cselect_b32 s83, 0x80, 0
	s_add_u32 s76, s76, s83
	s_addc_u32 s77, s77, 0
	s_add_u32 vcc_lo, vcc_lo, s83
	s_addc_u32 vcc_hi, vcc_hi, 0
	s_add_i32 s82, s82, 1
	s_waitcnt vmcnt(8)
	s_waitcnt lgkmcnt(0)
	s_barrier
	v_mfma_f32_16x16x32_bf16 v[54:57], v[166:169], v[202:205], v[54:57]
	v_mfma_f32_16x16x32_bf16 v[50:53], v[174:177], v[202:205], v[50:53]
	v_mfma_f32_16x16x32_bf16 v[38:41], v[166:169], v[212:215], v[38:41]
	v_mfma_f32_16x16x32_bf16 v[34:37], v[174:177], v[212:215], v[34:37]
	v_mfma_f32_16x16x32_bf16 v[22:25], v[166:169], v[220:223], v[22:25]
	v_mfma_f32_16x16x32_bf16 v[18:21], v[174:177], v[220:223], v[18:21]
	v_mfma_f32_16x16x32_bf16 v[6:9], v[166:169], v[228:231], v[6:9]
	v_mfma_f32_16x16x32_bf16 v[2:5], v[174:177], v[228:231], v[2:5]
	v_mfma_f32_16x16x32_bf16 v[54:57], v[170:173], v[208:211], v[54:57]
	v_mfma_f32_16x16x32_bf16 v[50:53], v[178:181], v[208:211], v[50:53]
	v_mfma_f32_16x16x32_bf16 v[38:41], v[170:173], v[216:219], v[38:41]
	v_mfma_f32_16x16x32_bf16 v[34:37], v[178:181], v[216:219], v[34:37]
	v_mfma_f32_16x16x32_bf16 v[22:25], v[170:173], v[224:227], v[22:25]
	v_mfma_f32_16x16x32_bf16 v[18:21], v[178:181], v[224:227], v[18:21]
	v_mfma_f32_16x16x32_bf16 v[6:9], v[170:173], v[232:235], v[6:9]
	v_mfma_f32_16x16x32_bf16 v[2:5], v[178:181], v[232:235], v[2:5]
	s_barrier
	v_add_u32_e32 v136, 0x1c000, v147
	ds_read_b128 v[166:169], v136
	ds_read_b128 v[170:173], v136 offset:1024
	ds_read_b128 v[174:177], v136 offset:2048
	ds_read_b128 v[178:181], v136 offset:3072
	ds_read_b128 v[202:205], v165 offset:49152
	ds_read_b128 v[208:211], v165 offset:50176
	ds_read_b128 v[212:215], v165 offset:51200
	ds_read_b128 v[216:219], v165 offset:52224
	ds_read_b128 v[220:223], v165 offset:53248
	ds_read_b128 v[224:227], v165 offset:54272
	ds_read_b128 v[228:231], v165 offset:55296
	ds_read_b128 v[232:235], v165 offset:56320
	v_lshl_add_u64 v[136:137], s[76:77], 0, v[0:1]
	s_add_i32 m0, s94, 0x4000
	v_lshl_add_u64 v[144:145], s[76:77], 0, v[130:131]
	global_load_lds_dwordx4 v[136:137], off
	s_add_i32 m0, s94, 0x6000
	s_nop 0
	global_load_lds_dwordx4 v[144:145], off
	v_lshl_add_u64 v[182:183], vcc, 0, v[0:1]
	s_add_i32 m0, s93, 0x14000
	v_lshl_add_u64 v[236:237], vcc, 0, v[130:131]
	global_load_lds_dwordx4 v[182:183], off
	s_add_i32 m0, s93, 0x16000
	s_nop 0
	global_load_lds_dwordx4 v[236:237], off
	s_cmp_lt_u32 s82, s59
	s_cselect_b32 s83, 0x80, 0
	s_add_u32 s76, s76, s83
	s_addc_u32 s77, s77, 0
	s_add_u32 vcc_lo, vcc_lo, s83
	s_addc_u32 vcc_hi, vcc_hi, 0
	s_add_i32 s82, s82, 1
	s_waitcnt vmcnt(8)
	s_waitcnt lgkmcnt(0)
	s_barrier
	v_mfma_f32_16x16x32_bf16 v[54:57], v[166:169], v[202:205], v[54:57]
	v_mfma_f32_16x16x32_bf16 v[50:53], v[174:177], v[202:205], v[50:53]
	v_mfma_f32_16x16x32_bf16 v[38:41], v[166:169], v[212:215], v[38:41]
	v_mfma_f32_16x16x32_bf16 v[34:37], v[174:177], v[212:215], v[34:37]
	v_mfma_f32_16x16x32_bf16 v[22:25], v[166:169], v[220:223], v[22:25]
	v_mfma_f32_16x16x32_bf16 v[18:21], v[174:177], v[220:223], v[18:21]
	v_mfma_f32_16x16x32_bf16 v[6:9], v[166:169], v[228:231], v[6:9]
	v_mfma_f32_16x16x32_bf16 v[2:5], v[174:177], v[228:231], v[2:5]
	v_mfma_f32_16x16x32_bf16 v[54:57], v[170:173], v[208:211], v[54:57]
	v_mfma_f32_16x16x32_bf16 v[50:53], v[178:181], v[208:211], v[50:53]
	v_mfma_f32_16x16x32_bf16 v[38:41], v[170:173], v[216:219], v[38:41]
	v_mfma_f32_16x16x32_bf16 v[34:37], v[178:181], v[216:219], v[34:37]
	v_mfma_f32_16x16x32_bf16 v[22:25], v[170:173], v[224:227], v[22:25]
	v_mfma_f32_16x16x32_bf16 v[18:21], v[178:181], v[224:227], v[18:21]
	v_mfma_f32_16x16x32_bf16 v[6:9], v[170:173], v[232:235], v[6:9]
	v_mfma_f32_16x16x32_bf16 v[2:5], v[178:181], v[232:235], v[2:5]
	s_barrier
	v_add_u32_e32 v136, 0x10000, v147
	ds_read_b128 v[166:169], v136
	ds_read_b128 v[170:173], v136 offset:1024
	ds_read_b128 v[174:177], v136 offset:2048
	ds_read_b128 v[178:181], v136 offset:3072
	ds_read_b128 v[202:205], v165
	ds_read_b128 v[208:211], v165 offset:1024
	ds_read_b128 v[212:215], v165 offset:2048
	ds_read_b128 v[216:219], v165 offset:3072
	ds_read_b128 v[220:223], v165 offset:4096
	ds_read_b128 v[224:227], v165 offset:5120
	ds_read_b128 v[228:231], v165 offset:6144
	ds_read_b128 v[232:235], v165 offset:7168
	v_lshl_add_u64 v[136:137], s[76:77], 0, v[0:1]
	s_add_i32 m0, s94, 0xc000
	v_lshl_add_u64 v[144:145], s[76:77], 0, v[130:131]
	global_load_lds_dwordx4 v[136:137], off
	s_add_i32 m0, s94, 0xe000
	s_nop 0
	global_load_lds_dwordx4 v[144:145], off
	v_lshl_add_u64 v[182:183], vcc, 0, v[0:1]
	s_add_i32 m0, s93, 0x1c000
	v_lshl_add_u64 v[236:237], vcc, 0, v[130:131]
	global_load_lds_dwordx4 v[182:183], off
	s_add_i32 m0, s93, 0x1e000
	s_nop 0
	global_load_lds_dwordx4 v[236:237], off
	s_cmp_lt_u32 s82, s59
	s_cselect_b32 s83, 0x80, 0
	s_add_u32 s76, s76, s83
	s_addc_u32 s77, s77, 0
	s_add_u32 vcc_lo, vcc_lo, s83
	s_addc_u32 vcc_hi, vcc_hi, 0
	s_add_i32 s82, s82, 1
	s_waitcnt vmcnt(8)
	s_waitcnt lgkmcnt(0)
	s_barrier
; #define PG8_STAGE(bufoff, gbase, voff) do { _Pragma("unroll") for (int _i = 0; _i < 2; ++_i) \
;         __builtin_amdgcn_global_load_lds((const unsigned*)((const char*)(gbase) + (voff)[_i]), (PG8_LAS unsigned*)(lds + (bufoff) + ldsw + _i * 8192), 16, 0, 0); } while (0)
; #define PG8_LDA(dst, b, h) do { _Pragma("unroll") for (int m = 0; m < 4; ++m) _Pragma("unroll") for (int k = 0; k < 2; ++k) dst[m][k] = *(const PG8_LAS bf16x8*)(lds + PG8_SA(b, h) + aoff + m * 2048 + k * 1024); } while (0)
; #define PG8_LDB(dst, b, h) do { _Pragma("unroll") for (int n = 0; n < 2; ++n) _Pragma("unroll") for (int k = 0; k < 2; ++k) dst[n][k] = *(const PG8_LAS bf16x8*)(lds + PG8_SB(b, h) + boff + n * 2048 + k * 1024); } while (0)
; template <class Epi, class Sched, bool ALIGN_EPI = false, bool SP2 = false>
; __device__ __forceinline__ void gemm_phase(PG8_LAS unsigned char* lds, const Gemm g, const Sched& S, const Epi& E) {
;     ...
;         for (int t = 0; t < nt; t += 2) {
;             const bool last = (t == nt - 2);
;             const char* a1 = cA + (size_t)(t + 1) * kstep;
;             const char* a2 = last ? nA : cA + (size_t)(t + 2) * kstep; const char* b2 = last ? nB : cB + (size_t)(t + 2) * kstep;
;             const char* a3 = a2 + kstep; const char* b3 = b2 + kstep;
;             if (last && has_next) S.a_ready(nxt);
;             if constexpr (SP2) {
;             PG8_LDB(B0, 0, 0); PG8_LDB(B1, 0, 1); PG8_SCHED; PG8_LDA(At, 0, 0); PG8_STAGE(PG8_SA(1, 1), a1 + hstep, voffA);
;             PG8_WAIT_V(8); PG8_WAIT_L(0); PG8_BAR; PG8_MMA(0, 0, At, B0); PG8_MMA(0, 1, At, B1); PG8_BAR; PG8_SCHED;
;             PG8_LDA(At, 0, 1); PG8_STAGE(PG8_SB(0, 0), b2, voffB); PG8_STAGE(PG8_SB(0, 1), b2 + hstep, voffB); PG8_STAGE(PG8_SA(0, 0), a2, voffA);
;             PG8_WAIT_V(8); PG8_WAIT_L(0); PG8_BAR; PG8_MMA(1, 0, At, B0); PG8_MMA(1, 1, At, B1); PG8_BAR; PG8_SCHED;
;             PG8_LDB(B0, 1, 0); PG8_LDB(B1, 1, 1); PG8_SCHED; PG8_LDA(At, 1, 0); PG8_STAGE(PG8_SA(0, 1), a2 + hstep, voffA);
;             PG8_WAIT_V(8); PG8_WAIT_L(0); PG8_BAR; PG8_MMA(0, 0, At, B0); PG8_MMA(0, 1, At, B1); PG8_BAR; PG8_SCHED;
;             PG8_LDA(At, 1, 1); PG8_STAGE(PG8_SB(1, 0), b3, voffB); PG8_STAGE(PG8_SB(1, 1), b3 + hstep, voffB); PG8_STAGE(PG8_SA(1, 0), a3, voffA);
;             PG8_WAIT_V(8); PG8_WAIT_L(0); PG8_BAR; PG8_MMA(1, 0, At, B0); PG8_MMA(1, 1, At, B1); PG8_BAR; PG8_SCHED;
	v_mfma_f32_16x16x32_bf16 v[54:57], v[166:169], v[202:205], v[54:57]
	v_mfma_f32_16x16x32_bf16 v[50:53], v[174:177], v[202:205], v[50:53]
	v_mfma_f32_16x16x32_bf16 v[38:41], v[166:169], v[212:215], v[38:41]
	v_mfma_f32_16x16x32_bf16 v[34:37], v[174:177], v[212:215], v[34:37]
	v_mfma_f32_16x16x32_bf16 v[22:25], v[166:169], v[220:223], v[22:25]
	v_mfma_f32_16x16x32_bf16 v[18:21], v[174:177], v[220:223], v[18:21]
	v_mfma_f32_16x16x32_bf16 v[6:9], v[166:169], v[228:231], v[6:9]
	v_mfma_f32_16x16x32_bf16 v[2:5], v[174:177], v[228:231], v[2:5]
	v_mfma_f32_16x16x32_bf16 v[54:57], v[170:173], v[208:211], v[54:57]
	v_mfma_f32_16x16x32_bf16 v[50:53], v[178:181], v[208:211], v[50:53]
	v_mfma_f32_16x16x32_bf16 v[38:41], v[170:173], v[216:219], v[38:41]
	v_mfma_f32_16x16x32_bf16 v[34:37], v[178:181], v[216:219], v[34:37]
	v_mfma_f32_16x16x32_bf16 v[22:25], v[170:173], v[224:227], v[22:25]
	v_mfma_f32_16x16x32_bf16 v[18:21], v[178:181], v[224:227], v[18:21]
	v_mfma_f32_16x16x32_bf16 v[6:9], v[170:173], v[232:235], v[6:9]
	v_mfma_f32_16x16x32_bf16 v[2:5], v[178:181], v[232:235], v[2:5]
	s_barrier
	v_add_u32_e32 v136, 0x18000, v147
	ds_read_b128 v[166:169], v136
	ds_read_b128 v[170:173], v136 offset:1024
	ds_read_b128 v[174:177], v136 offset:2048
	ds_read_b128 v[178:181], v136 offset:3072
	ds_read_b128 v[202:205], v165 offset:32768
	ds_read_b128 v[208:211], v165 offset:33792
	ds_read_b128 v[212:215], v165 offset:34816
	ds_read_b128 v[216:219], v165 offset:35840
	ds_read_b128 v[220:223], v165 offset:36864
	ds_read_b128 v[224:227], v165 offset:37888
	ds_read_b128 v[228:231], v165 offset:38912
	ds_read_b128 v[232:235], v165 offset:39936
	v_lshl_add_u64 v[136:137], s[76:77], 0, v[0:1]
	s_add_i32 m0, s94, 0x0
	v_lshl_add_u64 v[144:145], s[76:77], 0, v[130:131]
	global_load_lds_dwordx4 v[136:137], off
	s_add_i32 m0, s94, 0x2000
	s_nop 0
	global_load_lds_dwordx4 v[144:145], off
	v_lshl_add_u64 v[182:183], vcc, 0, v[0:1]
	s_add_i32 m0, s93, 0x10000
	v_lshl_add_u64 v[236:237], vcc, 0, v[130:131]
	global_load_lds_dwordx4 v[182:183], off
	s_add_i32 m0, s93, 0x12000
	s_nop 0
	global_load_lds_dwordx4 v[236:237], off
	s_cmp_lt_u32 s82, s59
	s_cselect_b32 s83, 0x80, 0
	s_add_u32 s76, s76, s83
	s_addc_u32 s77, s77, 0
	s_add_u32 vcc_lo, vcc_lo, s83
	s_addc_u32 vcc_hi, vcc_hi, 0
	s_add_i32 s82, s82, 1
	s_waitcnt vmcnt(8)
	s_waitcnt lgkmcnt(0)
	s_barrier
	v_mfma_f32_16x16x32_bf16 v[54:57], v[166:169], v[202:205], v[54:57]
	v_mfma_f32_16x16x32_bf16 v[50:53], v[174:177], v[202:205], v[50:53]
	v_mfma_f32_16x16x32_bf16 v[38:41], v[166:169], v[212:215], v[38:41]
	v_mfma_f32_16x16x32_bf16 v[34:37], v[174:177], v[212:215], v[34:37]
	v_mfma_f32_16x16x32_bf16 v[22:25], v[166:169], v[220:223], v[22:25]
	v_mfma_f32_16x16x32_bf16 v[18:21], v[174:177], v[220:223], v[18:21]
	v_mfma_f32_16x16x32_bf16 v[6:9], v[166:169], v[228:231], v[6:9]
	v_mfma_f32_16x16x32_bf16 v[2:5], v[174:177], v[228:231], v[2:5]
	v_mfma_f32_16x16x32_bf16 v[54:57], v[170:173], v[208:211], v[54:57]
	v_mfma_f32_16x16x32_bf16 v[50:53], v[178:181], v[208:211], v[50:53]
	v_mfma_f32_16x16x32_bf16 v[38:41], v[170:173], v[216:219], v[38:41]
	v_mfma_f32_16x16x32_bf16 v[34:37], v[178:181], v[216:219], v[34:37]
	v_mfma_f32_16x16x32_bf16 v[22:25], v[170:173], v[224:227], v[22:25]
	v_mfma_f32_16x16x32_bf16 v[18:21], v[178:181], v[224:227], v[18:21]
	v_mfma_f32_16x16x32_bf16 v[6:9], v[170:173], v[232:235], v[6:9]
	v_mfma_f32_16x16x32_bf16 v[2:5], v[178:181], v[232:235], v[2:5]
	s_barrier
	s_add_i32 s83, s82, -3
	s_cmp_lt_u32 s83, s79
	s_cbranch_scc1 .Lkq_4_loop
	s_mov_b64 s[76:77], s[8:9]
	s_mov_b64 vcc, s[46:47]
	v_lshl_add_u64 v[136:137], vcc, 0, v[0:1]
	s_add_i32 m0, s93, 0x10000
	v_lshl_add_u64 v[144:145], vcc, 0, v[130:131]
	global_load_lds_dwordx4 v[136:137], off
	s_add_i32 m0, s93, 0x12000
	s_nop 0
	global_load_lds_dwordx4 v[144:145], off
	s_add_u32 vcc_lo, vcc_lo, s10
	s_addc_u32 vcc_hi, vcc_hi, 0
	v_lshl_add_u64 v[136:137], vcc, 0, v[0:1]
	s_add_i32 m0, s93, 0x14000
	v_lshl_add_u64 v[144:145], vcc, 0, v[130:131]
	global_load_lds_dwordx4 v[136:137], off
	s_add_i32 m0, s93, 0x16000
	s_nop 0
	global_load_lds_dwordx4 v[144:145], off
	v_lshl_add_u64 v[136:137], s[76:77], 0, v[0:1]
	s_add_i32 m0, s94, 0x0
	v_lshl_add_u64 v[144:145], s[76:77], 0, v[130:131]
	global_load_lds_dwordx4 v[136:137], off
	s_add_i32 m0, s94, 0x2000
	s_nop 0
	global_load_lds_dwordx4 v[144:145], off
	s_add_u32 s76, s76, s10
	s_addc_u32 s77, s77, 0
	v_lshl_add_u64 v[136:137], s[76:77], 0, v[0:1]
	s_add_i32 m0, s94, 0x4000
	v_lshl_add_u64 v[144:145], s[76:77], 0, v[130:131]
	global_load_lds_dwordx4 v[136:137], off
	s_add_i32 m0, s94, 0x6000
	s_nop 0
	global_load_lds_dwordx4 v[144:145], off
	s_add_u32 s76, s8, 0x80
	s_addc_u32 s77, s9, 0
	s_add_u32 vcc_lo, s46, 0x80
	s_addc_u32 vcc_hi, s47, 0
	v_lshl_add_u64 v[136:137], vcc, 0, v[0:1]
	s_add_i32 m0, s93, 0x18000
	v_lshl_add_u64 v[144:145], vcc, 0, v[130:131]
	global_load_lds_dwordx4 v[136:137], off
	s_add_i32 m0, s93, 0x1a000
	s_nop 0
	global_load_lds_dwordx4 v[144:145], off
	s_add_u32 vcc_lo, vcc_lo, s10
	s_addc_u32 vcc_hi, vcc_hi, 0
	v_lshl_add_u64 v[136:137], vcc, 0, v[0:1]
	s_add_i32 m0, s93, 0x1c000
	v_lshl_add_u64 v[144:145], vcc, 0, v[130:131]
	global_load_lds_dwordx4 v[136:137], off
	s_add_i32 m0, s93, 0x1e000
	s_nop 0
	global_load_lds_dwordx4 v[144:145], off
	v_lshl_add_u64 v[136:137], s[76:77], 0, v[0:1]
	s_add_i32 m0, s94, 0x8000
	v_lshl_add_u64 v[144:145], s[76:77], 0, v[130:131]
	global_load_lds_dwordx4 v[136:137], off
	s_add_i32 m0, s94, 0xa000
	s_nop 0
	global_load_lds_dwordx4 v[144:145], off

; #define PG8_WAIT_V(n) asm volatile("s_waitcnt vmcnt(" #n ")" ::: "memory")
; #define PG8_BAR __builtin_amdgcn_s_barrier()
; template <class Epi, class Sched, bool ALIGN_EPI = false, bool SP2 = false>
; __device__ __forceinline__ void gemm_phase(PG8_LAS unsigned char* lds, const Gemm g, const Sched& S, const Epi& E) {
;     ...
;     PG8_WAIT_V(0);
;     if constexpr (!ALIGN_EPI) { if (wr == 0) PG8_BAR; }
;     PG8_BAR;
; __device__ __forceinline__ void xcd_barrier(const XcdBarrier& b) {
;     asm volatile("s_waitcnt vmcnt(0)" ::: "memory");
;     __syncthreads();
;     if (threadIdx.x == 0) {
;         unsigned* bar = b.bar;
;         __builtin_amdgcn_s_waitcnt(0);
;         unsigned nloc = b.st[0], nx = b.st[1];
.LBB0_929:
	s_setprio 0
	s_waitcnt vmcnt(0)
	s_barrier
	s_mov_b64 s[2:3], exec
	v_readlane_b32 s6, v253, 0
	v_readlane_b32 s7, v253, 1
	s_and_b64 s[6:7], s[2:3], s[6:7]
	s_movk_i32 s22, 0x4000
	s_mov_b32 s1, 0x26000
	v_readlane_b32 s96, v254, 60
	s_mov_b64 exec, s[6:7]
	s_cbranch_execnz .LBB0_930
	s_getpc_b64 s[98:99]

; __device__ __forceinline__ unsigned xb_ld(unsigned* p)              { return __hip_atomic_load(p, __ATOMIC_RELAXED, __HIP_MEMORY_SCOPE_AGENT); }
; #define XB_SPIN(cond, bar) do { unsigned _sp = 0; while (cond) { __builtin_amdgcn_s_sleep(1); \
;     if ((++_sp & 255u) == 0u) { if (xb_ld(&(bar)[XB_TMO])) break; if (_sp > XB_SPIN_CAP) { atomicAdd(&(bar)[XB_TMO], 1u); break; } } } } while (0)
; __device__ __forceinline__ void xcd_barrier(const XcdBarrier& b) {
;     ...
;             else XB_SPIN(xb_ld(&bar[XB_TOPGEN]) == tg, bar);
.LBB0_971:
	s_cmp_lt_u32 s20, 0x40001
	s_mov_b64 s[16:17], 0
	s_cselect_b64 s[18:19], -1, 0
	s_and_b64 vcc, exec, s[18:19]
	s_cbranch_vccnz .LBB0_968
	s_branch .LBB0_965
	s_nop 0
	s_nop 0
	s_nop 0
	s_nop 0
	s_nop 0
	s_nop 0
	s_nop 0
	s_nop 0
